# IEEE 1/x expansions replaced by v_rcp_f32 + one Newton step (f32), mqk conv-weight loads prefetched one group ahead
# speedup vs baseline: 1.0344x; 1.0084x over previous
; __device__ __forceinline__ unsigned xb_ld(unsigned* p)              { return __hip_atomic_load(p, __ATOMIC_RELAXED, __HIP_MEMORY_SCOPE_AGENT); }
; __device__ __forceinline__ void xcd_barrier_complete(unsigned* bar, unsigned x, unsigned& nloc, unsigned& nx) {
;     const unsigned G = gridDim.x * gridDim.y * gridDim.z;
;     unsigned sum, cnt, mine, sp = 0u;
;     for (;;) {
;         sum = 0u; cnt = 0u; mine = 0u;
; #pragma unroll
;         for (unsigned j = 0; j < 16; ++j) { const unsigned c = xb_ld(&bar[XB_XCNT(j)]); sum += c; cnt += (c > 0u) ? 1u : 0u; mine = (j == x) ? c : mine; }
;         if (sum == G) break;
;         __builtin_amdgcn_s_sleep(1);
;         if ((++sp & 255u) == 0u) { if (xb_ld(&bar[XB_TMO])) break; if (sp > XB_SPIN_CAP) { atomicAdd(&bar[XB_TMO], 1u); break; } }
;     }
;     nloc = mine > 0u ? mine : 1u; nx = cnt > 0u ? cnt : 1u;
; }
; __global__ void __launch_bounds__(512, 2) mega(Params P0) {
;     ...
;     XcdBarrier xb = xcd_barrier_post((unsigned*)((unsigned char*)P0.out + DO_BAR), xst);
;     typedef const Params __attribute__((address_space(4))) * KArgP;
;     const int ph_lo = P0.ph_lo, ph_hi = P0.ph_hi;
;     for (int ph = ph_lo; ph <= ph_hi; ++ph) {
;         int tid = threadIdx.x; asm volatile("" : "+v"(tid));
;         int G = gridDim.x, bid = blockIdx.x; asm volatile("" : "+s"(G)); asm volatile("" : "+s"(bid));
;         KArgP kp = (KArgP)__builtin_amdgcn_kernarg_segment_ptr(); asm volatile("" : "+s"(kp));
.LBB0_6:
	s_cmp_lt_i32 s80, 0
	s_cselect_b64 s[4:5], -1, 0
	v_writelane_b32 v253, s4, 4
	v_lshrrev_b32_e32 v1, 20, v0
	v_writelane_b32 v254, s78, 0
	v_writelane_b32 v253, s5, 5
	s_add_u32 s4, s12, 0x6380200
	s_addc_u32 s5, s13, 0
	s_add_u32 s18, s12, 0x6380400
	s_addc_u32 s19, s13, 0
	s_add_u32 s20, s12, 0x6380500
	s_addc_u32 s21, s13, 0
	s_add_u32 s22, s12, 0x6380600
	s_addc_u32 s23, s13, 0
	s_add_u32 s34, s12, 0x6380700
	s_addc_u32 s35, s13, 0
	s_add_u32 s36, s12, 0x6380800
	s_addc_u32 s37, s13, 0
	s_add_u32 s76, s12, 0x6380900
	s_addc_u32 s77, s13, 0
	s_add_u32 s84, s12, 0x6380a00
	s_addc_u32 s85, s13, 0
	s_add_u32 s56, s12, 0x6380b00
	s_addc_u32 s57, s13, 0
	s_add_u32 s86, s12, 0x6380c00
	s_addc_u32 s87, s13, 0
	s_add_u32 s90, s12, 0x6380d00
	s_addc_u32 s91, s13, 0
	s_add_u32 s40, s12, 0x6380e00
	s_addc_u32 s41, s13, 0
	s_add_u32 s42, s12, 0x6380f00
	s_addc_u32 s43, s13, 0
	s_add_u32 s44, s12, 0x6381000
	s_addc_u32 s45, s13, 0
	s_add_u32 s46, s12, 0x6381100
	s_addc_u32 s47, s13, 0
	s_add_u32 s48, s12, 0x6381200
	s_addc_u32 s49, s13, 0
	s_add_u32 s50, s12, 0x6381300
	s_addc_u32 s51, s13, 0
	v_writelane_b32 v253, s4, 6
	s_cmp_eq_u32 s8, 15
	v_writelane_b32 v254, s79, 1
	v_writelane_b32 v253, s5, 7
	s_cselect_b64 s[4:5], -1, 0
	v_writelane_b32 v253, s4, 8
	s_cmp_eq_u32 s8, 14
	v_writelane_b32 v254, s18, 2
	v_writelane_b32 v253, s5, 9
	s_cselect_b64 s[4:5], -1, 0
	v_writelane_b32 v253, s4, 10
	s_cmp_eq_u32 s8, 13
	v_writelane_b32 v254, s19, 3
	v_writelane_b32 v253, s5, 11
	s_cselect_b64 s[4:5], -1, 0
	v_writelane_b32 v253, s4, 12
	s_cmp_eq_u32 s8, 12
	v_writelane_b32 v254, s20, 4
	v_writelane_b32 v253, s5, 13
	s_cselect_b64 s[4:5], -1, 0
	v_writelane_b32 v253, s4, 14
	s_cmp_eq_u32 s8, 11
	v_writelane_b32 v254, s21, 5
	v_writelane_b32 v253, s5, 15
	s_cselect_b64 s[4:5], -1, 0
	v_writelane_b32 v253, s4, 16
	s_cmp_eq_u32 s8, 10
	v_writelane_b32 v254, s22, 6
	v_writelane_b32 v253, s5, 17
	s_cselect_b64 s[4:5], -1, 0
	v_writelane_b32 v253, s4, 18
	s_cmp_eq_u32 s8, 9
	v_writelane_b32 v254, s23, 7
	v_writelane_b32 v253, s5, 19
	s_cselect_b64 s[4:5], -1, 0
	v_writelane_b32 v253, s4, 20
	s_cmp_eq_u32 s8, 8
	v_writelane_b32 v254, s34, 8
	v_writelane_b32 v253, s5, 21
	s_cselect_b64 s[4:5], -1, 0
	v_writelane_b32 v253, s4, 22
	s_cmp_eq_u32 s8, 7
	v_writelane_b32 v254, s35, 9
	v_writelane_b32 v253, s5, 23
	s_cselect_b64 s[4:5], -1, 0
	v_writelane_b32 v253, s4, 24
	s_cmp_eq_u32 s8, 6
	v_writelane_b32 v254, s36, 10
	v_writelane_b32 v253, s5, 25
	s_cselect_b64 s[4:5], -1, 0
	v_writelane_b32 v253, s4, 26
	s_cmp_eq_u32 s8, 5
	v_writelane_b32 v254, s37, 11
	v_writelane_b32 v253, s5, 27
	s_cselect_b64 s[4:5], -1, 0
	v_writelane_b32 v253, s4, 28
	s_cmp_eq_u32 s8, 4
	v_writelane_b32 v254, s76, 12
	v_writelane_b32 v253, s5, 29
	s_cselect_b64 s[4:5], -1, 0
	v_writelane_b32 v253, s4, 30
	s_cmp_eq_u32 s8, 3
	v_writelane_b32 v254, s77, 13
	v_writelane_b32 v253, s5, 31
	s_cselect_b64 s[4:5], -1, 0
	v_writelane_b32 v253, s4, 32
	s_cmp_eq_u32 s8, 2
	v_lshrrev_b32_e32 v0, 10, v0
	v_writelane_b32 v253, s5, 33
	s_cselect_b64 s[4:5], -1, 0
	v_writelane_b32 v253, s4, 34
	s_cmp_eq_u32 s8, 1
	v_writelane_b32 v254, s84, 14
	v_writelane_b32 v253, s5, 35
	s_cselect_b64 s[4:5], -1, 0
	v_writelane_b32 v253, s4, 36
	s_cmp_eq_u32 s8, 0
	v_or_b32_e32 v0, v0, v1
	v_writelane_b32 v253, s5, 37
	s_cselect_b64 s[4:5], -1, 0
	v_writelane_b32 v253, s4, 38
	v_writelane_b32 v254, s85, 15
	v_writelane_b32 v254, s56, 16
	v_writelane_b32 v253, s5, 39
	s_lshl_b32 s4, s8, 8
	s_add_u32 s2, s2, s4
	s_addc_u32 s3, s3, 0
	s_add_u32 s4, s2, 0x1400
	s_addc_u32 s5, s3, 0
	v_writelane_b32 v253, s4, 40
	s_add_u32 s2, s2, 0x2400
	s_addc_u32 s3, s3, 0
	v_writelane_b32 v253, s5, 41
	v_writelane_b32 v253, s2, 42
	v_writelane_b32 v254, s57, 17
	v_writelane_b32 v254, s86, 18
	v_writelane_b32 v253, s3, 43
	s_add_u32 s2, s12, 0x6383400
	s_addc_u32 s3, s13, 0
	v_writelane_b32 v253, s2, 44
	s_add_u32 s0, s12, 0x6383500
	s_addc_u32 s1, s13, 0
	v_writelane_b32 v253, s3, 45
	v_writelane_b32 v253, s0, 46
	v_writelane_b32 v254, s87, 19
	v_writelane_b32 v254, s90, 20
	v_writelane_b32 v253, s1, 47
	s_movk_i32 s0, 0x3ff
	v_readlane_b32 s2, v253, 0
	v_readlane_b32 s3, v253, 1
	s_load_dword s1, s[2:3], 0xe0
	v_and_or_b32 v0, v0, s0, v162
	s_mul_i32 s0, s83, s82
	v_writelane_b32 v254, s91, 21
	v_writelane_b32 v254, s40, 22
	s_waitcnt lgkmcnt(0)
	s_mul_i32 s0, s0, s1
	v_writelane_b32 v253, s0, 48
	s_add_i32 s0, 0, 0x18400
	v_writelane_b32 v253, s0, 49
	s_add_i32 s0, 0, 0x1a400
	v_writelane_b32 v253, s0, 50
	s_add_i32 s0, 0, 0x1c400
	v_writelane_b32 v253, s0, 51
	s_add_i32 s0, 0, 0x1e400
	v_writelane_b32 v253, s0, 52
	s_add_i32 s0, 0, 0x10400
	v_writelane_b32 v253, s0, 53
	s_add_i32 s0, 0, 0x12400
	v_writelane_b32 v254, s41, 23
	v_writelane_b32 v253, s0, 54
	s_add_i32 s0, 0, 0x14400
	v_writelane_b32 v254, s42, 24
	v_writelane_b32 v253, s0, 55
	s_add_i32 s0, 0, 0x16400
	v_writelane_b32 v254, s43, 25
	v_writelane_b32 v253, s0, 56
	s_add_i32 s0, 0, 0x25a44
	v_writelane_b32 v254, s44, 26
	v_writelane_b32 v253, s0, 57
	s_add_i32 s0, 0, 0x25a78
	v_writelane_b32 v254, s45, 27
	v_writelane_b32 v253, s0, 58
	s_add_i32 s0, 0, 0x25ff0
	v_writelane_b32 v254, s46, 28
	v_writelane_b32 v253, s0, 59
	s_add_i32 s0, 0, 0x25ff4
	v_writelane_b32 v254, s47, 29
	v_mbcnt_lo_u32_b32 v2, -1, 0
	v_writelane_b32 v253, s0, 60
	v_cmp_eq_u32_e64 s[2:3], 0, v0
	v_writelane_b32 v254, s48, 30
	v_mbcnt_hi_u32_b32 v203, -1, v2
	s_nop 1
	v_writelane_b32 v253, s2, 61
	v_writelane_b32 v254, s49, 31
	v_mov_b32_e32 v1, 0
	v_bfrev_b32_e32 v2, 0.5
	v_writelane_b32 v253, s3, 62
	v_writelane_b32 v254, s50, 32
	v_mov_b32_e32 v163, v1
	v_mov_b32_e32 v208, 0x3ecc95a3
	v_mov_b32_e32 v209, 1.0
	v_mov_b32_e32 v210, 0x358637bd
	v_mov_b32_e32 v168, 0x3f317218
	v_mov_b32_e32 v212, 0x7f800000
	v_mov_b32_e32 v213, 0x7fc00000
	v_mov_b32_e32 v214, 0xff800000
	v_mov_b32_e32 v215, 0x3f80
	v_lshl_or_b32 v216, v203, 2, v2
	v_mov_b32_e32 v217, 0xff61b1e6
	v_mov_b32_e32 v218, 0x3db504f3
	v_not_b32_e32 v221, 31
	s_movk_i32 s27, 0xc0
	s_movk_i32 s83, 0x2000
	s_movk_i32 s33, 0x60
	s_movk_i32 s25, 0x80
	s_movk_i32 s1, 0x90
	s_movk_i32 s31, 0xa0
	s_movk_i32 s97, 0xe0
	s_add_i32 s29, 0, 0x22a00
	s_mov_b32 s30, 0x800000
	s_movk_i32 s95, 0x2c00
	s_mov_b32 s39, 0
	s_mov_b64 s[58:59], 0x80
	v_writelane_b32 v253, s88, 63
	v_writelane_b32 v254, s51, 33
	s_branch .LBB0_10

; #define TRFRAGX(img, ks) trfrag_(lds, (img) + 32u * (32u * (ks)) + FB.txb, (img) + 32u * (32u * (ks) + 4u) + FB.txb)
; #define MFMA16(a, b, c) __builtin_amdgcn_mfma_f32_16x16x32_bf16((a), (b), (c), 0, 0, 0)
; __device__ void mix_sweep(const Params& P, LAS unsigned char* lds, int tok0, int pos0, int seqlen, int hd, int dir, bool state_only, bool final_pass,
;                           f32x4 (&Cacc)[9], float& m_state, float& aseg_sum, float lgam) {
;     ...
;             if (is_m) { f32x4 a = Cacc[8] * decay;
; #pragma unroll
;                 for (int ks = 0; ks < 4; ++ks) { const bf16x8 vx = TRFRAGX(IMG_VX, ks); O[8] = MFMA16(vx, pf[ks], O[8]); a = MFMA16(vx, kf[ks], a); }
;                 Cacc[8] = a; }
;             __builtin_amdgcn_s_setprio(0);
;             float hs = 1.0f;
;             if (is_m) { const float den = __shfl(O[8][0], fr); hs = 1.0f / fmaxf(fabsf(den), vemt[irow]); }
.LBB0_365:
	s_andn2_b64 vcc, exec, s[16:17]
	v_mov_b32_e32 v0, 1.0
	s_cbranch_vccnz .LBB0_367
	v_mov_b32_e32 v140, v158
	v_mov_b32_e32 v141, v158
	v_pk_mul_f32 v[74:75], v[74:75], v[140:141]
	v_mov_b32_e32 v140, v156
	v_mov_b32_e32 v141, v156
	v_add_u32_e32 v0, 0x20000, v167
	v_pk_mul_f32 v[38:39], v[38:39], v[140:141]
	ds_read_b64_tr_b16 v[140:141], v0
	v_add_u32_e32 v0, 0x20080, v167
	ds_read_b64_tr_b16 v[142:143], v0
	v_mov_b32_e32 v159, v158
	v_pk_mul_f32 v[72:73], v[72:73], v[158:159]
	v_add_u32_e32 v0, 0x20400, v167
	v_mov_b32_e32 v157, v156
	s_waitcnt lgkmcnt(0)
	v_mfma_f32_16x16x32_bf16 v[72:75], v[140:143], v[100:103], v[72:75]
	ds_read_b64_tr_b16 v[100:101], v0
	v_add_u32_e32 v0, 0x20480, v167
	ds_read_b64_tr_b16 v[102:103], v0
	v_add_u32_e32 v0, 0x20800, v167
	s_waitcnt lgkmcnt(0)
	v_mfma_f32_16x16x32_bf16 v[72:75], v[100:103], v[88:91], v[72:75]
	ds_read_b64_tr_b16 v[88:89], v0
	v_add_u32_e32 v0, 0x20880, v167
	ds_read_b64_tr_b16 v[90:91], v0
	v_pk_mul_f32 v[36:37], v[36:37], v[156:157]
	v_add_u32_e32 v0, 0x20c00, v167
	s_waitcnt lgkmcnt(0)
	v_mfma_f32_16x16x32_bf16 v[72:75], v[88:91], v[84:87], v[72:75]
	ds_read_b64_tr_b16 v[84:85], v0
	v_add_u32_e32 v0, 0x20c80, v167
	ds_read_b64_tr_b16 v[86:87], v0
	v_mfma_f32_16x16x32_bf16 v[36:39], v[140:143], v[108:111], v[36:39]
	v_mfma_f32_16x16x32_bf16 v[36:39], v[100:103], v[92:95], v[36:39]
	v_mfma_f32_16x16x32_bf16 v[36:39], v[88:91], v[104:107], v[36:39]
	s_waitcnt lgkmcnt(0)
	v_mfma_f32_16x16x32_bf16 v[36:39], v[84:87], v[96:99], v[36:39]
	v_mfma_f32_16x16x32_bf16 v[72:75], v[84:87], v[76:79], v[72:75]
	s_setprio 0
	v_and_or_b32 v0, v203, 64, v169
	v_lshlrev_b32_e32 v0, 2, v0
	s_nop 4
	v_add_u32_e32 v73, 0x22800, v220
	ds_read_b32 v73, v73
	ds_bpermute_b32 v0, v0, v72
	s_waitcnt lgkmcnt(1)
	v_max_f32_e32 v72, v73, v73
	s_waitcnt lgkmcnt(0)
	v_max_f32_e64 v0, |v0|, |v0|
	v_max_f32_e32 v0, v0, v72
	v_rcp_f32_e32 v72, v0
	s_nop 0
	v_fma_f32 v75, -v0, v72, 1.0
	v_fma_f32 v0, v75, v72, v72

; __device__ __forceinline__ float bf_lo(unsigned w) { return __uint_as_float(w << 16); }
; __device__ __forceinline__ float bf_hi(unsigned w) { return __uint_as_float(w & 0xffff0000u); }
; __device__ void mix_sweep(const Params& P, LAS unsigned char* lds, int tok0, int pos0, int seqlen, int hd, int dir, bool state_only, bool final_pass,
;                           f32x4 (&Cacc)[9], float& m_state, float& aseg_sum, float lgam) {
;     ...
;                 float sum = 0.f;
;                 const bf16_t* grow = proj + (size_t)(tok + irow) * NPROJ + gcol + 4 * fg;
;                 u32x2 hbv[8], gvv[8];
; #pragma unroll
;                 for (int nt = 0; nt < 8; ++nt) { hbv[nt] = *(const u32x2*)(mrow + 16 * nt); gvv[nt] = *(const u32x2*)(grow + 16 * nt); }
;                 __builtin_amdgcn_sched_barrier(0);
; #pragma unroll
;                 for (int nt = 0; nt < 8; ++nt) { const u32x2 hb = hbv[nt];
;                     O[nt][0] = O[nt][0] * hs + bf_lo(hb.x); O[nt][1] = O[nt][1] * hs + bf_hi(hb.x); O[nt][2] = O[nt][2] * hs + bf_lo(hb.y); O[nt][3] = O[nt][3] * hs + bf_hi(hb.y);
;                     sum += O[nt][0] + O[nt][1] + O[nt][2] + O[nt][3]; }
;                 sum += __shfl_xor(sum, 16); sum += __shfl_xor(sum, 32);
;                 const float mu = sum * (1.0f / 128.0f); float sq = 0.f;
; #pragma unroll
;                 for (int nt = 0; nt < 8; ++nt)
; #pragma unroll
;                     for (int e = 0; e < 4; ++e) { const float d = O[nt][e] - mu; sq += d * d; }
;                 sq += __shfl_xor(sq, 16); sq += __shfl_xor(sq, 32);
;                 const float rs = rsqrtf(sq * (1.0f / 128.0f) + 1e-5f);
.LBB0_369:
	s_andn2_b64 vcc, exec, s[16:17]
	s_cbranch_vccnz .LBB0_97
	v_lshlrev_b64 v[74:75], 13, v[74:75]
	v_lshl_add_u64 v[74:75], v[152:153], 0, v[74:75]
	global_load_dwordx2 v[88:89], v[72:73], off
	global_load_dwordx2 v[92:93], v[72:73], off offset:32
	global_load_dwordx2 v[96:97], v[72:73], off offset:64
	global_load_dwordx2 v[98:99], v[72:73], off offset:96
	global_load_dwordx2 v[148:149], v[74:75], off
	global_load_dwordx2 v[146:147], v[74:75], off offset:32
	global_load_dwordx2 v[110:111], v[74:75], off offset:64
	global_load_dwordx2 v[104:105], v[74:75], off offset:96
	global_load_dwordx2 v[150:151], v[72:73], off offset:128
	global_load_dwordx2 v[156:157], v[72:73], off offset:160
	global_load_dwordx2 v[158:159], v[72:73], off offset:192
	global_load_dwordx2 v[170:171], v[72:73], off offset:224
	global_load_dwordx2 v[94:95], v[74:75], off offset:128
	global_load_dwordx2 v[84:85], v[74:75], off offset:160
	global_load_dwordx2 v[76:77], v[74:75], off offset:192
	s_nop 0
	global_load_dwordx2 v[74:75], v[74:75], off offset:224
	v_mov_b32_e32 v100, v80
	v_mov_b32_e32 v101, v112
	s_waitcnt vmcnt(14)
	v_lshlrev_b32_e32 v103, 16, v92
	v_lshlrev_b32_e32 v102, 16, v88
	v_mov_b32_e32 v112, v81
	v_and_b32_e32 v81, 0xffff0000, v92
	v_and_b32_e32 v80, 0xffff0000, v88
	v_pk_fma_f32 v[144:145], v[100:101], v[0:1], v[102:103] op_sel_hi:[1,0,1]
	v_pk_fma_f32 v[142:143], v[112:113], v[0:1], v[80:81] op_sel_hi:[1,0,1]
	v_mov_b32_e32 v80, v82
	v_mov_b32_e32 v81, v114
	v_lshlrev_b32_e32 v101, 16, v93
	v_lshlrev_b32_e32 v100, 16, v89
	v_pk_fma_f32 v[140:141], v[80:81], v[0:1], v[100:101] op_sel_hi:[1,0,1]
	v_mov_b32_e32 v114, v83
	v_and_b32_e32 v81, 0xffff0000, v93
	v_and_b32_e32 v80, 0xffff0000, v89
	v_pk_fma_f32 v[114:115], v[114:115], v[0:1], v[80:81] op_sel_hi:[1,0,1]
	v_pk_add_f32 v[80:81], v[144:145], v[142:143]
	s_waitcnt vmcnt(12)
	v_lshlrev_b32_e32 v90, 16, v98
	v_pk_add_f32 v[80:81], v[140:141], v[80:81]
	v_and_b32_e32 v106, 0xffff0000, v98
	v_pk_add_f32 v[80:81], v[114:115], v[80:81]
	v_fmac_f32_e32 v90, v128, v0
	v_add_f32_e32 v80, 0, v80
	v_add_f32_e32 v86, v80, v81
	v_lshlrev_b32_e32 v80, 16, v96
	v_and_b32_e32 v81, 0xffff0000, v96
	v_pk_fma_f32 v[112:113], v[120:121], v[0:1], v[80:81] op_sel_hi:[1,0,1]
	v_and_b32_e32 v81, 0xffff0000, v97
	v_lshlrev_b32_e32 v80, 16, v97
	v_pk_fma_f32 v[108:109], v[122:123], v[0:1], v[80:81] op_sel_hi:[1,0,1]
	v_pk_add_f32 v[80:81], v[112:113], v[112:113] op_sel:[0,1] op_sel_hi:[1,0]
	v_fmac_f32_e32 v106, v129, v0
	v_pk_add_f32 v[80:81], v[108:109], v[80:81]
	s_waitcnt vmcnt(7)
	v_and_b32_e32 v107, 0xffff0000, v150
	v_and_b32_e32 v92, 0xffff0000, v151
	v_mov_b32_e32 v82, v130
	v_mov_b32_e32 v83, v136
	v_lshlrev_b32_e32 v89, 16, v150
	v_lshlrev_b32_e32 v88, 16, v99
	v_pk_add_f32 v[80:81], v[108:109], v[80:81] op_sel:[1,0] op_sel_hi:[0,1]
	v_pk_fma_f32 v[102:103], v[82:83], v[0:1], v[88:89] op_sel_hi:[1,0,1]
	v_pk_add_f32 v[100:101], v[90:91], v[106:107]
	v_pk_mov_b32 v[82:83], v[130:131], v[138:139] op_sel:[1,0]
	v_and_b32_e32 v88, 0xffff0000, v99
	v_lshlrev_b32_e32 v89, 16, v151
	v_mov_b32_e32 v81, v92
	v_pk_fma_f32 v[96:97], v[82:83], v[0:1], v[88:89] op_sel_hi:[1,0,1]
	v_pk_add_f32 v[92:93], v[86:87], v[80:81]
	v_pk_add_f32 v[80:81], v[102:103], v[100:101]
	s_waitcnt vmcnt(4)
	v_and_b32_e32 v91, 0xffff0000, v171
	v_pk_add_f32 v[80:81], v[96:97], v[80:81]
	v_mov_b32_e32 v120, v126
	v_pk_add_f32 v[82:83], v[92:93], v[80:81]
	v_lshlrev_b32_e32 v80, 16, v156
	v_and_b32_e32 v81, 0xffff0000, v156
	v_pk_fma_f32 v[86:87], v[132:133], v[0:1], v[80:81] op_sel_hi:[1,0,1]
	v_and_b32_e32 v81, 0xffff0000, v157
	v_lshlrev_b32_e32 v80, 16, v157
	v_pk_fma_f32 v[80:81], v[134:135], v[0:1], v[80:81] op_sel_hi:[1,0,1]
	v_pk_add_f32 v[88:89], v[86:87], v[86:87] op_sel:[0,1] op_sel_hi:[1,0]
	v_pk_add_f32 v[82:83], v[82:83], v[82:83] op_sel:[0,1] op_sel_hi:[1,0]
	v_pk_add_f32 v[88:89], v[80:81], v[88:89]
	v_mov_b32_e32 v121, v116
	v_pk_add_f32 v[88:89], v[80:81], v[88:89] op_sel:[1,0] op_sel_hi:[0,1]
	v_lshlrev_b32_e32 v117, 16, v170
	v_lshlrev_b32_e32 v116, 16, v159
	v_mov_b32_e32 v83, v78
	v_mov_b32_e32 v89, v91
	v_pk_fma_f32 v[120:121], v[120:121], v[0:1], v[116:117] op_sel_hi:[1,0,1]
	v_pk_mov_b32 v[116:117], v[126:127], v[118:119] op_sel:[1,0]
	v_pk_add_f32 v[126:127], v[82:83], v[88:89]
	v_and_b32_e32 v82, 64, v203
	v_xor_b32_e32 v78, 16, v203
	v_add_u32_e32 v91, 64, v82
	v_cmp_lt_i32_e32 vcc, v78, v91
	v_and_b32_e32 v83, 0xffff0000, v158
	v_lshlrev_b32_e32 v82, 16, v158
	v_cndmask_b32_e32 v78, v203, v78, vcc
	v_pk_fma_f32 v[82:83], v[124:125], v[0:1], v[82:83] op_sel_hi:[1,0,1]
	v_and_b32_e32 v99, 0xffff0000, v170
	v_lshlrev_b32_e32 v100, 2, v78
	v_mov_b32_e32 v78, v82
	v_mov_b32_e32 v98, v83
	v_and_b32_e32 v118, 0xffff0000, v159
	v_lshlrev_b32_e32 v119, 16, v171
	v_pk_add_f32 v[78:79], v[78:79], v[98:99]
	v_pk_fma_f32 v[122:123], v[116:117], v[0:1], v[118:119] op_sel_hi:[1,0,1]
	v_pk_add_f32 v[88:89], v[120:121], v[78:79]
	global_load_dwordx4 v[116:119], v[154:155], off
	v_pk_add_f32 v[88:89], v[122:123], v[88:89]
	s_nop 0
	v_pk_add_f32 v[88:89], v[126:127], v[88:89]
	s_nop 0
	v_add_f32_e32 v0, v88, v89
	ds_bpermute_b32 v78, v100, v0
	v_xor_b32_e32 v88, 32, v203
	v_cmp_lt_i32_e32 vcc, v88, v91
	s_waitcnt lgkmcnt(0)
	v_add_f32_e32 v0, v0, v78
	v_cndmask_b32_e32 v88, v203, v88, vcc
	v_lshlrev_b32_e32 v107, 2, v88
	ds_bpermute_b32 v78, v107, v0
	s_waitcnt lgkmcnt(0)
; __device__ __forceinline__ unsigned cvt_pk_bf16(float lo, float hi) { unsigned r; asm volatile("v_cvt_pk_bf16_f32 %0, %1, %2" : "=v"(r) : "v"(lo), "v"(hi)); return r; }
; __device__ __forceinline__ float bf_lo(unsigned w) { return __uint_as_float(w << 16); }
; __device__ __forceinline__ float bf_hi(unsigned w) { return __uint_as_float(w & 0xffff0000u); }
; __device__ __forceinline__ float sigmoidf_(float x) { return 1.0f / (1.0f + __expf(-x)); }
; __device__ void mix_sweep(const Params& P, LAS unsigned char* lds, int tok0, int pos0, int seqlen, int hd, int dir, bool state_only, bool final_pass,
;                           f32x4 (&Cacc)[9], float& m_state, float& aseg_sum, float lgam) {
;     ...
;                 const float mu = sum * (1.0f / 128.0f); float sq = 0.f;
; #pragma unroll
;                 for (int nt = 0; nt < 8; ++nt)
; #pragma unroll
;                     for (int e = 0; e < 4; ++e) { const float d = O[nt][e] - mu; sq += d * d; }
;                 sq += __shfl_xor(sq, 16); sq += __shfl_xor(sq, 32);
;                 const float rs = rsqrtf(sq * (1.0f / 128.0f) + 1e-5f);
; #pragma unroll
;                 for (int nt = 0; nt < 8; ++nt) { const u32x2 gv = gvv[nt]; const f32x4 gw = *(const f32x4*)(gnw + 16 * nt + 4 * fg);
;                     float gt[4] = {bf_lo(gv.x), bf_hi(gv.x), bf_lo(gv.y), bf_hi(gv.y)}; float y[4];
; #pragma unroll
;                     for (int e = 0; e < 4; ++e) { const float sg = sigmoidf_(gt[e]); const float gate = is_m ? sg : gt[e] * sg; y[e] = (O[nt][e] - mu) * rs * gw[e] * gate; }
;                     u32x2 v; v.x = cvt_pk_bf16(y[0], y[1]); v.y = cvt_pk_bf16(y[2], y[3]); *(u32x2*)(mrow + 16 * nt) = v; }
	v_add_f32_e32 v78, v0, v78
	v_fmamk_f32 v125, v78, 0xbc000000, v142
	v_fmamk_f32 v124, v78, 0xbc000000, v144
	v_mul_f32_e32 v88, v125, v125
	v_fmac_f32_e32 v88, v124, v124
	v_fmamk_f32 v126, v78, 0xbc000000, v140
	v_fmac_f32_e32 v88, v126, v126
	v_fmamk_f32 v114, v78, 0xbc000000, v114
	v_fmac_f32_e32 v88, v114, v114
	v_fmac_f32_e32 v145, 0xbc000000, v78
	v_fmac_f32_e32 v88, v145, v145
	v_fmac_f32_e32 v143, 0xbc000000, v78
	v_fmac_f32_e32 v88, v143, v143
	v_fmac_f32_e32 v141, 0xbc000000, v78
	v_fmac_f32_e32 v88, v141, v141
	v_fmac_f32_e32 v115, 0xbc000000, v78
	v_fmac_f32_e32 v88, v115, v115
	v_fmamk_f32 v112, v78, 0xbc000000, v112
	v_fmac_f32_e32 v88, v112, v112
	v_fmac_f32_e32 v113, 0xbc000000, v78
	v_fmac_f32_e32 v88, v113, v113
	v_fmamk_f32 v108, v78, 0xbc000000, v108
	v_fmac_f32_e32 v88, v108, v108
	v_fmac_f32_e32 v109, 0xbc000000, v78
	v_fmac_f32_e32 v88, v109, v109
	v_fmac_f32_e32 v90, 0xbc000000, v78
	v_fmac_f32_e32 v88, v90, v90
	v_fmac_f32_e32 v106, 0xbc000000, v78
	v_fmac_f32_e32 v88, v106, v106
	v_fmamk_f32 v92, v78, 0xbc000000, v102
	v_fmac_f32_e32 v88, v92, v92
	v_fmamk_f32 v91, v78, 0xbc000000, v96
	v_fmac_f32_e32 v88, v91, v91
	v_fmac_f32_e32 v103, 0xbc000000, v78
	v_fmac_f32_e32 v88, v103, v103
	v_fmac_f32_e32 v101, 0xbc000000, v78
	v_fmac_f32_e32 v88, v101, v101
	v_fmac_f32_e32 v97, 0xbc000000, v78
	v_fmac_f32_e32 v88, v97, v97
	v_fmac_f32_e32 v93, 0xbc000000, v78
	v_fmac_f32_e32 v88, v93, v93
	v_fmamk_f32 v86, v78, 0xbc000000, v86
	v_fmac_f32_e32 v88, v86, v86
	v_fmac_f32_e32 v87, 0xbc000000, v78
	v_mul_f32_e32 v0, 0x3c000000, v78
	v_fmac_f32_e32 v88, v87, v87
	v_fmamk_f32 v80, v78, 0xbc000000, v80
	v_fmac_f32_e32 v88, v80, v80
	v_fmac_f32_e32 v81, 0xbc000000, v78
	v_pk_add_f32 v[98:99], v[82:83], v[0:1] op_sel_hi:[1,0] neg_lo:[0,1] neg_hi:[0,1]
	v_fmac_f32_e32 v88, v81, v81
	v_pk_mul_f32 v[82:83], v[98:99], v[98:99]
	s_nop 0
	v_add_f32_e32 v78, v82, v88
	v_add_f32_e32 v78, v83, v78
	v_mov_b32_e32 v82, v122
	v_mov_b32_e32 v83, v120
	v_pk_add_f32 v[88:89], v[82:83], v[0:1] op_sel_hi:[1,0] neg_lo:[0,1] neg_hi:[0,1]
	v_mov_b32_e32 v120, v79
	v_pk_mul_f32 v[82:83], v[88:89], v[88:89]
	v_mov_b32_e32 v122, v127
	v_add_f32_e32 v78, v83, v78
	v_add_f32_e32 v96, v82, v78
	v_pk_add_f32 v[82:83], v[120:121], v[0:1] op_sel_hi:[1,0] neg_lo:[0,1] neg_hi:[0,1]
	s_nop 0
	v_pk_mul_f32 v[78:79], v[82:83], v[82:83]
	s_nop 0
	v_add_f32_e32 v79, v79, v96
	v_add_f32_e32 v96, v78, v79
	v_pk_add_f32 v[78:79], v[122:123], v[0:1] op_sel_hi:[1,0] neg_lo:[0,1] neg_hi:[0,1]
	v_and_b32_e32 v122, 0xffff0000, v149
	v_pk_mul_f32 v[120:121], v[78:79], v[78:79]
	s_nop 0
	v_add_f32_e32 v0, v121, v96
	v_add_f32_e32 v0, v120, v0
	ds_bpermute_b32 v96, v100, v0
	v_and_b32_e32 v120, 0xffff0000, v148
	v_lshlrev_b32_e32 v121, 16, v149
	s_waitcnt lgkmcnt(0)
	v_add_f32_e32 v0, v0, v96
	ds_bpermute_b32 v96, v107, v0
	s_waitcnt lgkmcnt(0)
	v_add_f32_e32 v0, v0, v96
	v_mov_b32_e32 v96, 0x3727c5ac
	v_fmamk_f32 v0, v0, 0x3c000000, v96
	v_mul_f32_e32 v96, 0x4b800000, v0
	v_cmp_gt_f32_e32 vcc, s30, v0
	s_nop 1
	v_cndmask_b32_e32 v0, v0, v96, vcc
	v_lshlrev_b32_e32 v96, 16, v148
	v_mul_f32_e32 v100, 0xbfb8aa3b, v96
	v_rsq_f32_e32 v0, v0
	v_exp_f32_e32 v100, v100
	v_mul_f32_e32 v102, 0x45800000, v0
	v_add_f32_e32 v100, 1.0, v100
	v_cndmask_b32_e32 v0, v0, v102, vcc
	v_mul_f32_e32 v114, v114, v0
	s_waitcnt vmcnt(0)
	v_mul_f32_e32 v114, v119, v114
	v_mul_f32_e32 v112, v112, v0
	v_mul_f32_e32 v107, 0xbfb8aa3b, v120
	v_exp_f32_e32 v107, v107
	v_rcp_f32_e32 v102, v100
	s_nop 0
	v_fma_f32 v127, -v100, v102, 1.0
	v_fma_f32 v100, v127, v102, v102
	v_mul_f32_e32 v96, v100, v96
	v_cndmask_b32_e64 v96, v96, v100, s[40:41]
	v_add_f32_e32 v100, 1.0, v107
	v_div_scale_f32 v102, s[16:17], v100, v100, 1.0
	v_rcp_f32_e32 v107, v102
	v_mul_f32_e32 v123, v124, v0
	v_mul_f32_e32 v116, v116, v123
	v_mul_f32_e32 v96, v96, v116
	v_fma_f32 v116, -v102, v107, 1.0
	v_fmac_f32_e32 v107, v116, v107
	v_div_scale_f32 v116, vcc, 1.0, v100, 1.0
	v_mul_f32_e32 v123, v116, v107
	v_fma_f32 v124, -v102, v123, v116
	v_fmac_f32_e32 v123, v124, v107
	v_fma_f32 v102, -v102, v123, v116
	v_div_fmas_f32 v102, v102, v107, v123
	v_mul_f32_e32 v107, 0xbfb8aa3b, v121
	v_exp_f32_e32 v107, v107
	v_div_fixup_f32 v100, v102, v100, 1.0
	v_mul_f32_e32 v102, v100, v120
	v_cndmask_b32_e64 v100, v102, v100, s[40:41]
	v_add_f32_e32 v102, 1.0, v107
	v_mul_f32_e32 v120, v125, v0
	v_mul_f32_e32 v117, v117, v120
	v_mul_f32_e32 v100, v100, v117
	v_mul_f32_e32 v116, 0xbfb8aa3b, v122
	v_exp_f32_e32 v116, v116
	v_rcp_f32_e32 v107, v102
	s_nop 0
	v_fma_f32 v123, -v102, v107, 1.0
	v_fma_f32 v102, v123, v107, v107
	v_mul_f32_e32 v107, v102, v121
	v_cndmask_b32_e64 v102, v107, v102, s[40:41]
	v_add_f32_e32 v107, 1.0, v116
	v_mul_f32_e32 v120, v126, v0
	v_mul_f32_e32 v118, v118, v120
	v_mul_f32_e32 v102, v102, v118
	v_rcp_f32_e32 v116, v107
	s_nop 0
	v_fma_f32 v121, -v107, v116, 1.0
	v_fma_f32 v107, v121, v116, v116
	v_mul_f32_e32 v116, v107, v122
	v_cndmask_b32_e64 v107, v116, v107, s[40:41]
	v_mul_f32_e32 v107, v107, v114
	v_cvt_pk_bf16_f32 v116, v96, v100
	v_cvt_pk_bf16_f32 v117, v102, v107
	global_store_dwordx2 v[72:73], v[116:117], off
	global_load_dwordx4 v[116:119], v[154:155], off offset:64
	v_lshlrev_b32_e32 v96, 16, v146
	v_mul_f32_e32 v100, 0xbfb8aa3b, v96
	v_exp_f32_e32 v100, v100
	v_and_b32_e32 v114, 0xffff0000, v146
	v_lshlrev_b32_e32 v120, 16, v147
	v_and_b32_e32 v121, 0xffff0000, v147
	v_add_f32_e32 v100, 1.0, v100
	v_mul_f32_e32 v108, v108, v0
	v_mul_f32_e32 v90, v90, v0
	v_mul_f32_e32 v106, v106, v0
	v_mul_f32_e32 v107, 0xbfb8aa3b, v114
	v_exp_f32_e32 v107, v107
	v_rcp_f32_e32 v102, v100
	s_nop 0
	v_fma_f32 v123, -v100, v102, 1.0
	v_fma_f32 v100, v123, v102, v102
	v_mul_f32_e32 v96, v100, v96
	v_cndmask_b32_e64 v96, v96, v100, s[40:41]
	v_add_f32_e32 v100, 1.0, v107
	v_mul_f32_e32 v122, v145, v0
	v_mul_f32_e32 v92, v92, v0
	v_mul_f32_e32 v91, v91, v0
	v_mul_f32_e32 v101, v101, v0
	v_mul_f32_e32 v97, v97, v0
	v_mul_f32_e32 v93, v93, v0
	v_mul_f32_e32 v86, v86, v0
	v_mul_f32_e32 v87, v87, v0
	v_mul_f32_e32 v80, v80, v0
	v_mul_f32_e32 v81, v81, v0
	v_mul_f32_e32 v89, v89, v0
	v_mul_f32_e32 v83, v83, v0
	v_mul_f32_e32 v82, v82, v0
	v_mul_f32_e32 v79, v79, v0
	s_waitcnt vmcnt(0)
; __device__ __forceinline__ unsigned cvt_pk_bf16(float lo, float hi) { unsigned r; asm volatile("v_cvt_pk_bf16_f32 %0, %1, %2" : "=v"(r) : "v"(lo), "v"(hi)); return r; }
; __device__ __forceinline__ float bf_lo(unsigned w) { return __uint_as_float(w << 16); }
; __device__ __forceinline__ float bf_hi(unsigned w) { return __uint_as_float(w & 0xffff0000u); }
; __device__ __forceinline__ float sigmoidf_(float x) { return 1.0f / (1.0f + __expf(-x)); }
; __device__ void mix_sweep(const Params& P, LAS unsigned char* lds, int tok0, int pos0, int seqlen, int hd, int dir, bool state_only, bool final_pass,
;                           f32x4 (&Cacc)[9], float& m_state, float& aseg_sum, float lgam) {
;     ...
; #pragma unroll
;                 for (int nt = 0; nt < 8; ++nt) { const u32x2 gv = gvv[nt]; const f32x4 gw = *(const f32x4*)(gnw + 16 * nt + 4 * fg);
;                     float gt[4] = {bf_lo(gv.x), bf_hi(gv.x), bf_lo(gv.y), bf_hi(gv.y)}; float y[4];
; #pragma unroll
;                     for (int e = 0; e < 4; ++e) { const float sg = sigmoidf_(gt[e]); const float gate = is_m ? sg : gt[e] * sg; y[e] = (O[nt][e] - mu) * rs * gw[e] * gate; }
;                     u32x2 v; v.x = cvt_pk_bf16(y[0], y[1]); v.y = cvt_pk_bf16(y[2], y[3]); *(u32x2*)(mrow + 16 * nt) = v; }
	v_mul_f32_e32 v116, v116, v122
	v_mul_f32_e32 v96, v96, v116
	v_mul_f32_e32 v107, 0xbfb8aa3b, v120
	v_exp_f32_e32 v107, v107
	v_rcp_f32_e32 v102, v100
	s_nop 0
	v_fma_f32 v123, -v100, v102, 1.0
	v_fma_f32 v100, v123, v102, v102
	v_mul_f32_e32 v102, v100, v114
	v_cndmask_b32_e64 v100, v102, v100, s[40:41]
	v_add_f32_e32 v102, 1.0, v107
	v_mul_f32_e32 v116, v143, v0
	v_mul_f32_e32 v116, v117, v116
	v_mul_f32_e32 v100, v100, v116
	v_mul_f32_e32 v114, 0xbfb8aa3b, v121
	v_exp_f32_e32 v114, v114
	v_rcp_f32_e32 v107, v102
	s_nop 0
	v_fma_f32 v122, -v102, v107, 1.0
	v_fma_f32 v102, v122, v107, v107
	v_mul_f32_e32 v107, v102, v120
	v_cndmask_b32_e64 v102, v107, v102, s[40:41]
	v_add_f32_e32 v107, 1.0, v114
	v_mul_f32_e32 v117, v141, v0
	v_mul_f32_e32 v117, v118, v117
	v_mul_f32_e32 v102, v102, v117
	v_rcp_f32_e32 v114, v107
	s_nop 0
	v_fma_f32 v120, -v107, v114, 1.0
	v_fma_f32 v107, v120, v114, v114
	v_mul_f32_e32 v114, v107, v121
	v_cndmask_b32_e64 v107, v114, v107, s[40:41]
	v_mul_f32_e32 v114, v115, v0
	v_mul_f32_e32 v114, v119, v114
	v_mul_f32_e32 v107, v107, v114
	v_cvt_pk_bf16_f32 v114, v96, v100
	v_cvt_pk_bf16_f32 v115, v102, v107
	global_store_dwordx2 v[72:73], v[114:115], off offset:32
	global_load_dwordx4 v[114:117], v[154:155], off offset:128
	v_lshlrev_b32_e32 v96, 16, v110
	v_mul_f32_e32 v100, 0xbfb8aa3b, v96
	v_exp_f32_e32 v100, v100
	v_and_b32_e32 v110, 0xffff0000, v110
	v_lshlrev_b32_e32 v118, 16, v111
	v_and_b32_e32 v111, 0xffff0000, v111
	v_add_f32_e32 v100, 1.0, v100
	s_waitcnt vmcnt(0)
	v_mul_f32_e32 v112, v114, v112
	v_mul_f32_e32 v107, 0xbfb8aa3b, v110
	v_exp_f32_e32 v107, v107
	v_rcp_f32_e32 v102, v100
	s_nop 0
	v_fma_f32 v120, -v100, v102, 1.0
	v_fma_f32 v100, v120, v102, v102
	v_mul_f32_e32 v96, v100, v96
	v_cndmask_b32_e64 v96, v96, v100, s[40:41]
	v_add_f32_e32 v100, 1.0, v107
	v_mul_f32_e32 v96, v96, v112
	v_mul_f32_e32 v108, v116, v108
	v_mul_f32_e32 v107, 0xbfb8aa3b, v118
	v_exp_f32_e32 v107, v107
	v_rcp_f32_e32 v102, v100
	s_nop 0
	v_fma_f32 v114, -v100, v102, 1.0
	v_fma_f32 v100, v114, v102, v102
	v_mul_f32_e32 v102, v100, v110
	v_cndmask_b32_e64 v100, v102, v100, s[40:41]
	v_add_f32_e32 v102, 1.0, v107
	v_mul_f32_e32 v112, v113, v0
	v_mul_f32_e32 v112, v115, v112
	v_mul_f32_e32 v100, v100, v112
	v_mul_f32_e32 v110, 0xbfb8aa3b, v111
	v_exp_f32_e32 v110, v110
	v_rcp_f32_e32 v107, v102
	s_nop 0
	v_fma_f32 v114, -v102, v107, 1.0
	v_fma_f32 v102, v114, v107, v107
	v_mul_f32_e32 v107, v102, v118
	v_cndmask_b32_e64 v102, v107, v102, s[40:41]
	v_add_f32_e32 v107, 1.0, v110
	v_mul_f32_e32 v102, v102, v108
	v_rcp_f32_e32 v113, v107
	s_nop 0
	v_fma_f32 v114, -v107, v113, 1.0
	v_fma_f32 v107, v114, v113, v113
	v_mul_f32_e32 v108, v107, v111
	v_cndmask_b32_e64 v107, v108, v107, s[40:41]
	v_mul_f32_e32 v108, v109, v0
	v_mul_f32_e32 v108, v117, v108
	v_mul_f32_e32 v107, v107, v108
	v_cvt_pk_bf16_f32 v108, v96, v100
	v_cvt_pk_bf16_f32 v109, v102, v107
	global_store_dwordx2 v[72:73], v[108:109], off offset:64
	global_load_dwordx4 v[108:111], v[154:155], off offset:192
	v_lshlrev_b32_e32 v96, 16, v104
	v_mul_f32_e32 v100, 0xbfb8aa3b, v96
	v_exp_f32_e32 v100, v100
	v_and_b32_e32 v104, 0xffff0000, v104
	v_lshlrev_b32_e32 v112, 16, v105
	v_and_b32_e32 v105, 0xffff0000, v105
	v_add_f32_e32 v100, 1.0, v100
	s_waitcnt vmcnt(0)
	v_mul_f32_e32 v90, v108, v90
	v_mul_f32_e32 v107, 0xbfb8aa3b, v104
	v_exp_f32_e32 v107, v107
	v_rcp_f32_e32 v102, v100
	s_nop 0
	v_fma_f32 v114, -v100, v102, 1.0
	v_fma_f32 v100, v114, v102, v102
	v_mul_f32_e32 v96, v100, v96
	v_cndmask_b32_e64 v96, v96, v100, s[40:41]
	v_add_f32_e32 v100, 1.0, v107
	v_mul_f32_e32 v90, v96, v90
	v_mul_f32_e32 v106, v109, v106
	v_mul_f32_e32 v92, v110, v92
	v_mul_f32_e32 v102, 0xbfb8aa3b, v112
	v_exp_f32_e32 v102, v102
	v_rcp_f32_e32 v108, v100
	s_nop 0
	v_fma_f32 v113, -v100, v108, 1.0
	v_fma_f32 v96, v113, v108, v108
	v_mul_f32_e32 v100, v96, v104
	v_cndmask_b32_e64 v96, v100, v96, s[40:41]
	v_add_f32_e32 v100, 1.0, v102
	v_mul_f32_e32 v96, v96, v106
	v_mul_f32_e32 v91, v111, v91
	v_cvt_pk_bf16_f32 v90, v90, v96
	v_mul_f32_e32 v104, 0xbfb8aa3b, v105
	v_exp_f32_e32 v104, v104
	v_rcp_f32_e32 v102, v100
	s_nop 0
	v_fma_f32 v107, -v100, v102, 1.0
	v_fma_f32 v100, v107, v102, v102
	v_mul_f32_e32 v102, v100, v112
	v_cndmask_b32_e64 v100, v102, v100, s[40:41]
	v_add_f32_e32 v102, 1.0, v104
	v_mul_f32_e32 v92, v100, v92
	v_rcp_f32_e32 v107, v102
	s_nop 0
	v_fma_f32 v108, -v102, v107, 1.0
	v_fma_f32 v100, v108, v107, v107
	v_mul_f32_e32 v102, v100, v105
	v_cndmask_b32_e64 v100, v102, v100, s[40:41]
	v_mul_f32_e32 v91, v100, v91
	v_cvt_pk_bf16_f32 v91, v92, v91
	global_store_dwordx2 v[72:73], v[90:91], off offset:96
	global_load_dwordx4 v[104:107], v[154:155], off offset:256
	v_lshlrev_b32_e32 v90, 16, v94
	v_mul_f32_e32 v91, 0xbfb8aa3b, v90
	v_exp_f32_e32 v91, v91
	v_and_b32_e32 v94, 0xffff0000, v94
	v_lshlrev_b32_e32 v100, 16, v95
	v_and_b32_e32 v95, 0xffff0000, v95
	v_add_f32_e32 v91, 1.0, v91
	s_waitcnt vmcnt(0)
; __device__ __forceinline__ unsigned cvt_pk_bf16(float lo, float hi) { unsigned r; asm volatile("v_cvt_pk_bf16_f32 %0, %1, %2" : "=v"(r) : "v"(lo), "v"(hi)); return r; }
; __device__ __forceinline__ float bf_lo(unsigned w) { return __uint_as_float(w << 16); }
; __device__ __forceinline__ float bf_hi(unsigned w) { return __uint_as_float(w & 0xffff0000u); }
; __device__ __forceinline__ float sigmoidf_(float x) { return 1.0f / (1.0f + __expf(-x)); }
; __device__ void mix_sweep(const Params& P, LAS unsigned char* lds, int tok0, int pos0, int seqlen, int hd, int dir, bool state_only, bool final_pass,
;                           f32x4 (&Cacc)[9], float& m_state, float& aseg_sum, float lgam) {
;     ...
; #pragma unroll
;                 for (int nt = 0; nt < 8; ++nt) { const u32x2 gv = gvv[nt]; const f32x4 gw = *(const f32x4*)(gnw + 16 * nt + 4 * fg);
;                     float gt[4] = {bf_lo(gv.x), bf_hi(gv.x), bf_lo(gv.y), bf_hi(gv.y)}; float y[4];
; #pragma unroll
;                     for (int e = 0; e < 4; ++e) { const float sg = sigmoidf_(gt[e]); const float gate = is_m ? sg : gt[e] * sg; y[e] = (O[nt][e] - mu) * rs * gw[e] * gate; }
;                     u32x2 v; v.x = cvt_pk_bf16(y[0], y[1]); v.y = cvt_pk_bf16(y[2], y[3]); *(u32x2*)(mrow + 16 * nt) = v; }
	v_mul_f32_e32 v101, v105, v101
	v_mul_f32_e32 v96, 0xbfb8aa3b, v94
	v_exp_f32_e32 v96, v96
	v_rcp_f32_e32 v92, v91
	s_nop 0
	v_fma_f32 v108, -v91, v92, 1.0
	v_fma_f32 v91, v108, v92, v92
	v_mul_f32_e32 v90, v91, v90
	v_cndmask_b32_e64 v90, v90, v91, s[40:41]
	v_add_f32_e32 v91, 1.0, v96
	v_div_scale_f32 v92, s[16:17], v91, v91, 1.0
	v_rcp_f32_e32 v96, v92
	v_mul_f32_e32 v102, v103, v0
	v_mul_f32_e32 v102, v104, v102
	v_mul_f32_e32 v90, v90, v102
	v_fma_f32 v102, -v92, v96, 1.0
	v_fmac_f32_e32 v96, v102, v96
	v_div_scale_f32 v102, vcc, 1.0, v91, 1.0
	v_mul_f32_e32 v103, v102, v96
	v_fma_f32 v104, -v92, v103, v102
	v_fmac_f32_e32 v103, v104, v96
	v_fma_f32 v92, -v92, v103, v102
	v_div_fmas_f32 v92, v92, v96, v103
	v_mul_f32_e32 v96, 0xbfb8aa3b, v100
	v_exp_f32_e32 v96, v96
	v_div_fixup_f32 v91, v92, v91, 1.0
	v_mul_f32_e32 v92, v91, v94
	v_cndmask_b32_e64 v91, v92, v91, s[40:41]
	v_add_f32_e32 v92, 1.0, v96
	v_mul_f32_e32 v91, v91, v101
	v_mul_f32_e32 v97, v106, v97
	v_mul_f32_e32 v93, v107, v93
	v_mul_f32_e32 v96, 0xbfb8aa3b, v95
	v_exp_f32_e32 v96, v96
	v_rcp_f32_e32 v94, v92
	s_nop 0
	v_fma_f32 v102, -v92, v94, 1.0
	v_fma_f32 v92, v102, v94, v94
	v_mul_f32_e32 v94, v92, v100
	v_cndmask_b32_e64 v92, v94, v92, s[40:41]
	v_add_f32_e32 v94, 1.0, v96
	v_mul_f32_e32 v92, v92, v97
	v_cvt_pk_bf16_f32 v90, v90, v91
	v_rcp_f32_e32 v96, v94
	s_nop 0
	v_fma_f32 v101, -v94, v96, 1.0
	v_fma_f32 v94, v101, v96, v96
	v_mul_f32_e32 v95, v94, v95
	v_cndmask_b32_e64 v94, v95, v94, s[40:41]
	v_mul_f32_e32 v93, v94, v93
	v_cvt_pk_bf16_f32 v91, v92, v93
	global_store_dwordx2 v[72:73], v[90:91], off offset:128
	global_load_dwordx4 v[90:93], v[154:155], off offset:320
	v_lshlrev_b32_e32 v94, 16, v84
	v_mul_f32_e32 v95, 0xbfb8aa3b, v94
	v_exp_f32_e32 v95, v95
	v_and_b32_e32 v84, 0xffff0000, v84
	v_lshlrev_b32_e32 v100, 16, v85
	v_and_b32_e32 v85, 0xffff0000, v85
	v_add_f32_e32 v95, 1.0, v95
	s_waitcnt vmcnt(0)
	v_mul_f32_e32 v86, v90, v86
	v_mul_f32_e32 v97, 0xbfb8aa3b, v84
	v_exp_f32_e32 v97, v97
	v_rcp_f32_e32 v96, v95
	s_nop 0
	v_fma_f32 v102, -v95, v96, 1.0
	v_fma_f32 v95, v102, v96, v96
	v_mul_f32_e32 v94, v95, v94
	v_cndmask_b32_e64 v94, v94, v95, s[40:41]
	v_add_f32_e32 v95, 1.0, v97
	v_mul_f32_e32 v86, v94, v86
	v_mul_f32_e32 v87, v91, v87
	v_mul_f32_e32 v80, v92, v80
	v_mul_f32_e32 v94, 0xbfb8aa3b, v100
	v_exp_f32_e32 v94, v94
	v_rcp_f32_e32 v101, v95
	s_nop 0
	v_fma_f32 v97, -v95, v101, 1.0
	v_fma_f32 v90, v97, v101, v101
	v_mul_f32_e32 v84, v90, v84
	v_cndmask_b32_e64 v84, v84, v90, s[40:41]
	v_add_f32_e32 v90, 1.0, v94
	v_mul_f32_e32 v84, v84, v87
	v_mul_f32_e32 v81, v93, v81
	v_mul_f32_e32 v91, 0xbfb8aa3b, v85
	v_exp_f32_e32 v91, v91
	v_rcp_f32_e32 v96, v90
	s_nop 0
	v_fma_f32 v95, -v90, v96, 1.0
	v_fma_f32 v87, v95, v96, v96
	v_mul_f32_e32 v90, v87, v100
	v_cndmask_b32_e64 v87, v90, v87, s[40:41]
	v_add_f32_e32 v90, 1.0, v91
	v_mul_f32_e32 v87, v87, v80
	v_rcp_f32_e32 v92, v90
	s_nop 0
	v_fma_f32 v95, -v90, v92, 1.0
	v_fma_f32 v80, v95, v92, v92
	v_mul_f32_e32 v85, v80, v85
	v_cndmask_b32_e64 v80, v85, v80, s[40:41]
	v_mul_f32_e32 v81, v80, v81
	v_cvt_pk_bf16_f32 v80, v86, v84
	v_cvt_pk_bf16_f32 v81, v87, v81
	global_store_dwordx2 v[72:73], v[80:81], off offset:160
	global_load_dwordx4 v[84:87], v[154:155], off offset:384
	v_lshlrev_b32_e32 v80, 16, v76
	v_mul_f32_e32 v81, 0xbfb8aa3b, v80
	v_exp_f32_e32 v81, v81
	v_and_b32_e32 v76, 0xffff0000, v76
	v_lshlrev_b32_e32 v92, 16, v77
	v_and_b32_e32 v77, 0xffff0000, v77
	v_add_f32_e32 v81, 1.0, v81
	s_waitcnt vmcnt(0)
	v_mul_f32_e32 v86, v86, v89
	v_mul_f32_e32 v91, 0xbfb8aa3b, v76
	v_exp_f32_e32 v91, v91
	v_rcp_f32_e32 v90, v81
	s_nop 0
	v_fma_f32 v94, -v81, v90, 1.0
	v_fma_f32 v81, v94, v90, v90
	v_mul_f32_e32 v80, v81, v80
	v_cndmask_b32_e64 v80, v80, v81, s[40:41]
	v_add_f32_e32 v81, 1.0, v91
	v_mul_f32_e32 v93, v98, v0
	v_mul_f32_e32 v84, v84, v93
	v_mul_f32_e32 v80, v80, v84
	v_mul_f32_e32 v90, 0xbfb8aa3b, v92
	v_exp_f32_e32 v90, v90
	v_rcp_f32_e32 v94, v81
	s_nop 0
	v_fma_f32 v91, -v81, v94, 1.0
	v_fma_f32 v81, v91, v94, v94
	v_mul_f32_e32 v76, v81, v76
	v_cndmask_b32_e64 v76, v76, v81, s[40:41]
	v_add_f32_e32 v81, 1.0, v90
	v_mul_f32_e32 v91, v99, v0
	v_mul_f32_e32 v85, v85, v91
	v_mul_f32_e32 v76, v76, v85
	v_mul_f32_e32 v85, 0xbfb8aa3b, v77
	v_exp_f32_e32 v85, v85
	v_rcp_f32_e32 v84, v81
	s_nop 0
	v_fma_f32 v93, -v81, v84, 1.0
	v_fma_f32 v81, v93, v84, v84
	v_mul_f32_e32 v84, v81, v92
	v_cndmask_b32_e64 v81, v84, v81, s[40:41]
	v_add_f32_e32 v84, 1.0, v85
	v_mul_f32_e32 v81, v81, v86
	v_cvt_pk_bf16_f32 v76, v80, v76
	v_rcp_f32_e32 v85, v84
	s_nop 0
	v_fma_f32 v89, -v84, v85, 1.0
	v_fma_f32 v84, v89, v85, v85
	v_mul_f32_e32 v77, v84, v77
	v_cndmask_b32_e64 v77, v77, v84, s[40:41]
	v_mul_f32_e32 v84, v88, v0
	v_mul_f32_e32 v84, v87, v84
	v_mul_f32_e32 v77, v77, v84
	v_cvt_pk_bf16_f32 v77, v81, v77
	global_store_dwordx2 v[72:73], v[76:77], off offset:192
	global_load_dwordx4 v[84:87], v[154:155], off offset:448
	v_lshlrev_b32_e32 v76, 16, v74
	v_mul_f32_e32 v77, 0xbfb8aa3b, v76
	v_exp_f32_e32 v77, v77
	v_and_b32_e32 v74, 0xffff0000, v74
	v_lshlrev_b32_e32 v88, 16, v75
	v_and_b32_e32 v75, 0xffff0000, v75
	v_add_f32_e32 v77, 1.0, v77
	v_mul_f32_e32 v0, v78, v0
	v_mul_f32_e32 v81, 0xbfb8aa3b, v74
	v_exp_f32_e32 v81, v81
	v_rcp_f32_e32 v80, v77
	s_nop 0
	v_fma_f32 v90, -v77, v80, 1.0
	v_fma_f32 v77, v90, v80, v80
	v_mul_f32_e32 v76, v77, v76
	v_cndmask_b32_e64 v76, v76, v77, s[40:41]
	v_add_f32_e32 v77, 1.0, v81
	s_waitcnt vmcnt(0)
	v_mul_f32_e32 v83, v84, v83
	v_mul_f32_e32 v76, v76, v83
	v_mul_f32_e32 v81, 0xbfb8aa3b, v88
	v_exp_f32_e32 v81, v81
	v_rcp_f32_e32 v80, v77
	s_nop 0
	v_fma_f32 v89, -v77, v80, 1.0
	v_fma_f32 v77, v89, v80, v80
	v_mul_f32_e32 v74, v77, v74
	v_cndmask_b32_e64 v74, v74, v77, s[40:41]
	v_add_f32_e32 v77, 1.0, v81
	v_mul_f32_e32 v82, v85, v82
	v_mul_f32_e32 v74, v74, v82
	v_mul_f32_e32 v79, v86, v79
	v_mul_f32_e32 v81, 0xbfb8aa3b, v75
	v_exp_f32_e32 v81, v81
	v_rcp_f32_e32 v80, v77
	s_nop 0
	v_fma_f32 v83, -v77, v80, 1.0
	v_fma_f32 v77, v83, v80, v80
	v_mul_f32_e32 v80, v77, v88
	v_cndmask_b32_e64 v77, v80, v77, s[40:41]
	v_add_f32_e32 v80, 1.0, v81
	v_mul_f32_e32 v77, v77, v79
	v_mul_f32_e32 v0, v87, v0
	v_cvt_pk_bf16_f32 v74, v76, v74
	v_rcp_f32_e32 v83, v80
	s_nop 0
	v_fma_f32 v84, -v80, v83, 1.0
	v_fma_f32 v79, v84, v83, v83
	v_mul_f32_e32 v75, v79, v75
	v_cndmask_b32_e64 v75, v75, v79, s[40:41]
	v_mul_f32_e32 v0, v75, v0
	v_cvt_pk_bf16_f32 v75, v77, v0
	global_store_dwordx2 v[72:73], v[74:75], off offset:224
	s_branch .LBB0_97

; __device__ __forceinline__ unsigned cvt_pk_bf16(float lo, float hi) { unsigned r; asm volatile("v_cvt_pk_bf16_f32 %0, %1, %2" : "=v"(r) : "v"(lo), "v"(hi)); return r; }
; __device__ __forceinline__ float bf_lo(unsigned w) { return __uint_as_float(w << 16); }
; __device__ __forceinline__ float bf_hi(unsigned w) { return __uint_as_float(w & 0xffff0000u); }
; __device__ __forceinline__ float sigmoidf_(float x) { return 1.0f / (1.0f + __expf(-x)); }
; __device__ void phase_conv(const Params& P, const int G, const int bid) {
;     ...
;     for (int it = bid * 512 + tid; it < 512 * 2 * 128; it += G * 512) { const int ch = it & 127, which = (it >> 7) & 1, g = it >> 8; const int col = ch * 8;
;         const int gs = g < 256 ? (g & 127) : ((g - 256) & 31), ng = g < 256 ? 128 : 32; const bool seq_first = gs == 0, seq_last = gs == ng - 1;
;         const bf16_t* pp = which ? HQ + (size_t)(g * 4 + 2) * 1024 : HQ + (size_t)((seq_first ? g : g - 1) * 4 + 3) * 1024;
;         const bf16_t* pc = HQ + (size_t)(g * 4 + (which ? 3 : 0)) * 1024;
;         const bf16_t* pn = which ? HQ + (size_t)((seq_last ? g : g + 1) * 4 + 0) * 1024 : HQ + (size_t)(g * 4 + 1) * 1024;
;         const float mp = (!which && seq_first) ? 0.f : 1.f, mn = (which && seq_last) ? 0.f : 1.f, mul = col < 512 ? 0.08838834764831845f : 1.0f;
;         const u32x4 gp = *(const u32x4*)(pp + col), gc = *(const u32x4*)(pc + col), gn = *(const u32x4*)(pn + col); u32x4 ov;
; #pragma unroll
;         for (int q = 0; q < 4; ++q) { const int c = col + 2 * q;
;             const float u0 = bf_lo(gp[q]) * mp * cw[c] + bf_lo(gc[q]) * cw[1024 + c] + bf_lo(gn[q]) * mn * cw[2048 + c] + cbv[c];
;             const float u1 = bf_hi(gp[q]) * mp * cw[c + 1] + bf_hi(gc[q]) * cw[1024 + c + 1] + bf_hi(gn[q]) * mn * cw[2048 + c + 1] + cbv[c + 1];
;             ov[q] = cvt_pk_bf16(u0 * sigmoidf_(u0) * mul, u1 * sigmoidf_(u1) * mul); }
.LBB0_578:
	s_or_b64 exec, exec, s[8:9]
	v_and_b32_e32 v14, 0x3f8, v21
	s_movk_i32 s11, 0x200
	s_and_b64 s[8:9], s[40:41], s[42:43]
	v_cmp_gt_u32_e64 s[40:41], s11, v14
	v_or_b32_e32 v8, v7, v5
	v_or_b32_e32 v0, v0, v6
	v_cndmask_b32_e64 v24, 1.0, v218, s[40:41]
	v_readlane_b32 s40, v254, 34
	v_ashrrev_i32_e32 v3, 31, v2
	v_ashrrev_i32_e32 v9, 31, v8
	v_ashrrev_i32_e32 v5, 31, v4
	v_cmp_eq_u32_e32 vcc, 0, v0
	v_lshlrev_b32_e32 v0, 1, v14
	v_lshlrev_b32_e32 v14, 2, v14
	v_mov_b32_e32 v15, v1
	v_readlane_b32 s52, v254, 46
	v_readlane_b32 s53, v254, 47
	v_lshlrev_b64 v[2:3], 11, v[2:3]
	v_lshlrev_b64 v[8:9], 11, v[8:9]
	v_lshlrev_b64 v[4:5], 11, v[4:5]
	v_readlane_b32 s41, v254, 35
	v_lshl_add_u64 v[16:17], s[52:53], 0, v[14:15]
	s_movk_i32 s11, 0x1000
	v_lshl_add_u64 v[2:3], s[4:5], 0, v[2:3]
	v_lshl_add_u64 v[8:9], s[4:5], 0, v[8:9]
	v_lshl_add_u64 v[10:11], s[4:5], 0, v[4:5]
	v_add_co_u32_e64 v18, s[40:41], s11, v16
	v_lshl_add_u64 v[2:3], v[2:3], 0, v[0:1]
	v_lshl_add_u64 v[6:7], v[8:9], 0, v[0:1]
	v_lshl_add_u64 v[10:11], v[10:11], 0, v[0:1]
	v_addc_co_u32_e64 v19, s[40:41], 0, v17, s[40:41]
	global_load_dwordx4 v[2:5], v[2:3], off
	v_add_co_u32_e64 v16, s[40:41], s83, v16
	global_load_dwordx4 v[6:9], v[6:7], off
	s_nop 0
	v_addc_co_u32_e64 v17, s[40:41], 0, v17, s[40:41]
	global_load_dwordx4 v[10:13], v[10:11], off
	v_readlane_b32 s54, v254, 48
	global_load_dwordx2 v[26:27], v14, s[52:53]
	v_readlane_b32 s55, v254, 49
	global_load_dwordx2 v[28:29], v[16:17], off offset:-4096
	global_load_dwordx2 v[30:31], v[16:17], off
	s_nop 2
	global_load_dwordx2 v[32:33], v14, s[54:55]
	v_add_u32_e32 v20, s0, v20
	v_add_u32_e32 v21, s10, v21
	v_readlane_b32 s42, v254, 36
	v_readlane_b32 s43, v254, 37
	v_readlane_b32 s44, v254, 38
	v_readlane_b32 s45, v254, 39
	v_readlane_b32 s46, v254, 40
	v_readlane_b32 s47, v254, 41
	v_readlane_b32 s48, v254, 42
	v_readlane_b32 s49, v254, 43
	v_readlane_b32 s50, v254, 44
	v_readlane_b32 s51, v254, 45
	s_waitcnt vmcnt(6)
	v_lshlrev_b32_e32 v34, 16, v2
	s_waitcnt vmcnt(5)
	v_lshlrev_b32_e32 v38, 16, v6
	v_and_b32_e32 v39, 0xffff0000, v6
	v_lshlrev_b32_e32 v40, 16, v7
	v_and_b32_e32 v41, 0xffff0000, v7
	v_cndmask_b32_e64 v7, 1.0, 0, s[8:9]
	v_cndmask_b32_e64 v6, 1.0, 0, vcc
	s_waitcnt vmcnt(4)
	v_lshlrev_b32_e32 v35, 16, v10
	v_pk_mul_f32 v[34:35], v[6:7], v[34:35]
	s_waitcnt vmcnt(3)
	v_mov_b32_e32 v36, v26
	s_waitcnt vmcnt(1)
	v_mov_b32_e32 v37, v30
	v_pk_mul_f32 v[34:35], v[36:37], v[34:35]
	v_mov_b32_e32 v30, v27
	v_fma_f32 v26, v28, v38, v34
	v_add_f32_e32 v26, v26, v35
	s_waitcnt vmcnt(0)
	v_add_f32_e32 v28, v32, v26
	v_and_b32_e32 v35, 0xffff0000, v10
	v_mul_f32_e32 v10, 0xbfb8aa3b, v28
	v_exp_f32_e32 v10, v10
	v_and_b32_e32 v34, 0xffff0000, v2
	v_pk_mul_f32 v[34:35], v[6:7], v[34:35]
	v_lshlrev_b32_e32 v32, 16, v3
	v_pk_mul_f32 v[26:27], v[34:35], v[30:31]
	v_add_f32_e32 v10, 1.0, v10
	v_fma_f32 v2, v29, v39, v26
	v_add_f32_e32 v2, v2, v27
	v_add_f32_e32 v2, v33, v2
	v_lshlrev_b32_e32 v33, 16, v11
	v_pk_mul_f32 v[32:33], v[6:7], v[32:33]
	v_rcp_f32_e32 v26, v10
	s_nop 0
	v_fma_f32 v30, -v10, v26, 1.0
	v_fma_f32 v10, v30, v26, v26
	v_mul_f32_e32 v26, 0xbfb8aa3b, v2
	v_exp_f32_e32 v26, v26
	v_mul_f32_e32 v10, v28, v10
	v_mul_f32_e32 v10, v24, v10
	v_and_b32_e32 v11, 0xffff0000, v11
	v_add_f32_e32 v26, 1.0, v26
	v_lshlrev_b32_e32 v25, 16, v8
	v_and_b32_e32 v15, 0xffff0000, v8
	v_lshlrev_b32_e32 v8, 16, v9
	v_rcp_f32_e32 v27, v26
	s_nop 0
	v_fma_f32 v30, -v26, v27, 1.0
	v_fma_f32 v26, v30, v27, v27
	v_mul_f32_e32 v2, v2, v26
	v_mul_f32_e32 v2, v24, v2
	v_cvt_pk_bf16_f32 v2, v10, v2
	global_load_dwordx2 v[26:27], v14, s[52:53] offset:8
	global_load_dwordx2 v[28:29], v[18:19], off offset:8
	global_load_dwordx2 v[30:31], v[16:17], off offset:8
	s_waitcnt vmcnt(2)
	v_mov_b32_e32 v34, v26
	s_waitcnt vmcnt(0)
	v_mov_b32_e32 v35, v30
	v_pk_mul_f32 v[32:33], v[32:33], v[34:35]
	v_mov_b32_e32 v30, v27
	v_fma_f32 v10, v28, v40, v32
	v_add_f32_e32 v10, v10, v33
	global_load_dwordx2 v[32:33], v14, s[54:55] offset:8
	s_waitcnt vmcnt(0)
; __device__ __forceinline__ unsigned cvt_pk_bf16(float lo, float hi) { unsigned r; asm volatile("v_cvt_pk_bf16_f32 %0, %1, %2" : "=v"(r) : "v"(lo), "v"(hi)); return r; }
; __device__ __forceinline__ float bf_lo(unsigned w) { return __uint_as_float(w << 16); }
; __device__ __forceinline__ float bf_hi(unsigned w) { return __uint_as_float(w & 0xffff0000u); }
; __device__ __forceinline__ float sigmoidf_(float x) { return 1.0f / (1.0f + __expf(-x)); }
; __device__ void phase_conv(const Params& P, const int G, const int bid) {
;     ...
;         const u32x4 gp = *(const u32x4*)(pp + col), gc = *(const u32x4*)(pc + col), gn = *(const u32x4*)(pn + col); u32x4 ov;
; #pragma unroll
;         for (int q = 0; q < 4; ++q) { const int c = col + 2 * q;
;             const float u0 = bf_lo(gp[q]) * mp * cw[c] + bf_lo(gc[q]) * cw[1024 + c] + bf_lo(gn[q]) * mn * cw[2048 + c] + cbv[c];
;             const float u1 = bf_hi(gp[q]) * mp * cw[c + 1] + bf_hi(gc[q]) * cw[1024 + c + 1] + bf_hi(gn[q]) * mn * cw[2048 + c + 1] + cbv[c + 1];
;             ov[q] = cvt_pk_bf16(u0 * sigmoidf_(u0) * mul, u1 * sigmoidf_(u1) * mul); }
;         *(u32x4*)(proj + (size_t)(g * 64 + (which ? 63 : 0)) * NPROJ + 2048 + col) = ov; }
	v_add_f32_e32 v26, v32, v10
	v_and_b32_e32 v10, 0xffff0000, v3
	v_pk_mul_f32 v[10:11], v[6:7], v[10:11]
	s_nop 0
	v_pk_mul_f32 v[10:11], v[10:11], v[30:31]
	v_lshlrev_b32_e32 v31, 16, v12
	v_fma_f32 v3, v29, v41, v10
	v_mul_f32_e32 v10, 0xbfb8aa3b, v26
	v_exp_f32_e32 v10, v10
	v_add_f32_e32 v3, v3, v11
	v_add_f32_e32 v3, v33, v3
	v_add_f32_e32 v10, 1.0, v10
	s_nop 0
	v_rcp_f32_e32 v11, v10
	s_nop 0
	v_fma_f32 v29, -v10, v11, 1.0
	v_fma_f32 v10, v29, v11, v11
	v_mul_f32_e32 v11, 0xbfb8aa3b, v3
	v_exp_f32_e32 v11, v11
	v_mul_f32_e32 v10, v26, v10
	v_mul_f32_e32 v10, v24, v10
	v_add_f32_e32 v11, 1.0, v11
	s_nop 0
	v_rcp_f32_e32 v26, v11
	s_nop 0
	v_fma_f32 v29, -v11, v26, 1.0
	v_fma_f32 v11, v29, v26, v26
	v_mul_f32_e32 v3, v3, v11
	v_mul_f32_e32 v3, v24, v3
	v_cvt_pk_bf16_f32 v3, v10, v3
	global_load_dwordx2 v[10:11], v14, s[52:53] offset:16
	global_load_dwordx2 v[26:27], v[18:19], off offset:16
	global_load_dwordx2 v[28:29], v[16:17], off offset:16
	v_lshlrev_b32_e32 v30, 16, v4
	v_pk_mul_f32 v[30:31], v[6:7], v[30:31]
	s_waitcnt vmcnt(2)
	v_mov_b32_e32 v32, v10
	s_waitcnt vmcnt(0)
	v_mov_b32_e32 v33, v28
	v_pk_mul_f32 v[30:31], v[30:31], v[32:33]
	v_and_b32_e32 v33, 0xffff0000, v12
	v_fma_f32 v10, v26, v25, v30
	v_add_f32_e32 v10, v10, v31
	global_load_dwordx2 v[30:31], v14, s[54:55] offset:16
	v_and_b32_e32 v32, 0xffff0000, v4
	v_pk_mul_f32 v[32:33], v[6:7], v[32:33]
	v_mov_b32_e32 v28, v11
	s_waitcnt vmcnt(0)
	v_add_f32_e32 v25, v30, v10
	v_pk_mul_f32 v[10:11], v[32:33], v[28:29]
	s_nop 0
	v_fma_f32 v4, v27, v15, v10
	v_mul_f32_e32 v10, 0xbfb8aa3b, v25
	v_exp_f32_e32 v10, v10
	v_add_f32_e32 v4, v4, v11
	v_add_f32_e32 v4, v31, v4
	v_add_f32_e32 v10, 1.0, v10
	s_nop 0
	v_rcp_f32_e32 v11, v10
	s_nop 0
	v_fma_f32 v26, -v10, v11, 1.0
	v_fma_f32 v10, v26, v11, v11
	v_mul_f32_e32 v11, 0xbfb8aa3b, v4
	v_exp_f32_e32 v11, v11
	v_mul_f32_e32 v10, v25, v10
	v_mul_f32_e32 v10, v24, v10
	v_add_f32_e32 v11, 1.0, v11
	s_nop 0
	v_rcp_f32_e32 v12, v11
	s_nop 0
	v_fma_f32 v26, -v11, v12, 1.0
	v_fma_f32 v11, v26, v12, v12
	v_mul_f32_e32 v4, v4, v11
	v_mul_f32_e32 v4, v24, v4
	v_cvt_pk_bf16_f32 v4, v10, v4
	global_load_dwordx2 v[10:11], v14, s[52:53] offset:24
	s_nop 0
	global_load_dwordx2 v[18:19], v[18:19], off offset:24
	v_lshlrev_b32_e32 v27, 16, v13
	global_load_dwordx2 v[16:17], v[16:17], off offset:24
	v_lshlrev_b32_e32 v26, 16, v5
	global_load_dwordx2 v[14:15], v14, s[54:55] offset:24
	v_pk_mul_f32 v[26:27], v[6:7], v[26:27]
	v_and_b32_e32 v12, 0xffff0000, v9
	v_and_b32_e32 v9, 0xffff0000, v13
	s_waitcnt vmcnt(3)
	v_mov_b32_e32 v28, v10
	s_waitcnt vmcnt(1)
	v_mov_b32_e32 v29, v16
	v_pk_mul_f32 v[26:27], v[26:27], v[28:29]
	v_mov_b32_e32 v16, v11
	v_fma_f32 v8, v18, v8, v26
	v_add_f32_e32 v8, v8, v27
	s_waitcnt vmcnt(0)
	v_add_f32_e32 v10, v14, v8
	v_and_b32_e32 v8, 0xffff0000, v5
	v_pk_mul_f32 v[6:7], v[6:7], v[8:9]
	s_nop 0
	v_pk_mul_f32 v[6:7], v[6:7], v[16:17]
	s_nop 0
	v_fma_f32 v5, v19, v12, v6
	v_mul_f32_e32 v6, 0xbfb8aa3b, v10
	v_exp_f32_e32 v6, v6
	v_add_f32_e32 v5, v5, v7
	v_add_f32_e32 v5, v15, v5
	v_add_f32_e32 v6, 1.0, v6
	s_nop 0
	v_rcp_f32_e32 v7, v6
	s_nop 0
	v_fma_f32 v11, -v6, v7, 1.0
	v_fma_f32 v6, v11, v7, v7
	v_mul_f32_e32 v7, 0xbfb8aa3b, v5
	v_exp_f32_e32 v7, v7
	v_mul_f32_e32 v6, v10, v6
	v_mul_f32_e32 v6, v24, v6
	v_add_f32_e32 v7, 1.0, v7
	s_mov_b32 s8, 0x1ffff
	v_rcp_f32_e32 v8, v7
	s_nop 0
	v_fma_f32 v11, -v7, v8, 1.0
	v_fma_f32 v7, v11, v8, v8
	v_mul_f32_e32 v5, v5, v7
	v_mul_f32_e32 v5, v24, v5
	v_cvt_pk_bf16_f32 v5, v6, v5
	v_lshl_or_b32 v6, v22, 6, v23
	v_ashrrev_i32_e32 v7, 31, v6
	v_lshlrev_b64 v[6:7], 13, v[6:7]
	v_lshl_add_u64 v[6:7], s[22:23], 0, v[6:7]
	v_lshl_add_u64 v[6:7], v[6:7], 0, v[0:1]
	v_add_co_u32_e32 v6, vcc, 0x1000, v6
	s_nop 1
	v_addc_co_u32_e32 v7, vcc, 0, v7, vcc
	v_cmp_lt_i32_e32 vcc, s8, v20
	s_or_b64 s[6:7], vcc, s[6:7]
	global_store_dwordx4 v[6:7], v[2:5], off
	s_andn2_b64 exec, exec, s[6:7]
	s_cbranch_execz .LBB0_587

; __device__ __forceinline__ unsigned cvt_pk_bf16(float lo, float hi) { unsigned r; asm volatile("v_cvt_pk_bf16_f32 %0, %1, %2" : "=v"(r) : "v"(lo), "v"(hi)); return r; }
; __device__ __forceinline__ float sigmoidf_(float x) { return 1.0f / (1.0f + __expf(-x)); }
; __device__ __forceinline__ float dppf_prev(float cur, float below) { return __uint_as_float(dpp_prev(__float_as_uint(cur), __float_as_uint(below))); }
; __device__ __forceinline__ float dppf_next(float cur, float above) { return __uint_as_float(dpp_next(__float_as_uint(cur), __float_as_uint(above))); }
;     __device__ __forceinline__ void operator()(AccT& acc, const Unit& u, int wr, int wc, int fr, int fq) const {
;     ...
;                 for (int bj = 0; bj < 2; ++bj) { const int mc = mc0 + bj * 128; const float mul = mc < 512 ? 0.08838834764831845f : 1.0f;
; #pragma unroll
;                     for (int n = 0; n < 2; ++n) {
;                         const f32x4 w0 = *(const f32x4*)(cw + mc + 4 * n), w1 = *(const f32x4*)(cw + 1024 + mc + 4 * n), w2 = *(const f32x4*)(cw + 2048 + mc + 4 * n), b = *(const f32x4*)(cb + mc + 4 * n);
; #pragma unroll
;                         for (int m = 0; m < 4; ++m) { const int lr = m * 16 + fr; const f32x4 gc = acc[ai][bj][m][n]; f32x4 o;
; #pragma unroll
;                             for (int j = 0; j < 4; ++j) { const float gp = dppf_prev(gc[j], m > 0 ? acc[ai][bj][m - 1][n][j] : 0.f), gn = dppf_next(gc[j], m < 3 ? acc[ai][bj][m + 1][n][j] : 0.f);
;                                 const float uu = gp * w0[j] + gc[j] * w1[j] + gn * w2[j] + b[j]; o[j] = uu * sigmoidf_(uu) * mul; }
;                             u32x2 w; w.x = cvt_pk_bf16(o[0], o[1]); w.y = cvt_pk_bf16(o[2], o[3]);
;                             *(u32x2*)(O + (size_t)(grp * 64 + lr) * NPROJ + col0 + bj * 128 + 4 * n) = w;
;                             if (m == 0 || m == 3) { if (lr < 2 || lr > 61) { u32x2 wg; wg.x = cvt_pk_bf16(gc[0], gc[1]); wg.y = cvt_pk_bf16(gc[2], gc[3]);
;                                 *(u32x2*)(HQ + (size_t)(grp * 4 + (lr < 2 ? lr : lr - 60)) * 1024 + mc + 4 * n) = wg; } } } } } }
.LBB0_680:
	s_and_b64 vcc, exec, s[2:3]
	s_cbranch_vccz .LBB0_600
	s_movk_i32 s2, 0xa00
	v_ashrrev_i32_e32 v159, 31, v158
	v_cmp_gt_i32_e32 vcc, s2, v158
	s_movk_i32 s2, 0xe000
	v_lshlrev_b64 v[130:131], 2, v[158:159]
	s_mov_b32 s3, -1
	v_readlane_b32 s60, v254, 34
	v_lshl_add_u64 v[138:139], v[130:131], 0, s[2:3]
	v_readlane_b32 s72, v254, 46
	v_readlane_b32 s73, v254, 47
	v_readlane_b32 s74, v254, 48
	v_readlane_b32 s75, v254, 49
	v_lshl_add_u64 v[174:175], s[72:73], 0, v[138:139]
	v_lshl_add_u64 v[160:161], s[72:73], 0, v[130:131]
	global_load_dwordx4 v[142:145], v[174:175], off
	global_load_dwordx4 v[130:133], v[160:161], off offset:-4096
	global_load_dwordx4 v[134:137], v[160:161], off
	v_lshl_add_u64 v[176:177], s[74:75], 0, v[138:139]
	global_load_dwordx4 v[138:141], v[176:177], off
	v_mov_b32_e32 v178, v1
	v_mov_b32_e32 v165, v1
	v_cndmask_b32_e32 v191, 1.0, v218, vcc
	v_mov_b32_dpp v178, v178 row_ror:1 row_mask:0xf bank_mask:0xf
	v_mov_b32_e32 v164, v178
	v_mov_b32_dpp v165, v122 row_ror:15 row_mask:0xf bank_mask:0xf
	v_mov_b32_e32 v179, v1
	v_mov_b32_dpp v164, v126 row_shr:1 row_mask:0xf bank_mask:0xf
	v_mov_b32_dpp v165, v126 row_shl:1 row_mask:0xf bank_mask:0xf
	v_mov_b32_dpp v179, v125 row_ror:15 row_mask:0xf bank_mask:0xf
	s_lshl_b32 s0, s0, 2
	s_add_i32 s0, s0, s13
	v_mov_b32_dpp v179, v129 row_shl:1 row_mask:0xf bank_mask:0xf
	s_lshl_b32 s5, s0, 6
	s_lshl_b32 s4, s0, 2
	v_readlane_b32 s61, v254, 35
	v_readlane_b32 s62, v254, 36
	v_readlane_b32 s63, v254, 37
	v_readlane_b32 s64, v254, 38
	v_readlane_b32 s65, v254, 39
	v_readlane_b32 s66, v254, 40
	v_readlane_b32 s67, v254, 41
	v_readlane_b32 s68, v254, 42
	v_readlane_b32 s69, v254, 43
	v_readlane_b32 s70, v254, 44
	v_readlane_b32 s71, v254, 45
	s_waitcnt vmcnt(0)
	global_load_dwordx4 v[196:199], v[174:175], off offset:16
	global_load_dwordx4 v[204:207], v[160:161], off offset:-4080
	global_load_dwordx4 v[222:225], v[160:161], off offset:16
	global_load_dwordx4 v[226:229], v[176:177], off offset:16
	v_mov_b32_e32 v182, v142
	v_mov_b32_e32 v183, v134
	v_pk_mul_f32 v[164:165], v[182:183], v[164:165]
	v_mov_b32_e32 v184, v144
	v_fma_f32 v0, v126, v130, v164
	v_add_f32_e32 v0, v0, v165
	v_add_f32_e32 v0, v138, v0
	v_mul_f32_e32 v134, 0xbfb8aa3b, v0
	v_exp_f32_e32 v134, v134
	v_mov_b32_e32 v185, v136
	v_add_f32_e32 v134, 1.0, v134
	s_nop 0
	v_mov_b32_e32 v165, v1
	v_rcp_f32_e32 v142, v134
	s_nop 0
	v_fma_f32 v166, -v134, v142, 1.0
	v_fma_f32 v134, v166, v142, v142
	v_mov_b32_e32 v164, v178
	v_mov_b32_dpp v165, v123 row_ror:15 row_mask:0xf bank_mask:0xf
	v_mul_f32_e32 v0, v0, v134
	v_mov_b32_dpp v164, v127 row_shr:1 row_mask:0xf bank_mask:0xf
	v_mov_b32_dpp v165, v127 row_shl:1 row_mask:0xf bank_mask:0xf
	v_mov_b32_e32 v134, v143
	v_pk_mul_f32 v[142:143], v[134:135], v[164:165]
	v_mul_f32_e32 v0, v191, v0
	v_fma_f32 v142, v127, v131, v142
	v_add_f32_e32 v142, v142, v143
	v_add_f32_e32 v142, v139, v142
	v_mul_f32_e32 v143, 0xbfb8aa3b, v142
	v_exp_f32_e32 v143, v143
	s_nop 0
	v_add_f32_e32 v143, 1.0, v143
	s_nop 0
	v_mov_b32_e32 v165, v1
	v_rcp_f32_e32 v164, v143
	s_nop 0
	v_fma_f32 v167, -v143, v164, 1.0
	v_fma_f32 v143, v167, v164, v164
	v_mov_b32_e32 v164, v178
	v_mov_b32_dpp v165, v124 row_ror:15 row_mask:0xf bank_mask:0xf
	v_mul_f32_e32 v142, v142, v143
	v_mov_b32_dpp v164, v128 row_shr:1 row_mask:0xf bank_mask:0xf
	v_mov_b32_dpp v165, v128 row_shl:1 row_mask:0xf bank_mask:0xf
	v_pk_mul_f32 v[164:165], v[184:185], v[164:165]
	v_mov_b32_dpp v178, v129 row_shr:1 row_mask:0xf bank_mask:0xf
	v_fma_f32 v136, v128, v132, v164
	v_add_f32_e32 v136, v136, v165
	v_add_f32_e32 v136, v140, v136
	v_mul_f32_e32 v143, 0xbfb8aa3b, v136
	v_exp_f32_e32 v143, v143
	v_mul_f32_e32 v142, v191, v142
	v_cvt_pk_bf16_f32 v142, v0, v142
	v_subrev_u32_e32 v0, 62, v190
	v_add_f32_e32 v143, 1.0, v143
	s_nop 0
	v_rcp_f32_e32 v144, v143
	s_nop 0
	v_fma_f32 v166, -v143, v144, 1.0
	v_fma_f32 v143, v166, v144, v144
	v_mul_f32_e32 v136, v136, v143
	v_mul_f32_e32 v143, v191, v136
	v_mov_b32_e32 v136, v145
	v_pk_mul_f32 v[144:145], v[136:137], v[178:179]
	s_nop 0
	v_fma_f32 v144, v129, v133, v144
	v_add_f32_e32 v144, v144, v145
	v_add_f32_e32 v144, v141, v144
	v_mul_f32_e32 v145, 0xbfb8aa3b, v144
	v_exp_f32_e32 v145, v145
	s_nop 0
	v_add_f32_e32 v145, 1.0, v145
	s_movk_i32 s2, 0xffc4
	v_cmp_gt_u32_e64 s[42:43], s2, v0
	v_subrev_u32_e32 v0, 60, v190
	v_rcp_f32_e32 v164, v145
	s_nop 0
	v_fma_f32 v167, -v145, v164, 1.0
	v_fma_f32 v145, v167, v164, v164
	v_mul_f32_e32 v144, v144, v145
	v_mul_f32_e32 v144, v191, v144
	v_cvt_pk_bf16_f32 v143, v143, v144
	v_add_u32_e32 v144, s5, v190
	v_ashrrev_i32_e32 v145, 31, v144
	v_lshlrev_b64 v[144:145], 13, v[144:145]
	v_lshl_add_u64 v[144:145], s[22:23], 0, v[144:145]
	v_lshl_add_u64 v[144:145], v[158:159], 1, v[144:145]
	global_store_dwordx2 v[144:145], v[142:143], off
	s_and_saveexec_b64 s[2:3], s[42:43]
	s_cbranch_execz .LBB0_683
	v_cmp_gt_i32_e32 vcc, 2, v190
	v_cvt_pk_bf16_f32 v142, v126, v127
	v_cvt_pk_bf16_f32 v143, v128, v129
	s_nop 1
	v_cndmask_b32_e32 v164, v0, v190, vcc
	v_add_u32_e32 v164, s4, v164
	v_ashrrev_i32_e32 v165, 31, v164
	v_lshlrev_b64 v[164:165], 11, v[164:165]
	v_lshl_add_u64 v[164:165], s[48:49], 0, v[164:165]
	v_lshl_add_u64 v[164:165], v[158:159], 1, v[164:165]
	global_store_dwordx2 v[164:165], v[142:143], off offset:-4096
; __device__ __forceinline__ unsigned cvt_pk_bf16(float lo, float hi) { unsigned r; asm volatile("v_cvt_pk_bf16_f32 %0, %1, %2" : "=v"(r) : "v"(lo), "v"(hi)); return r; }
; __device__ __forceinline__ float sigmoidf_(float x) { return 1.0f / (1.0f + __expf(-x)); }
; __device__ __forceinline__ float dppf_prev(float cur, float below) { return __uint_as_float(dpp_prev(__float_as_uint(cur), __float_as_uint(below))); }
; __device__ __forceinline__ float dppf_next(float cur, float above) { return __uint_as_float(dpp_next(__float_as_uint(cur), __float_as_uint(above))); }
;     __device__ __forceinline__ void operator()(AccT& acc, const Unit& u, int wr, int wc, int fr, int fq) const {
;     ...
;                         for (int m = 0; m < 4; ++m) { const int lr = m * 16 + fr; const f32x4 gc = acc[ai][bj][m][n]; f32x4 o;
; #pragma unroll
;                             for (int j = 0; j < 4; ++j) { const float gp = dppf_prev(gc[j], m > 0 ? acc[ai][bj][m - 1][n][j] : 0.f), gn = dppf_next(gc[j], m < 3 ? acc[ai][bj][m + 1][n][j] : 0.f);
;                                 const float uu = gp * w0[j] + gc[j] * w1[j] + gn * w2[j] + b[j]; o[j] = uu * sigmoidf_(uu) * mul; }
;                             u32x2 w; w.x = cvt_pk_bf16(o[0], o[1]); w.y = cvt_pk_bf16(o[2], o[3]);
;                             *(u32x2*)(O + (size_t)(grp * 64 + lr) * NPROJ + col0 + bj * 128 + 4 * n) = w;
.LBB0_683:
	s_or_b64 exec, exec, s[2:3]
	v_mov_b32_e32 v142, v1
	v_mov_b32_e32 v143, v1
	v_add_u32_e32 v192, 16, v190
	v_mov_b32_dpp v142, v126 row_ror:1 row_mask:0xf bank_mask:0xf
	v_mov_b32_dpp v143, v118 row_ror:15 row_mask:0xf bank_mask:0xf
	v_add_u32_e32 v193, 32, v190
	v_mov_b32_dpp v142, v122 row_shr:1 row_mask:0xf bank_mask:0xf
	v_mov_b32_dpp v143, v122 row_shl:1 row_mask:0xf bank_mask:0xf
	v_pk_mul_f32 v[142:143], v[182:183], v[142:143]
	s_nop 0
	v_fma_f32 v126, v122, v130, v142
	v_add_f32_e32 v126, v126, v143
	v_add_f32_e32 v126, v138, v126
	v_mul_f32_e32 v142, 0xbfb8aa3b, v126
	v_exp_f32_e32 v142, v142
	s_nop 0
	v_add_f32_e32 v142, 1.0, v142
	s_nop 0
	v_rcp_f32_e32 v143, v142
	s_nop 0
	v_fma_f32 v166, -v142, v143, 1.0
	v_fma_f32 v142, v166, v143, v143
	v_mul_f32_e32 v126, v126, v142
	v_mul_f32_e32 v142, v191, v126
	v_mov_b32_e32 v126, v1
	s_nop 1
	v_mov_b32_dpp v126, v127 row_ror:1 row_mask:0xf bank_mask:0xf
	v_mov_b32_e32 v127, v1
	s_nop 0
	v_mov_b32_dpp v126, v123 row_shr:1 row_mask:0xf bank_mask:0xf
	v_mov_b32_dpp v127, v119 row_ror:15 row_mask:0xf bank_mask:0xf
	s_nop 1
	v_mov_b32_dpp v127, v123 row_shl:1 row_mask:0xf bank_mask:0xf
	v_pk_mul_f32 v[126:127], v[134:135], v[126:127]
	s_nop 0
	v_fma_f32 v126, v123, v131, v126
	v_add_f32_e32 v126, v126, v127
	v_add_f32_e32 v126, v139, v126
	v_mul_f32_e32 v127, 0xbfb8aa3b, v126
	v_exp_f32_e32 v127, v127
	s_nop 0
	v_add_f32_e32 v127, 1.0, v127
	s_nop 0
	v_rcp_f32_e32 v143, v127
	s_nop 0
	v_fma_f32 v166, -v127, v143, 1.0
	v_fma_f32 v127, v166, v143, v143
	v_mul_f32_e32 v126, v126, v127
	v_mul_f32_e32 v143, v191, v126
	v_mov_b32_e32 v126, v1
	v_mov_b32_e32 v127, v1
	s_nop 0
	v_mov_b32_dpp v126, v128 row_ror:1 row_mask:0xf bank_mask:0xf
	v_mov_b32_dpp v127, v120 row_ror:15 row_mask:0xf bank_mask:0xf
	s_nop 0
	v_mov_b32_dpp v126, v124 row_shr:1 row_mask:0xf bank_mask:0xf
	v_mov_b32_dpp v127, v124 row_shl:1 row_mask:0xf bank_mask:0xf
	v_pk_mul_f32 v[126:127], v[184:185], v[126:127]
	s_nop 0
	v_fma_f32 v126, v124, v132, v126
	v_add_f32_e32 v126, v126, v127
	v_add_f32_e32 v126, v140, v126
	v_mul_f32_e32 v127, 0xbfb8aa3b, v126
	v_exp_f32_e32 v127, v127
	s_nop 0
	v_add_f32_e32 v127, 1.0, v127
	s_nop 0
	v_rcp_f32_e32 v128, v127
	s_nop 0
	v_fma_f32 v166, -v127, v128, 1.0
	v_fma_f32 v127, v166, v128, v128
	v_mul_f32_e32 v126, v126, v127
	v_mul_f32_e32 v128, v191, v126
	v_mov_b32_e32 v126, v1
	v_mov_b32_e32 v127, v1
	s_nop 0
	v_mov_b32_dpp v126, v129 row_ror:1 row_mask:0xf bank_mask:0xf
	v_mov_b32_dpp v127, v121 row_ror:15 row_mask:0xf bank_mask:0xf
	s_nop 0
	v_mov_b32_dpp v126, v125 row_shr:1 row_mask:0xf bank_mask:0xf
	v_mov_b32_dpp v127, v125 row_shl:1 row_mask:0xf bank_mask:0xf
	v_pk_mul_f32 v[126:127], v[136:137], v[126:127]
	s_nop 0
	v_fma_f32 v126, v125, v133, v126
	v_add_f32_e32 v126, v126, v127
	v_add_f32_e32 v126, v141, v126
	v_mul_f32_e32 v127, 0xbfb8aa3b, v126
	v_exp_f32_e32 v127, v127
	s_nop 0
	v_add_f32_e32 v127, 1.0, v127
	s_nop 0
	v_rcp_f32_e32 v129, v127
	s_nop 0
	v_fma_f32 v166, -v127, v129, 1.0
	v_fma_f32 v127, v166, v129, v129
	v_mul_f32_e32 v126, v126, v127
	v_mul_f32_e32 v127, v191, v126
	v_cvt_pk_bf16_f32 v126, v142, v143
	v_cvt_pk_bf16_f32 v127, v128, v127
	v_add_u32_e32 v128, s5, v192
	v_ashrrev_i32_e32 v129, 31, v128
	v_lshlrev_b64 v[128:129], 13, v[128:129]
	v_lshl_add_u64 v[128:129], s[22:23], 0, v[128:129]
	v_lshlrev_b64 v[142:143], 1, v[158:159]
	v_lshl_add_u64 v[178:179], v[128:129], 0, v[142:143]
	global_store_dwordx2 v[178:179], v[126:127], off
	v_mov_b32_e32 v126, v1
	v_mov_b32_e32 v127, v1
	s_nop 0
	v_mov_b32_dpp v126, v122 row_ror:1 row_mask:0xf bank_mask:0xf
	v_mov_b32_dpp v127, v114 row_ror:15 row_mask:0xf bank_mask:0xf
	s_nop 0
	v_mov_b32_dpp v126, v118 row_shr:1 row_mask:0xf bank_mask:0xf
	v_mov_b32_dpp v127, v118 row_shl:1 row_mask:0xf bank_mask:0xf
	v_pk_mul_f32 v[126:127], v[182:183], v[126:127]
	s_nop 0
	v_fma_f32 v122, v118, v130, v126
	v_add_f32_e32 v122, v122, v127
	v_add_f32_e32 v122, v138, v122
	v_mul_f32_e32 v126, 0xbfb8aa3b, v122
	v_exp_f32_e32 v126, v126
	s_nop 0
	v_add_f32_e32 v126, 1.0, v126
	s_nop 0
	v_rcp_f32_e32 v127, v126
	s_nop 0
	v_fma_f32 v164, -v126, v127, 1.0
	v_fma_f32 v126, v164, v127, v127
	v_mul_f32_e32 v122, v122, v126
	v_mul_f32_e32 v126, v191, v122
	v_mov_b32_e32 v122, v1
	s_nop 1
	v_mov_b32_dpp v122, v123 row_ror:1 row_mask:0xf bank_mask:0xf
	v_mov_b32_e32 v123, v1
	s_nop 0
	v_mov_b32_dpp v122, v119 row_shr:1 row_mask:0xf bank_mask:0xf
	v_mov_b32_dpp v123, v115 row_ror:15 row_mask:0xf bank_mask:0xf
	s_nop 1
	v_mov_b32_dpp v123, v119 row_shl:1 row_mask:0xf bank_mask:0xf
	v_pk_mul_f32 v[122:123], v[134:135], v[122:123]
	s_nop 0
	v_fma_f32 v122, v119, v131, v122
	v_add_f32_e32 v122, v122, v123
	v_add_f32_e32 v122, v139, v122
	v_mul_f32_e32 v123, 0xbfb8aa3b, v122
	v_exp_f32_e32 v123, v123
	s_nop 0
	v_add_f32_e32 v123, 1.0, v123
	s_nop 0
	v_rcp_f32_e32 v127, v123
	s_nop 0
	v_fma_f32 v164, -v123, v127, 1.0
	v_fma_f32 v123, v164, v127, v127
	v_mul_f32_e32 v122, v122, v123
	v_mul_f32_e32 v127, v191, v122
	v_mov_b32_e32 v122, v1
	v_mov_b32_e32 v123, v1
	s_nop 0
	v_mov_b32_dpp v122, v124 row_ror:1 row_mask:0xf bank_mask:0xf
	v_mov_b32_dpp v123, v116 row_ror:15 row_mask:0xf bank_mask:0xf
	s_nop 0
	v_mov_b32_dpp v122, v120 row_shr:1 row_mask:0xf bank_mask:0xf
	v_mov_b32_dpp v123, v120 row_shl:1 row_mask:0xf bank_mask:0xf
	v_pk_mul_f32 v[122:123], v[184:185], v[122:123]
	s_nop 0
	v_fma_f32 v122, v120, v132, v122
	v_add_f32_e32 v122, v122, v123
	v_add_f32_e32 v122, v140, v122
	v_mul_f32_e32 v123, 0xbfb8aa3b, v122
	v_exp_f32_e32 v123, v123
	s_nop 0
	v_add_f32_e32 v123, 1.0, v123
	s_nop 0
	v_rcp_f32_e32 v124, v123
	s_nop 0
; __device__ __forceinline__ unsigned cvt_pk_bf16(float lo, float hi) { unsigned r; asm volatile("v_cvt_pk_bf16_f32 %0, %1, %2" : "=v"(r) : "v"(lo), "v"(hi)); return r; }
; __device__ __forceinline__ float sigmoidf_(float x) { return 1.0f / (1.0f + __expf(-x)); }
; __device__ __forceinline__ float dppf_prev(float cur, float below) { return __uint_as_float(dpp_prev(__float_as_uint(cur), __float_as_uint(below))); }
; __device__ __forceinline__ float dppf_next(float cur, float above) { return __uint_as_float(dpp_next(__float_as_uint(cur), __float_as_uint(above))); }
;     __device__ __forceinline__ void operator()(AccT& acc, const Unit& u, int wr, int wc, int fr, int fq) const {
;     ...
;                         for (int m = 0; m < 4; ++m) { const int lr = m * 16 + fr; const f32x4 gc = acc[ai][bj][m][n]; f32x4 o;
; #pragma unroll
;                             for (int j = 0; j < 4; ++j) { const float gp = dppf_prev(gc[j], m > 0 ? acc[ai][bj][m - 1][n][j] : 0.f), gn = dppf_next(gc[j], m < 3 ? acc[ai][bj][m + 1][n][j] : 0.f);
;                                 const float uu = gp * w0[j] + gc[j] * w1[j] + gn * w2[j] + b[j]; o[j] = uu * sigmoidf_(uu) * mul; }
;                             u32x2 w; w.x = cvt_pk_bf16(o[0], o[1]); w.y = cvt_pk_bf16(o[2], o[3]);
;                             *(u32x2*)(O + (size_t)(grp * 64 + lr) * NPROJ + col0 + bj * 128 + 4 * n) = w;
;                             if (m == 0 || m == 3) { if (lr < 2 || lr > 61) { u32x2 wg; wg.x = cvt_pk_bf16(gc[0], gc[1]); wg.y = cvt_pk_bf16(gc[2], gc[3]);
;                                 *(u32x2*)(HQ + (size_t)(grp * 4 + (lr < 2 ? lr : lr - 60)) * 1024 + mc + 4 * n) = wg; } } } } } }
	v_fma_f32 v164, -v123, v124, 1.0
	v_fma_f32 v123, v164, v124, v124
	v_mul_f32_e32 v122, v122, v123
	v_mul_f32_e32 v124, v191, v122
	v_mov_b32_e32 v122, v1
	v_mov_b32_e32 v123, v1
	s_nop 0
	v_mov_b32_dpp v122, v125 row_ror:1 row_mask:0xf bank_mask:0xf
	v_mov_b32_dpp v123, v117 row_ror:15 row_mask:0xf bank_mask:0xf
	s_nop 0
	v_mov_b32_dpp v122, v121 row_shr:1 row_mask:0xf bank_mask:0xf
	v_mov_b32_dpp v123, v121 row_shl:1 row_mask:0xf bank_mask:0xf
	v_pk_mul_f32 v[122:123], v[136:137], v[122:123]
	s_nop 0
	v_fma_f32 v122, v121, v133, v122
	v_add_f32_e32 v122, v122, v123
	v_add_f32_e32 v122, v141, v122
	v_mul_f32_e32 v123, 0xbfb8aa3b, v122
	v_exp_f32_e32 v123, v123
	s_nop 0
	v_add_f32_e32 v123, 1.0, v123
	s_nop 0
	v_rcp_f32_e32 v125, v123
	s_nop 0
	v_fma_f32 v164, -v123, v125, 1.0
	v_fma_f32 v123, v164, v125, v125
	v_mul_f32_e32 v122, v122, v123
	v_mul_f32_e32 v123, v191, v122
	v_cvt_pk_bf16_f32 v122, v126, v127
	v_cvt_pk_bf16_f32 v123, v124, v123
	v_add_u32_e32 v124, s5, v193
	v_ashrrev_i32_e32 v125, 31, v124
	v_lshlrev_b64 v[124:125], 13, v[124:125]
	v_lshl_add_u64 v[124:125], s[22:23], 0, v[124:125]
	v_lshl_add_u64 v[180:181], v[124:125], 0, v[142:143]
	v_mov_b32_e32 v125, v1
	global_store_dwordx2 v[180:181], v[122:123], off
	v_mov_b32_e32 v122, v1
	v_mov_b32_dpp v125, v125 row_ror:15 row_mask:0xf bank_mask:0xf
	v_mov_b32_e32 v123, v125
	v_mov_b32_dpp v122, v118 row_ror:1 row_mask:0xf bank_mask:0xf
	s_nop 0
	v_mov_b32_dpp v123, v114 row_shl:1 row_mask:0xf bank_mask:0xf
	v_mov_b32_dpp v122, v114 row_shr:1 row_mask:0xf bank_mask:0xf
	v_pk_mul_f32 v[122:123], v[182:183], v[122:123]
	s_nop 0
	v_fma_f32 v118, v114, v130, v122
	v_add_f32_e32 v118, v118, v123
	v_add_f32_e32 v118, v138, v118
	v_mul_f32_e32 v122, 0xbfb8aa3b, v118
	v_exp_f32_e32 v122, v122
	s_nop 0
	v_add_f32_e32 v122, 1.0, v122
	s_nop 0
	v_rcp_f32_e32 v123, v122
	s_nop 0
	v_fma_f32 v127, -v122, v123, 1.0
	v_fma_f32 v122, v127, v123, v123
	v_mul_f32_e32 v118, v118, v122
	v_mul_f32_e32 v122, v191, v118
	v_mov_b32_e32 v118, v1
	s_nop 1
	v_mov_b32_dpp v118, v119 row_ror:1 row_mask:0xf bank_mask:0xf
	v_mov_b32_e32 v119, v125
	s_nop 0
	v_mov_b32_dpp v118, v115 row_shr:1 row_mask:0xf bank_mask:0xf
	v_mov_b32_dpp v119, v115 row_shl:1 row_mask:0xf bank_mask:0xf
	v_pk_mul_f32 v[118:119], v[134:135], v[118:119]
	s_nop 0
	v_fma_f32 v118, v115, v131, v118
	v_add_f32_e32 v118, v118, v119
	v_add_f32_e32 v118, v139, v118
	v_mul_f32_e32 v119, 0xbfb8aa3b, v118
	v_exp_f32_e32 v119, v119
	s_nop 0
	v_add_f32_e32 v119, 1.0, v119
	s_nop 0
	v_rcp_f32_e32 v123, v119
	s_nop 0
	v_fma_f32 v127, -v119, v123, 1.0
	v_fma_f32 v119, v127, v123, v123
	v_mul_f32_e32 v118, v118, v119
	v_mul_f32_e32 v123, v191, v118
	v_mov_b32_e32 v118, v1
	v_mov_b32_e32 v119, v125
	v_mov_b32_dpp v125, v117 row_shl:1 row_mask:0xf bank_mask:0xf
	v_mov_b32_dpp v118, v120 row_ror:1 row_mask:0xf bank_mask:0xf
	v_mov_b32_dpp v119, v116 row_shl:1 row_mask:0xf bank_mask:0xf
	s_nop 0
	v_mov_b32_dpp v118, v116 row_shr:1 row_mask:0xf bank_mask:0xf
	v_pk_mul_f32 v[118:119], v[184:185], v[118:119]
	s_nop 0
	v_fma_f32 v118, v116, v132, v118
	v_add_f32_e32 v118, v118, v119
	v_add_f32_e32 v118, v140, v118
	v_mul_f32_e32 v119, 0xbfb8aa3b, v118
	v_exp_f32_e32 v119, v119
	s_nop 0
	v_add_f32_e32 v119, 1.0, v119
	s_nop 0
	v_mov_b32_e32 v124, v1
	v_rcp_f32_e32 v120, v119
	s_nop 0
	v_fma_f32 v127, -v119, v120, 1.0
	v_fma_f32 v119, v127, v120, v120
	v_mul_f32_e32 v118, v118, v119
	v_mov_b32_dpp v124, v121 row_ror:1 row_mask:0xf bank_mask:0xf
	v_mul_f32_e32 v120, v191, v118
	s_nop 0
	v_mov_b32_dpp v124, v117 row_shr:1 row_mask:0xf bank_mask:0xf
	v_pk_mul_f32 v[118:119], v[136:137], v[124:125]
	v_add_u32_e32 v136, 48, v190
	v_fma_f32 v118, v117, v133, v118
	v_add_f32_e32 v118, v118, v119
	v_add_f32_e32 v118, v141, v118
	v_mul_f32_e32 v119, 0xbfb8aa3b, v118
	v_exp_f32_e32 v119, v119
	v_add_u32_e32 v137, -12, v190
	v_add_f32_e32 v119, 1.0, v119
	s_movk_i32 s2, 0xffc4
	v_rcp_f32_e32 v121, v119
	s_nop 0
	v_fma_f32 v126, -v119, v121, 1.0
	v_fma_f32 v119, v126, v121, v121
	v_mul_f32_e32 v118, v118, v119
	v_mul_f32_e32 v119, v191, v118
	v_cvt_pk_bf16_f32 v118, v122, v123
	v_cvt_pk_bf16_f32 v119, v120, v119
	v_add_u32_e32 v120, s5, v136
	v_ashrrev_i32_e32 v121, 31, v120
	v_lshlrev_b64 v[120:121], 13, v[120:121]
	v_lshl_add_u64 v[120:121], s[22:23], 0, v[120:121]
	v_lshl_add_u64 v[130:131], v[120:121], 0, v[142:143]
	global_store_dwordx2 v[130:131], v[118:119], off
	v_add_u32_e32 v118, -14, v190
	v_cmp_gt_u32_e64 s[44:45], s2, v118
	s_and_saveexec_b64 s[2:3], s[44:45]
	s_cbranch_execz .LBB0_685
	s_movk_i32 s5, 0xffd2
	v_cmp_gt_i32_e32 vcc, s5, v190
	v_cvt_pk_bf16_f32 v114, v114, v115
	v_cvt_pk_bf16_f32 v115, v116, v117
	s_nop 1
	v_cndmask_b32_e32 v116, v137, v136, vcc
	v_add_u32_e32 v116, s4, v116
	v_ashrrev_i32_e32 v117, 31, v116
	v_lshlrev_b64 v[116:117], 11, v[116:117]
	v_lshl_add_u64 v[116:117], s[48:49], 0, v[116:117]
	v_lshl_add_u64 v[116:117], v[158:159], 1, v[116:117]
	global_store_dwordx2 v[116:117], v[114:115], off offset:-4096
; __device__ __forceinline__ unsigned cvt_pk_bf16(float lo, float hi) { unsigned r; asm volatile("v_cvt_pk_bf16_f32 %0, %1, %2" : "=v"(r) : "v"(lo), "v"(hi)); return r; }
; __device__ __forceinline__ float dppf_prev(float cur, float below) { return __uint_as_float(dpp_prev(__float_as_uint(cur), __float_as_uint(below))); }
; __device__ __forceinline__ float dppf_next(float cur, float above) { return __uint_as_float(dpp_next(__float_as_uint(cur), __float_as_uint(above))); }
; __device__ __forceinline__ float sigmoidf_(float x) { return 1.0f / (1.0f + __expf(-x)); }
;     __device__ __forceinline__ void operator()(AccT& acc, const Unit& u, int wr, int wc, int fr, int fq) const {
;     ...
;                         const f32x4 w0 = *(const f32x4*)(cw + mc + 4 * n), w1 = *(const f32x4*)(cw + 1024 + mc + 4 * n), w2 = *(const f32x4*)(cw + 2048 + mc + 4 * n), b = *(const f32x4*)(cb + mc + 4 * n);
; #pragma unroll
;                         for (int m = 0; m < 4; ++m) { const int lr = m * 16 + fr; const f32x4 gc = acc[ai][bj][m][n]; f32x4 o;
; #pragma unroll
;                             for (int j = 0; j < 4; ++j) { const float gp = dppf_prev(gc[j], m > 0 ? acc[ai][bj][m - 1][n][j] : 0.f), gn = dppf_next(gc[j], m < 3 ? acc[ai][bj][m + 1][n][j] : 0.f);
;                                 const float uu = gp * w0[j] + gc[j] * w1[j] + gn * w2[j] + b[j]; o[j] = uu * sigmoidf_(uu) * mul; }
;                             u32x2 w; w.x = cvt_pk_bf16(o[0], o[1]); w.y = cvt_pk_bf16(o[2], o[3]);
;                             *(u32x2*)(O + (size_t)(grp * 64 + lr) * NPROJ + col0 + bj * 128 + 4 * n) = w;
;                             if (m == 0 || m == 3) { if (lr < 2 || lr > 61) { u32x2 wg; wg.x = cvt_pk_bf16(gc[0], gc[1]); wg.y = cvt_pk_bf16(gc[2], gc[3]);
;                                 *(u32x2*)(HQ + (size_t)(grp * 4 + (lr < 2 ? lr : lr - 60)) * 1024 + mc + 4 * n) = wg; } } } } } }
.LBB0_685:
	s_or_b64 exec, exec, s[2:3]
	v_add_co_u32_e32 v114, vcc, 0x1000, v174
	s_waitcnt vmcnt(4)
	v_mov_b64_e32 v[126:127], v[196:197]
	v_mov_b64_e32 v[128:129], v[198:199]
	s_nop 0
	v_addc_co_u32_e32 v115, vcc, 0, v175, vcc
	v_add_co_u32_e32 v118, vcc, 0x2000, v174
	v_mov_b64_e32 v[114:115], v[204:205]
	v_mov_b64_e32 v[116:117], v[206:207]
	s_nop 0
	v_addc_co_u32_e32 v119, vcc, 0, v175, vcc
	v_mov_b64_e32 v[118:119], v[222:223]
	v_mov_b64_e32 v[120:121], v[224:225]
	s_nop 0
	v_mov_b64_e32 v[122:123], v[226:227]
	v_mov_b64_e32 v[124:125], v[228:229]
	global_load_dwordx4 v[196:199], v[174:175], off offset:512
	global_load_dwordx4 v[204:207], v[160:161], off offset:-3584
	global_load_dwordx4 v[222:225], v[160:161], off offset:512
	global_load_dwordx4 v[226:229], v[176:177], off offset:512
	v_mov_b32_e32 v134, v1
	v_mov_b32_e32 v139, v1
	s_waitcnt vmcnt(4)
	v_mov_b32_e32 v132, v126
	v_mov_b32_dpp v134, v134 row_ror:1 row_mask:0xf bank_mask:0xf
	v_mov_b32_e32 v138, v134
	v_mov_b32_dpp v139, v106 row_ror:15 row_mask:0xf bank_mask:0xf
	v_mov_b32_e32 v133, v118
	v_mov_b32_dpp v138, v110 row_shr:1 row_mask:0xf bank_mask:0xf
	v_mov_b32_dpp v139, v110 row_shl:1 row_mask:0xf bank_mask:0xf
	v_pk_mul_f32 v[138:139], v[132:133], v[138:139]
	s_nop 0
	v_fma_f32 v118, v110, v114, v138
	v_add_f32_e32 v118, v118, v139
	v_add_f32_e32 v118, v122, v118
	v_mul_f32_e32 v126, 0xbfb8aa3b, v118
	v_exp_f32_e32 v126, v126
	s_nop 0
	v_add_f32_e32 v126, 1.0, v126
	s_nop 0
	v_rcp_f32_e32 v135, v126
	s_nop 0
	v_fma_f32 v140, -v126, v135, 1.0
	v_fma_f32 v126, v140, v135, v135
	v_mov_b32_e32 v141, v1
	v_mul_f32_e32 v118, v118, v126
	v_mov_b32_e32 v140, v134
	v_mov_b32_dpp v141, v107 row_ror:15 row_mask:0xf bank_mask:0xf
	v_mul_f32_e32 v138, v191, v118
	v_mov_b32_dpp v140, v111 row_shr:1 row_mask:0xf bank_mask:0xf
	v_mov_b32_dpp v141, v111 row_shl:1 row_mask:0xf bank_mask:0xf
	v_mov_b32_e32 v118, v127
	v_pk_mul_f32 v[126:127], v[118:119], v[140:141]
	s_nop 0
	v_fma_f32 v126, v111, v115, v126
	v_add_f32_e32 v126, v126, v127
	v_add_f32_e32 v126, v123, v126
	v_mul_f32_e32 v127, 0xbfb8aa3b, v126
	v_exp_f32_e32 v127, v127
	s_nop 0
	v_add_f32_e32 v127, 1.0, v127
	s_nop 0
	v_rcp_f32_e32 v135, v127
	s_nop 0
	v_fma_f32 v141, -v127, v135, 1.0
	v_fma_f32 v127, v141, v135, v135
	v_mov_b32_e32 v141, v1
	v_mul_f32_e32 v126, v126, v127
	v_mov_b32_e32 v140, v134
	v_mov_b32_dpp v141, v108 row_ror:15 row_mask:0xf bank_mask:0xf
	v_mul_f32_e32 v139, v191, v126
	v_mov_b32_dpp v140, v112 row_shr:1 row_mask:0xf bank_mask:0xf
	v_mov_b32_dpp v141, v112 row_shl:1 row_mask:0xf bank_mask:0xf
	v_mov_b32_e32 v126, v128
	v_mov_b32_e32 v127, v120
	v_pk_mul_f32 v[140:141], v[126:127], v[140:141]
	v_mov_b32_dpp v134, v113 row_shr:1 row_mask:0xf bank_mask:0xf
	v_fma_f32 v120, v112, v116, v140
	v_add_f32_e32 v120, v120, v141
	v_add_f32_e32 v120, v124, v120
	v_mul_f32_e32 v128, 0xbfb8aa3b, v120
	v_exp_f32_e32 v128, v128
	s_nop 0
	v_add_f32_e32 v128, 1.0, v128
	s_nop 0
	v_rcp_f32_e32 v135, v128
	s_nop 0
	v_fma_f32 v164, -v128, v135, 1.0
	v_fma_f32 v128, v164, v135, v135
	v_mov_b32_e32 v135, v1
	v_mul_f32_e32 v120, v120, v128
	v_mul_f32_e32 v140, v191, v120
	v_mov_b32_dpp v135, v109 row_ror:15 row_mask:0xf bank_mask:0xf
	v_mov_b32_e32 v120, v129
	s_nop 0
	v_mov_b32_dpp v135, v113 row_shl:1 row_mask:0xf bank_mask:0xf
	v_pk_mul_f32 v[128:129], v[120:121], v[134:135]
	s_nop 0
	v_fma_f32 v128, v113, v117, v128
	v_add_f32_e32 v128, v128, v129
	v_add_f32_e32 v128, v125, v128
	v_mul_f32_e32 v129, 0xbfb8aa3b, v128
	v_exp_f32_e32 v129, v129
	s_nop 0
	v_add_f32_e32 v129, 1.0, v129
	s_nop 0
	v_rcp_f32_e32 v134, v129
	s_nop 0
	v_fma_f32 v164, -v129, v134, 1.0
	v_fma_f32 v129, v164, v134, v134
	v_mul_f32_e32 v128, v128, v129
	v_mul_f32_e32 v129, v191, v128
	v_cvt_pk_bf16_f32 v128, v138, v139
	v_cvt_pk_bf16_f32 v129, v140, v129
	global_store_dwordx2 v[144:145], v[128:129], off offset:8
	s_and_saveexec_b64 s[2:3], s[42:43]
	s_cbranch_execz .LBB0_687
	v_cmp_gt_i32_e32 vcc, 2, v190
	v_cvt_pk_bf16_f32 v128, v110, v111
	v_cvt_pk_bf16_f32 v129, v112, v113
	s_nop 1
	v_cndmask_b32_e32 v134, v0, v190, vcc
	v_add_u32_e32 v134, s4, v134
	v_ashrrev_i32_e32 v135, 31, v134
	v_lshlrev_b64 v[134:135], 11, v[134:135]
	v_lshl_add_u64 v[134:135], s[48:49], 0, v[134:135]
	v_lshl_add_u64 v[134:135], v[158:159], 1, v[134:135]
	global_store_dwordx2 v[134:135], v[128:129], off offset:-4088
; __device__ __forceinline__ unsigned cvt_pk_bf16(float lo, float hi) { unsigned r; asm volatile("v_cvt_pk_bf16_f32 %0, %1, %2" : "=v"(r) : "v"(lo), "v"(hi)); return r; }
; __device__ __forceinline__ float dppf_prev(float cur, float below) { return __uint_as_float(dpp_prev(__float_as_uint(cur), __float_as_uint(below))); }
; __device__ __forceinline__ float dppf_next(float cur, float above) { return __uint_as_float(dpp_next(__float_as_uint(cur), __float_as_uint(above))); }
; __device__ __forceinline__ float sigmoidf_(float x) { return 1.0f / (1.0f + __expf(-x)); }
;     __device__ __forceinline__ void operator()(AccT& acc, const Unit& u, int wr, int wc, int fr, int fq) const {
;     ...
;                             for (int j = 0; j < 4; ++j) { const float gp = dppf_prev(gc[j], m > 0 ? acc[ai][bj][m - 1][n][j] : 0.f), gn = dppf_next(gc[j], m < 3 ? acc[ai][bj][m + 1][n][j] : 0.f);
;                                 const float uu = gp * w0[j] + gc[j] * w1[j] + gn * w2[j] + b[j]; o[j] = uu * sigmoidf_(uu) * mul; }
;                             u32x2 w; w.x = cvt_pk_bf16(o[0], o[1]); w.y = cvt_pk_bf16(o[2], o[3]);
;                             *(u32x2*)(O + (size_t)(grp * 64 + lr) * NPROJ + col0 + bj * 128 + 4 * n) = w;
.LBB0_687:
	s_or_b64 exec, exec, s[2:3]
	v_mov_b32_e32 v128, v1
	v_mov_b32_e32 v129, v1
	s_nop 0
	v_mov_b32_dpp v128, v110 row_ror:1 row_mask:0xf bank_mask:0xf
	v_mov_b32_dpp v129, v102 row_ror:15 row_mask:0xf bank_mask:0xf
	s_nop 0
	v_mov_b32_dpp v128, v106 row_shr:1 row_mask:0xf bank_mask:0xf
	v_mov_b32_dpp v129, v106 row_shl:1 row_mask:0xf bank_mask:0xf
	v_pk_mul_f32 v[128:129], v[132:133], v[128:129]
	s_nop 0
	v_fma_f32 v110, v106, v114, v128
	v_add_f32_e32 v110, v110, v129
	v_add_f32_e32 v110, v122, v110
	v_mul_f32_e32 v128, 0xbfb8aa3b, v110
	v_exp_f32_e32 v128, v128
	s_nop 0
	v_add_f32_e32 v128, 1.0, v128
	s_nop 0
	v_rcp_f32_e32 v129, v128
	s_nop 0
	v_fma_f32 v138, -v128, v129, 1.0
	v_fma_f32 v128, v138, v129, v129
	v_mul_f32_e32 v110, v110, v128
	v_mul_f32_e32 v128, v191, v110
	v_mov_b32_e32 v110, v1
	s_nop 1
	v_mov_b32_dpp v110, v111 row_ror:1 row_mask:0xf bank_mask:0xf
	v_mov_b32_e32 v111, v1
	s_nop 0
	v_mov_b32_dpp v110, v107 row_shr:1 row_mask:0xf bank_mask:0xf
	v_mov_b32_dpp v111, v103 row_ror:15 row_mask:0xf bank_mask:0xf
	s_nop 1
	v_mov_b32_dpp v111, v107 row_shl:1 row_mask:0xf bank_mask:0xf
	v_pk_mul_f32 v[110:111], v[118:119], v[110:111]
	s_nop 0
	v_fma_f32 v110, v107, v115, v110
	v_add_f32_e32 v110, v110, v111
	v_add_f32_e32 v110, v123, v110
	v_mul_f32_e32 v111, 0xbfb8aa3b, v110
	v_exp_f32_e32 v111, v111
	s_nop 0
	v_add_f32_e32 v111, 1.0, v111
	s_nop 0
	v_rcp_f32_e32 v129, v111
	s_nop 0
	v_fma_f32 v138, -v111, v129, 1.0
	v_fma_f32 v111, v138, v129, v129
	v_mul_f32_e32 v110, v110, v111
	v_mul_f32_e32 v129, v191, v110
	v_mov_b32_e32 v110, v1
	v_mov_b32_e32 v111, v1
	s_nop 0
	v_mov_b32_dpp v110, v112 row_ror:1 row_mask:0xf bank_mask:0xf
	v_mov_b32_dpp v111, v104 row_ror:15 row_mask:0xf bank_mask:0xf
	s_nop 0
	v_mov_b32_dpp v110, v108 row_shr:1 row_mask:0xf bank_mask:0xf
	v_mov_b32_dpp v111, v108 row_shl:1 row_mask:0xf bank_mask:0xf
	v_pk_mul_f32 v[110:111], v[126:127], v[110:111]
	s_nop 0
	v_fma_f32 v110, v108, v116, v110
	v_add_f32_e32 v110, v110, v111
	v_add_f32_e32 v110, v124, v110
	v_mul_f32_e32 v111, 0xbfb8aa3b, v110
	v_exp_f32_e32 v111, v111
	s_nop 0
	v_add_f32_e32 v111, 1.0, v111
	s_nop 0
	v_rcp_f32_e32 v112, v111
	s_nop 0
	v_fma_f32 v138, -v111, v112, 1.0
	v_fma_f32 v111, v138, v112, v112
	v_mul_f32_e32 v110, v110, v111
	v_mul_f32_e32 v112, v191, v110
	v_mov_b32_e32 v110, v1
	v_mov_b32_e32 v111, v1
	s_nop 0
	v_mov_b32_dpp v110, v113 row_ror:1 row_mask:0xf bank_mask:0xf
	v_mov_b32_dpp v111, v105 row_ror:15 row_mask:0xf bank_mask:0xf
	s_nop 0
	v_mov_b32_dpp v110, v109 row_shr:1 row_mask:0xf bank_mask:0xf
	v_mov_b32_dpp v111, v109 row_shl:1 row_mask:0xf bank_mask:0xf
	v_pk_mul_f32 v[110:111], v[120:121], v[110:111]
	s_nop 0
	v_fma_f32 v110, v109, v117, v110
	v_add_f32_e32 v110, v110, v111
	v_add_f32_e32 v110, v125, v110
	v_mul_f32_e32 v111, 0xbfb8aa3b, v110
	v_exp_f32_e32 v111, v111
	s_nop 0
	v_add_f32_e32 v111, 1.0, v111
	s_nop 0
	v_rcp_f32_e32 v113, v111
	s_nop 0
	v_fma_f32 v138, -v111, v113, 1.0
	v_fma_f32 v111, v138, v113, v113
	v_mul_f32_e32 v110, v110, v111
	v_mul_f32_e32 v111, v191, v110
	v_cvt_pk_bf16_f32 v110, v128, v129
	v_cvt_pk_bf16_f32 v111, v112, v111
	global_store_dwordx2 v[178:179], v[110:111], off offset:8
	v_mov_b32_e32 v110, v1
	v_mov_b32_e32 v111, v1
	s_nop 0
	v_mov_b32_dpp v110, v106 row_ror:1 row_mask:0xf bank_mask:0xf
	v_mov_b32_dpp v111, v98 row_ror:15 row_mask:0xf bank_mask:0xf
	s_nop 0
	v_mov_b32_dpp v110, v102 row_shr:1 row_mask:0xf bank_mask:0xf
	v_mov_b32_dpp v111, v102 row_shl:1 row_mask:0xf bank_mask:0xf
	v_pk_mul_f32 v[110:111], v[132:133], v[110:111]
	s_nop 0
	v_fma_f32 v106, v102, v114, v110
	v_add_f32_e32 v106, v106, v111
	v_add_f32_e32 v106, v122, v106
	v_mul_f32_e32 v110, 0xbfb8aa3b, v106
	v_exp_f32_e32 v110, v110
	s_nop 0
	v_add_f32_e32 v110, 1.0, v110
	s_nop 0
	v_rcp_f32_e32 v111, v110
	s_nop 0
	v_fma_f32 v128, -v110, v111, 1.0
	v_fma_f32 v110, v128, v111, v111
	v_mul_f32_e32 v106, v106, v110
	v_mul_f32_e32 v110, v191, v106
	v_mov_b32_e32 v106, v1
	s_nop 1
	v_mov_b32_dpp v106, v107 row_ror:1 row_mask:0xf bank_mask:0xf
	v_mov_b32_e32 v107, v1
	s_nop 0
	v_mov_b32_dpp v106, v103 row_shr:1 row_mask:0xf bank_mask:0xf
	v_mov_b32_dpp v107, v99 row_ror:15 row_mask:0xf bank_mask:0xf
	s_nop 1
	v_mov_b32_dpp v107, v103 row_shl:1 row_mask:0xf bank_mask:0xf
	v_pk_mul_f32 v[106:107], v[118:119], v[106:107]
	s_nop 0
	v_fma_f32 v106, v103, v115, v106
	v_add_f32_e32 v106, v106, v107
	v_add_f32_e32 v106, v123, v106
	v_mul_f32_e32 v107, 0xbfb8aa3b, v106
	v_exp_f32_e32 v107, v107
	s_nop 0
	v_add_f32_e32 v107, 1.0, v107
	s_nop 0
	v_rcp_f32_e32 v111, v107
	s_nop 0
	v_fma_f32 v128, -v107, v111, 1.0
	v_fma_f32 v107, v128, v111, v111
	v_mul_f32_e32 v106, v106, v107
	v_mul_f32_e32 v111, v191, v106
	v_mov_b32_e32 v106, v1
	v_mov_b32_e32 v107, v1
	s_nop 0
	v_mov_b32_dpp v106, v108 row_ror:1 row_mask:0xf bank_mask:0xf
	v_mov_b32_dpp v107, v100 row_ror:15 row_mask:0xf bank_mask:0xf
	s_nop 0
	v_mov_b32_dpp v106, v104 row_shr:1 row_mask:0xf bank_mask:0xf
	v_mov_b32_dpp v107, v104 row_shl:1 row_mask:0xf bank_mask:0xf
	v_pk_mul_f32 v[106:107], v[126:127], v[106:107]
	s_nop 0
	v_fma_f32 v106, v104, v116, v106
	v_add_f32_e32 v106, v106, v107
	v_add_f32_e32 v106, v124, v106
	v_mul_f32_e32 v107, 0xbfb8aa3b, v106
	v_exp_f32_e32 v107, v107
	s_nop 0
	v_add_f32_e32 v107, 1.0, v107
	s_nop 0
	v_rcp_f32_e32 v108, v107
	s_nop 0
	v_fma_f32 v128, -v107, v108, 1.0
	v_fma_f32 v107, v128, v108, v108
	v_mul_f32_e32 v106, v106, v107
	v_mul_f32_e32 v108, v191, v106
	v_mov_b32_e32 v106, v1
	v_mov_b32_e32 v107, v1
	s_nop 0
	v_mov_b32_dpp v106, v109 row_ror:1 row_mask:0xf bank_mask:0xf
	v_mov_b32_dpp v107, v101 row_ror:15 row_mask:0xf bank_mask:0xf
; __device__ __forceinline__ unsigned cvt_pk_bf16(float lo, float hi) { unsigned r; asm volatile("v_cvt_pk_bf16_f32 %0, %1, %2" : "=v"(r) : "v"(lo), "v"(hi)); return r; }
; __device__ __forceinline__ float dppf_prev(float cur, float below) { return __uint_as_float(dpp_prev(__float_as_uint(cur), __float_as_uint(below))); }
; __device__ __forceinline__ float dppf_next(float cur, float above) { return __uint_as_float(dpp_next(__float_as_uint(cur), __float_as_uint(above))); }
; __device__ __forceinline__ float sigmoidf_(float x) { return 1.0f / (1.0f + __expf(-x)); }
;     __device__ __forceinline__ void operator()(AccT& acc, const Unit& u, int wr, int wc, int fr, int fq) const {
;     ...
;                         const f32x4 w0 = *(const f32x4*)(cw + mc + 4 * n), w1 = *(const f32x4*)(cw + 1024 + mc + 4 * n), w2 = *(const f32x4*)(cw + 2048 + mc + 4 * n), b = *(const f32x4*)(cb + mc + 4 * n);
; #pragma unroll
;                         for (int m = 0; m < 4; ++m) { const int lr = m * 16 + fr; const f32x4 gc = acc[ai][bj][m][n]; f32x4 o;
; #pragma unroll
;                             for (int j = 0; j < 4; ++j) { const float gp = dppf_prev(gc[j], m > 0 ? acc[ai][bj][m - 1][n][j] : 0.f), gn = dppf_next(gc[j], m < 3 ? acc[ai][bj][m + 1][n][j] : 0.f);
;                                 const float uu = gp * w0[j] + gc[j] * w1[j] + gn * w2[j] + b[j]; o[j] = uu * sigmoidf_(uu) * mul; }
;                             u32x2 w; w.x = cvt_pk_bf16(o[0], o[1]); w.y = cvt_pk_bf16(o[2], o[3]);
;                             *(u32x2*)(O + (size_t)(grp * 64 + lr) * NPROJ + col0 + bj * 128 + 4 * n) = w;
;                             if (m == 0 || m == 3) { if (lr < 2 || lr > 61) { u32x2 wg; wg.x = cvt_pk_bf16(gc[0], gc[1]); wg.y = cvt_pk_bf16(gc[2], gc[3]);
;                                 *(u32x2*)(HQ + (size_t)(grp * 4 + (lr < 2 ? lr : lr - 60)) * 1024 + mc + 4 * n) = wg; } } } } } }
	s_nop 0
	v_mov_b32_dpp v106, v105 row_shr:1 row_mask:0xf bank_mask:0xf
	v_mov_b32_dpp v107, v105 row_shl:1 row_mask:0xf bank_mask:0xf
	v_pk_mul_f32 v[106:107], v[120:121], v[106:107]
	s_nop 0
	v_fma_f32 v106, v105, v117, v106
	v_add_f32_e32 v106, v106, v107
	v_add_f32_e32 v106, v125, v106
	v_mul_f32_e32 v107, 0xbfb8aa3b, v106
	v_exp_f32_e32 v107, v107
	s_nop 0
	v_add_f32_e32 v107, 1.0, v107
	s_nop 0
	v_rcp_f32_e32 v109, v107
	s_nop 0
	v_fma_f32 v128, -v107, v109, 1.0
	v_fma_f32 v107, v128, v109, v109
	v_mul_f32_e32 v106, v106, v107
	v_mul_f32_e32 v107, v191, v106
	v_cvt_pk_bf16_f32 v106, v110, v111
	v_mov_b32_e32 v109, v1
	v_cvt_pk_bf16_f32 v107, v108, v107
	global_store_dwordx2 v[180:181], v[106:107], off offset:8
	v_mov_b32_e32 v106, v1
	v_mov_b32_dpp v109, v109 row_ror:15 row_mask:0xf bank_mask:0xf
	v_mov_b32_e32 v107, v109
	v_mov_b32_dpp v106, v102 row_ror:1 row_mask:0xf bank_mask:0xf
	s_nop 0
	v_mov_b32_dpp v107, v98 row_shl:1 row_mask:0xf bank_mask:0xf
	v_mov_b32_dpp v106, v98 row_shr:1 row_mask:0xf bank_mask:0xf
	v_pk_mul_f32 v[106:107], v[132:133], v[106:107]
	s_nop 0
	v_fma_f32 v102, v98, v114, v106
	v_add_f32_e32 v102, v102, v107
	v_add_f32_e32 v102, v122, v102
	v_mul_f32_e32 v106, 0xbfb8aa3b, v102
	v_exp_f32_e32 v106, v106
	s_nop 0
	v_add_f32_e32 v106, 1.0, v106
	s_nop 0
	v_rcp_f32_e32 v107, v106
	s_nop 0
	v_fma_f32 v111, -v106, v107, 1.0
	v_fma_f32 v106, v111, v107, v107
	v_mul_f32_e32 v102, v102, v106
	v_mul_f32_e32 v106, v191, v102
	v_mov_b32_e32 v102, v1
	s_nop 1
	v_mov_b32_dpp v102, v103 row_ror:1 row_mask:0xf bank_mask:0xf
	v_mov_b32_e32 v103, v109
	s_nop 0
	v_mov_b32_dpp v102, v99 row_shr:1 row_mask:0xf bank_mask:0xf
	v_mov_b32_dpp v103, v99 row_shl:1 row_mask:0xf bank_mask:0xf
	v_pk_mul_f32 v[102:103], v[118:119], v[102:103]
	s_nop 0
	v_fma_f32 v102, v99, v115, v102
	v_add_f32_e32 v102, v102, v103
	v_add_f32_e32 v102, v123, v102
	v_mul_f32_e32 v103, 0xbfb8aa3b, v102
	v_exp_f32_e32 v103, v103
	s_nop 0
	v_add_f32_e32 v103, 1.0, v103
	s_nop 0
	v_rcp_f32_e32 v107, v103
	s_nop 0
	v_fma_f32 v111, -v103, v107, 1.0
	v_fma_f32 v103, v111, v107, v107
	v_mul_f32_e32 v102, v102, v103
	v_mul_f32_e32 v107, v191, v102
	v_mov_b32_e32 v102, v1
	v_mov_b32_e32 v103, v109
	v_mov_b32_dpp v109, v101 row_shl:1 row_mask:0xf bank_mask:0xf
	v_mov_b32_dpp v102, v104 row_ror:1 row_mask:0xf bank_mask:0xf
	v_mov_b32_dpp v103, v100 row_shl:1 row_mask:0xf bank_mask:0xf
	s_nop 0
	v_mov_b32_dpp v102, v100 row_shr:1 row_mask:0xf bank_mask:0xf
	v_pk_mul_f32 v[102:103], v[126:127], v[102:103]
	s_nop 0
	v_fma_f32 v102, v100, v116, v102
	v_add_f32_e32 v102, v102, v103
	v_add_f32_e32 v102, v124, v102
	v_mul_f32_e32 v103, 0xbfb8aa3b, v102
	v_exp_f32_e32 v103, v103
	s_nop 0
	v_add_f32_e32 v103, 1.0, v103
	s_nop 0
	v_mov_b32_e32 v108, v1
	v_rcp_f32_e32 v104, v103
	s_nop 0
	v_fma_f32 v111, -v103, v104, 1.0
	v_fma_f32 v103, v111, v104, v104
	v_mul_f32_e32 v102, v102, v103
	v_mov_b32_dpp v108, v105 row_ror:1 row_mask:0xf bank_mask:0xf
	v_mul_f32_e32 v104, v191, v102
	s_nop 0
	v_mov_b32_dpp v108, v101 row_shr:1 row_mask:0xf bank_mask:0xf
	v_pk_mul_f32 v[102:103], v[120:121], v[108:109]
	s_nop 0
	v_fma_f32 v102, v101, v117, v102
	v_add_f32_e32 v102, v102, v103
	v_add_f32_e32 v102, v125, v102
	v_mul_f32_e32 v103, 0xbfb8aa3b, v102
	v_exp_f32_e32 v103, v103
	s_nop 0
	v_add_f32_e32 v103, 1.0, v103
	s_nop 0
	v_rcp_f32_e32 v105, v103
	s_nop 0
	v_fma_f32 v110, -v103, v105, 1.0
	v_fma_f32 v103, v110, v105, v105
	v_mul_f32_e32 v102, v102, v103
	v_mul_f32_e32 v103, v191, v102
	v_cvt_pk_bf16_f32 v102, v106, v107
	v_cvt_pk_bf16_f32 v103, v104, v103
	global_store_dwordx2 v[130:131], v[102:103], off offset:8
	s_and_saveexec_b64 s[2:3], s[44:45]
	s_cbranch_execz .LBB0_689
	s_movk_i32 s5, 0xffd2
	v_cmp_gt_i32_e32 vcc, s5, v190
	v_cvt_pk_bf16_f32 v98, v98, v99
	v_cvt_pk_bf16_f32 v99, v100, v101
	s_nop 1
	v_cndmask_b32_e32 v100, v137, v136, vcc
	v_add_u32_e32 v100, s4, v100
	v_ashrrev_i32_e32 v101, 31, v100
	v_lshlrev_b64 v[100:101], 11, v[100:101]
	v_lshl_add_u64 v[100:101], s[48:49], 0, v[100:101]
	v_lshl_add_u64 v[100:101], v[158:159], 1, v[100:101]
	global_store_dwordx2 v[100:101], v[98:99], off offset:-4088
.LBB0_689:
	s_or_b64 exec, exec, s[2:3]
	s_movk_i32 s2, 0x980
	v_cmp_gt_i32_e32 vcc, s2, v158
	v_readlane_b32 s60, v254, 34
	v_readlane_b32 s74, v254, 48
	v_cndmask_b32_e32 v120, 1.0, v218, vcc
	v_add_co_u32_e32 v98, vcc, 0xfffff000, v160
	v_readlane_b32 s75, v254, 49
	s_nop 0
	v_addc_co_u32_e32 v99, vcc, -1, v161, vcc
	s_waitcnt vmcnt(4)
	v_mov_b64_e32 v[110:111], v[196:197]
	v_mov_b64_e32 v[112:113], v[198:199]
	s_nop 0
	v_mov_b64_e32 v[98:99], v[204:205]
	v_mov_b64_e32 v[100:101], v[206:207]
	v_mov_b64_e32 v[102:103], v[222:223]
	v_mov_b64_e32 v[104:105], v[224:225]
	v_lshl_add_u64 v[114:115], v[158:159], 2, s[74:75]
	v_add_co_u32_e32 v106, vcc, 0xfffff000, v114
	v_mov_b32_e32 v118, v1
	s_nop 0
	v_addc_co_u32_e32 v107, vcc, -1, v115, vcc
	v_mov_b64_e32 v[106:107], v[226:227]
	v_mov_b64_e32 v[108:109], v[228:229]
	global_load_dwordx4 v[196:199], v[174:175], off offset:528
	global_load_dwordx4 v[204:207], v[160:161], off offset:-3568
	global_load_dwordx4 v[222:225], v[160:161], off offset:528
	global_load_dwordx4 v[226:229], v[176:177], off offset:528
	v_mov_b32_dpp v118, v118 row_ror:1 row_mask:0xf bank_mask:0xf
	v_mov_b32_e32 v123, v1
	v_mov_b32_e32 v122, v118
	v_readlane_b32 s61, v254, 35
	v_mov_b32_dpp v123, v90 row_ror:15 row_mask:0xf bank_mask:0xf
	v_mov_b32_dpp v122, v94 row_shr:1 row_mask:0xf bank_mask:0xf
	v_readlane_b32 s62, v254, 36
	v_mov_b32_dpp v123, v94 row_shl:1 row_mask:0xf bank_mask:0xf
	v_readlane_b32 s63, v254, 37
	v_readlane_b32 s64, v254, 38
	v_readlane_b32 s65, v254, 39
	v_readlane_b32 s66, v254, 40
	v_readlane_b32 s67, v254, 41
	v_readlane_b32 s68, v254, 42
	v_readlane_b32 s69, v254, 43
	v_readlane_b32 s70, v254, 44
	v_readlane_b32 s71, v254, 45
	v_readlane_b32 s72, v254, 46
	v_readlane_b32 s73, v254, 47
	s_waitcnt vmcnt(4)
; __device__ __forceinline__ unsigned cvt_pk_bf16(float lo, float hi) { unsigned r; asm volatile("v_cvt_pk_bf16_f32 %0, %1, %2" : "=v"(r) : "v"(lo), "v"(hi)); return r; }
; __device__ __forceinline__ float dppf_prev(float cur, float below) { return __uint_as_float(dpp_prev(__float_as_uint(cur), __float_as_uint(below))); }
; __device__ __forceinline__ float dppf_next(float cur, float above) { return __uint_as_float(dpp_next(__float_as_uint(cur), __float_as_uint(above))); }
; __device__ __forceinline__ float sigmoidf_(float x) { return 1.0f / (1.0f + __expf(-x)); }
;     __device__ __forceinline__ void operator()(AccT& acc, const Unit& u, int wr, int wc, int fr, int fq) const {
;     ...
;                             for (int j = 0; j < 4; ++j) { const float gp = dppf_prev(gc[j], m > 0 ? acc[ai][bj][m - 1][n][j] : 0.f), gn = dppf_next(gc[j], m < 3 ? acc[ai][bj][m + 1][n][j] : 0.f);
;                                 const float uu = gp * w0[j] + gc[j] * w1[j] + gn * w2[j] + b[j]; o[j] = uu * sigmoidf_(uu) * mul; }
;                             u32x2 w; w.x = cvt_pk_bf16(o[0], o[1]); w.y = cvt_pk_bf16(o[2], o[3]);
;                             *(u32x2*)(O + (size_t)(grp * 64 + lr) * NPROJ + col0 + bj * 128 + 4 * n) = w;
;                             if (m == 0 || m == 3) { if (lr < 2 || lr > 61) { u32x2 wg; wg.x = cvt_pk_bf16(gc[0], gc[1]); wg.y = cvt_pk_bf16(gc[2], gc[3]);
;                                 *(u32x2*)(HQ + (size_t)(grp * 4 + (lr < 2 ? lr : lr - 60)) * 1024 + mc + 4 * n) = wg; } } } } } }
	v_mov_b32_e32 v116, v110
	v_mov_b32_e32 v117, v102
	v_pk_mul_f32 v[122:123], v[116:117], v[122:123]
	s_nop 0
	v_fma_f32 v102, v94, v98, v122
	v_add_f32_e32 v102, v102, v123
	v_add_f32_e32 v102, v106, v102
	v_mul_f32_e32 v110, 0xbfb8aa3b, v102
	v_exp_f32_e32 v110, v110
	s_nop 0
	v_add_f32_e32 v110, 1.0, v110
	s_nop 0
	v_rcp_f32_e32 v119, v110
	s_nop 0
	v_fma_f32 v123, -v110, v119, 1.0
	v_fma_f32 v110, v123, v119, v119
	v_mov_b32_e32 v123, v1
	v_mul_f32_e32 v102, v102, v110
	v_mov_b32_e32 v122, v118
	v_mov_b32_dpp v123, v91 row_ror:15 row_mask:0xf bank_mask:0xf
	v_mul_f32_e32 v121, v120, v102
	v_mov_b32_dpp v122, v95 row_shr:1 row_mask:0xf bank_mask:0xf
	v_mov_b32_dpp v123, v95 row_shl:1 row_mask:0xf bank_mask:0xf
	v_mov_b32_e32 v102, v111
	v_pk_mul_f32 v[110:111], v[102:103], v[122:123]
	s_nop 0
	v_fma_f32 v110, v95, v99, v110
	v_add_f32_e32 v110, v110, v111
	v_add_f32_e32 v110, v107, v110
	v_mul_f32_e32 v111, 0xbfb8aa3b, v110
	v_exp_f32_e32 v111, v111
	s_nop 0
	v_add_f32_e32 v111, 1.0, v111
	s_nop 0
	v_rcp_f32_e32 v119, v111
	s_nop 0
	v_fma_f32 v124, -v111, v119, 1.0
	v_fma_f32 v111, v124, v119, v119
	v_mov_b32_e32 v125, v1
	v_mul_f32_e32 v110, v110, v111
	v_mov_b32_e32 v124, v118
	v_mov_b32_dpp v125, v92 row_ror:15 row_mask:0xf bank_mask:0xf
	v_mul_f32_e32 v122, v120, v110
	v_mov_b32_dpp v124, v96 row_shr:1 row_mask:0xf bank_mask:0xf
	v_mov_b32_dpp v125, v96 row_shl:1 row_mask:0xf bank_mask:0xf
	v_mov_b32_e32 v110, v112
	v_mov_b32_e32 v111, v104
	v_pk_mul_f32 v[124:125], v[110:111], v[124:125]
	v_mov_b32_dpp v118, v97 row_shr:1 row_mask:0xf bank_mask:0xf
	v_fma_f32 v104, v96, v100, v124
	v_add_f32_e32 v104, v104, v125
	v_add_f32_e32 v104, v108, v104
	v_mul_f32_e32 v112, 0xbfb8aa3b, v104
	v_exp_f32_e32 v112, v112
	s_nop 0
	v_add_f32_e32 v112, 1.0, v112
	s_nop 0
	v_rcp_f32_e32 v119, v112
	s_nop 0
	v_fma_f32 v125, -v112, v119, 1.0
	v_fma_f32 v112, v125, v119, v119
	v_mov_b32_e32 v119, v1
	v_mul_f32_e32 v104, v104, v112
	v_mul_f32_e32 v123, v120, v104
	v_mov_b32_dpp v119, v93 row_ror:15 row_mask:0xf bank_mask:0xf
	v_mov_b32_e32 v104, v113
	s_nop 0
	v_mov_b32_dpp v119, v97 row_shl:1 row_mask:0xf bank_mask:0xf
	v_pk_mul_f32 v[112:113], v[104:105], v[118:119]
	s_nop 0
	v_fma_f32 v112, v97, v101, v112
	v_add_f32_e32 v112, v112, v113
	v_add_f32_e32 v112, v109, v112
	v_mul_f32_e32 v113, 0xbfb8aa3b, v112
	v_exp_f32_e32 v113, v113
	s_nop 0
	v_add_f32_e32 v113, 1.0, v113
	s_nop 0
	v_rcp_f32_e32 v118, v113
	s_nop 0
	v_fma_f32 v125, -v113, v118, 1.0
	v_fma_f32 v113, v125, v118, v118
	v_mul_f32_e32 v112, v112, v113
	v_mul_f32_e32 v113, v120, v112
	v_cvt_pk_bf16_f32 v112, v121, v122
	v_cvt_pk_bf16_f32 v113, v123, v113
	global_store_dwordx2 v[144:145], v[112:113], off offset:256
	s_and_saveexec_b64 s[2:3], s[42:43]
	s_cbranch_execz .LBB0_691
	v_cmp_gt_i32_e32 vcc, 2, v190
	v_cvt_pk_bf16_f32 v112, v94, v95
	v_cvt_pk_bf16_f32 v113, v96, v97
	s_nop 1
	v_cndmask_b32_e32 v118, v0, v190, vcc
	v_add_u32_e32 v118, s4, v118
	v_ashrrev_i32_e32 v119, 31, v118
	v_lshlrev_b64 v[118:119], 11, v[118:119]
	v_lshl_add_u64 v[118:119], s[48:49], 0, v[118:119]
	v_lshl_add_u64 v[118:119], v[158:159], 1, v[118:119]
	global_store_dwordx2 v[118:119], v[112:113], off offset:-3840
.LBB0_691:
	s_or_b64 exec, exec, s[2:3]
	v_mov_b32_e32 v112, v1
	v_mov_b32_e32 v113, v1
	s_nop 0
	v_mov_b32_dpp v112, v94 row_ror:1 row_mask:0xf bank_mask:0xf
	v_mov_b32_dpp v113, v86 row_ror:15 row_mask:0xf bank_mask:0xf
	s_nop 0
	v_mov_b32_dpp v112, v90 row_shr:1 row_mask:0xf bank_mask:0xf
	v_mov_b32_dpp v113, v90 row_shl:1 row_mask:0xf bank_mask:0xf
	v_pk_mul_f32 v[112:113], v[116:117], v[112:113]
	s_nop 0
	v_fma_f32 v94, v90, v98, v112
	v_add_f32_e32 v94, v94, v113
	v_add_f32_e32 v94, v106, v94
	v_mul_f32_e32 v112, 0xbfb8aa3b, v94
	v_exp_f32_e32 v112, v112
	s_nop 0
	v_add_f32_e32 v112, 1.0, v112
	s_nop 0
	v_rcp_f32_e32 v113, v112
	s_nop 0
	v_fma_f32 v121, -v112, v113, 1.0
	v_fma_f32 v112, v121, v113, v113
	v_mul_f32_e32 v94, v94, v112
	v_mul_f32_e32 v112, v120, v94
	v_mov_b32_e32 v94, v1
	s_nop 1
	v_mov_b32_dpp v94, v95 row_ror:1 row_mask:0xf bank_mask:0xf
	v_mov_b32_e32 v95, v1
	s_nop 0
	v_mov_b32_dpp v94, v91 row_shr:1 row_mask:0xf bank_mask:0xf
	v_mov_b32_dpp v95, v87 row_ror:15 row_mask:0xf bank_mask:0xf
	s_nop 1
	v_mov_b32_dpp v95, v91 row_shl:1 row_mask:0xf bank_mask:0xf
	v_pk_mul_f32 v[94:95], v[102:103], v[94:95]
	s_nop 0
	v_fma_f32 v94, v91, v99, v94
	v_add_f32_e32 v94, v94, v95
	v_add_f32_e32 v94, v107, v94
	v_mul_f32_e32 v95, 0xbfb8aa3b, v94
	v_exp_f32_e32 v95, v95
	s_nop 0
	v_add_f32_e32 v95, 1.0, v95
	s_nop 0
	v_rcp_f32_e32 v113, v95
	s_nop 0
	v_fma_f32 v121, -v95, v113, 1.0
	v_fma_f32 v95, v121, v113, v113
	v_mul_f32_e32 v94, v94, v95
	v_mul_f32_e32 v113, v120, v94
	v_mov_b32_e32 v94, v1
	v_mov_b32_e32 v95, v1
	s_nop 0
	v_mov_b32_dpp v94, v96 row_ror:1 row_mask:0xf bank_mask:0xf
	v_mov_b32_dpp v95, v88 row_ror:15 row_mask:0xf bank_mask:0xf
	s_nop 0
	v_mov_b32_dpp v94, v92 row_shr:1 row_mask:0xf bank_mask:0xf
	v_mov_b32_dpp v95, v92 row_shl:1 row_mask:0xf bank_mask:0xf
	v_pk_mul_f32 v[94:95], v[110:111], v[94:95]
	s_nop 0
	v_fma_f32 v94, v92, v100, v94
	v_add_f32_e32 v94, v94, v95
	v_add_f32_e32 v94, v108, v94
	v_mul_f32_e32 v95, 0xbfb8aa3b, v94
	v_exp_f32_e32 v95, v95
	s_nop 0
	v_add_f32_e32 v95, 1.0, v95
	s_nop 0
	v_rcp_f32_e32 v96, v95
	s_nop 0
	v_fma_f32 v121, -v95, v96, 1.0
	v_fma_f32 v95, v121, v96, v96
	v_mul_f32_e32 v94, v94, v95
	v_mul_f32_e32 v96, v120, v94
	v_mov_b32_e32 v94, v1
	v_mov_b32_e32 v95, v1
	s_nop 0
	v_mov_b32_dpp v94, v97 row_ror:1 row_mask:0xf bank_mask:0xf
	v_mov_b32_dpp v95, v89 row_ror:15 row_mask:0xf bank_mask:0xf
	s_nop 0
	v_mov_b32_dpp v94, v93 row_shr:1 row_mask:0xf bank_mask:0xf
; __device__ __forceinline__ unsigned cvt_pk_bf16(float lo, float hi) { unsigned r; asm volatile("v_cvt_pk_bf16_f32 %0, %1, %2" : "=v"(r) : "v"(lo), "v"(hi)); return r; }
; __device__ __forceinline__ float dppf_prev(float cur, float below) { return __uint_as_float(dpp_prev(__float_as_uint(cur), __float_as_uint(below))); }
; __device__ __forceinline__ float dppf_next(float cur, float above) { return __uint_as_float(dpp_next(__float_as_uint(cur), __float_as_uint(above))); }
; __device__ __forceinline__ float sigmoidf_(float x) { return 1.0f / (1.0f + __expf(-x)); }
;     __device__ __forceinline__ void operator()(AccT& acc, const Unit& u, int wr, int wc, int fr, int fq) const {
;     ...
;                             for (int j = 0; j < 4; ++j) { const float gp = dppf_prev(gc[j], m > 0 ? acc[ai][bj][m - 1][n][j] : 0.f), gn = dppf_next(gc[j], m < 3 ? acc[ai][bj][m + 1][n][j] : 0.f);
;                                 const float uu = gp * w0[j] + gc[j] * w1[j] + gn * w2[j] + b[j]; o[j] = uu * sigmoidf_(uu) * mul; }
;                             u32x2 w; w.x = cvt_pk_bf16(o[0], o[1]); w.y = cvt_pk_bf16(o[2], o[3]);
;                             *(u32x2*)(O + (size_t)(grp * 64 + lr) * NPROJ + col0 + bj * 128 + 4 * n) = w;
;                             if (m == 0 || m == 3) { if (lr < 2 || lr > 61) { u32x2 wg; wg.x = cvt_pk_bf16(gc[0], gc[1]); wg.y = cvt_pk_bf16(gc[2], gc[3]);
;                                 *(u32x2*)(HQ + (size_t)(grp * 4 + (lr < 2 ? lr : lr - 60)) * 1024 + mc + 4 * n) = wg; } } } } } }
	v_mov_b32_dpp v95, v93 row_shl:1 row_mask:0xf bank_mask:0xf
	v_pk_mul_f32 v[94:95], v[104:105], v[94:95]
	s_nop 0
	v_fma_f32 v94, v93, v101, v94
	v_add_f32_e32 v94, v94, v95
	v_add_f32_e32 v94, v109, v94
	v_mul_f32_e32 v95, 0xbfb8aa3b, v94
	v_exp_f32_e32 v95, v95
	s_nop 0
	v_add_f32_e32 v95, 1.0, v95
	s_nop 0
	v_rcp_f32_e32 v97, v95
	s_nop 0
	v_fma_f32 v121, -v95, v97, 1.0
	v_fma_f32 v95, v121, v97, v97
	v_mul_f32_e32 v94, v94, v95
	v_mul_f32_e32 v95, v120, v94
	v_cvt_pk_bf16_f32 v94, v112, v113
	v_cvt_pk_bf16_f32 v95, v96, v95
	global_store_dwordx2 v[178:179], v[94:95], off offset:256
	v_mov_b32_e32 v94, v1
	v_mov_b32_e32 v95, v1
	s_nop 0
	v_mov_b32_dpp v94, v90 row_ror:1 row_mask:0xf bank_mask:0xf
	v_mov_b32_dpp v95, v82 row_ror:15 row_mask:0xf bank_mask:0xf
	s_nop 0
	v_mov_b32_dpp v94, v86 row_shr:1 row_mask:0xf bank_mask:0xf
	v_mov_b32_dpp v95, v86 row_shl:1 row_mask:0xf bank_mask:0xf
	v_pk_mul_f32 v[94:95], v[116:117], v[94:95]
	s_nop 0
	v_fma_f32 v90, v86, v98, v94
	v_add_f32_e32 v90, v90, v95
	v_add_f32_e32 v90, v106, v90
	v_mul_f32_e32 v94, 0xbfb8aa3b, v90
	v_exp_f32_e32 v94, v94
	s_nop 0
	v_add_f32_e32 v94, 1.0, v94
	s_nop 0
	v_rcp_f32_e32 v95, v94
	s_nop 0
	v_fma_f32 v112, -v94, v95, 1.0
	v_fma_f32 v94, v112, v95, v95
	v_mul_f32_e32 v90, v90, v94
	v_mul_f32_e32 v94, v120, v90
	v_mov_b32_e32 v90, v1
	s_nop 1
	v_mov_b32_dpp v90, v91 row_ror:1 row_mask:0xf bank_mask:0xf
	v_mov_b32_e32 v91, v1
	s_nop 0
	v_mov_b32_dpp v90, v87 row_shr:1 row_mask:0xf bank_mask:0xf
	v_mov_b32_dpp v91, v83 row_ror:15 row_mask:0xf bank_mask:0xf
	s_nop 1
	v_mov_b32_dpp v91, v87 row_shl:1 row_mask:0xf bank_mask:0xf
	v_pk_mul_f32 v[90:91], v[102:103], v[90:91]
	s_nop 0
	v_fma_f32 v90, v87, v99, v90
	v_add_f32_e32 v90, v90, v91
	v_add_f32_e32 v90, v107, v90
	v_mul_f32_e32 v91, 0xbfb8aa3b, v90
	v_exp_f32_e32 v91, v91
	s_nop 0
	v_add_f32_e32 v91, 1.0, v91
	s_nop 0
	v_rcp_f32_e32 v95, v91
	s_nop 0
	v_fma_f32 v112, -v91, v95, 1.0
	v_fma_f32 v91, v112, v95, v95
	v_mul_f32_e32 v90, v90, v91
	v_mul_f32_e32 v95, v120, v90
	v_mov_b32_e32 v90, v1
	v_mov_b32_e32 v91, v1
	s_nop 0
	v_mov_b32_dpp v90, v92 row_ror:1 row_mask:0xf bank_mask:0xf
	v_mov_b32_dpp v91, v84 row_ror:15 row_mask:0xf bank_mask:0xf
	s_nop 0
	v_mov_b32_dpp v90, v88 row_shr:1 row_mask:0xf bank_mask:0xf
	v_mov_b32_dpp v91, v88 row_shl:1 row_mask:0xf bank_mask:0xf
	v_pk_mul_f32 v[90:91], v[110:111], v[90:91]
	s_nop 0
	v_fma_f32 v90, v88, v100, v90
	v_add_f32_e32 v90, v90, v91
	v_add_f32_e32 v90, v108, v90
	v_mul_f32_e32 v91, 0xbfb8aa3b, v90
	v_exp_f32_e32 v91, v91
	s_nop 0
	v_add_f32_e32 v91, 1.0, v91
	s_nop 0
	v_rcp_f32_e32 v92, v91
	s_nop 0
	v_fma_f32 v112, -v91, v92, 1.0
	v_fma_f32 v91, v112, v92, v92
	v_mul_f32_e32 v90, v90, v91
	v_mul_f32_e32 v92, v120, v90
	v_mov_b32_e32 v90, v1
	v_mov_b32_e32 v91, v1
	s_nop 0
	v_mov_b32_dpp v90, v93 row_ror:1 row_mask:0xf bank_mask:0xf
	v_mov_b32_dpp v91, v85 row_ror:15 row_mask:0xf bank_mask:0xf
	s_nop 0
	v_mov_b32_dpp v90, v89 row_shr:1 row_mask:0xf bank_mask:0xf
	v_mov_b32_dpp v91, v89 row_shl:1 row_mask:0xf bank_mask:0xf
	v_pk_mul_f32 v[90:91], v[104:105], v[90:91]
	s_nop 0
	v_fma_f32 v90, v89, v101, v90
	v_add_f32_e32 v90, v90, v91
	v_add_f32_e32 v90, v109, v90
	v_mul_f32_e32 v91, 0xbfb8aa3b, v90
	v_exp_f32_e32 v91, v91
	s_nop 0
	v_add_f32_e32 v91, 1.0, v91
	s_nop 0
	v_rcp_f32_e32 v93, v91
	s_nop 0
	v_fma_f32 v112, -v91, v93, 1.0
	v_fma_f32 v91, v112, v93, v93
	v_mul_f32_e32 v90, v90, v91
	v_mul_f32_e32 v91, v120, v90
	v_cvt_pk_bf16_f32 v90, v94, v95
	v_mov_b32_e32 v93, v1
	v_cvt_pk_bf16_f32 v91, v92, v91
	global_store_dwordx2 v[180:181], v[90:91], off offset:256
	v_mov_b32_e32 v90, v1
	v_mov_b32_dpp v93, v93 row_ror:15 row_mask:0xf bank_mask:0xf
	v_mov_b32_e32 v91, v93
	v_mov_b32_dpp v90, v86 row_ror:1 row_mask:0xf bank_mask:0xf
	s_nop 0
	v_mov_b32_dpp v91, v82 row_shl:1 row_mask:0xf bank_mask:0xf
	v_mov_b32_dpp v90, v82 row_shr:1 row_mask:0xf bank_mask:0xf
	v_pk_mul_f32 v[90:91], v[116:117], v[90:91]
	s_nop 0
	v_fma_f32 v86, v82, v98, v90
	v_add_f32_e32 v86, v86, v91
	v_add_f32_e32 v86, v106, v86
	v_mul_f32_e32 v90, 0xbfb8aa3b, v86
	v_exp_f32_e32 v90, v90
	s_nop 0
	v_add_f32_e32 v90, 1.0, v90
	s_nop 0
	v_rcp_f32_e32 v91, v90
	s_nop 0
	v_fma_f32 v95, -v90, v91, 1.0
	v_fma_f32 v90, v95, v91, v91
	v_mul_f32_e32 v86, v86, v90
	v_mul_f32_e32 v90, v120, v86
	v_mov_b32_e32 v86, v1
	s_nop 1
	v_mov_b32_dpp v86, v87 row_ror:1 row_mask:0xf bank_mask:0xf
	v_mov_b32_e32 v87, v93
	s_nop 0
	v_mov_b32_dpp v86, v83 row_shr:1 row_mask:0xf bank_mask:0xf
	v_mov_b32_dpp v87, v83 row_shl:1 row_mask:0xf bank_mask:0xf
	v_pk_mul_f32 v[86:87], v[102:103], v[86:87]
	s_nop 0
	v_fma_f32 v86, v83, v99, v86
	v_add_f32_e32 v86, v86, v87
	v_add_f32_e32 v86, v107, v86
	v_mul_f32_e32 v87, 0xbfb8aa3b, v86
	v_exp_f32_e32 v87, v87
	s_nop 0
	v_add_f32_e32 v87, 1.0, v87
	s_nop 0
	v_rcp_f32_e32 v91, v87
	s_nop 0
	v_fma_f32 v95, -v87, v91, 1.0
	v_fma_f32 v87, v95, v91, v91
	v_mul_f32_e32 v86, v86, v87
	v_mul_f32_e32 v91, v120, v86
	v_mov_b32_e32 v86, v1
	v_mov_b32_e32 v87, v93
	v_mov_b32_dpp v93, v85 row_shl:1 row_mask:0xf bank_mask:0xf
	v_mov_b32_dpp v86, v88 row_ror:1 row_mask:0xf bank_mask:0xf
	v_mov_b32_dpp v87, v84 row_shl:1 row_mask:0xf bank_mask:0xf
	s_nop 0
	v_mov_b32_dpp v86, v84 row_shr:1 row_mask:0xf bank_mask:0xf
	v_pk_mul_f32 v[86:87], v[110:111], v[86:87]
	s_nop 0
	v_fma_f32 v86, v84, v100, v86
	v_add_f32_e32 v86, v86, v87
	v_add_f32_e32 v86, v108, v86
	v_mul_f32_e32 v87, 0xbfb8aa3b, v86
	v_exp_f32_e32 v87, v87
	s_nop 0
	v_add_f32_e32 v87, 1.0, v87
	s_nop 0
	v_mov_b32_e32 v92, v1
	v_rcp_f32_e32 v88, v87
	s_nop 0
	v_fma_f32 v95, -v87, v88, 1.0
	v_fma_f32 v87, v95, v88, v88
	v_mul_f32_e32 v86, v86, v87
	v_mov_b32_dpp v92, v89 row_ror:1 row_mask:0xf bank_mask:0xf
	v_mul_f32_e32 v88, v120, v86
	s_nop 0
	v_mov_b32_dpp v92, v85 row_shr:1 row_mask:0xf bank_mask:0xf
	v_pk_mul_f32 v[86:87], v[104:105], v[92:93]
	s_nop 0
	v_fma_f32 v86, v85, v101, v86
	v_add_f32_e32 v86, v86, v87
	v_add_f32_e32 v86, v109, v86
	v_mul_f32_e32 v87, 0xbfb8aa3b, v86
	v_exp_f32_e32 v87, v87
	s_nop 0
	v_add_f32_e32 v87, 1.0, v87
	s_nop 0
	v_rcp_f32_e32 v89, v87
	s_nop 0
	v_fma_f32 v94, -v87, v89, 1.0
	v_fma_f32 v87, v94, v89, v89
	v_mul_f32_e32 v86, v86, v87
	v_mul_f32_e32 v87, v120, v86
	v_cvt_pk_bf16_f32 v86, v90, v91
	v_cvt_pk_bf16_f32 v87, v88, v87
	global_store_dwordx2 v[130:131], v[86:87], off offset:256
	s_and_saveexec_b64 s[2:3], s[44:45]
	s_cbranch_execz .LBB0_693
	s_movk_i32 s5, 0xffd2
	v_cmp_gt_i32_e32 vcc, s5, v190
	v_cvt_pk_bf16_f32 v82, v82, v83
	v_cvt_pk_bf16_f32 v83, v84, v85
	s_nop 1
	v_cndmask_b32_e32 v84, v137, v136, vcc
	v_add_u32_e32 v84, s4, v84
	v_ashrrev_i32_e32 v85, 31, v84
	v_lshlrev_b64 v[84:85], 11, v[84:85]
	v_lshl_add_u64 v[84:85], s[48:49], 0, v[84:85]
	v_lshl_add_u64 v[84:85], v[158:159], 1, v[84:85]
	global_store_dwordx2 v[84:85], v[82:83], off offset:-3840
; __device__ __forceinline__ unsigned cvt_pk_bf16(float lo, float hi) { unsigned r; asm volatile("v_cvt_pk_bf16_f32 %0, %1, %2" : "=v"(r) : "v"(lo), "v"(hi)); return r; }
; __device__ __forceinline__ float dppf_prev(float cur, float below) { return __uint_as_float(dpp_prev(__float_as_uint(cur), __float_as_uint(below))); }
; __device__ __forceinline__ float dppf_next(float cur, float above) { return __uint_as_float(dpp_next(__float_as_uint(cur), __float_as_uint(above))); }
; __device__ __forceinline__ float sigmoidf_(float x) { return 1.0f / (1.0f + __expf(-x)); }
;     __device__ __forceinline__ void operator()(AccT& acc, const Unit& u, int wr, int wc, int fr, int fq) const {
;     ...
;                         const f32x4 w0 = *(const f32x4*)(cw + mc + 4 * n), w1 = *(const f32x4*)(cw + 1024 + mc + 4 * n), w2 = *(const f32x4*)(cw + 2048 + mc + 4 * n), b = *(const f32x4*)(cb + mc + 4 * n);
; #pragma unroll
;                         for (int m = 0; m < 4; ++m) { const int lr = m * 16 + fr; const f32x4 gc = acc[ai][bj][m][n]; f32x4 o;
; #pragma unroll
;                             for (int j = 0; j < 4; ++j) { const float gp = dppf_prev(gc[j], m > 0 ? acc[ai][bj][m - 1][n][j] : 0.f), gn = dppf_next(gc[j], m < 3 ? acc[ai][bj][m + 1][n][j] : 0.f);
;                                 const float uu = gp * w0[j] + gc[j] * w1[j] + gn * w2[j] + b[j]; o[j] = uu * sigmoidf_(uu) * mul; }
;                             u32x2 w; w.x = cvt_pk_bf16(o[0], o[1]); w.y = cvt_pk_bf16(o[2], o[3]);
;                             *(u32x2*)(O + (size_t)(grp * 64 + lr) * NPROJ + col0 + bj * 128 + 4 * n) = w;
;                             if (m == 0 || m == 3) { if (lr < 2 || lr > 61) { u32x2 wg; wg.x = cvt_pk_bf16(gc[0], gc[1]); wg.y = cvt_pk_bf16(gc[2], gc[3]);
;                                 *(u32x2*)(HQ + (size_t)(grp * 4 + (lr < 2 ? lr : lr - 60)) * 1024 + mc + 4 * n) = wg; } } } } } }
.LBB0_693:
	s_or_b64 exec, exec, s[2:3]
	s_movk_i32 s2, 0xe200
	s_mov_b32 s3, -1
	v_lshl_add_u64 v[100:101], v[160:161], 0, s[2:3]
	v_add_co_u32_e32 v82, vcc, 0x1000, v100
	s_waitcnt vmcnt(4)
	v_mov_b64_e32 v[94:95], v[196:197]
	v_mov_b64_e32 v[96:97], v[198:199]
	s_nop 0
	v_addc_co_u32_e32 v83, vcc, 0, v101, vcc
	v_add_co_u32_e32 v86, vcc, 0x2000, v100
	v_lshl_add_u64 v[98:99], v[114:115], 0, s[2:3]
	s_nop 0
	v_addc_co_u32_e32 v87, vcc, 0, v101, vcc
	v_mov_b64_e32 v[82:83], v[204:205]
	v_mov_b64_e32 v[84:85], v[206:207]
	s_nop 0
	v_mov_b64_e32 v[86:87], v[222:223]
	v_mov_b64_e32 v[88:89], v[224:225]
	s_nop 0
	v_mov_b64_e32 v[90:91], v[226:227]
	v_mov_b64_e32 v[92:93], v[228:229]
	global_load_dwordx4 v[196:199], v[174:175], off
	global_load_dwordx4 v[204:207], v[160:161], off offset:-4096
	global_load_dwordx4 v[222:225], v[160:161], off
	global_load_dwordx4 v[226:229], v[176:177], off
	v_mov_b32_e32 v104, v1
	v_mov_b32_e32 v107, v1
	s_waitcnt vmcnt(4)
	v_mov_b32_e32 v102, v94
	v_mov_b32_dpp v104, v104 row_ror:1 row_mask:0xf bank_mask:0xf
	v_mov_b32_e32 v106, v104
	v_mov_b32_dpp v107, v74 row_ror:15 row_mask:0xf bank_mask:0xf
	v_mov_b32_e32 v103, v86
	v_mov_b32_dpp v106, v78 row_shr:1 row_mask:0xf bank_mask:0xf
	v_mov_b32_dpp v107, v78 row_shl:1 row_mask:0xf bank_mask:0xf
	v_pk_mul_f32 v[106:107], v[102:103], v[106:107]
	s_nop 0
	v_fma_f32 v86, v78, v82, v106
	v_add_f32_e32 v86, v86, v107
	v_add_f32_e32 v86, v90, v86
	v_mul_f32_e32 v94, 0xbfb8aa3b, v86
	v_exp_f32_e32 v94, v94
	s_nop 0
	v_add_f32_e32 v94, 1.0, v94
	s_nop 0
	v_rcp_f32_e32 v105, v94
	s_nop 0
	v_fma_f32 v108, -v94, v105, 1.0
	v_fma_f32 v94, v108, v105, v105
	v_mov_b32_e32 v109, v1
	v_mul_f32_e32 v86, v86, v94
	v_mov_b32_e32 v108, v104
	v_mov_b32_dpp v109, v75 row_ror:15 row_mask:0xf bank_mask:0xf
	v_mul_f32_e32 v106, v120, v86
	v_mov_b32_dpp v108, v79 row_shr:1 row_mask:0xf bank_mask:0xf
	v_mov_b32_dpp v109, v79 row_shl:1 row_mask:0xf bank_mask:0xf
	v_mov_b32_e32 v86, v95
	v_pk_mul_f32 v[94:95], v[86:87], v[108:109]
	s_nop 0
	v_fma_f32 v94, v79, v83, v94
	v_add_f32_e32 v94, v94, v95
	v_add_f32_e32 v94, v91, v94
	v_mul_f32_e32 v95, 0xbfb8aa3b, v94
	v_exp_f32_e32 v95, v95
	s_nop 0
	v_add_f32_e32 v95, 1.0, v95
	s_nop 0
	v_rcp_f32_e32 v105, v95
	s_nop 0
	v_fma_f32 v109, -v95, v105, 1.0
	v_fma_f32 v95, v109, v105, v105
	v_mov_b32_e32 v109, v1
	v_mul_f32_e32 v94, v94, v95
	v_mov_b32_e32 v108, v104
	v_mov_b32_dpp v109, v76 row_ror:15 row_mask:0xf bank_mask:0xf
	v_mul_f32_e32 v107, v120, v94
	v_mov_b32_dpp v108, v80 row_shr:1 row_mask:0xf bank_mask:0xf
	v_mov_b32_dpp v109, v80 row_shl:1 row_mask:0xf bank_mask:0xf
	v_mov_b32_e32 v94, v96
	v_mov_b32_e32 v95, v88
	v_pk_mul_f32 v[108:109], v[94:95], v[108:109]
	v_mov_b32_dpp v104, v81 row_shr:1 row_mask:0xf bank_mask:0xf
	v_fma_f32 v88, v80, v84, v108
	v_add_f32_e32 v88, v88, v109
	v_add_f32_e32 v88, v92, v88
	v_mul_f32_e32 v96, 0xbfb8aa3b, v88
	v_exp_f32_e32 v96, v96
	s_nop 0
	v_add_f32_e32 v96, 1.0, v96
	s_nop 0
	v_rcp_f32_e32 v105, v96
	s_nop 0
	v_fma_f32 v110, -v96, v105, 1.0
	v_fma_f32 v96, v110, v105, v105
	v_mov_b32_e32 v105, v1
	v_mul_f32_e32 v88, v88, v96
	v_mul_f32_e32 v108, v120, v88
	v_mov_b32_dpp v105, v77 row_ror:15 row_mask:0xf bank_mask:0xf
	v_mov_b32_e32 v88, v97
	s_nop 0
	v_mov_b32_dpp v105, v81 row_shl:1 row_mask:0xf bank_mask:0xf
	v_pk_mul_f32 v[96:97], v[88:89], v[104:105]
	s_nop 0
	v_fma_f32 v96, v81, v85, v96
	v_add_f32_e32 v96, v96, v97
	v_add_f32_e32 v96, v93, v96
	v_mul_f32_e32 v97, 0xbfb8aa3b, v96
	v_exp_f32_e32 v97, v97
	s_nop 0
	v_add_f32_e32 v97, 1.0, v97
	s_nop 0
	v_rcp_f32_e32 v104, v97
	s_nop 0
	v_fma_f32 v110, -v97, v104, 1.0
	v_fma_f32 v97, v110, v104, v104
	v_mul_f32_e32 v96, v96, v97
	v_mul_f32_e32 v97, v120, v96
	v_cvt_pk_bf16_f32 v96, v106, v107
	v_cvt_pk_bf16_f32 v97, v108, v97
	global_store_dwordx2 v[144:145], v[96:97], off offset:264
	s_and_saveexec_b64 s[2:3], s[42:43]
	s_cbranch_execz .LBB0_695
	v_cmp_gt_i32_e32 vcc, 2, v190
	v_cvt_pk_bf16_f32 v96, v78, v79
	v_cvt_pk_bf16_f32 v97, v80, v81
	s_nop 1
	v_cndmask_b32_e32 v104, v0, v190, vcc
	v_add_u32_e32 v104, s4, v104
	v_ashrrev_i32_e32 v105, 31, v104
	v_lshlrev_b64 v[104:105], 11, v[104:105]
	v_lshl_add_u64 v[104:105], s[48:49], 0, v[104:105]
	v_lshl_add_u64 v[104:105], v[158:159], 1, v[104:105]
	global_store_dwordx2 v[104:105], v[96:97], off offset:-3832
; __device__ __forceinline__ unsigned cvt_pk_bf16(float lo, float hi) { unsigned r; asm volatile("v_cvt_pk_bf16_f32 %0, %1, %2" : "=v"(r) : "v"(lo), "v"(hi)); return r; }
; __device__ __forceinline__ float dppf_prev(float cur, float below) { return __uint_as_float(dpp_prev(__float_as_uint(cur), __float_as_uint(below))); }
; __device__ __forceinline__ float dppf_next(float cur, float above) { return __uint_as_float(dpp_next(__float_as_uint(cur), __float_as_uint(above))); }
; __device__ __forceinline__ float sigmoidf_(float x) { return 1.0f / (1.0f + __expf(-x)); }
;     __device__ __forceinline__ void operator()(AccT& acc, const Unit& u, int wr, int wc, int fr, int fq) const {
;     ...
;                             for (int j = 0; j < 4; ++j) { const float gp = dppf_prev(gc[j], m > 0 ? acc[ai][bj][m - 1][n][j] : 0.f), gn = dppf_next(gc[j], m < 3 ? acc[ai][bj][m + 1][n][j] : 0.f);
;                                 const float uu = gp * w0[j] + gc[j] * w1[j] + gn * w2[j] + b[j]; o[j] = uu * sigmoidf_(uu) * mul; }
;                             u32x2 w; w.x = cvt_pk_bf16(o[0], o[1]); w.y = cvt_pk_bf16(o[2], o[3]);
;                             *(u32x2*)(O + (size_t)(grp * 64 + lr) * NPROJ + col0 + bj * 128 + 4 * n) = w;
;                             if (m == 0 || m == 3) { if (lr < 2 || lr > 61) { u32x2 wg; wg.x = cvt_pk_bf16(gc[0], gc[1]); wg.y = cvt_pk_bf16(gc[2], gc[3]);
;                                 *(u32x2*)(HQ + (size_t)(grp * 4 + (lr < 2 ? lr : lr - 60)) * 1024 + mc + 4 * n) = wg; } } } } } }
.LBB0_695:
	s_or_b64 exec, exec, s[2:3]
	v_mov_b32_e32 v96, v1
	v_mov_b32_e32 v97, v1
	s_nop 0
	v_mov_b32_dpp v96, v78 row_ror:1 row_mask:0xf bank_mask:0xf
	v_mov_b32_dpp v97, v70 row_ror:15 row_mask:0xf bank_mask:0xf
	s_nop 0
	v_mov_b32_dpp v96, v74 row_shr:1 row_mask:0xf bank_mask:0xf
	v_mov_b32_dpp v97, v74 row_shl:1 row_mask:0xf bank_mask:0xf
	v_pk_mul_f32 v[96:97], v[102:103], v[96:97]
	s_nop 0
	v_fma_f32 v78, v74, v82, v96
	v_add_f32_e32 v78, v78, v97
	v_add_f32_e32 v78, v90, v78
	v_mul_f32_e32 v96, 0xbfb8aa3b, v78
	v_exp_f32_e32 v96, v96
	s_nop 0
	v_add_f32_e32 v96, 1.0, v96
	s_nop 0
	v_rcp_f32_e32 v97, v96
	s_nop 0
	v_fma_f32 v106, -v96, v97, 1.0
	v_fma_f32 v96, v106, v97, v97
	v_mul_f32_e32 v78, v78, v96
	v_mul_f32_e32 v96, v120, v78
	v_mov_b32_e32 v78, v1
	s_nop 1
	v_mov_b32_dpp v78, v79 row_ror:1 row_mask:0xf bank_mask:0xf
	v_mov_b32_e32 v79, v1
	s_nop 0
	v_mov_b32_dpp v78, v75 row_shr:1 row_mask:0xf bank_mask:0xf
	v_mov_b32_dpp v79, v71 row_ror:15 row_mask:0xf bank_mask:0xf
	s_nop 1
	v_mov_b32_dpp v79, v75 row_shl:1 row_mask:0xf bank_mask:0xf
	v_pk_mul_f32 v[78:79], v[86:87], v[78:79]
	s_nop 0
	v_fma_f32 v78, v75, v83, v78
	v_add_f32_e32 v78, v78, v79
	v_add_f32_e32 v78, v91, v78
	v_mul_f32_e32 v79, 0xbfb8aa3b, v78
	v_exp_f32_e32 v79, v79
	s_nop 0
	v_add_f32_e32 v79, 1.0, v79
	s_nop 0
	v_rcp_f32_e32 v97, v79
	s_nop 0
	v_fma_f32 v106, -v79, v97, 1.0
	v_fma_f32 v79, v106, v97, v97
	v_mul_f32_e32 v78, v78, v79
	v_mul_f32_e32 v97, v120, v78
	v_mov_b32_e32 v78, v1
	v_mov_b32_e32 v79, v1
	s_nop 0
	v_mov_b32_dpp v78, v80 row_ror:1 row_mask:0xf bank_mask:0xf
	v_mov_b32_dpp v79, v72 row_ror:15 row_mask:0xf bank_mask:0xf
	s_nop 0
	v_mov_b32_dpp v78, v76 row_shr:1 row_mask:0xf bank_mask:0xf
	v_mov_b32_dpp v79, v76 row_shl:1 row_mask:0xf bank_mask:0xf
	v_pk_mul_f32 v[78:79], v[94:95], v[78:79]
	s_nop 0
	v_fma_f32 v78, v76, v84, v78
	v_add_f32_e32 v78, v78, v79
	v_add_f32_e32 v78, v92, v78
	v_mul_f32_e32 v79, 0xbfb8aa3b, v78
	v_exp_f32_e32 v79, v79
	s_nop 0
	v_add_f32_e32 v79, 1.0, v79
	s_nop 0
	v_rcp_f32_e32 v80, v79
	s_nop 0
	v_fma_f32 v106, -v79, v80, 1.0
	v_fma_f32 v79, v106, v80, v80
	v_mul_f32_e32 v78, v78, v79
	v_mul_f32_e32 v80, v120, v78
	v_mov_b32_e32 v78, v1
	v_mov_b32_e32 v79, v1
	s_nop 0
	v_mov_b32_dpp v78, v81 row_ror:1 row_mask:0xf bank_mask:0xf
	v_mov_b32_dpp v79, v73 row_ror:15 row_mask:0xf bank_mask:0xf
	s_nop 0
	v_mov_b32_dpp v78, v77 row_shr:1 row_mask:0xf bank_mask:0xf
	v_mov_b32_dpp v79, v77 row_shl:1 row_mask:0xf bank_mask:0xf
	v_pk_mul_f32 v[78:79], v[88:89], v[78:79]
	s_nop 0
	v_fma_f32 v78, v77, v85, v78
	v_add_f32_e32 v78, v78, v79
	v_add_f32_e32 v78, v93, v78
	v_mul_f32_e32 v79, 0xbfb8aa3b, v78
	v_exp_f32_e32 v79, v79
	s_nop 0
	v_add_f32_e32 v79, 1.0, v79
	s_nop 0
	v_rcp_f32_e32 v81, v79
	s_nop 0
	v_fma_f32 v106, -v79, v81, 1.0
	v_fma_f32 v79, v106, v81, v81
	v_mul_f32_e32 v78, v78, v79
	v_mul_f32_e32 v79, v120, v78
	v_cvt_pk_bf16_f32 v78, v96, v97
	v_cvt_pk_bf16_f32 v79, v80, v79
	global_store_dwordx2 v[178:179], v[78:79], off offset:264
	v_mov_b32_e32 v78, v1
	v_mov_b32_e32 v79, v1
	s_nop 0
	v_mov_b32_dpp v78, v74 row_ror:1 row_mask:0xf bank_mask:0xf
	v_mov_b32_dpp v79, v66 row_ror:15 row_mask:0xf bank_mask:0xf
	s_nop 0
	v_mov_b32_dpp v78, v70 row_shr:1 row_mask:0xf bank_mask:0xf
	v_mov_b32_dpp v79, v70 row_shl:1 row_mask:0xf bank_mask:0xf
	v_pk_mul_f32 v[78:79], v[102:103], v[78:79]
	s_nop 0
	v_fma_f32 v74, v70, v82, v78
	v_add_f32_e32 v74, v74, v79
	v_add_f32_e32 v74, v90, v74
	v_mul_f32_e32 v78, 0xbfb8aa3b, v74
	v_exp_f32_e32 v78, v78
	s_nop 0
	v_add_f32_e32 v78, 1.0, v78
	s_nop 0
	v_rcp_f32_e32 v79, v78
	s_nop 0
	v_fma_f32 v96, -v78, v79, 1.0
	v_fma_f32 v78, v96, v79, v79
	v_mul_f32_e32 v74, v74, v78
	v_mul_f32_e32 v78, v120, v74
	v_mov_b32_e32 v74, v1
	s_nop 1
	v_mov_b32_dpp v74, v75 row_ror:1 row_mask:0xf bank_mask:0xf
	v_mov_b32_e32 v75, v1
	s_nop 0
	v_mov_b32_dpp v74, v71 row_shr:1 row_mask:0xf bank_mask:0xf
	v_mov_b32_dpp v75, v67 row_ror:15 row_mask:0xf bank_mask:0xf
	s_nop 1
	v_mov_b32_dpp v75, v71 row_shl:1 row_mask:0xf bank_mask:0xf
	v_pk_mul_f32 v[74:75], v[86:87], v[74:75]
	s_nop 0
	v_fma_f32 v74, v71, v83, v74
	v_add_f32_e32 v74, v74, v75
	v_add_f32_e32 v74, v91, v74
	v_mul_f32_e32 v75, 0xbfb8aa3b, v74
	v_exp_f32_e32 v75, v75
	s_nop 0
	v_add_f32_e32 v75, 1.0, v75
	s_nop 0
	v_rcp_f32_e32 v79, v75
	s_nop 0
	v_fma_f32 v96, -v75, v79, 1.0
	v_fma_f32 v75, v96, v79, v79
	v_mul_f32_e32 v74, v74, v75
	v_mul_f32_e32 v79, v120, v74
	v_mov_b32_e32 v74, v1
	v_mov_b32_e32 v75, v1
	s_nop 0
	v_mov_b32_dpp v74, v76 row_ror:1 row_mask:0xf bank_mask:0xf
	v_mov_b32_dpp v75, v68 row_ror:15 row_mask:0xf bank_mask:0xf
	s_nop 0
	v_mov_b32_dpp v74, v72 row_shr:1 row_mask:0xf bank_mask:0xf
	v_mov_b32_dpp v75, v72 row_shl:1 row_mask:0xf bank_mask:0xf
	v_pk_mul_f32 v[74:75], v[94:95], v[74:75]
	s_nop 0
	v_fma_f32 v74, v72, v84, v74
	v_add_f32_e32 v74, v74, v75
	v_add_f32_e32 v74, v92, v74
	v_mul_f32_e32 v75, 0xbfb8aa3b, v74
	v_exp_f32_e32 v75, v75
	s_nop 0
	v_add_f32_e32 v75, 1.0, v75
	s_nop 0
	v_rcp_f32_e32 v76, v75
	s_nop 0
	v_fma_f32 v96, -v75, v76, 1.0
	v_fma_f32 v75, v96, v76, v76
	v_mul_f32_e32 v74, v74, v75
	v_mul_f32_e32 v76, v120, v74
	v_mov_b32_e32 v74, v1
	v_mov_b32_e32 v75, v1
	s_nop 0
	v_mov_b32_dpp v74, v77 row_ror:1 row_mask:0xf bank_mask:0xf
	v_mov_b32_dpp v75, v69 row_ror:15 row_mask:0xf bank_mask:0xf
	s_nop 0
	v_mov_b32_dpp v74, v73 row_shr:1 row_mask:0xf bank_mask:0xf
	v_mov_b32_dpp v75, v73 row_shl:1 row_mask:0xf bank_mask:0xf
	v_pk_mul_f32 v[74:75], v[88:89], v[74:75]
	s_nop 0
	v_fma_f32 v74, v73, v85, v74
	v_add_f32_e32 v74, v74, v75
	v_add_f32_e32 v74, v93, v74
	v_mul_f32_e32 v75, 0xbfb8aa3b, v74
; __device__ __forceinline__ unsigned cvt_pk_bf16(float lo, float hi) { unsigned r; asm volatile("v_cvt_pk_bf16_f32 %0, %1, %2" : "=v"(r) : "v"(lo), "v"(hi)); return r; }
; __device__ __forceinline__ float dppf_prev(float cur, float below) { return __uint_as_float(dpp_prev(__float_as_uint(cur), __float_as_uint(below))); }
; __device__ __forceinline__ float dppf_next(float cur, float above) { return __uint_as_float(dpp_next(__float_as_uint(cur), __float_as_uint(above))); }
; __device__ __forceinline__ float sigmoidf_(float x) { return 1.0f / (1.0f + __expf(-x)); }
;     __device__ __forceinline__ void operator()(AccT& acc, const Unit& u, int wr, int wc, int fr, int fq) const {
;     ...
;             for (int ai = 0; ai < 2; ++ai) { const int grp = u.pm * 4 + ai * 2 + wr;
; #pragma unroll
;                 for (int bj = 0; bj < 2; ++bj) { const int mc = mc0 + bj * 128; const float mul = mc < 512 ? 0.08838834764831845f : 1.0f;
; #pragma unroll
;                     for (int n = 0; n < 2; ++n) {
;                         const f32x4 w0 = *(const f32x4*)(cw + mc + 4 * n), w1 = *(const f32x4*)(cw + 1024 + mc + 4 * n), w2 = *(const f32x4*)(cw + 2048 + mc + 4 * n), b = *(const f32x4*)(cb + mc + 4 * n);
; #pragma unroll
;                         for (int m = 0; m < 4; ++m) { const int lr = m * 16 + fr; const f32x4 gc = acc[ai][bj][m][n]; f32x4 o;
; #pragma unroll
;                             for (int j = 0; j < 4; ++j) { const float gp = dppf_prev(gc[j], m > 0 ? acc[ai][bj][m - 1][n][j] : 0.f), gn = dppf_next(gc[j], m < 3 ? acc[ai][bj][m + 1][n][j] : 0.f);
;                                 const float uu = gp * w0[j] + gc[j] * w1[j] + gn * w2[j] + b[j]; o[j] = uu * sigmoidf_(uu) * mul; }
;                             u32x2 w; w.x = cvt_pk_bf16(o[0], o[1]); w.y = cvt_pk_bf16(o[2], o[3]);
;                             *(u32x2*)(O + (size_t)(grp * 64 + lr) * NPROJ + col0 + bj * 128 + 4 * n) = w;
;                             if (m == 0 || m == 3) { if (lr < 2 || lr > 61) { u32x2 wg; wg.x = cvt_pk_bf16(gc[0], gc[1]); wg.y = cvt_pk_bf16(gc[2], gc[3]);
;                                 *(u32x2*)(HQ + (size_t)(grp * 4 + (lr < 2 ? lr : lr - 60)) * 1024 + mc + 4 * n) = wg; } } } } } }
	v_exp_f32_e32 v75, v75
	s_nop 0
	v_add_f32_e32 v75, 1.0, v75
	s_nop 0
	v_rcp_f32_e32 v77, v75
	s_nop 0
	v_fma_f32 v96, -v75, v77, 1.0
	v_fma_f32 v75, v96, v77, v77
	v_mul_f32_e32 v74, v74, v75
	v_mul_f32_e32 v75, v120, v74
	v_cvt_pk_bf16_f32 v74, v78, v79
	v_mov_b32_e32 v77, v1
	v_cvt_pk_bf16_f32 v75, v76, v75
	global_store_dwordx2 v[180:181], v[74:75], off offset:264
	v_mov_b32_e32 v74, v1
	v_mov_b32_dpp v77, v77 row_ror:15 row_mask:0xf bank_mask:0xf
	v_mov_b32_e32 v75, v77
	v_mov_b32_dpp v74, v70 row_ror:1 row_mask:0xf bank_mask:0xf
	s_nop 0
	v_mov_b32_dpp v75, v66 row_shl:1 row_mask:0xf bank_mask:0xf
	v_mov_b32_dpp v74, v66 row_shr:1 row_mask:0xf bank_mask:0xf
	v_pk_mul_f32 v[74:75], v[102:103], v[74:75]
	s_nop 0
	v_fma_f32 v70, v66, v82, v74
	v_add_f32_e32 v70, v70, v75
	v_add_f32_e32 v70, v90, v70
	v_mul_f32_e32 v74, 0xbfb8aa3b, v70
	v_exp_f32_e32 v74, v74
	s_nop 0
	v_add_f32_e32 v74, 1.0, v74
	s_nop 0
	v_rcp_f32_e32 v75, v74
	s_nop 0
	v_fma_f32 v79, -v74, v75, 1.0
	v_fma_f32 v74, v79, v75, v75
	v_mul_f32_e32 v70, v70, v74
	v_mul_f32_e32 v74, v120, v70
	v_mov_b32_e32 v70, v1
	s_nop 1
	v_mov_b32_dpp v70, v71 row_ror:1 row_mask:0xf bank_mask:0xf
	v_mov_b32_e32 v71, v77
	s_nop 0
	v_mov_b32_dpp v70, v67 row_shr:1 row_mask:0xf bank_mask:0xf
	v_mov_b32_dpp v71, v67 row_shl:1 row_mask:0xf bank_mask:0xf
	v_pk_mul_f32 v[70:71], v[86:87], v[70:71]
	s_nop 0
	v_fma_f32 v70, v67, v83, v70
	v_add_f32_e32 v70, v70, v71
	v_add_f32_e32 v70, v91, v70
	v_mul_f32_e32 v71, 0xbfb8aa3b, v70
	v_exp_f32_e32 v71, v71
	s_nop 0
	v_add_f32_e32 v71, 1.0, v71
	s_nop 0
	v_rcp_f32_e32 v75, v71
	s_nop 0
	v_fma_f32 v79, -v71, v75, 1.0
	v_fma_f32 v71, v79, v75, v75
	v_mul_f32_e32 v70, v70, v71
	v_mul_f32_e32 v75, v120, v70
	v_mov_b32_e32 v70, v1
	v_mov_b32_e32 v71, v77
	v_mov_b32_dpp v77, v69 row_shl:1 row_mask:0xf bank_mask:0xf
	v_mov_b32_dpp v70, v72 row_ror:1 row_mask:0xf bank_mask:0xf
	v_mov_b32_dpp v71, v68 row_shl:1 row_mask:0xf bank_mask:0xf
	s_nop 0
	v_mov_b32_dpp v70, v68 row_shr:1 row_mask:0xf bank_mask:0xf
	v_pk_mul_f32 v[70:71], v[94:95], v[70:71]
	s_nop 0
	v_fma_f32 v70, v68, v84, v70
	v_add_f32_e32 v70, v70, v71
	v_add_f32_e32 v70, v92, v70
	v_mul_f32_e32 v71, 0xbfb8aa3b, v70
	v_exp_f32_e32 v71, v71
	s_nop 0
	v_add_f32_e32 v71, 1.0, v71
	s_nop 0
	v_mov_b32_e32 v76, v1
	v_rcp_f32_e32 v72, v71
	s_nop 0
	v_fma_f32 v79, -v71, v72, 1.0
	v_fma_f32 v71, v79, v72, v72
	v_mul_f32_e32 v70, v70, v71
	v_mov_b32_dpp v76, v73 row_ror:1 row_mask:0xf bank_mask:0xf
	v_mul_f32_e32 v72, v120, v70
	s_nop 0
	v_mov_b32_dpp v76, v69 row_shr:1 row_mask:0xf bank_mask:0xf
	v_pk_mul_f32 v[70:71], v[88:89], v[76:77]
	s_nop 0
	v_fma_f32 v70, v69, v85, v70
	v_add_f32_e32 v70, v70, v71
	v_add_f32_e32 v70, v93, v70
	v_mul_f32_e32 v71, 0xbfb8aa3b, v70
	v_exp_f32_e32 v71, v71
	s_nop 0
	v_add_f32_e32 v71, 1.0, v71
	s_nop 0
	v_rcp_f32_e32 v73, v71
	s_nop 0
	v_fma_f32 v78, -v71, v73, 1.0
	v_fma_f32 v71, v78, v73, v73
	v_mul_f32_e32 v70, v70, v71
	v_mul_f32_e32 v71, v120, v70
	v_cvt_pk_bf16_f32 v70, v74, v75
	v_cvt_pk_bf16_f32 v71, v72, v71
	global_store_dwordx2 v[130:131], v[70:71], off offset:264
	s_and_saveexec_b64 s[2:3], s[44:45]
	s_cbranch_execz .LBB0_697
	s_movk_i32 s5, 0xffd2
	v_cmp_gt_i32_e32 vcc, s5, v190
	v_cvt_pk_bf16_f32 v66, v66, v67
	v_cvt_pk_bf16_f32 v67, v68, v69
	s_nop 1
	v_cndmask_b32_e32 v68, v137, v136, vcc
	v_add_u32_e32 v68, s4, v68
	v_ashrrev_i32_e32 v69, 31, v68
	v_lshlrev_b64 v[68:69], 11, v[68:69]
	v_lshl_add_u64 v[68:69], s[48:49], 0, v[68:69]
	v_lshl_add_u64 v[68:69], v[158:159], 1, v[68:69]
	global_store_dwordx2 v[68:69], v[66:67], off offset:-3832
.LBB0_697:
	s_or_b64 exec, exec, s[2:3]
	s_waitcnt vmcnt(4)
	v_mov_b64_e32 v[78:79], v[196:197]
	v_mov_b64_e32 v[80:81], v[198:199]
	v_mov_b64_e32 v[66:67], v[204:205]
	v_mov_b64_e32 v[68:69], v[206:207]
	v_mov_b64_e32 v[70:71], v[222:223]
	v_mov_b64_e32 v[72:73], v[224:225]
	v_mov_b64_e32 v[74:75], v[226:227]
	v_mov_b64_e32 v[76:77], v[228:229]
	global_load_dwordx4 v[196:199], v[174:175], off offset:16
	global_load_dwordx4 v[204:207], v[160:161], off offset:-4080
	global_load_dwordx4 v[222:225], v[160:161], off offset:16
	global_load_dwordx4 v[226:229], v[176:177], off offset:16
	v_mov_b32_e32 v82, v1
	v_mov_b32_e32 v87, v1
	s_add_i32 s0, s0, 2
	v_mov_b32_dpp v82, v82 row_ror:1 row_mask:0xf bank_mask:0xf
	v_mov_b32_e32 v86, v82
	v_mov_b32_dpp v87, v58 row_ror:15 row_mask:0xf bank_mask:0xf
	s_lshl_b32 s4, s0, 6
	v_mov_b32_dpp v86, v62 row_shr:1 row_mask:0xf bank_mask:0xf
	v_mov_b32_dpp v87, v62 row_shl:1 row_mask:0xf bank_mask:0xf
	s_lshl_b32 s0, s0, 2
	s_waitcnt vmcnt(4)
; __device__ __forceinline__ unsigned cvt_pk_bf16(float lo, float hi) { unsigned r; asm volatile("v_cvt_pk_bf16_f32 %0, %1, %2" : "=v"(r) : "v"(lo), "v"(hi)); return r; }
; __device__ __forceinline__ float dppf_prev(float cur, float below) { return __uint_as_float(dpp_prev(__float_as_uint(cur), __float_as_uint(below))); }
; __device__ __forceinline__ float dppf_next(float cur, float above) { return __uint_as_float(dpp_next(__float_as_uint(cur), __float_as_uint(above))); }
; __device__ __forceinline__ float sigmoidf_(float x) { return 1.0f / (1.0f + __expf(-x)); }
;     __device__ __forceinline__ void operator()(AccT& acc, const Unit& u, int wr, int wc, int fr, int fq) const {
;     ...
;                         for (int m = 0; m < 4; ++m) { const int lr = m * 16 + fr; const f32x4 gc = acc[ai][bj][m][n]; f32x4 o;
; #pragma unroll
;                             for (int j = 0; j < 4; ++j) { const float gp = dppf_prev(gc[j], m > 0 ? acc[ai][bj][m - 1][n][j] : 0.f), gn = dppf_next(gc[j], m < 3 ? acc[ai][bj][m + 1][n][j] : 0.f);
;                                 const float uu = gp * w0[j] + gc[j] * w1[j] + gn * w2[j] + b[j]; o[j] = uu * sigmoidf_(uu) * mul; }
;                             u32x2 w; w.x = cvt_pk_bf16(o[0], o[1]); w.y = cvt_pk_bf16(o[2], o[3]);
;                             *(u32x2*)(O + (size_t)(grp * 64 + lr) * NPROJ + col0 + bj * 128 + 4 * n) = w;
;                             if (m == 0 || m == 3) { if (lr < 2 || lr > 61) { u32x2 wg; wg.x = cvt_pk_bf16(gc[0], gc[1]); wg.y = cvt_pk_bf16(gc[2], gc[3]);
;                                 *(u32x2*)(HQ + (size_t)(grp * 4 + (lr < 2 ? lr : lr - 60)) * 1024 + mc + 4 * n) = wg; } } } } } }
	v_mov_b32_e32 v84, v78
	v_mov_b32_e32 v85, v70
	v_pk_mul_f32 v[86:87], v[84:85], v[86:87]
	s_nop 0
	v_fma_f32 v70, v62, v66, v86
	v_add_f32_e32 v70, v70, v87
	v_add_f32_e32 v70, v74, v70
	v_mul_f32_e32 v78, 0xbfb8aa3b, v70
	v_exp_f32_e32 v78, v78
	s_nop 0
	v_add_f32_e32 v78, 1.0, v78
	s_nop 0
	v_rcp_f32_e32 v83, v78
	s_nop 0
	v_fma_f32 v88, -v78, v83, 1.0
	v_fma_f32 v78, v88, v83, v83
	v_mov_b32_e32 v87, v1
	v_mul_f32_e32 v70, v70, v78
	v_mov_b32_e32 v86, v82
	v_mov_b32_dpp v87, v59 row_ror:15 row_mask:0xf bank_mask:0xf
	v_mul_f32_e32 v78, v191, v70
	v_mov_b32_dpp v86, v63 row_shr:1 row_mask:0xf bank_mask:0xf
	v_mov_b32_dpp v87, v63 row_shl:1 row_mask:0xf bank_mask:0xf
	v_mov_b32_e32 v70, v79
	v_pk_mul_f32 v[86:87], v[70:71], v[86:87]
	s_nop 0
	v_fma_f32 v79, v63, v67, v86
	v_add_f32_e32 v79, v79, v87
	v_add_f32_e32 v79, v75, v79
	v_mul_f32_e32 v83, 0xbfb8aa3b, v79
	v_exp_f32_e32 v83, v83
	s_nop 0
	v_add_f32_e32 v83, 1.0, v83
	s_nop 0
	v_mov_b32_e32 v89, v1
	v_mov_b32_e32 v88, v82
	v_rcp_f32_e32 v86, v83
	s_nop 0
	v_fma_f32 v90, -v83, v86, 1.0
	v_fma_f32 v83, v90, v86, v86
	v_mov_b32_dpp v89, v60 row_ror:15 row_mask:0xf bank_mask:0xf
	v_mov_b32_dpp v88, v64 row_shr:1 row_mask:0xf bank_mask:0xf
	v_mov_b32_e32 v86, v80
	v_mov_b32_dpp v89, v64 row_shl:1 row_mask:0xf bank_mask:0xf
	v_mov_b32_e32 v87, v72
	v_pk_mul_f32 v[88:89], v[86:87], v[88:89]
	v_mul_f32_e32 v79, v79, v83
	v_fma_f32 v72, v64, v68, v88
	v_add_f32_e32 v72, v72, v89
	v_add_f32_e32 v72, v76, v72
	v_mul_f32_e32 v80, 0xbfb8aa3b, v72
	v_exp_f32_e32 v80, v80
	v_mov_b32_dpp v82, v65 row_shr:1 row_mask:0xf bank_mask:0xf
	v_mul_f32_e32 v79, v191, v79
	v_add_f32_e32 v80, 1.0, v80
	s_nop 0
	v_rcp_f32_e32 v83, v80
	s_nop 0
	v_fma_f32 v90, -v80, v83, 1.0
	v_fma_f32 v80, v90, v83, v83
	v_mov_b32_e32 v83, v1
	v_mul_f32_e32 v72, v72, v80
	v_mul_f32_e32 v88, v191, v72
	v_mov_b32_dpp v83, v61 row_ror:15 row_mask:0xf bank_mask:0xf
	v_mov_b32_e32 v72, v81
	s_nop 0
	v_mov_b32_dpp v83, v65 row_shl:1 row_mask:0xf bank_mask:0xf
	v_pk_mul_f32 v[80:81], v[72:73], v[82:83]
	s_nop 0
	v_fma_f32 v80, v65, v69, v80
	v_add_f32_e32 v80, v80, v81
	v_add_f32_e32 v80, v77, v80
	v_mul_f32_e32 v81, 0xbfb8aa3b, v80
	v_exp_f32_e32 v81, v81
	s_nop 0
	v_add_f32_e32 v81, 1.0, v81
	s_nop 0
	v_rcp_f32_e32 v82, v81
	s_nop 0
	v_fma_f32 v90, -v81, v82, 1.0
	v_fma_f32 v81, v90, v82, v82
	v_mul_f32_e32 v80, v80, v81
	v_mul_f32_e32 v81, v191, v80
	v_cvt_pk_bf16_f32 v80, v78, v79
	v_add_u32_e32 v78, s4, v190
	v_ashrrev_i32_e32 v79, 31, v78
	v_lshlrev_b64 v[78:79], 13, v[78:79]
	v_lshl_add_u64 v[78:79], s[22:23], 0, v[78:79]
	v_lshl_add_u64 v[78:79], v[158:159], 1, v[78:79]
	v_cvt_pk_bf16_f32 v81, v88, v81
	global_store_dwordx2 v[78:79], v[80:81], off
	s_and_saveexec_b64 s[2:3], s[42:43]
	s_cbranch_execz .LBB0_699
	v_cmp_gt_i32_e32 vcc, 2, v190
	v_cvt_pk_bf16_f32 v80, v62, v63
	v_cvt_pk_bf16_f32 v81, v64, v65
	s_nop 1
	v_cndmask_b32_e32 v82, v0, v190, vcc
	v_add_u32_e32 v82, s0, v82
	v_ashrrev_i32_e32 v83, 31, v82
	v_lshlrev_b64 v[82:83], 11, v[82:83]
	v_lshl_add_u64 v[82:83], s[48:49], 0, v[82:83]
	v_lshl_add_u64 v[82:83], v[158:159], 1, v[82:83]
	global_store_dwordx2 v[82:83], v[80:81], off offset:-4096
.LBB0_699:
	s_or_b64 exec, exec, s[2:3]
	v_mov_b32_e32 v80, v1
	v_mov_b32_e32 v81, v1
	s_nop 0
	v_mov_b32_dpp v80, v62 row_ror:1 row_mask:0xf bank_mask:0xf
	v_mov_b32_dpp v81, v54 row_ror:15 row_mask:0xf bank_mask:0xf
	s_nop 0
	v_mov_b32_dpp v80, v58 row_shr:1 row_mask:0xf bank_mask:0xf
	v_mov_b32_dpp v81, v58 row_shl:1 row_mask:0xf bank_mask:0xf
	v_pk_mul_f32 v[80:81], v[84:85], v[80:81]
	s_nop 0
	v_fma_f32 v62, v58, v66, v80
	v_add_f32_e32 v62, v62, v81
	v_add_f32_e32 v62, v74, v62
	v_mul_f32_e32 v80, 0xbfb8aa3b, v62
	v_exp_f32_e32 v80, v80
	s_nop 0
	v_add_f32_e32 v80, 1.0, v80
	s_nop 0
	v_rcp_f32_e32 v81, v80
	s_nop 0
	v_fma_f32 v88, -v80, v81, 1.0
	v_fma_f32 v80, v88, v81, v81
	v_mul_f32_e32 v62, v62, v80
	v_mul_f32_e32 v80, v191, v62
	v_mov_b32_e32 v62, v1
	s_nop 1
	v_mov_b32_dpp v62, v63 row_ror:1 row_mask:0xf bank_mask:0xf
	v_mov_b32_e32 v63, v1
	s_nop 0
	v_mov_b32_dpp v62, v59 row_shr:1 row_mask:0xf bank_mask:0xf
	v_mov_b32_dpp v63, v55 row_ror:15 row_mask:0xf bank_mask:0xf
	s_nop 1
	v_mov_b32_dpp v63, v59 row_shl:1 row_mask:0xf bank_mask:0xf
	v_pk_mul_f32 v[62:63], v[70:71], v[62:63]
	s_nop 0
	v_fma_f32 v62, v59, v67, v62
	v_add_f32_e32 v62, v62, v63
	v_add_f32_e32 v62, v75, v62
	v_mul_f32_e32 v63, 0xbfb8aa3b, v62
	v_exp_f32_e32 v63, v63
	s_nop 0
	v_add_f32_e32 v63, 1.0, v63
	s_nop 0
	v_rcp_f32_e32 v81, v63
	s_nop 0
	v_fma_f32 v88, -v63, v81, 1.0
	v_fma_f32 v63, v88, v81, v81
	v_mul_f32_e32 v62, v62, v63
	v_mul_f32_e32 v81, v191, v62
	v_mov_b32_e32 v62, v1
	v_mov_b32_e32 v63, v1
	s_nop 0
	v_mov_b32_dpp v62, v64 row_ror:1 row_mask:0xf bank_mask:0xf
	v_mov_b32_dpp v63, v56 row_ror:15 row_mask:0xf bank_mask:0xf
	s_nop 0
	v_mov_b32_dpp v62, v60 row_shr:1 row_mask:0xf bank_mask:0xf
	v_mov_b32_dpp v63, v60 row_shl:1 row_mask:0xf bank_mask:0xf
	v_pk_mul_f32 v[62:63], v[86:87], v[62:63]
	s_nop 0
	v_fma_f32 v62, v60, v68, v62
	v_add_f32_e32 v62, v62, v63
	v_add_f32_e32 v62, v76, v62
	v_mul_f32_e32 v63, 0xbfb8aa3b, v62
	v_exp_f32_e32 v63, v63
	s_nop 0
	v_add_f32_e32 v63, 1.0, v63
	s_nop 0
	v_rcp_f32_e32 v64, v63
	s_nop 0
	v_fma_f32 v88, -v63, v64, 1.0
	v_fma_f32 v63, v88, v64, v64
	v_mul_f32_e32 v62, v62, v63
	v_mul_f32_e32 v64, v191, v62
	v_mov_b32_e32 v62, v1
	v_mov_b32_e32 v63, v1
	s_nop 0
	v_mov_b32_dpp v62, v65 row_ror:1 row_mask:0xf bank_mask:0xf
	v_mov_b32_dpp v63, v57 row_ror:15 row_mask:0xf bank_mask:0xf
	s_nop 0
	v_mov_b32_dpp v62, v61 row_shr:1 row_mask:0xf bank_mask:0xf
	v_mov_b32_dpp v63, v61 row_shl:1 row_mask:0xf bank_mask:0xf
; __device__ __forceinline__ unsigned cvt_pk_bf16(float lo, float hi) { unsigned r; asm volatile("v_cvt_pk_bf16_f32 %0, %1, %2" : "=v"(r) : "v"(lo), "v"(hi)); return r; }
; __device__ __forceinline__ float dppf_prev(float cur, float below) { return __uint_as_float(dpp_prev(__float_as_uint(cur), __float_as_uint(below))); }
; __device__ __forceinline__ float dppf_next(float cur, float above) { return __uint_as_float(dpp_next(__float_as_uint(cur), __float_as_uint(above))); }
; __device__ __forceinline__ float sigmoidf_(float x) { return 1.0f / (1.0f + __expf(-x)); }
;     __device__ __forceinline__ void operator()(AccT& acc, const Unit& u, int wr, int wc, int fr, int fq) const {
;     ...
;                         for (int m = 0; m < 4; ++m) { const int lr = m * 16 + fr; const f32x4 gc = acc[ai][bj][m][n]; f32x4 o;
; #pragma unroll
;                             for (int j = 0; j < 4; ++j) { const float gp = dppf_prev(gc[j], m > 0 ? acc[ai][bj][m - 1][n][j] : 0.f), gn = dppf_next(gc[j], m < 3 ? acc[ai][bj][m + 1][n][j] : 0.f);
;                                 const float uu = gp * w0[j] + gc[j] * w1[j] + gn * w2[j] + b[j]; o[j] = uu * sigmoidf_(uu) * mul; }
;                             u32x2 w; w.x = cvt_pk_bf16(o[0], o[1]); w.y = cvt_pk_bf16(o[2], o[3]);
;                             *(u32x2*)(O + (size_t)(grp * 64 + lr) * NPROJ + col0 + bj * 128 + 4 * n) = w;
;                             if (m == 0 || m == 3) { if (lr < 2 || lr > 61) { u32x2 wg; wg.x = cvt_pk_bf16(gc[0], gc[1]); wg.y = cvt_pk_bf16(gc[2], gc[3]);
;                                 *(u32x2*)(HQ + (size_t)(grp * 4 + (lr < 2 ? lr : lr - 60)) * 1024 + mc + 4 * n) = wg; } } } } } }
	v_pk_mul_f32 v[62:63], v[72:73], v[62:63]
	s_nop 0
	v_fma_f32 v62, v61, v69, v62
	v_add_f32_e32 v62, v62, v63
	v_add_f32_e32 v62, v77, v62
	v_mul_f32_e32 v63, 0xbfb8aa3b, v62
	v_exp_f32_e32 v63, v63
	s_nop 0
	v_add_f32_e32 v63, 1.0, v63
	s_nop 0
	v_rcp_f32_e32 v65, v63
	s_nop 0
	v_fma_f32 v88, -v63, v65, 1.0
	v_fma_f32 v63, v88, v65, v65
	v_mul_f32_e32 v62, v62, v63
	v_mul_f32_e32 v63, v191, v62
	v_cvt_pk_bf16_f32 v62, v80, v81
	v_cvt_pk_bf16_f32 v63, v64, v63
	v_add_u32_e32 v64, s4, v192
	v_ashrrev_i32_e32 v65, 31, v64
	v_lshlrev_b64 v[64:65], 13, v[64:65]
	v_lshl_add_u64 v[64:65], s[22:23], 0, v[64:65]
	v_lshl_add_u64 v[80:81], v[64:65], 0, v[142:143]
	global_store_dwordx2 v[80:81], v[62:63], off
	v_mov_b32_e32 v62, v1
	v_mov_b32_e32 v63, v1
	s_nop 0
	v_mov_b32_dpp v62, v58 row_ror:1 row_mask:0xf bank_mask:0xf
	v_mov_b32_dpp v63, v50 row_ror:15 row_mask:0xf bank_mask:0xf
	s_nop 0
	v_mov_b32_dpp v62, v54 row_shr:1 row_mask:0xf bank_mask:0xf
	v_mov_b32_dpp v63, v54 row_shl:1 row_mask:0xf bank_mask:0xf
	v_pk_mul_f32 v[62:63], v[84:85], v[62:63]
	s_nop 0
	v_fma_f32 v58, v54, v66, v62
	v_add_f32_e32 v58, v58, v63
	v_add_f32_e32 v58, v74, v58
	v_mul_f32_e32 v62, 0xbfb8aa3b, v58
	v_exp_f32_e32 v62, v62
	s_nop 0
	v_add_f32_e32 v62, 1.0, v62
	s_nop 0
	v_rcp_f32_e32 v63, v62
	s_nop 0
	v_fma_f32 v82, -v62, v63, 1.0
	v_fma_f32 v62, v82, v63, v63
	v_mul_f32_e32 v58, v58, v62
	v_mul_f32_e32 v62, v191, v58
	v_mov_b32_e32 v58, v1
	s_nop 1
	v_mov_b32_dpp v58, v59 row_ror:1 row_mask:0xf bank_mask:0xf
	v_mov_b32_e32 v59, v1
	s_nop 0
	v_mov_b32_dpp v58, v55 row_shr:1 row_mask:0xf bank_mask:0xf
	v_mov_b32_dpp v59, v51 row_ror:15 row_mask:0xf bank_mask:0xf
	s_nop 1
	v_mov_b32_dpp v59, v55 row_shl:1 row_mask:0xf bank_mask:0xf
	v_pk_mul_f32 v[58:59], v[70:71], v[58:59]
	s_nop 0
	v_fma_f32 v58, v55, v67, v58
	v_add_f32_e32 v58, v58, v59
	v_add_f32_e32 v58, v75, v58
	v_mul_f32_e32 v59, 0xbfb8aa3b, v58
	v_exp_f32_e32 v59, v59
	s_nop 0
	v_add_f32_e32 v59, 1.0, v59
	s_nop 0
	v_rcp_f32_e32 v63, v59
	s_nop 0
	v_fma_f32 v82, -v59, v63, 1.0
	v_fma_f32 v59, v82, v63, v63
	v_mul_f32_e32 v58, v58, v59
	v_mul_f32_e32 v63, v191, v58
	v_mov_b32_e32 v58, v1
	v_mov_b32_e32 v59, v1
	s_nop 0
	v_mov_b32_dpp v58, v60 row_ror:1 row_mask:0xf bank_mask:0xf
	v_mov_b32_dpp v59, v52 row_ror:15 row_mask:0xf bank_mask:0xf
	s_nop 0
	v_mov_b32_dpp v58, v56 row_shr:1 row_mask:0xf bank_mask:0xf
	v_mov_b32_dpp v59, v56 row_shl:1 row_mask:0xf bank_mask:0xf
	v_pk_mul_f32 v[58:59], v[86:87], v[58:59]
	s_nop 0
	v_fma_f32 v58, v56, v68, v58
	v_add_f32_e32 v58, v58, v59
	v_add_f32_e32 v58, v76, v58
	v_mul_f32_e32 v59, 0xbfb8aa3b, v58
	v_exp_f32_e32 v59, v59
	s_nop 0
	v_add_f32_e32 v59, 1.0, v59
	s_nop 0
	v_rcp_f32_e32 v60, v59
	s_nop 0
	v_fma_f32 v82, -v59, v60, 1.0
	v_fma_f32 v59, v82, v60, v60
	v_mul_f32_e32 v58, v58, v59
	v_mul_f32_e32 v60, v191, v58
	v_mov_b32_e32 v58, v1
	v_mov_b32_e32 v59, v1
	s_nop 0
	v_mov_b32_dpp v58, v61 row_ror:1 row_mask:0xf bank_mask:0xf
	v_mov_b32_dpp v59, v53 row_ror:15 row_mask:0xf bank_mask:0xf
	s_nop 0
	v_mov_b32_dpp v58, v57 row_shr:1 row_mask:0xf bank_mask:0xf
	v_mov_b32_dpp v59, v57 row_shl:1 row_mask:0xf bank_mask:0xf
	v_pk_mul_f32 v[58:59], v[72:73], v[58:59]
	s_nop 0
	v_fma_f32 v58, v57, v69, v58
	v_add_f32_e32 v58, v58, v59
	v_add_f32_e32 v58, v77, v58
	v_mul_f32_e32 v59, 0xbfb8aa3b, v58
	v_exp_f32_e32 v59, v59
	s_nop 0
	v_add_f32_e32 v59, 1.0, v59
	s_nop 0
	v_rcp_f32_e32 v61, v59
	s_nop 0
	v_fma_f32 v82, -v59, v61, 1.0
	v_fma_f32 v59, v82, v61, v61
	v_mul_f32_e32 v58, v58, v59
	v_mul_f32_e32 v59, v191, v58
	v_cvt_pk_bf16_f32 v58, v62, v63
	v_cvt_pk_bf16_f32 v59, v60, v59
	v_add_u32_e32 v60, s4, v193
	v_ashrrev_i32_e32 v61, 31, v60
	v_lshlrev_b64 v[60:61], 13, v[60:61]
	v_lshl_add_u64 v[60:61], s[22:23], 0, v[60:61]
	v_lshl_add_u64 v[82:83], v[60:61], 0, v[142:143]
	v_mov_b32_e32 v61, v1
	global_store_dwordx2 v[82:83], v[58:59], off
	v_mov_b32_e32 v58, v1
	v_mov_b32_dpp v61, v61 row_ror:15 row_mask:0xf bank_mask:0xf
	v_mov_b32_e32 v59, v61
	v_mov_b32_dpp v58, v54 row_ror:1 row_mask:0xf bank_mask:0xf
	s_nop 0
	v_mov_b32_dpp v59, v50 row_shl:1 row_mask:0xf bank_mask:0xf
	v_mov_b32_dpp v58, v50 row_shr:1 row_mask:0xf bank_mask:0xf
	v_pk_mul_f32 v[58:59], v[84:85], v[58:59]
	s_nop 0
	v_fma_f32 v54, v50, v66, v58
	v_add_f32_e32 v54, v54, v59
	v_add_f32_e32 v54, v74, v54
	v_mul_f32_e32 v58, 0xbfb8aa3b, v54
	v_exp_f32_e32 v58, v58
	s_nop 0
	v_add_f32_e32 v58, 1.0, v58
	s_nop 0
	v_rcp_f32_e32 v59, v58
	s_nop 0
	v_fma_f32 v63, -v58, v59, 1.0
	v_fma_f32 v58, v63, v59, v59
	v_mul_f32_e32 v54, v54, v58
	v_mul_f32_e32 v58, v191, v54
	v_mov_b32_e32 v54, v1
	s_nop 1
	v_mov_b32_dpp v54, v55 row_ror:1 row_mask:0xf bank_mask:0xf
	v_mov_b32_e32 v55, v61
	s_nop 0
	v_mov_b32_dpp v54, v51 row_shr:1 row_mask:0xf bank_mask:0xf
	v_mov_b32_dpp v55, v51 row_shl:1 row_mask:0xf bank_mask:0xf
	v_pk_mul_f32 v[54:55], v[70:71], v[54:55]
	s_nop 0
	v_fma_f32 v54, v51, v67, v54
	v_add_f32_e32 v54, v54, v55
	v_add_f32_e32 v54, v75, v54
	v_mul_f32_e32 v55, 0xbfb8aa3b, v54
	v_exp_f32_e32 v55, v55
	s_nop 0
	v_add_f32_e32 v55, 1.0, v55
	s_nop 0
	v_rcp_f32_e32 v59, v55
	s_nop 0
	v_fma_f32 v63, -v55, v59, 1.0
	v_fma_f32 v55, v63, v59, v59
	v_mul_f32_e32 v54, v54, v55
	v_mul_f32_e32 v59, v191, v54
	v_mov_b32_e32 v54, v1
	v_mov_b32_e32 v55, v61
	v_mov_b32_dpp v61, v53 row_shl:1 row_mask:0xf bank_mask:0xf
	v_mov_b32_dpp v54, v56 row_ror:1 row_mask:0xf bank_mask:0xf
	v_mov_b32_dpp v55, v52 row_shl:1 row_mask:0xf bank_mask:0xf
	s_nop 0
	v_mov_b32_dpp v54, v52 row_shr:1 row_mask:0xf bank_mask:0xf
	v_pk_mul_f32 v[54:55], v[86:87], v[54:55]
	s_nop 0
	v_fma_f32 v54, v52, v68, v54
	v_add_f32_e32 v54, v54, v55
	v_add_f32_e32 v54, v76, v54
	v_mul_f32_e32 v55, 0xbfb8aa3b, v54
	v_exp_f32_e32 v55, v55
	s_nop 0
	v_add_f32_e32 v55, 1.0, v55
	s_nop 0
	v_mov_b32_e32 v60, v1
	v_rcp_f32_e32 v56, v55
	s_nop 0
	v_fma_f32 v63, -v55, v56, 1.0
	v_fma_f32 v55, v63, v56, v56
	v_mul_f32_e32 v54, v54, v55
	v_mov_b32_dpp v60, v57 row_ror:1 row_mask:0xf bank_mask:0xf
	v_mul_f32_e32 v56, v191, v54
	s_nop 0
	v_mov_b32_dpp v60, v53 row_shr:1 row_mask:0xf bank_mask:0xf
	v_pk_mul_f32 v[54:55], v[72:73], v[60:61]
	s_nop 0
	v_fma_f32 v54, v53, v69, v54
	v_add_f32_e32 v54, v54, v55
	v_add_f32_e32 v54, v77, v54
	v_mul_f32_e32 v55, 0xbfb8aa3b, v54
	v_exp_f32_e32 v55, v55
	s_nop 0
	v_add_f32_e32 v55, 1.0, v55
	s_nop 0
	v_rcp_f32_e32 v57, v55
	s_nop 0
	v_fma_f32 v62, -v55, v57, 1.0
	v_fma_f32 v55, v62, v57, v57
	v_mul_f32_e32 v54, v54, v55
	v_mul_f32_e32 v55, v191, v54
	v_cvt_pk_bf16_f32 v54, v58, v59
	v_cvt_pk_bf16_f32 v55, v56, v55
	v_add_u32_e32 v56, s4, v136
	v_ashrrev_i32_e32 v57, 31, v56
	v_lshlrev_b64 v[56:57], 13, v[56:57]
	v_lshl_add_u64 v[56:57], s[22:23], 0, v[56:57]
	v_lshl_add_u64 v[66:67], v[56:57], 0, v[142:143]
	global_store_dwordx2 v[66:67], v[54:55], off
	s_and_saveexec_b64 s[2:3], s[44:45]
	s_cbranch_execz .LBB0_701
; __device__ __forceinline__ unsigned cvt_pk_bf16(float lo, float hi) { unsigned r; asm volatile("v_cvt_pk_bf16_f32 %0, %1, %2" : "=v"(r) : "v"(lo), "v"(hi)); return r; }
; __device__ __forceinline__ float dppf_prev(float cur, float below) { return __uint_as_float(dpp_prev(__float_as_uint(cur), __float_as_uint(below))); }
; __device__ __forceinline__ float dppf_next(float cur, float above) { return __uint_as_float(dpp_next(__float_as_uint(cur), __float_as_uint(above))); }
; __device__ __forceinline__ float sigmoidf_(float x) { return 1.0f / (1.0f + __expf(-x)); }
;     __device__ __forceinline__ void operator()(AccT& acc, const Unit& u, int wr, int wc, int fr, int fq) const {
;     ...
;                         const f32x4 w0 = *(const f32x4*)(cw + mc + 4 * n), w1 = *(const f32x4*)(cw + 1024 + mc + 4 * n), w2 = *(const f32x4*)(cw + 2048 + mc + 4 * n), b = *(const f32x4*)(cb + mc + 4 * n);
; #pragma unroll
;                         for (int m = 0; m < 4; ++m) { const int lr = m * 16 + fr; const f32x4 gc = acc[ai][bj][m][n]; f32x4 o;
; #pragma unroll
;                             for (int j = 0; j < 4; ++j) { const float gp = dppf_prev(gc[j], m > 0 ? acc[ai][bj][m - 1][n][j] : 0.f), gn = dppf_next(gc[j], m < 3 ? acc[ai][bj][m + 1][n][j] : 0.f);
;                                 const float uu = gp * w0[j] + gc[j] * w1[j] + gn * w2[j] + b[j]; o[j] = uu * sigmoidf_(uu) * mul; }
;                             u32x2 w; w.x = cvt_pk_bf16(o[0], o[1]); w.y = cvt_pk_bf16(o[2], o[3]);
;                             *(u32x2*)(O + (size_t)(grp * 64 + lr) * NPROJ + col0 + bj * 128 + 4 * n) = w;
;                             if (m == 0 || m == 3) { if (lr < 2 || lr > 61) { u32x2 wg; wg.x = cvt_pk_bf16(gc[0], gc[1]); wg.y = cvt_pk_bf16(gc[2], gc[3]);
;                                 *(u32x2*)(HQ + (size_t)(grp * 4 + (lr < 2 ? lr : lr - 60)) * 1024 + mc + 4 * n) = wg; } } } } } }
	s_movk_i32 s4, 0xffd2
	v_cmp_gt_i32_e32 vcc, s4, v190
	v_cvt_pk_bf16_f32 v50, v50, v51
	v_cvt_pk_bf16_f32 v51, v52, v53
	s_nop 1
	v_cndmask_b32_e32 v52, v137, v136, vcc
	v_add_u32_e32 v52, s0, v52
	v_ashrrev_i32_e32 v53, 31, v52
	v_lshlrev_b64 v[52:53], 11, v[52:53]
	v_lshl_add_u64 v[52:53], s[48:49], 0, v[52:53]
	v_lshl_add_u64 v[52:53], v[158:159], 1, v[52:53]
	global_store_dwordx2 v[52:53], v[50:51], off offset:-4096
.LBB0_701:
	s_or_b64 exec, exec, s[2:3]
	s_mov_b64 s[2:3], 0x1010
	v_lshl_add_u64 v[50:51], v[174:175], 0, s[2:3]
	s_mov_b64 s[2:3], 0x2010
	v_lshl_add_u64 v[54:55], v[174:175], 0, s[2:3]
	s_waitcnt vmcnt(4)
	v_mov_b64_e32 v[62:63], v[196:197]
	v_mov_b64_e32 v[64:65], v[198:199]
	s_nop 0
	v_mov_b64_e32 v[50:51], v[204:205]
	v_mov_b64_e32 v[52:53], v[206:207]
	s_nop 0
	v_mov_b64_e32 v[54:55], v[222:223]
	v_mov_b64_e32 v[56:57], v[224:225]
	s_nop 0
	v_mov_b64_e32 v[58:59], v[226:227]
	v_mov_b64_e32 v[60:61], v[228:229]
	global_load_dwordx4 v[196:199], v[174:175], off offset:512
	global_load_dwordx4 v[204:207], v[160:161], off offset:-3584
	global_load_dwordx4 v[222:225], v[160:161], off offset:512
	global_load_dwordx4 v[226:229], v[176:177], off offset:512
	v_mov_b32_e32 v70, v1
	v_mov_b32_e32 v73, v1
	s_waitcnt vmcnt(4)
	v_mov_b32_e32 v68, v62
	v_mov_b32_dpp v70, v70 row_ror:1 row_mask:0xf bank_mask:0xf
	v_mov_b32_e32 v72, v70
	v_mov_b32_dpp v73, v42 row_ror:15 row_mask:0xf bank_mask:0xf
	v_mov_b32_e32 v69, v54
	v_mov_b32_dpp v72, v46 row_shr:1 row_mask:0xf bank_mask:0xf
	v_mov_b32_dpp v73, v46 row_shl:1 row_mask:0xf bank_mask:0xf
	v_pk_mul_f32 v[72:73], v[68:69], v[72:73]
	s_nop 0
	v_fma_f32 v54, v46, v50, v72
	v_add_f32_e32 v54, v54, v73
	v_add_f32_e32 v54, v58, v54
	v_mul_f32_e32 v62, 0xbfb8aa3b, v54
	v_exp_f32_e32 v62, v62
	s_nop 0
	v_add_f32_e32 v62, 1.0, v62
	s_nop 0
	v_rcp_f32_e32 v71, v62
	s_nop 0
	v_fma_f32 v74, -v62, v71, 1.0
	v_fma_f32 v62, v74, v71, v71
	v_mov_b32_e32 v75, v1
	v_mul_f32_e32 v54, v54, v62
	v_mov_b32_e32 v74, v70
	v_mov_b32_dpp v75, v43 row_ror:15 row_mask:0xf bank_mask:0xf
	v_mul_f32_e32 v72, v191, v54
	v_mov_b32_dpp v74, v47 row_shr:1 row_mask:0xf bank_mask:0xf
	v_mov_b32_dpp v75, v47 row_shl:1 row_mask:0xf bank_mask:0xf
	v_mov_b32_e32 v54, v63
	v_pk_mul_f32 v[62:63], v[54:55], v[74:75]
	s_nop 0
	v_fma_f32 v62, v47, v51, v62
	v_add_f32_e32 v62, v62, v63
	v_add_f32_e32 v62, v59, v62
	v_mul_f32_e32 v63, 0xbfb8aa3b, v62
	v_exp_f32_e32 v63, v63
	s_nop 0
	v_add_f32_e32 v63, 1.0, v63
	s_nop 0
	v_rcp_f32_e32 v71, v63
	s_nop 0
	v_fma_f32 v75, -v63, v71, 1.0
	v_fma_f32 v63, v75, v71, v71
	v_mov_b32_e32 v75, v1
	v_mul_f32_e32 v62, v62, v63
	v_mov_b32_e32 v74, v70
	v_mov_b32_dpp v75, v44 row_ror:15 row_mask:0xf bank_mask:0xf
	v_mul_f32_e32 v73, v191, v62
	v_mov_b32_dpp v74, v48 row_shr:1 row_mask:0xf bank_mask:0xf
	v_mov_b32_dpp v75, v48 row_shl:1 row_mask:0xf bank_mask:0xf
	v_mov_b32_e32 v62, v64
	v_mov_b32_e32 v63, v56
	v_pk_mul_f32 v[74:75], v[62:63], v[74:75]
	v_mov_b32_dpp v70, v49 row_shr:1 row_mask:0xf bank_mask:0xf
	v_fma_f32 v56, v48, v52, v74
	v_add_f32_e32 v56, v56, v75
	v_add_f32_e32 v56, v60, v56
	v_mul_f32_e32 v64, 0xbfb8aa3b, v56
	v_exp_f32_e32 v64, v64
	s_nop 0
	v_add_f32_e32 v64, 1.0, v64
	s_nop 0
	v_rcp_f32_e32 v71, v64
	s_nop 0
	v_fma_f32 v76, -v64, v71, 1.0
	v_fma_f32 v64, v76, v71, v71
	v_mov_b32_e32 v71, v1
	v_mul_f32_e32 v56, v56, v64
	v_mul_f32_e32 v74, v191, v56
	v_mov_b32_dpp v71, v45 row_ror:15 row_mask:0xf bank_mask:0xf
	v_mov_b32_e32 v56, v65
	s_nop 0
	v_mov_b32_dpp v71, v49 row_shl:1 row_mask:0xf bank_mask:0xf
	v_pk_mul_f32 v[64:65], v[56:57], v[70:71]
	s_nop 0
	v_fma_f32 v64, v49, v53, v64
	v_add_f32_e32 v64, v64, v65
	v_add_f32_e32 v64, v61, v64
	v_mul_f32_e32 v65, 0xbfb8aa3b, v64
	v_exp_f32_e32 v65, v65
	s_nop 0
	v_add_f32_e32 v65, 1.0, v65
	s_nop 0
	v_rcp_f32_e32 v70, v65
	s_nop 0
	v_fma_f32 v76, -v65, v70, 1.0
	v_fma_f32 v65, v76, v70, v70
	v_mul_f32_e32 v64, v64, v65
	v_mul_f32_e32 v65, v191, v64
	v_cvt_pk_bf16_f32 v64, v72, v73
	v_cvt_pk_bf16_f32 v65, v74, v65
	global_store_dwordx2 v[78:79], v[64:65], off offset:8
	s_and_saveexec_b64 s[2:3], s[42:43]
	s_cbranch_execz .LBB0_703
	v_cmp_gt_i32_e32 vcc, 2, v190
	v_cvt_pk_bf16_f32 v64, v46, v47
	v_cvt_pk_bf16_f32 v65, v48, v49
	s_nop 1
	v_cndmask_b32_e32 v70, v0, v190, vcc
	v_add_u32_e32 v70, s0, v70
	v_ashrrev_i32_e32 v71, 31, v70
	v_lshlrev_b64 v[70:71], 11, v[70:71]
	v_lshl_add_u64 v[70:71], s[48:49], 0, v[70:71]
	v_lshl_add_u64 v[70:71], v[158:159], 1, v[70:71]
	global_store_dwordx2 v[70:71], v[64:65], off offset:-4088
; __device__ __forceinline__ unsigned cvt_pk_bf16(float lo, float hi) { unsigned r; asm volatile("v_cvt_pk_bf16_f32 %0, %1, %2" : "=v"(r) : "v"(lo), "v"(hi)); return r; }
; __device__ __forceinline__ float dppf_prev(float cur, float below) { return __uint_as_float(dpp_prev(__float_as_uint(cur), __float_as_uint(below))); }
; __device__ __forceinline__ float dppf_next(float cur, float above) { return __uint_as_float(dpp_next(__float_as_uint(cur), __float_as_uint(above))); }
; __device__ __forceinline__ float sigmoidf_(float x) { return 1.0f / (1.0f + __expf(-x)); }
;     __device__ __forceinline__ void operator()(AccT& acc, const Unit& u, int wr, int wc, int fr, int fq) const {
;     ...
;                             for (int j = 0; j < 4; ++j) { const float gp = dppf_prev(gc[j], m > 0 ? acc[ai][bj][m - 1][n][j] : 0.f), gn = dppf_next(gc[j], m < 3 ? acc[ai][bj][m + 1][n][j] : 0.f);
;                                 const float uu = gp * w0[j] + gc[j] * w1[j] + gn * w2[j] + b[j]; o[j] = uu * sigmoidf_(uu) * mul; }
;                             u32x2 w; w.x = cvt_pk_bf16(o[0], o[1]); w.y = cvt_pk_bf16(o[2], o[3]);
;                             *(u32x2*)(O + (size_t)(grp * 64 + lr) * NPROJ + col0 + bj * 128 + 4 * n) = w;
;                             if (m == 0 || m == 3) { if (lr < 2 || lr > 61) { u32x2 wg; wg.x = cvt_pk_bf16(gc[0], gc[1]); wg.y = cvt_pk_bf16(gc[2], gc[3]);
;                                 *(u32x2*)(HQ + (size_t)(grp * 4 + (lr < 2 ? lr : lr - 60)) * 1024 + mc + 4 * n) = wg; } } } } } }
.LBB0_703:
	s_or_b64 exec, exec, s[2:3]
	v_mov_b32_e32 v64, v1
	v_mov_b32_e32 v65, v1
	s_nop 0
	v_mov_b32_dpp v64, v46 row_ror:1 row_mask:0xf bank_mask:0xf
	v_mov_b32_dpp v65, v38 row_ror:15 row_mask:0xf bank_mask:0xf
	s_nop 0
	v_mov_b32_dpp v64, v42 row_shr:1 row_mask:0xf bank_mask:0xf
	v_mov_b32_dpp v65, v42 row_shl:1 row_mask:0xf bank_mask:0xf
	v_pk_mul_f32 v[64:65], v[68:69], v[64:65]
	s_nop 0
	v_fma_f32 v46, v42, v50, v64
	v_add_f32_e32 v46, v46, v65
	v_add_f32_e32 v46, v58, v46
	v_mul_f32_e32 v64, 0xbfb8aa3b, v46
	v_exp_f32_e32 v64, v64
	s_nop 0
	v_add_f32_e32 v64, 1.0, v64
	s_nop 0
	v_rcp_f32_e32 v65, v64
	s_nop 0
	v_fma_f32 v72, -v64, v65, 1.0
	v_fma_f32 v64, v72, v65, v65
	v_mul_f32_e32 v46, v46, v64
	v_mul_f32_e32 v64, v191, v46
	v_mov_b32_e32 v46, v1
	s_nop 1
	v_mov_b32_dpp v46, v47 row_ror:1 row_mask:0xf bank_mask:0xf
	v_mov_b32_e32 v47, v1
	s_nop 0
	v_mov_b32_dpp v46, v43 row_shr:1 row_mask:0xf bank_mask:0xf
	v_mov_b32_dpp v47, v39 row_ror:15 row_mask:0xf bank_mask:0xf
	s_nop 1
	v_mov_b32_dpp v47, v43 row_shl:1 row_mask:0xf bank_mask:0xf
	v_pk_mul_f32 v[46:47], v[54:55], v[46:47]
	s_nop 0
	v_fma_f32 v46, v43, v51, v46
	v_add_f32_e32 v46, v46, v47
	v_add_f32_e32 v46, v59, v46
	v_mul_f32_e32 v47, 0xbfb8aa3b, v46
	v_exp_f32_e32 v47, v47
	s_nop 0
	v_add_f32_e32 v47, 1.0, v47
	s_nop 0
	v_rcp_f32_e32 v65, v47
	s_nop 0
	v_fma_f32 v72, -v47, v65, 1.0
	v_fma_f32 v47, v72, v65, v65
	v_mul_f32_e32 v46, v46, v47
	v_mul_f32_e32 v65, v191, v46
	v_mov_b32_e32 v46, v1
	v_mov_b32_e32 v47, v1
	s_nop 0
	v_mov_b32_dpp v46, v48 row_ror:1 row_mask:0xf bank_mask:0xf
	v_mov_b32_dpp v47, v40 row_ror:15 row_mask:0xf bank_mask:0xf
	s_nop 0
	v_mov_b32_dpp v46, v44 row_shr:1 row_mask:0xf bank_mask:0xf
	v_mov_b32_dpp v47, v44 row_shl:1 row_mask:0xf bank_mask:0xf
	v_pk_mul_f32 v[46:47], v[62:63], v[46:47]
	s_nop 0
	v_fma_f32 v46, v44, v52, v46
	v_add_f32_e32 v46, v46, v47
	v_add_f32_e32 v46, v60, v46
	v_mul_f32_e32 v47, 0xbfb8aa3b, v46
	v_exp_f32_e32 v47, v47
	s_nop 0
	v_add_f32_e32 v47, 1.0, v47
	s_nop 0
	v_rcp_f32_e32 v48, v47
	s_nop 0
	v_fma_f32 v72, -v47, v48, 1.0
	v_fma_f32 v47, v72, v48, v48
	v_mul_f32_e32 v46, v46, v47
	v_mul_f32_e32 v48, v191, v46
	v_mov_b32_e32 v46, v1
	v_mov_b32_e32 v47, v1
	s_nop 0
	v_mov_b32_dpp v46, v49 row_ror:1 row_mask:0xf bank_mask:0xf
	v_mov_b32_dpp v47, v41 row_ror:15 row_mask:0xf bank_mask:0xf
	s_nop 0
	v_mov_b32_dpp v46, v45 row_shr:1 row_mask:0xf bank_mask:0xf
	v_mov_b32_dpp v47, v45 row_shl:1 row_mask:0xf bank_mask:0xf
	v_pk_mul_f32 v[46:47], v[56:57], v[46:47]
	s_nop 0
	v_fma_f32 v46, v45, v53, v46
	v_add_f32_e32 v46, v46, v47
	v_add_f32_e32 v46, v61, v46
	v_mul_f32_e32 v47, 0xbfb8aa3b, v46
	v_exp_f32_e32 v47, v47
	s_nop 0
	v_add_f32_e32 v47, 1.0, v47
	s_nop 0
	v_rcp_f32_e32 v49, v47
	s_nop 0
	v_fma_f32 v72, -v47, v49, 1.0
	v_fma_f32 v47, v72, v49, v49
	v_mul_f32_e32 v46, v46, v47
	v_mul_f32_e32 v47, v191, v46
	v_cvt_pk_bf16_f32 v46, v64, v65
	v_cvt_pk_bf16_f32 v47, v48, v47
	global_store_dwordx2 v[80:81], v[46:47], off offset:8
	v_mov_b32_e32 v46, v1
	v_mov_b32_e32 v47, v1
	s_nop 0
	v_mov_b32_dpp v46, v42 row_ror:1 row_mask:0xf bank_mask:0xf
	v_mov_b32_dpp v47, v34 row_ror:15 row_mask:0xf bank_mask:0xf
	s_nop 0
	v_mov_b32_dpp v46, v38 row_shr:1 row_mask:0xf bank_mask:0xf
	v_mov_b32_dpp v47, v38 row_shl:1 row_mask:0xf bank_mask:0xf
	v_pk_mul_f32 v[46:47], v[68:69], v[46:47]
	s_nop 0
	v_fma_f32 v42, v38, v50, v46
	v_add_f32_e32 v42, v42, v47
	v_add_f32_e32 v42, v58, v42
	v_mul_f32_e32 v46, 0xbfb8aa3b, v42
	v_exp_f32_e32 v46, v46
	s_nop 0
	v_add_f32_e32 v46, 1.0, v46
	s_nop 0
	v_rcp_f32_e32 v47, v46
	s_nop 0
	v_fma_f32 v64, -v46, v47, 1.0
	v_fma_f32 v46, v64, v47, v47
	v_mul_f32_e32 v42, v42, v46
	v_mul_f32_e32 v46, v191, v42
	v_mov_b32_e32 v42, v1
	s_nop 1
	v_mov_b32_dpp v42, v43 row_ror:1 row_mask:0xf bank_mask:0xf
	v_mov_b32_e32 v43, v1
	s_nop 0
	v_mov_b32_dpp v42, v39 row_shr:1 row_mask:0xf bank_mask:0xf
	v_mov_b32_dpp v43, v35 row_ror:15 row_mask:0xf bank_mask:0xf
	s_nop 1
	v_mov_b32_dpp v43, v39 row_shl:1 row_mask:0xf bank_mask:0xf
	v_pk_mul_f32 v[42:43], v[54:55], v[42:43]
	s_nop 0
	v_fma_f32 v42, v39, v51, v42
	v_add_f32_e32 v42, v42, v43
	v_add_f32_e32 v42, v59, v42
	v_mul_f32_e32 v43, 0xbfb8aa3b, v42
	v_exp_f32_e32 v43, v43
	s_nop 0
	v_add_f32_e32 v43, 1.0, v43
	s_nop 0
	v_rcp_f32_e32 v47, v43
	s_nop 0
	v_fma_f32 v64, -v43, v47, 1.0
	v_fma_f32 v43, v64, v47, v47
	v_mul_f32_e32 v42, v42, v43
	v_mul_f32_e32 v47, v191, v42
	v_mov_b32_e32 v42, v1
	v_mov_b32_e32 v43, v1
	s_nop 0
	v_mov_b32_dpp v42, v44 row_ror:1 row_mask:0xf bank_mask:0xf
	v_mov_b32_dpp v43, v36 row_ror:15 row_mask:0xf bank_mask:0xf
	s_nop 0
	v_mov_b32_dpp v42, v40 row_shr:1 row_mask:0xf bank_mask:0xf
	v_mov_b32_dpp v43, v40 row_shl:1 row_mask:0xf bank_mask:0xf
	v_pk_mul_f32 v[42:43], v[62:63], v[42:43]
	s_nop 0
	v_fma_f32 v42, v40, v52, v42
	v_add_f32_e32 v42, v42, v43
	v_add_f32_e32 v42, v60, v42
	v_mul_f32_e32 v43, 0xbfb8aa3b, v42
	v_exp_f32_e32 v43, v43
	s_nop 0
	v_add_f32_e32 v43, 1.0, v43
	s_nop 0
	v_rcp_f32_e32 v44, v43
	s_nop 0
	v_fma_f32 v64, -v43, v44, 1.0
	v_fma_f32 v43, v64, v44, v44
	v_mul_f32_e32 v42, v42, v43
	v_mul_f32_e32 v44, v191, v42
	v_mov_b32_e32 v42, v1
	v_mov_b32_e32 v43, v1
	s_nop 0
	v_mov_b32_dpp v42, v45 row_ror:1 row_mask:0xf bank_mask:0xf
	v_mov_b32_dpp v43, v37 row_ror:15 row_mask:0xf bank_mask:0xf
	s_nop 0
	v_mov_b32_dpp v42, v41 row_shr:1 row_mask:0xf bank_mask:0xf
	v_mov_b32_dpp v43, v41 row_shl:1 row_mask:0xf bank_mask:0xf
	v_pk_mul_f32 v[42:43], v[56:57], v[42:43]
	s_nop 0
	v_fma_f32 v42, v41, v53, v42
	v_add_f32_e32 v42, v42, v43
	v_add_f32_e32 v42, v61, v42
	v_mul_f32_e32 v43, 0xbfb8aa3b, v42
	v_exp_f32_e32 v43, v43
; __device__ __forceinline__ unsigned cvt_pk_bf16(float lo, float hi) { unsigned r; asm volatile("v_cvt_pk_bf16_f32 %0, %1, %2" : "=v"(r) : "v"(lo), "v"(hi)); return r; }
; __device__ __forceinline__ float dppf_prev(float cur, float below) { return __uint_as_float(dpp_prev(__float_as_uint(cur), __float_as_uint(below))); }
; __device__ __forceinline__ float dppf_next(float cur, float above) { return __uint_as_float(dpp_next(__float_as_uint(cur), __float_as_uint(above))); }
; __device__ __forceinline__ float sigmoidf_(float x) { return 1.0f / (1.0f + __expf(-x)); }
;     __device__ __forceinline__ void operator()(AccT& acc, const Unit& u, int wr, int wc, int fr, int fq) const {
;     ...
;                         const f32x4 w0 = *(const f32x4*)(cw + mc + 4 * n), w1 = *(const f32x4*)(cw + 1024 + mc + 4 * n), w2 = *(const f32x4*)(cw + 2048 + mc + 4 * n), b = *(const f32x4*)(cb + mc + 4 * n);
; #pragma unroll
;                         for (int m = 0; m < 4; ++m) { const int lr = m * 16 + fr; const f32x4 gc = acc[ai][bj][m][n]; f32x4 o;
; #pragma unroll
;                             for (int j = 0; j < 4; ++j) { const float gp = dppf_prev(gc[j], m > 0 ? acc[ai][bj][m - 1][n][j] : 0.f), gn = dppf_next(gc[j], m < 3 ? acc[ai][bj][m + 1][n][j] : 0.f);
;                                 const float uu = gp * w0[j] + gc[j] * w1[j] + gn * w2[j] + b[j]; o[j] = uu * sigmoidf_(uu) * mul; }
;                             u32x2 w; w.x = cvt_pk_bf16(o[0], o[1]); w.y = cvt_pk_bf16(o[2], o[3]);
;                             *(u32x2*)(O + (size_t)(grp * 64 + lr) * NPROJ + col0 + bj * 128 + 4 * n) = w;
;                             if (m == 0 || m == 3) { if (lr < 2 || lr > 61) { u32x2 wg; wg.x = cvt_pk_bf16(gc[0], gc[1]); wg.y = cvt_pk_bf16(gc[2], gc[3]);
;                                 *(u32x2*)(HQ + (size_t)(grp * 4 + (lr < 2 ? lr : lr - 60)) * 1024 + mc + 4 * n) = wg; } } } } } }
	s_nop 0
	v_add_f32_e32 v43, 1.0, v43
	s_nop 0
	v_rcp_f32_e32 v45, v43
	s_nop 0
	v_fma_f32 v64, -v43, v45, 1.0
	v_fma_f32 v43, v64, v45, v45
	v_mul_f32_e32 v42, v42, v43
	v_mul_f32_e32 v43, v191, v42
	v_cvt_pk_bf16_f32 v42, v46, v47
	v_mov_b32_e32 v45, v1
	v_cvt_pk_bf16_f32 v43, v44, v43
	global_store_dwordx2 v[82:83], v[42:43], off offset:8
	v_mov_b32_e32 v42, v1
	v_mov_b32_dpp v45, v45 row_ror:15 row_mask:0xf bank_mask:0xf
	v_mov_b32_e32 v43, v45
	v_mov_b32_dpp v42, v38 row_ror:1 row_mask:0xf bank_mask:0xf
	s_nop 0
	v_mov_b32_dpp v43, v34 row_shl:1 row_mask:0xf bank_mask:0xf
	v_mov_b32_dpp v42, v34 row_shr:1 row_mask:0xf bank_mask:0xf
	v_pk_mul_f32 v[42:43], v[68:69], v[42:43]
	s_nop 0
	v_fma_f32 v38, v34, v50, v42
	v_add_f32_e32 v38, v38, v43
	v_add_f32_e32 v38, v58, v38
	v_mul_f32_e32 v42, 0xbfb8aa3b, v38
	v_exp_f32_e32 v42, v42
	s_nop 0
	v_add_f32_e32 v42, 1.0, v42
	s_nop 0
	v_rcp_f32_e32 v43, v42
	s_nop 0
	v_fma_f32 v47, -v42, v43, 1.0
	v_fma_f32 v42, v47, v43, v43
	v_mul_f32_e32 v38, v38, v42
	v_mul_f32_e32 v42, v191, v38
	v_mov_b32_e32 v38, v1
	s_nop 1
	v_mov_b32_dpp v38, v39 row_ror:1 row_mask:0xf bank_mask:0xf
	v_mov_b32_e32 v39, v45
	s_nop 0
	v_mov_b32_dpp v38, v35 row_shr:1 row_mask:0xf bank_mask:0xf
	v_mov_b32_dpp v39, v35 row_shl:1 row_mask:0xf bank_mask:0xf
	v_pk_mul_f32 v[38:39], v[54:55], v[38:39]
	s_nop 0
	v_fma_f32 v38, v35, v51, v38
	v_add_f32_e32 v38, v38, v39
	v_add_f32_e32 v38, v59, v38
	v_mul_f32_e32 v39, 0xbfb8aa3b, v38
	v_exp_f32_e32 v39, v39
	s_nop 0
	v_add_f32_e32 v39, 1.0, v39
	s_nop 0
	v_rcp_f32_e32 v43, v39
	s_nop 0
	v_fma_f32 v47, -v39, v43, 1.0
	v_fma_f32 v39, v47, v43, v43
	v_mul_f32_e32 v38, v38, v39
	v_mul_f32_e32 v43, v191, v38
	v_mov_b32_e32 v38, v1
	v_mov_b32_e32 v39, v45
	v_mov_b32_dpp v45, v37 row_shl:1 row_mask:0xf bank_mask:0xf
	v_mov_b32_dpp v38, v40 row_ror:1 row_mask:0xf bank_mask:0xf
	v_mov_b32_dpp v39, v36 row_shl:1 row_mask:0xf bank_mask:0xf
	s_nop 0
	v_mov_b32_dpp v38, v36 row_shr:1 row_mask:0xf bank_mask:0xf
	v_pk_mul_f32 v[38:39], v[62:63], v[38:39]
	s_nop 0
	v_fma_f32 v38, v36, v52, v38
	v_add_f32_e32 v38, v38, v39
	v_add_f32_e32 v38, v60, v38
	v_mul_f32_e32 v39, 0xbfb8aa3b, v38
	v_exp_f32_e32 v39, v39
	s_nop 0
	v_add_f32_e32 v39, 1.0, v39
	s_nop 0
	v_mov_b32_e32 v44, v1
	v_rcp_f32_e32 v40, v39
	s_nop 0
	v_fma_f32 v47, -v39, v40, 1.0
	v_fma_f32 v39, v47, v40, v40
	v_mul_f32_e32 v38, v38, v39
	v_mov_b32_dpp v44, v41 row_ror:1 row_mask:0xf bank_mask:0xf
	v_mul_f32_e32 v40, v191, v38
	s_nop 0
	v_mov_b32_dpp v44, v37 row_shr:1 row_mask:0xf bank_mask:0xf
	v_pk_mul_f32 v[38:39], v[56:57], v[44:45]
	s_nop 0
	v_fma_f32 v38, v37, v53, v38
	v_add_f32_e32 v38, v38, v39
	v_add_f32_e32 v38, v61, v38
	v_mul_f32_e32 v39, 0xbfb8aa3b, v38
	v_exp_f32_e32 v39, v39
	s_nop 0
	v_add_f32_e32 v39, 1.0, v39
	s_nop 0
	v_rcp_f32_e32 v41, v39
	s_nop 0
	v_fma_f32 v46, -v39, v41, 1.0
	v_fma_f32 v39, v46, v41, v41
	v_mul_f32_e32 v38, v38, v39
	v_mul_f32_e32 v39, v191, v38
	v_cvt_pk_bf16_f32 v38, v42, v43
	v_cvt_pk_bf16_f32 v39, v40, v39
	global_store_dwordx2 v[66:67], v[38:39], off offset:8
	s_and_saveexec_b64 s[2:3], s[44:45]
	s_cbranch_execz .LBB0_705
	s_movk_i32 s4, 0xffd2
	v_cmp_gt_i32_e32 vcc, s4, v190
	v_cvt_pk_bf16_f32 v34, v34, v35
	v_cvt_pk_bf16_f32 v35, v36, v37
	s_nop 1
	v_cndmask_b32_e32 v36, v137, v136, vcc
	v_add_u32_e32 v36, s0, v36
	v_ashrrev_i32_e32 v37, 31, v36
	v_lshlrev_b64 v[36:37], 11, v[36:37]
	v_lshl_add_u64 v[36:37], s[48:49], 0, v[36:37]
	v_lshl_add_u64 v[36:37], v[158:159], 1, v[36:37]
	global_store_dwordx2 v[36:37], v[34:35], off offset:-4088
.LBB0_705:
	s_or_b64 exec, exec, s[2:3]
	s_waitcnt vmcnt(4)
	v_mov_b64_e32 v[46:47], v[196:197]
	v_mov_b64_e32 v[48:49], v[198:199]
	v_mov_b64_e32 v[34:35], v[204:205]
	v_mov_b64_e32 v[36:37], v[206:207]
	v_mov_b64_e32 v[38:39], v[222:223]
	v_mov_b64_e32 v[40:41], v[224:225]
	v_mov_b64_e32 v[42:43], v[226:227]
	v_mov_b64_e32 v[44:45], v[228:229]
	global_load_dwordx4 v[196:199], v[174:175], off offset:528
	global_load_dwordx4 v[204:207], v[160:161], off offset:-3568
	global_load_dwordx4 v[222:225], v[160:161], off offset:528
	global_load_dwordx4 v[226:229], v[176:177], off offset:528
	v_mov_b32_e32 v52, v1
	v_mov_b32_e32 v55, v1
	s_waitcnt vmcnt(4)
	v_mov_b32_e32 v50, v46
	v_mov_b32_dpp v52, v52 row_ror:1 row_mask:0xf bank_mask:0xf
	v_mov_b32_e32 v54, v52
	v_mov_b32_dpp v55, v26 row_ror:15 row_mask:0xf bank_mask:0xf
	v_mov_b32_e32 v51, v38
	v_mov_b32_dpp v54, v30 row_shr:1 row_mask:0xf bank_mask:0xf
	v_mov_b32_dpp v55, v30 row_shl:1 row_mask:0xf bank_mask:0xf
	v_pk_mul_f32 v[54:55], v[50:51], v[54:55]
	s_nop 0
	v_fma_f32 v38, v30, v34, v54
	v_add_f32_e32 v38, v38, v55
	v_add_f32_e32 v38, v42, v38
	v_mul_f32_e32 v46, 0xbfb8aa3b, v38
	v_exp_f32_e32 v46, v46
	s_nop 0
	v_add_f32_e32 v46, 1.0, v46
	s_nop 0
	v_rcp_f32_e32 v53, v46
	s_nop 0
	v_fma_f32 v56, -v46, v53, 1.0
	v_fma_f32 v46, v56, v53, v53
	v_mov_b32_e32 v57, v1
	v_mul_f32_e32 v38, v38, v46
	v_mov_b32_e32 v56, v52
	v_mov_b32_dpp v57, v27 row_ror:15 row_mask:0xf bank_mask:0xf
	v_mul_f32_e32 v54, v120, v38
	v_mov_b32_dpp v56, v31 row_shr:1 row_mask:0xf bank_mask:0xf
	v_mov_b32_dpp v57, v31 row_shl:1 row_mask:0xf bank_mask:0xf
	v_mov_b32_e32 v38, v47
	v_pk_mul_f32 v[46:47], v[38:39], v[56:57]
	s_nop 0
	v_fma_f32 v46, v31, v35, v46
	v_add_f32_e32 v46, v46, v47
	v_add_f32_e32 v46, v43, v46
	v_mul_f32_e32 v47, 0xbfb8aa3b, v46
	v_exp_f32_e32 v47, v47
	s_nop 0
	v_add_f32_e32 v47, 1.0, v47
	s_nop 0
	v_rcp_f32_e32 v53, v47
	s_nop 0
	v_fma_f32 v57, -v47, v53, 1.0
	v_fma_f32 v47, v57, v53, v53
	v_mov_b32_e32 v57, v1
	v_mul_f32_e32 v46, v46, v47
	v_mov_b32_e32 v56, v52
	v_mov_b32_dpp v57, v28 row_ror:15 row_mask:0xf bank_mask:0xf
; __device__ __forceinline__ unsigned cvt_pk_bf16(float lo, float hi) { unsigned r; asm volatile("v_cvt_pk_bf16_f32 %0, %1, %2" : "=v"(r) : "v"(lo), "v"(hi)); return r; }
; __device__ __forceinline__ float dppf_prev(float cur, float below) { return __uint_as_float(dpp_prev(__float_as_uint(cur), __float_as_uint(below))); }
; __device__ __forceinline__ float dppf_next(float cur, float above) { return __uint_as_float(dpp_next(__float_as_uint(cur), __float_as_uint(above))); }
; __device__ __forceinline__ float sigmoidf_(float x) { return 1.0f / (1.0f + __expf(-x)); }
;     __device__ __forceinline__ void operator()(AccT& acc, const Unit& u, int wr, int wc, int fr, int fq) const {
;     ...
;                             for (int j = 0; j < 4; ++j) { const float gp = dppf_prev(gc[j], m > 0 ? acc[ai][bj][m - 1][n][j] : 0.f), gn = dppf_next(gc[j], m < 3 ? acc[ai][bj][m + 1][n][j] : 0.f);
;                                 const float uu = gp * w0[j] + gc[j] * w1[j] + gn * w2[j] + b[j]; o[j] = uu * sigmoidf_(uu) * mul; }
;                             u32x2 w; w.x = cvt_pk_bf16(o[0], o[1]); w.y = cvt_pk_bf16(o[2], o[3]);
;                             *(u32x2*)(O + (size_t)(grp * 64 + lr) * NPROJ + col0 + bj * 128 + 4 * n) = w;
;                             if (m == 0 || m == 3) { if (lr < 2 || lr > 61) { u32x2 wg; wg.x = cvt_pk_bf16(gc[0], gc[1]); wg.y = cvt_pk_bf16(gc[2], gc[3]);
;                                 *(u32x2*)(HQ + (size_t)(grp * 4 + (lr < 2 ? lr : lr - 60)) * 1024 + mc + 4 * n) = wg; } } } } } }
	v_mul_f32_e32 v55, v120, v46
	v_mov_b32_dpp v56, v32 row_shr:1 row_mask:0xf bank_mask:0xf
	v_mov_b32_dpp v57, v32 row_shl:1 row_mask:0xf bank_mask:0xf
	v_mov_b32_e32 v46, v48
	v_mov_b32_e32 v47, v40
	v_pk_mul_f32 v[56:57], v[46:47], v[56:57]
	v_mov_b32_dpp v52, v33 row_shr:1 row_mask:0xf bank_mask:0xf
	v_fma_f32 v40, v32, v36, v56
	v_add_f32_e32 v40, v40, v57
	v_add_f32_e32 v40, v44, v40
	v_mul_f32_e32 v48, 0xbfb8aa3b, v40
	v_exp_f32_e32 v48, v48
	s_nop 0
	v_add_f32_e32 v48, 1.0, v48
	s_nop 0
	v_rcp_f32_e32 v53, v48
	s_nop 0
	v_fma_f32 v58, -v48, v53, 1.0
	v_fma_f32 v48, v58, v53, v53
	v_mov_b32_e32 v53, v1
	v_mul_f32_e32 v40, v40, v48
	v_mul_f32_e32 v56, v120, v40
	v_mov_b32_dpp v53, v29 row_ror:15 row_mask:0xf bank_mask:0xf
	v_mov_b32_e32 v40, v49
	s_nop 0
	v_mov_b32_dpp v53, v33 row_shl:1 row_mask:0xf bank_mask:0xf
	v_pk_mul_f32 v[48:49], v[40:41], v[52:53]
	s_nop 0
	v_fma_f32 v48, v33, v37, v48
	v_add_f32_e32 v48, v48, v49
	v_add_f32_e32 v48, v45, v48
	v_mul_f32_e32 v49, 0xbfb8aa3b, v48
	v_exp_f32_e32 v49, v49
	s_nop 0
	v_add_f32_e32 v49, 1.0, v49
	s_nop 0
	v_rcp_f32_e32 v52, v49
	s_nop 0
	v_fma_f32 v58, -v49, v52, 1.0
	v_fma_f32 v49, v58, v52, v52
	v_mul_f32_e32 v48, v48, v49
	v_mul_f32_e32 v49, v120, v48
	v_cvt_pk_bf16_f32 v48, v54, v55
	v_cvt_pk_bf16_f32 v49, v56, v49
	global_store_dwordx2 v[78:79], v[48:49], off offset:256
	s_and_saveexec_b64 s[2:3], s[42:43]
	s_cbranch_execz .LBB0_707
	v_cmp_gt_i32_e32 vcc, 2, v190
	v_cvt_pk_bf16_f32 v48, v30, v31
	v_cvt_pk_bf16_f32 v49, v32, v33
	s_nop 1
	v_cndmask_b32_e32 v52, v0, v190, vcc
	v_add_u32_e32 v52, s0, v52
	v_ashrrev_i32_e32 v53, 31, v52
	v_lshlrev_b64 v[52:53], 11, v[52:53]
	v_lshl_add_u64 v[52:53], s[48:49], 0, v[52:53]
	v_lshl_add_u64 v[52:53], v[158:159], 1, v[52:53]
	global_store_dwordx2 v[52:53], v[48:49], off offset:-3840
.LBB0_707:
	s_or_b64 exec, exec, s[2:3]
	v_mov_b32_e32 v48, v1
	v_mov_b32_e32 v49, v1
	s_nop 0
	v_mov_b32_dpp v48, v30 row_ror:1 row_mask:0xf bank_mask:0xf
	v_mov_b32_dpp v49, v22 row_ror:15 row_mask:0xf bank_mask:0xf
	s_nop 0
	v_mov_b32_dpp v48, v26 row_shr:1 row_mask:0xf bank_mask:0xf
	v_mov_b32_dpp v49, v26 row_shl:1 row_mask:0xf bank_mask:0xf
	v_pk_mul_f32 v[48:49], v[50:51], v[48:49]
	s_nop 0
	v_fma_f32 v30, v26, v34, v48
	v_add_f32_e32 v30, v30, v49
	v_add_f32_e32 v30, v42, v30
	v_mul_f32_e32 v48, 0xbfb8aa3b, v30
	v_exp_f32_e32 v48, v48
	s_nop 0
	v_add_f32_e32 v48, 1.0, v48
	s_nop 0
	v_rcp_f32_e32 v49, v48
	s_nop 0
	v_fma_f32 v54, -v48, v49, 1.0
	v_fma_f32 v48, v54, v49, v49
	v_mul_f32_e32 v30, v30, v48
	v_mul_f32_e32 v48, v120, v30
	v_mov_b32_e32 v30, v1
	s_nop 1
	v_mov_b32_dpp v30, v31 row_ror:1 row_mask:0xf bank_mask:0xf
	v_mov_b32_e32 v31, v1
	s_nop 0
	v_mov_b32_dpp v30, v27 row_shr:1 row_mask:0xf bank_mask:0xf
	v_mov_b32_dpp v31, v23 row_ror:15 row_mask:0xf bank_mask:0xf
	s_nop 1
	v_mov_b32_dpp v31, v27 row_shl:1 row_mask:0xf bank_mask:0xf
	v_pk_mul_f32 v[30:31], v[38:39], v[30:31]
	s_nop 0
	v_fma_f32 v30, v27, v35, v30
	v_add_f32_e32 v30, v30, v31
	v_add_f32_e32 v30, v43, v30
	v_mul_f32_e32 v31, 0xbfb8aa3b, v30
	v_exp_f32_e32 v31, v31
	s_nop 0
	v_add_f32_e32 v31, 1.0, v31
	s_nop 0
	v_rcp_f32_e32 v49, v31
	s_nop 0
	v_fma_f32 v54, -v31, v49, 1.0
	v_fma_f32 v31, v54, v49, v49
	v_mul_f32_e32 v30, v30, v31
	v_mul_f32_e32 v49, v120, v30
	v_mov_b32_e32 v30, v1
	v_mov_b32_e32 v31, v1
	s_nop 0
	v_mov_b32_dpp v30, v32 row_ror:1 row_mask:0xf bank_mask:0xf
	v_mov_b32_dpp v31, v24 row_ror:15 row_mask:0xf bank_mask:0xf
	s_nop 0
	v_mov_b32_dpp v30, v28 row_shr:1 row_mask:0xf bank_mask:0xf
	v_mov_b32_dpp v31, v28 row_shl:1 row_mask:0xf bank_mask:0xf
	v_pk_mul_f32 v[30:31], v[46:47], v[30:31]
	s_nop 0
	v_fma_f32 v30, v28, v36, v30
	v_add_f32_e32 v30, v30, v31
	v_add_f32_e32 v30, v44, v30
	v_mul_f32_e32 v31, 0xbfb8aa3b, v30
	v_exp_f32_e32 v31, v31
	s_nop 0
	v_add_f32_e32 v31, 1.0, v31
	s_nop 0
	v_rcp_f32_e32 v32, v31
	s_nop 0
	v_fma_f32 v54, -v31, v32, 1.0
	v_fma_f32 v31, v54, v32, v32
	v_mul_f32_e32 v30, v30, v31
	v_mul_f32_e32 v32, v120, v30
	v_mov_b32_e32 v30, v1
	v_mov_b32_e32 v31, v1
	s_nop 0
	v_mov_b32_dpp v30, v33 row_ror:1 row_mask:0xf bank_mask:0xf
	v_mov_b32_dpp v31, v25 row_ror:15 row_mask:0xf bank_mask:0xf
	s_nop 0
	v_mov_b32_dpp v30, v29 row_shr:1 row_mask:0xf bank_mask:0xf
	v_mov_b32_dpp v31, v29 row_shl:1 row_mask:0xf bank_mask:0xf
	v_pk_mul_f32 v[30:31], v[40:41], v[30:31]
	s_nop 0
	v_fma_f32 v30, v29, v37, v30
	v_add_f32_e32 v30, v30, v31
	v_add_f32_e32 v30, v45, v30
	v_mul_f32_e32 v31, 0xbfb8aa3b, v30
	v_exp_f32_e32 v31, v31
	s_nop 0
	v_add_f32_e32 v31, 1.0, v31
	s_nop 0
	v_rcp_f32_e32 v33, v31
	s_nop 0
	v_fma_f32 v54, -v31, v33, 1.0
	v_fma_f32 v31, v54, v33, v33
	v_mul_f32_e32 v30, v30, v31
	v_mul_f32_e32 v31, v120, v30
	v_cvt_pk_bf16_f32 v30, v48, v49
	v_cvt_pk_bf16_f32 v31, v32, v31
	global_store_dwordx2 v[80:81], v[30:31], off offset:256
	v_mov_b32_e32 v30, v1
	v_mov_b32_e32 v31, v1
	s_nop 0
	v_mov_b32_dpp v30, v26 row_ror:1 row_mask:0xf bank_mask:0xf
	v_mov_b32_dpp v31, v18 row_ror:15 row_mask:0xf bank_mask:0xf
	s_nop 0
	v_mov_b32_dpp v30, v22 row_shr:1 row_mask:0xf bank_mask:0xf
	v_mov_b32_dpp v31, v22 row_shl:1 row_mask:0xf bank_mask:0xf
	v_pk_mul_f32 v[30:31], v[50:51], v[30:31]
	s_nop 0
	v_fma_f32 v26, v22, v34, v30
	v_add_f32_e32 v26, v26, v31
	v_add_f32_e32 v26, v42, v26
	v_mul_f32_e32 v30, 0xbfb8aa3b, v26
	v_exp_f32_e32 v30, v30
	s_nop 0
	v_add_f32_e32 v30, 1.0, v30
	s_nop 0
	v_rcp_f32_e32 v31, v30
	s_nop 0
	v_fma_f32 v48, -v30, v31, 1.0
	v_fma_f32 v30, v48, v31, v31
	v_mul_f32_e32 v26, v26, v30
	v_mul_f32_e32 v30, v120, v26
	v_mov_b32_e32 v26, v1
	s_nop 1
	v_mov_b32_dpp v26, v27 row_ror:1 row_mask:0xf bank_mask:0xf
	v_mov_b32_e32 v27, v1
; __device__ __forceinline__ unsigned cvt_pk_bf16(float lo, float hi) { unsigned r; asm volatile("v_cvt_pk_bf16_f32 %0, %1, %2" : "=v"(r) : "v"(lo), "v"(hi)); return r; }
; __device__ __forceinline__ float dppf_prev(float cur, float below) { return __uint_as_float(dpp_prev(__float_as_uint(cur), __float_as_uint(below))); }
; __device__ __forceinline__ float dppf_next(float cur, float above) { return __uint_as_float(dpp_next(__float_as_uint(cur), __float_as_uint(above))); }
; __device__ __forceinline__ float sigmoidf_(float x) { return 1.0f / (1.0f + __expf(-x)); }
;     __device__ __forceinline__ void operator()(AccT& acc, const Unit& u, int wr, int wc, int fr, int fq) const {
;     ...
;                             for (int j = 0; j < 4; ++j) { const float gp = dppf_prev(gc[j], m > 0 ? acc[ai][bj][m - 1][n][j] : 0.f), gn = dppf_next(gc[j], m < 3 ? acc[ai][bj][m + 1][n][j] : 0.f);
;                                 const float uu = gp * w0[j] + gc[j] * w1[j] + gn * w2[j] + b[j]; o[j] = uu * sigmoidf_(uu) * mul; }
;                             u32x2 w; w.x = cvt_pk_bf16(o[0], o[1]); w.y = cvt_pk_bf16(o[2], o[3]);
;                             *(u32x2*)(O + (size_t)(grp * 64 + lr) * NPROJ + col0 + bj * 128 + 4 * n) = w;
;                             if (m == 0 || m == 3) { if (lr < 2 || lr > 61) { u32x2 wg; wg.x = cvt_pk_bf16(gc[0], gc[1]); wg.y = cvt_pk_bf16(gc[2], gc[3]);
;                                 *(u32x2*)(HQ + (size_t)(grp * 4 + (lr < 2 ? lr : lr - 60)) * 1024 + mc + 4 * n) = wg; } } } } } }
	s_nop 0
	v_mov_b32_dpp v26, v23 row_shr:1 row_mask:0xf bank_mask:0xf
	v_mov_b32_dpp v27, v19 row_ror:15 row_mask:0xf bank_mask:0xf
	s_nop 1
	v_mov_b32_dpp v27, v23 row_shl:1 row_mask:0xf bank_mask:0xf
	v_pk_mul_f32 v[26:27], v[38:39], v[26:27]
	s_nop 0
	v_fma_f32 v26, v23, v35, v26
	v_add_f32_e32 v26, v26, v27
	v_add_f32_e32 v26, v43, v26
	v_mul_f32_e32 v27, 0xbfb8aa3b, v26
	v_exp_f32_e32 v27, v27
	s_nop 0
	v_add_f32_e32 v27, 1.0, v27
	s_nop 0
	v_rcp_f32_e32 v31, v27
	s_nop 0
	v_fma_f32 v48, -v27, v31, 1.0
	v_fma_f32 v27, v48, v31, v31
	v_mul_f32_e32 v26, v26, v27
	v_mul_f32_e32 v31, v120, v26
	v_mov_b32_e32 v26, v1
	v_mov_b32_e32 v27, v1
	s_nop 0
	v_mov_b32_dpp v26, v28 row_ror:1 row_mask:0xf bank_mask:0xf
	v_mov_b32_dpp v27, v20 row_ror:15 row_mask:0xf bank_mask:0xf
	s_nop 0
	v_mov_b32_dpp v26, v24 row_shr:1 row_mask:0xf bank_mask:0xf
	v_mov_b32_dpp v27, v24 row_shl:1 row_mask:0xf bank_mask:0xf
	v_pk_mul_f32 v[26:27], v[46:47], v[26:27]
	s_nop 0
	v_fma_f32 v26, v24, v36, v26
	v_add_f32_e32 v26, v26, v27
	v_add_f32_e32 v26, v44, v26
	v_mul_f32_e32 v27, 0xbfb8aa3b, v26
	v_exp_f32_e32 v27, v27
	s_nop 0
	v_add_f32_e32 v27, 1.0, v27
	s_nop 0
	v_rcp_f32_e32 v28, v27
	s_nop 0
	v_fma_f32 v48, -v27, v28, 1.0
	v_fma_f32 v27, v48, v28, v28
	v_mul_f32_e32 v26, v26, v27
	v_mul_f32_e32 v28, v120, v26
	v_mov_b32_e32 v26, v1
	v_mov_b32_e32 v27, v1
	s_nop 0
	v_mov_b32_dpp v26, v29 row_ror:1 row_mask:0xf bank_mask:0xf
	v_mov_b32_dpp v27, v21 row_ror:15 row_mask:0xf bank_mask:0xf
	s_nop 0
	v_mov_b32_dpp v26, v25 row_shr:1 row_mask:0xf bank_mask:0xf
	v_mov_b32_dpp v27, v25 row_shl:1 row_mask:0xf bank_mask:0xf
	v_pk_mul_f32 v[26:27], v[40:41], v[26:27]
	s_nop 0
	v_fma_f32 v26, v25, v37, v26
	v_add_f32_e32 v26, v26, v27
	v_add_f32_e32 v26, v45, v26
	v_mul_f32_e32 v27, 0xbfb8aa3b, v26
	v_exp_f32_e32 v27, v27
	s_nop 0
	v_add_f32_e32 v27, 1.0, v27
	s_nop 0
	v_rcp_f32_e32 v29, v27
	s_nop 0
	v_fma_f32 v48, -v27, v29, 1.0
	v_fma_f32 v27, v48, v29, v29
	v_mul_f32_e32 v26, v26, v27
	v_mul_f32_e32 v27, v120, v26
	v_cvt_pk_bf16_f32 v26, v30, v31
	v_mov_b32_e32 v29, v1
	v_cvt_pk_bf16_f32 v27, v28, v27
	global_store_dwordx2 v[82:83], v[26:27], off offset:256
	v_mov_b32_e32 v26, v1
	v_mov_b32_dpp v29, v29 row_ror:15 row_mask:0xf bank_mask:0xf
	v_mov_b32_e32 v27, v29
	v_mov_b32_dpp v26, v22 row_ror:1 row_mask:0xf bank_mask:0xf
	s_nop 0
	v_mov_b32_dpp v27, v18 row_shl:1 row_mask:0xf bank_mask:0xf
	v_mov_b32_dpp v26, v18 row_shr:1 row_mask:0xf bank_mask:0xf
	v_pk_mul_f32 v[26:27], v[50:51], v[26:27]
	s_nop 0
	v_fma_f32 v22, v18, v34, v26
	v_add_f32_e32 v22, v22, v27
	v_add_f32_e32 v22, v42, v22
	v_mul_f32_e32 v26, 0xbfb8aa3b, v22
	v_exp_f32_e32 v26, v26
	s_nop 0
	v_add_f32_e32 v26, 1.0, v26
	s_nop 0
	v_rcp_f32_e32 v27, v26
	s_nop 0
	v_fma_f32 v31, -v26, v27, 1.0
	v_fma_f32 v26, v31, v27, v27
	v_mul_f32_e32 v22, v22, v26
	v_mul_f32_e32 v26, v120, v22
	v_mov_b32_e32 v22, v1
	s_nop 1
	v_mov_b32_dpp v22, v23 row_ror:1 row_mask:0xf bank_mask:0xf
	v_mov_b32_e32 v23, v29
	s_nop 0
	v_mov_b32_dpp v22, v19 row_shr:1 row_mask:0xf bank_mask:0xf
	v_mov_b32_dpp v23, v19 row_shl:1 row_mask:0xf bank_mask:0xf
	v_pk_mul_f32 v[22:23], v[38:39], v[22:23]
	s_nop 0
	v_fma_f32 v22, v19, v35, v22
	v_add_f32_e32 v22, v22, v23
	v_add_f32_e32 v22, v43, v22
	v_mul_f32_e32 v23, 0xbfb8aa3b, v22
	v_exp_f32_e32 v23, v23
	s_nop 0
	v_add_f32_e32 v23, 1.0, v23
	s_nop 0
	v_rcp_f32_e32 v27, v23
	s_nop 0
	v_fma_f32 v31, -v23, v27, 1.0
	v_fma_f32 v23, v31, v27, v27
	v_mul_f32_e32 v22, v22, v23
	v_mul_f32_e32 v27, v120, v22
	v_mov_b32_e32 v22, v1
	v_mov_b32_e32 v23, v29
	v_mov_b32_dpp v29, v21 row_shl:1 row_mask:0xf bank_mask:0xf
	v_mov_b32_dpp v22, v24 row_ror:1 row_mask:0xf bank_mask:0xf
	v_mov_b32_dpp v23, v20 row_shl:1 row_mask:0xf bank_mask:0xf
	s_nop 0
	v_mov_b32_dpp v22, v20 row_shr:1 row_mask:0xf bank_mask:0xf
	v_pk_mul_f32 v[22:23], v[46:47], v[22:23]
	s_nop 0
	v_fma_f32 v22, v20, v36, v22
	v_add_f32_e32 v22, v22, v23
	v_add_f32_e32 v22, v44, v22
	v_mul_f32_e32 v23, 0xbfb8aa3b, v22
	v_exp_f32_e32 v23, v23
	s_nop 0
	v_add_f32_e32 v23, 1.0, v23
	s_nop 0
	v_mov_b32_e32 v28, v1
	v_rcp_f32_e32 v24, v23
	s_nop 0
	v_fma_f32 v31, -v23, v24, 1.0
	v_fma_f32 v23, v31, v24, v24
	v_mul_f32_e32 v22, v22, v23
	v_mov_b32_dpp v28, v25 row_ror:1 row_mask:0xf bank_mask:0xf
	v_mul_f32_e32 v24, v120, v22
	s_nop 0
	v_mov_b32_dpp v28, v21 row_shr:1 row_mask:0xf bank_mask:0xf
	v_pk_mul_f32 v[22:23], v[40:41], v[28:29]
	s_nop 0
	v_fma_f32 v22, v21, v37, v22
	v_add_f32_e32 v22, v22, v23
	v_add_f32_e32 v22, v45, v22
	v_mul_f32_e32 v23, 0xbfb8aa3b, v22
	v_exp_f32_e32 v23, v23
	s_nop 0
	v_add_f32_e32 v23, 1.0, v23
	s_nop 0
	v_rcp_f32_e32 v25, v23
	s_nop 0
	v_fma_f32 v30, -v23, v25, 1.0
	v_fma_f32 v23, v30, v25, v25
	v_mul_f32_e32 v22, v22, v23
	v_mul_f32_e32 v23, v120, v22
	v_cvt_pk_bf16_f32 v22, v26, v27
	v_cvt_pk_bf16_f32 v23, v24, v23
	global_store_dwordx2 v[66:67], v[22:23], off offset:256
	s_and_saveexec_b64 s[2:3], s[44:45]
	s_cbranch_execz .LBB0_709
	s_movk_i32 s4, 0xffd2
	v_cmp_gt_i32_e32 vcc, s4, v190
	v_cvt_pk_bf16_f32 v18, v18, v19
	v_cvt_pk_bf16_f32 v19, v20, v21
	s_nop 1
	v_cndmask_b32_e32 v20, v137, v136, vcc
	v_add_u32_e32 v20, s0, v20
	v_ashrrev_i32_e32 v21, 31, v20
	v_lshlrev_b64 v[20:21], 11, v[20:21]
	v_lshl_add_u64 v[20:21], s[48:49], 0, v[20:21]
	v_lshl_add_u64 v[20:21], v[158:159], 1, v[20:21]
	global_store_dwordx2 v[20:21], v[18:19], off offset:-3840
; __device__ __forceinline__ unsigned cvt_pk_bf16(float lo, float hi) { unsigned r; asm volatile("v_cvt_pk_bf16_f32 %0, %1, %2" : "=v"(r) : "v"(lo), "v"(hi)); return r; }
; __device__ __forceinline__ float sigmoidf_(float x) { return 1.0f / (1.0f + __expf(-x)); }
; __device__ __forceinline__ float dppf_prev(float cur, float below) { return __uint_as_float(dpp_prev(__float_as_uint(cur), __float_as_uint(below))); }
; __device__ __forceinline__ float dppf_next(float cur, float above) { return __uint_as_float(dpp_next(__float_as_uint(cur), __float_as_uint(above))); }
;     __device__ __forceinline__ void operator()(AccT& acc, const Unit& u, int wr, int wc, int fr, int fq) const {
;     ...
;                 for (int bj = 0; bj < 2; ++bj) { const int mc = mc0 + bj * 128; const float mul = mc < 512 ? 0.08838834764831845f : 1.0f;
; #pragma unroll
;                     for (int n = 0; n < 2; ++n) {
;                         const f32x4 w0 = *(const f32x4*)(cw + mc + 4 * n), w1 = *(const f32x4*)(cw + 1024 + mc + 4 * n), w2 = *(const f32x4*)(cw + 2048 + mc + 4 * n), b = *(const f32x4*)(cb + mc + 4 * n);
; #pragma unroll
;                         for (int m = 0; m < 4; ++m) { const int lr = m * 16 + fr; const f32x4 gc = acc[ai][bj][m][n]; f32x4 o;
; #pragma unroll
;                             for (int j = 0; j < 4; ++j) { const float gp = dppf_prev(gc[j], m > 0 ? acc[ai][bj][m - 1][n][j] : 0.f), gn = dppf_next(gc[j], m < 3 ? acc[ai][bj][m + 1][n][j] : 0.f);
;                                 const float uu = gp * w0[j] + gc[j] * w1[j] + gn * w2[j] + b[j]; o[j] = uu * sigmoidf_(uu) * mul; }
;                             u32x2 w; w.x = cvt_pk_bf16(o[0], o[1]); w.y = cvt_pk_bf16(o[2], o[3]);
;                             *(u32x2*)(O + (size_t)(grp * 64 + lr) * NPROJ + col0 + bj * 128 + 4 * n) = w;
;                             if (m == 0 || m == 3) { if (lr < 2 || lr > 61) { u32x2 wg; wg.x = cvt_pk_bf16(gc[0], gc[1]); wg.y = cvt_pk_bf16(gc[2], gc[3]);
;                                 *(u32x2*)(HQ + (size_t)(grp * 4 + (lr < 2 ? lr : lr - 60)) * 1024 + mc + 4 * n) = wg; } } } } } }
.LBB0_709:
	s_or_b64 exec, exec, s[2:3]
	s_mov_b64 s[2:3], 0x1010
	v_lshl_add_u64 v[18:19], v[100:101], 0, s[2:3]
	s_mov_b64 s[2:3], 0x2010
	v_lshl_add_u64 v[22:23], v[100:101], 0, s[2:3]
	s_waitcnt vmcnt(4)
	v_mov_b64_e32 v[30:31], v[196:197]
	v_mov_b64_e32 v[32:33], v[198:199]
	s_nop 0
	v_mov_b64_e32 v[18:19], v[204:205]
	v_mov_b64_e32 v[20:21], v[206:207]
	s_nop 0
	v_mov_b64_e32 v[22:23], v[222:223]
	v_mov_b64_e32 v[24:25], v[224:225]
	s_nop 0
	v_mov_b64_e32 v[26:27], v[226:227]
	v_mov_b64_e32 v[28:29], v[228:229]
	v_mov_b32_e32 v36, v1
	v_mov_b32_e32 v39, v1
	s_waitcnt vmcnt(0)
	v_mov_b32_e32 v34, v30
	v_mov_b32_dpp v36, v36 row_ror:1 row_mask:0xf bank_mask:0xf
	v_mov_b32_e32 v38, v36
	v_mov_b32_dpp v39, v10 row_ror:15 row_mask:0xf bank_mask:0xf
	v_mov_b32_e32 v35, v22
	v_mov_b32_dpp v38, v14 row_shr:1 row_mask:0xf bank_mask:0xf
	v_mov_b32_dpp v39, v14 row_shl:1 row_mask:0xf bank_mask:0xf
	v_pk_mul_f32 v[38:39], v[34:35], v[38:39]
	s_nop 0
	v_fma_f32 v22, v14, v18, v38
	v_add_f32_e32 v22, v22, v39
	v_add_f32_e32 v22, v26, v22
	v_mul_f32_e32 v30, 0xbfb8aa3b, v22
	v_exp_f32_e32 v30, v30
	s_nop 0
	v_add_f32_e32 v30, 1.0, v30
	s_nop 0
	v_rcp_f32_e32 v37, v30
	s_nop 0
	v_fma_f32 v40, -v30, v37, 1.0
	v_fma_f32 v30, v40, v37, v37
	v_mov_b32_e32 v41, v1
	v_mul_f32_e32 v22, v22, v30
	v_mov_b32_e32 v40, v36
	v_mov_b32_dpp v41, v11 row_ror:15 row_mask:0xf bank_mask:0xf
	v_mul_f32_e32 v38, v120, v22
	v_mov_b32_dpp v40, v15 row_shr:1 row_mask:0xf bank_mask:0xf
	v_mov_b32_dpp v41, v15 row_shl:1 row_mask:0xf bank_mask:0xf
	v_mov_b32_e32 v22, v31
	v_pk_mul_f32 v[30:31], v[22:23], v[40:41]
	s_nop 0
	v_fma_f32 v30, v15, v19, v30
	v_add_f32_e32 v30, v30, v31
	v_add_f32_e32 v30, v27, v30
	v_mul_f32_e32 v31, 0xbfb8aa3b, v30
	v_exp_f32_e32 v31, v31
	s_nop 0
	v_add_f32_e32 v31, 1.0, v31
	s_nop 0
	v_rcp_f32_e32 v37, v31
	s_nop 0
	v_fma_f32 v41, -v31, v37, 1.0
	v_fma_f32 v31, v41, v37, v37
	v_mov_b32_e32 v41, v1
	v_mul_f32_e32 v30, v30, v31
	v_mov_b32_e32 v40, v36
	v_mov_b32_dpp v41, v12 row_ror:15 row_mask:0xf bank_mask:0xf
	v_mul_f32_e32 v39, v120, v30
	v_mov_b32_dpp v40, v16 row_shr:1 row_mask:0xf bank_mask:0xf
	v_mov_b32_dpp v41, v16 row_shl:1 row_mask:0xf bank_mask:0xf
	v_mov_b32_e32 v30, v32
	v_mov_b32_e32 v31, v24
	v_pk_mul_f32 v[40:41], v[30:31], v[40:41]
	v_mov_b32_dpp v36, v17 row_shr:1 row_mask:0xf bank_mask:0xf
	v_fma_f32 v24, v16, v20, v40
	v_add_f32_e32 v24, v24, v41
	v_add_f32_e32 v24, v28, v24
	v_mul_f32_e32 v32, 0xbfb8aa3b, v24
	v_exp_f32_e32 v32, v32
	s_nop 0
	v_add_f32_e32 v32, 1.0, v32
	s_nop 0
	v_rcp_f32_e32 v37, v32
	s_nop 0
	v_fma_f32 v42, -v32, v37, 1.0
	v_fma_f32 v32, v42, v37, v37
	v_mov_b32_e32 v37, v1
	v_mul_f32_e32 v24, v24, v32
	v_mul_f32_e32 v40, v120, v24
	v_mov_b32_dpp v37, v13 row_ror:15 row_mask:0xf bank_mask:0xf
	v_mov_b32_e32 v24, v33
	s_nop 0
	v_mov_b32_dpp v37, v17 row_shl:1 row_mask:0xf bank_mask:0xf
	v_pk_mul_f32 v[32:33], v[24:25], v[36:37]
	s_nop 0
	v_fma_f32 v32, v17, v21, v32
	v_add_f32_e32 v32, v32, v33
	v_add_f32_e32 v32, v29, v32
	v_mul_f32_e32 v33, 0xbfb8aa3b, v32
	v_exp_f32_e32 v33, v33
	s_nop 0
	v_add_f32_e32 v33, 1.0, v33
	s_nop 0
	v_rcp_f32_e32 v36, v33
	s_nop 0
	v_fma_f32 v42, -v33, v36, 1.0
	v_fma_f32 v33, v42, v36, v36
	v_mul_f32_e32 v32, v32, v33
	v_mul_f32_e32 v33, v120, v32
	v_cvt_pk_bf16_f32 v32, v38, v39
	v_cvt_pk_bf16_f32 v33, v40, v33
	global_store_dwordx2 v[78:79], v[32:33], off offset:264
	s_and_saveexec_b64 s[2:3], s[42:43]
	s_cbranch_execz .LBB0_711
	v_cmp_gt_i32_e32 vcc, 2, v190
	v_cvt_pk_bf16_f32 v32, v14, v15
	v_cvt_pk_bf16_f32 v33, v16, v17
	s_nop 1
	v_cndmask_b32_e32 v0, v0, v190, vcc
	v_add_u32_e32 v36, s0, v0
	v_ashrrev_i32_e32 v37, 31, v36
	v_lshlrev_b64 v[36:37], 11, v[36:37]
	v_lshl_add_u64 v[36:37], s[48:49], 0, v[36:37]
	v_lshl_add_u64 v[36:37], v[158:159], 1, v[36:37]
	global_store_dwordx2 v[36:37], v[32:33], off offset:-3832
.LBB0_711:
	s_or_b64 exec, exec, s[2:3]
	v_mov_b32_e32 v32, v1
	v_mov_b32_e32 v33, v1
	s_nop 0
	v_mov_b32_dpp v32, v14 row_ror:1 row_mask:0xf bank_mask:0xf
	v_mov_b32_dpp v33, v6 row_ror:15 row_mask:0xf bank_mask:0xf
	s_nop 0
	v_mov_b32_dpp v32, v10 row_shr:1 row_mask:0xf bank_mask:0xf
	v_mov_b32_dpp v33, v10 row_shl:1 row_mask:0xf bank_mask:0xf
	v_pk_mul_f32 v[32:33], v[34:35], v[32:33]
	s_nop 0
	v_fma_f32 v0, v10, v18, v32
	v_add_f32_e32 v0, v0, v33
	v_add_f32_e32 v0, v26, v0
	v_mul_f32_e32 v14, 0xbfb8aa3b, v0
	v_exp_f32_e32 v14, v14
	s_nop 0
	v_add_f32_e32 v14, 1.0, v14
	s_nop 0
	v_rcp_f32_e32 v32, v14
	s_nop 0
	v_fma_f32 v37, -v14, v32, 1.0
	v_fma_f32 v14, v37, v32, v32
	v_mul_f32_e32 v0, v0, v14
	v_mov_b32_e32 v14, v1
	v_mul_f32_e32 v0, v120, v0
	s_nop 0
	v_mov_b32_dpp v14, v15 row_ror:1 row_mask:0xf bank_mask:0xf
	v_mov_b32_e32 v15, v1
	s_nop 0
	v_mov_b32_dpp v14, v11 row_shr:1 row_mask:0xf bank_mask:0xf
	v_mov_b32_dpp v15, v7 row_ror:15 row_mask:0xf bank_mask:0xf
	s_nop 1
	v_mov_b32_dpp v15, v11 row_shl:1 row_mask:0xf bank_mask:0xf
	v_pk_mul_f32 v[14:15], v[22:23], v[14:15]
	s_nop 0
	v_fma_f32 v14, v11, v19, v14
	v_add_f32_e32 v14, v14, v15
	v_add_f32_e32 v14, v27, v14
	v_mul_f32_e32 v15, 0xbfb8aa3b, v14
	v_exp_f32_e32 v15, v15
	s_nop 0
	v_add_f32_e32 v15, 1.0, v15
	s_nop 0
	v_rcp_f32_e32 v32, v15
	s_nop 0
	v_fma_f32 v37, -v15, v32, 1.0
	v_fma_f32 v15, v37, v32, v32
	v_mul_f32_e32 v14, v14, v15
	v_mul_f32_e32 v32, v120, v14
	v_mov_b32_e32 v14, v1
	v_mov_b32_e32 v15, v1
	s_nop 0
	v_mov_b32_dpp v14, v16 row_ror:1 row_mask:0xf bank_mask:0xf
	v_mov_b32_dpp v15, v8 row_ror:15 row_mask:0xf bank_mask:0xf
	s_nop 0
	v_mov_b32_dpp v14, v12 row_shr:1 row_mask:0xf bank_mask:0xf
	v_mov_b32_dpp v15, v12 row_shl:1 row_mask:0xf bank_mask:0xf
	v_pk_mul_f32 v[14:15], v[30:31], v[14:15]
; __device__ __forceinline__ unsigned cvt_pk_bf16(float lo, float hi) { unsigned r; asm volatile("v_cvt_pk_bf16_f32 %0, %1, %2" : "=v"(r) : "v"(lo), "v"(hi)); return r; }
; __device__ __forceinline__ float sigmoidf_(float x) { return 1.0f / (1.0f + __expf(-x)); }
; __device__ __forceinline__ float dppf_prev(float cur, float below) { return __uint_as_float(dpp_prev(__float_as_uint(cur), __float_as_uint(below))); }
; __device__ __forceinline__ float dppf_next(float cur, float above) { return __uint_as_float(dpp_next(__float_as_uint(cur), __float_as_uint(above))); }
;     __device__ __forceinline__ void operator()(AccT& acc, const Unit& u, int wr, int wc, int fr, int fq) const {
;     ...
;                         for (int m = 0; m < 4; ++m) { const int lr = m * 16 + fr; const f32x4 gc = acc[ai][bj][m][n]; f32x4 o;
; #pragma unroll
;                             for (int j = 0; j < 4; ++j) { const float gp = dppf_prev(gc[j], m > 0 ? acc[ai][bj][m - 1][n][j] : 0.f), gn = dppf_next(gc[j], m < 3 ? acc[ai][bj][m + 1][n][j] : 0.f);
;                                 const float uu = gp * w0[j] + gc[j] * w1[j] + gn * w2[j] + b[j]; o[j] = uu * sigmoidf_(uu) * mul; }
;                             u32x2 w; w.x = cvt_pk_bf16(o[0], o[1]); w.y = cvt_pk_bf16(o[2], o[3]);
;                             *(u32x2*)(O + (size_t)(grp * 64 + lr) * NPROJ + col0 + bj * 128 + 4 * n) = w;
	s_nop 0
	v_fma_f32 v14, v12, v20, v14
	v_add_f32_e32 v14, v14, v15
	v_add_f32_e32 v14, v28, v14
	v_mul_f32_e32 v15, 0xbfb8aa3b, v14
	v_exp_f32_e32 v15, v15
	s_nop 0
	v_add_f32_e32 v15, 1.0, v15
	s_nop 0
	v_rcp_f32_e32 v16, v15
	s_nop 0
	v_fma_f32 v37, -v15, v16, 1.0
	v_fma_f32 v15, v37, v16, v16
	v_mul_f32_e32 v14, v14, v15
	v_mul_f32_e32 v16, v120, v14
	v_mov_b32_e32 v14, v1
	v_mov_b32_e32 v15, v1
	s_nop 0
	v_mov_b32_dpp v14, v17 row_ror:1 row_mask:0xf bank_mask:0xf
	v_mov_b32_dpp v15, v9 row_ror:15 row_mask:0xf bank_mask:0xf
	s_nop 0
	v_mov_b32_dpp v14, v13 row_shr:1 row_mask:0xf bank_mask:0xf
	v_mov_b32_dpp v15, v13 row_shl:1 row_mask:0xf bank_mask:0xf
	v_pk_mul_f32 v[14:15], v[24:25], v[14:15]
	s_nop 0
	v_fma_f32 v14, v13, v21, v14
	v_add_f32_e32 v14, v14, v15
	v_add_f32_e32 v14, v29, v14
	v_mul_f32_e32 v15, 0xbfb8aa3b, v14
	v_exp_f32_e32 v15, v15
	s_nop 0
	v_add_f32_e32 v15, 1.0, v15
	s_nop 0
	v_rcp_f32_e32 v17, v15
	s_nop 0
	v_fma_f32 v37, -v15, v17, 1.0
	v_fma_f32 v15, v37, v17, v17
	v_mul_f32_e32 v14, v14, v15
	v_mul_f32_e32 v15, v120, v14
	v_cvt_pk_bf16_f32 v14, v0, v32
	v_cvt_pk_bf16_f32 v15, v16, v15
	global_store_dwordx2 v[80:81], v[14:15], off offset:264
	v_mov_b32_e32 v14, v1
	v_mov_b32_e32 v15, v1
	s_nop 0
	v_mov_b32_dpp v14, v10 row_ror:1 row_mask:0xf bank_mask:0xf
	v_mov_b32_dpp v15, v2 row_ror:15 row_mask:0xf bank_mask:0xf
	s_nop 0
	v_mov_b32_dpp v14, v6 row_shr:1 row_mask:0xf bank_mask:0xf
	v_mov_b32_dpp v15, v6 row_shl:1 row_mask:0xf bank_mask:0xf
	v_pk_mul_f32 v[14:15], v[34:35], v[14:15]
	s_nop 0
	v_fma_f32 v0, v6, v18, v14
	v_add_f32_e32 v0, v0, v15
	v_add_f32_e32 v0, v26, v0
	v_mul_f32_e32 v10, 0xbfb8aa3b, v0
	v_exp_f32_e32 v10, v10
	s_nop 0
	v_add_f32_e32 v10, 1.0, v10
	s_nop 0
	v_rcp_f32_e32 v14, v10
	s_nop 0
	v_fma_f32 v17, -v10, v14, 1.0
	v_fma_f32 v10, v17, v14, v14
	v_mul_f32_e32 v0, v0, v10
	v_mov_b32_e32 v10, v1
	v_mul_f32_e32 v0, v120, v0
	s_nop 0
	v_mov_b32_dpp v10, v11 row_ror:1 row_mask:0xf bank_mask:0xf
	v_mov_b32_e32 v11, v1
	s_nop 0
	v_mov_b32_dpp v10, v7 row_shr:1 row_mask:0xf bank_mask:0xf
	v_mov_b32_dpp v11, v3 row_ror:15 row_mask:0xf bank_mask:0xf
	s_nop 1
	v_mov_b32_dpp v11, v7 row_shl:1 row_mask:0xf bank_mask:0xf
	v_pk_mul_f32 v[10:11], v[22:23], v[10:11]
	s_nop 0
	v_fma_f32 v10, v7, v19, v10
	v_add_f32_e32 v10, v10, v11
	v_add_f32_e32 v10, v27, v10
	v_mul_f32_e32 v11, 0xbfb8aa3b, v10
	v_exp_f32_e32 v11, v11
	s_nop 0
	v_add_f32_e32 v11, 1.0, v11
	s_nop 0
	v_rcp_f32_e32 v14, v11
	s_nop 0
	v_fma_f32 v17, -v11, v14, 1.0
	v_fma_f32 v11, v17, v14, v14
	v_mul_f32_e32 v10, v10, v11
	v_mul_f32_e32 v14, v120, v10
	v_mov_b32_e32 v10, v1
	v_mov_b32_e32 v11, v1
	s_nop 0
	v_mov_b32_dpp v10, v12 row_ror:1 row_mask:0xf bank_mask:0xf
	v_mov_b32_dpp v11, v4 row_ror:15 row_mask:0xf bank_mask:0xf
	s_nop 0
	v_mov_b32_dpp v10, v8 row_shr:1 row_mask:0xf bank_mask:0xf
	v_mov_b32_dpp v11, v8 row_shl:1 row_mask:0xf bank_mask:0xf
	v_pk_mul_f32 v[10:11], v[30:31], v[10:11]
	s_nop 0
	v_fma_f32 v10, v8, v20, v10
	v_add_f32_e32 v10, v10, v11
	v_add_f32_e32 v10, v28, v10
	v_mul_f32_e32 v11, 0xbfb8aa3b, v10
	v_exp_f32_e32 v11, v11
	s_nop 0
	v_add_f32_e32 v11, 1.0, v11
	s_nop 0
	v_rcp_f32_e32 v12, v11
	s_nop 0
	v_fma_f32 v17, -v11, v12, 1.0
	v_fma_f32 v11, v17, v12, v12
	v_mul_f32_e32 v10, v10, v11
	v_mul_f32_e32 v12, v120, v10
	v_mov_b32_e32 v10, v1
	v_mov_b32_e32 v11, v1
	s_nop 0
	v_mov_b32_dpp v10, v13 row_ror:1 row_mask:0xf bank_mask:0xf
	v_mov_b32_dpp v11, v5 row_ror:15 row_mask:0xf bank_mask:0xf
	s_nop 0
	v_mov_b32_dpp v10, v9 row_shr:1 row_mask:0xf bank_mask:0xf
	v_mov_b32_dpp v11, v9 row_shl:1 row_mask:0xf bank_mask:0xf
	v_pk_mul_f32 v[10:11], v[24:25], v[10:11]
	s_nop 0
	v_fma_f32 v10, v9, v21, v10
	v_add_f32_e32 v10, v10, v11
	v_add_f32_e32 v10, v29, v10
	v_mul_f32_e32 v11, 0xbfb8aa3b, v10
	v_exp_f32_e32 v11, v11
	s_nop 0
	v_add_f32_e32 v11, 1.0, v11
	s_nop 0
	v_rcp_f32_e32 v13, v11
	s_nop 0
	v_fma_f32 v17, -v11, v13, 1.0
	v_fma_f32 v11, v17, v13, v13
	v_mul_f32_e32 v10, v10, v11
	v_mul_f32_e32 v11, v120, v10
	v_cvt_pk_bf16_f32 v10, v0, v14
	v_mov_b32_e32 v13, v1
	v_cvt_pk_bf16_f32 v11, v12, v11
	global_store_dwordx2 v[82:83], v[10:11], off offset:264
	v_mov_b32_e32 v10, v1
	v_mov_b32_dpp v13, v13 row_ror:15 row_mask:0xf bank_mask:0xf
	v_mov_b32_e32 v11, v13
	v_mov_b32_dpp v10, v6 row_ror:1 row_mask:0xf bank_mask:0xf
	s_nop 0
	v_mov_b32_dpp v11, v2 row_shl:1 row_mask:0xf bank_mask:0xf
	v_mov_b32_dpp v10, v2 row_shr:1 row_mask:0xf bank_mask:0xf
	v_pk_mul_f32 v[10:11], v[34:35], v[10:11]
	s_nop 0
	v_fma_f32 v0, v2, v18, v10
	v_add_f32_e32 v0, v0, v11
	v_add_f32_e32 v0, v26, v0
	v_mul_f32_e32 v6, 0xbfb8aa3b, v0
	v_exp_f32_e32 v6, v6
	s_nop 0
	v_add_f32_e32 v6, 1.0, v6
	s_nop 0
	v_rcp_f32_e32 v10, v6
	s_nop 0
	v_fma_f32 v14, -v6, v10, 1.0
	v_fma_f32 v6, v14, v10, v10
	v_mul_f32_e32 v0, v0, v6
	v_mov_b32_e32 v6, v1
	v_mul_f32_e32 v0, v120, v0
	s_nop 0
	v_mov_b32_dpp v6, v7 row_ror:1 row_mask:0xf bank_mask:0xf
	v_mov_b32_e32 v7, v13
	s_nop 0
	v_mov_b32_dpp v6, v3 row_shr:1 row_mask:0xf bank_mask:0xf
	v_mov_b32_dpp v7, v3 row_shl:1 row_mask:0xf bank_mask:0xf
	v_pk_mul_f32 v[6:7], v[22:23], v[6:7]
	s_nop 0
	v_fma_f32 v6, v3, v19, v6
	v_add_f32_e32 v6, v6, v7
	v_add_f32_e32 v6, v27, v6
	v_mul_f32_e32 v7, 0xbfb8aa3b, v6
	v_exp_f32_e32 v7, v7
	s_nop 0
	v_add_f32_e32 v7, 1.0, v7
	s_nop 0
	v_rcp_f32_e32 v10, v7
	s_nop 0
	v_fma_f32 v14, -v7, v10, 1.0
	v_fma_f32 v7, v14, v10, v10
	v_mul_f32_e32 v6, v6, v7
	v_mul_f32_e32 v10, v120, v6
	v_mov_b32_e32 v6, v1
	v_mov_b32_e32 v7, v13
	v_mov_b32_dpp v13, v5 row_shl:1 row_mask:0xf bank_mask:0xf
	v_mov_b32_dpp v6, v8 row_ror:1 row_mask:0xf bank_mask:0xf
	v_mov_b32_dpp v7, v4 row_shl:1 row_mask:0xf bank_mask:0xf
	s_nop 0
	v_mov_b32_dpp v6, v4 row_shr:1 row_mask:0xf bank_mask:0xf
	v_pk_mul_f32 v[6:7], v[30:31], v[6:7]
	s_nop 0
	v_fma_f32 v6, v4, v20, v6
	v_add_f32_e32 v6, v6, v7
	v_add_f32_e32 v6, v28, v6
	v_mul_f32_e32 v7, 0xbfb8aa3b, v6
	v_exp_f32_e32 v7, v7
	s_nop 0
	v_add_f32_e32 v7, 1.0, v7
	s_nop 0
	v_mov_b32_e32 v12, v1
	v_rcp_f32_e32 v8, v7
	s_nop 0
	v_fma_f32 v14, -v7, v8, 1.0
	v_fma_f32 v7, v14, v8, v8
	v_mul_f32_e32 v6, v6, v7
	v_mov_b32_dpp v12, v9 row_ror:1 row_mask:0xf bank_mask:0xf
	v_mul_f32_e32 v8, v120, v6
	s_nop 0
	v_mov_b32_dpp v12, v5 row_shr:1 row_mask:0xf bank_mask:0xf
	v_pk_mul_f32 v[6:7], v[24:25], v[12:13]
	s_nop 0
	v_fma_f32 v6, v5, v21, v6
	v_add_f32_e32 v6, v6, v7
	v_add_f32_e32 v6, v29, v6
	v_mul_f32_e32 v7, 0xbfb8aa3b, v6
	v_exp_f32_e32 v7, v7
	s_nop 0
	v_add_f32_e32 v7, 1.0, v7
	s_nop 0
	v_rcp_f32_e32 v9, v7
	s_nop 0
	v_fma_f32 v13, -v7, v9, 1.0
	v_fma_f32 v7, v13, v9, v9
	v_mul_f32_e32 v6, v6, v7
	v_mul_f32_e32 v7, v120, v6
	v_cvt_pk_bf16_f32 v6, v0, v10
	v_cvt_pk_bf16_f32 v7, v8, v7
	global_store_dwordx2 v[66:67], v[6:7], off offset:264
	s_and_saveexec_b64 s[2:3], s[44:45]
	s_cbranch_execz .LBB0_599
; __device__ __forceinline__ unsigned cvt_pk_bf16(float lo, float hi) { unsigned r; asm volatile("v_cvt_pk_bf16_f32 %0, %1, %2" : "=v"(r) : "v"(lo), "v"(hi)); return r; }
;     __device__ __forceinline__ void operator()(AccT& acc, const Unit& u, int wr, int wc, int fr, int fq) const {
;     ...
;                             if (m == 0 || m == 3) { if (lr < 2 || lr > 61) { u32x2 wg; wg.x = cvt_pk_bf16(gc[0], gc[1]); wg.y = cvt_pk_bf16(gc[2], gc[3]);
;                                 *(u32x2*)(HQ + (size_t)(grp * 4 + (lr < 2 ? lr : lr - 60)) * 1024 + mc + 4 * n) = wg; } } } } } }
	s_movk_i32 s4, 0xffd2
	v_cmp_gt_i32_e32 vcc, s4, v190
	v_cvt_pk_bf16_f32 v2, v2, v3
	v_cvt_pk_bf16_f32 v3, v4, v5
	s_nop 1
	v_cndmask_b32_e32 v0, v137, v136, vcc
	v_add_u32_e32 v4, s0, v0
	v_ashrrev_i32_e32 v5, 31, v4
	v_lshlrev_b64 v[4:5], 11, v[4:5]
	v_lshl_add_u64 v[4:5], s[48:49], 0, v[4:5]
	v_lshl_add_u64 v[4:5], v[158:159], 1, v[4:5]
	global_store_dwordx2 v[4:5], v[2:3], off offset:-3832
	s_branch .LBB0_599

; #define NTL(p) __builtin_nontemporal_load((const f32x4*)(p))
; #define NTS(v, p) __builtin_nontemporal_store((v), (f32x4*)(p))
; __device__ __forceinline__ float bf_lo(unsigned w) { return __uint_as_float(w << 16); }
; __device__ __forceinline__ float bf_hi(unsigned w) { return __uint_as_float(w & 0xffff0000u); }
;     __device__ __forceinline__ void operator()(AccT& acc, const Unit& u, int wr, int wc, int fr, int fq) const {
;     ...
;         const bf16_t* ppbase = (u.L < 256 ? T0 : T1) + (size_t)(u.L & 255) * 65536 + (wr * 64 + fr) * 256 + wc * 32 + 8 * fq;
;         { const float* hr = H + (size_t)row0 * DM + col0; const bf16_t* pp = ppbase;
;           hv[0][0] = NTL(hr); hv[0][1] = NTL(hr + 4); hv[0][2] = NTL(hr + 128); hv[0][3] = NTL(hr + 132);
;           pv[0][0] = *(const u32x4*)pp; pv[0][1] = *(const u32x4*)(pp + 128); rs[0] = rss2[row0]; }
; #pragma unroll
;         for (int r = 0; r < 8; ++r) { const int ai = r >> 2, m = r & 3; const int row = row0 + ai * 128 + m * 16;
;             if (r < 7) { const int rn = row0 + ((r + 1) >> 2) * 128 + ((r + 1) & 3) * 16; const float* hn = H + (size_t)rn * DM + col0; const bf16_t* pn = ppbase + (((r + 1) >> 2) * 128 + ((r + 1) & 3) * 16) * 256;
;                 hv[(r + 1) & 1][0] = NTL(hn); hv[(r + 1) & 1][1] = NTL(hn + 4); hv[(r + 1) & 1][2] = NTL(hn + 128); hv[(r + 1) & 1][3] = NTL(hn + 132);
;                 pv[(r + 1) & 1][0] = *(const u32x4*)pn; pv[(r + 1) & 1][1] = *(const u32x4*)(pn + 128); rs[(r + 1) & 1] = rss2[rn]; }
;             float* hp = H + (size_t)row * DM + col0; float ss = 0.f; const float rstd = rsqrtf(rs[r & 1] * (1.0f / DM) + 1e-6f);
; #pragma unroll
;             for (int bj = 0; bj < 2; ++bj) { const u32x4 pw = pv[r & 1][bj];
;                 const f32x4 b0 = *(const f32x4*)(bias + col0 + bj * 128), b1 = *(const f32x4*)(bias + col0 + bj * 128 + 4);
;                 const f32x4 p0 = (f32x4){bf_lo(pw.x), bf_hi(pw.x), bf_lo(pw.y), bf_hi(pw.y)}, p1 = (f32x4){bf_lo(pw.z), bf_hi(pw.z), bf_lo(pw.w), bf_hi(pw.w)};
;                 f32x4 g0 = acc[ai][bj][m][0] * rstd + b0, g1 = acc[ai][bj][m][1] * rstd + b1;
; #pragma unroll
;                 for (int j = 0; j < 4; ++j) { g0[j] = sigmoidf_(g0[j]); g1[j] = sigmoidf_(g1[j]); }
;                 const f32x4 v0 = hv[r & 1][2 * bj] + p0 * g0, v1 = hv[r & 1][2 * bj + 1] + p1 * g1;
;                 NTS(v0, hp + bj * 128); NTS(v1, hp + bj * 128 + 4);
.LBB0_781:
	v_mov_b32_e32 v130, v169
	v_mov_b32_e32 v145, v222
	v_add_u32_e32 v131, s79, v130
	v_lshl_add_u32 v186, s0, 8, v131
	s_lshl_b32 s0, s24, 8
	v_ashrrev_i32_e32 v187, 31, v186
	s_or_b32 s0, s0, s80
	v_lshl_add_u64 v[188:189], v[186:187], 2, s[34:35]
	s_cmpk_lt_i32 s26, 0x100
	global_load_dword v144, v[188:189], off
	s_cselect_b32 s3, s50, s53
	s_cselect_b32 s2, s51, s52
	s_lshl_b32 s4, s26, 17
	s_and_b32 s4, s4, 0x1fe0000
	s_add_u32 s2, s2, s4
	v_lshlrev_b32_e32 v132, 8, v131
	v_lshlrev_b32_e32 v130, 3, v145
	s_addc_u32 s3, s3, 0
	v_ashrrev_i32_e32 v133, 31, v132
	v_lshl_add_u64 v[132:133], v[132:133], 1, s[2:3]
	v_add_u32_e32 v192, s0, v130
	v_lshl_add_u64 v[132:133], v[132:133], 0, s[38:39]
	v_ashrrev_i32_e32 v131, 31, v130
	v_ashrrev_i32_e32 v193, 31, v192
	v_readlane_b32 s60, v255, 2
	v_lshl_add_u64 v[190:191], v[130:131], 1, v[132:133]
	v_lshlrev_b64 v[130:131], 2, v[192:193]
	v_readlane_b32 s72, v255, 14
	v_readlane_b32 s73, v255, 15
	global_load_dwordx4 v[138:141], v[190:191], off
	v_lshlrev_b64 v[132:133], 12, v[186:187]
	v_lshl_add_u64 v[184:185], s[72:73], 0, v[130:131]
	global_load_dwordx4 v[240:243], v[184:185], off
	global_load_dwordx4 v[244:247], v[184:185], off offset:16
	global_load_dwordx4 v[248:251], v[184:185], off offset:512
	global_load_dwordx4 v[232:235], v[184:185], off offset:528
	v_add_u32_e32 v198, 16, v186
	v_lshl_add_u64 v[132:133], s[22:23], 0, v[132:133]
	v_ashrrev_i32_e32 v199, 31, v198
	v_lshl_add_u64 v[142:143], v[132:133], 0, v[130:131]
	v_add_co_u32_e32 v132, vcc, s85, v190
	v_lshl_add_u64 v[134:135], v[198:199], 2, s[34:35]
	s_nop 0
	v_addc_co_u32_e32 v133, vcc, 0, v191, vcc
	global_load_dword v165, v[134:135], off
	global_load_dwordx4 v[170:173], v[142:143], off offset:16 nt
	global_load_dwordx4 v[194:197], v[142:143], off nt
	s_nop 0
	global_load_dwordx4 v[134:137], v[190:191], off offset:256
	global_load_dwordx4 v[158:161], v[132:133], off
	global_load_dwordx4 v[146:149], v[132:133], off offset:256
	v_readlane_b32 s61, v255, 3
	v_readlane_b32 s62, v255, 4
	v_readlane_b32 s63, v255, 5
	v_readlane_b32 s64, v255, 6
	v_readlane_b32 s65, v255, 7
	v_readlane_b32 s66, v255, 8
	v_readlane_b32 s67, v255, 9
	v_readlane_b32 s68, v255, 10
	v_readlane_b32 s69, v255, 11
	v_readlane_b32 s70, v255, 12
	v_readlane_b32 s71, v255, 13
	v_readlane_b32 s74, v255, 16
	v_readlane_b32 s75, v255, 17
	s_waitcnt vmcnt(11)
	v_fmamk_f32 v132, v144, 0x3a800000, v210
	v_mul_f32_e32 v133, 0x4b800000, v132
	v_cmp_gt_f32_e32 vcc, s30, v132
	s_waitcnt vmcnt(10)
	v_lshlrev_b32_e32 v166, 16, v140
	s_nop 0
	v_cndmask_b32_e32 v132, v132, v133, vcc
	v_rsq_f32_e32 v144, v132
	v_lshlrev_b32_e32 v132, 16, v138
	v_and_b32_e32 v133, 0xffff0000, v138
	v_lshlrev_b32_e32 v138, 16, v139
	v_mul_f32_e32 v164, 0x45800000, v144
	v_cndmask_b32_e32 v144, v144, v164, vcc
	s_waitcnt vmcnt(9)
	v_pk_fma_f32 v[124:125], v[124:125], v[144:145], v[242:243] op_sel_hi:[1,0,1]
	v_pk_fma_f32 v[122:123], v[122:123], v[144:145], v[240:241] op_sel_hi:[1,0,1]
	s_waitcnt vmcnt(8)
	v_pk_fma_f32 v[114:115], v[114:115], v[144:145], v[244:245] op_sel_hi:[1,0,1]
	v_mul_f32_e32 v122, 0xbfb8aa3b, v122
	v_mul_f32_e32 v123, 0xbfb8aa3b, v123
	v_mul_f32_e32 v151, 0xbfb8aa3b, v115
	v_mul_f32_e32 v115, 0xbfb8aa3b, v124
	v_mul_f32_e32 v150, 0xbfb8aa3b, v114
	v_exp_f32_e32 v114, v122
	v_exp_f32_e32 v124, v115
	v_exp_f32_e32 v115, v123
	v_mul_f32_e32 v125, 0xbfb8aa3b, v125
	v_exp_f32_e32 v125, v125
	v_exp_f32_e32 v122, v150
	v_pk_add_f32 v[114:115], v[114:115], 1.0 op_sel_hi:[1,0]
	v_pk_fma_f32 v[116:117], v[116:117], v[144:145], v[246:247] op_sel_hi:[1,0,1]
	v_pk_add_f32 v[124:125], v[124:125], 1.0 op_sel_hi:[1,0]
	v_div_scale_f32 v152, s[2:3], v114, v114, 1.0
	v_rcp_f32_e32 v155, v152
	v_exp_f32_e32 v123, v151
	v_fma_f32 v200, -v152, v155, 1.0
	v_div_scale_f32 v157, s[42:43], 1.0, v114, 1.0
	v_fmac_f32_e32 v155, v200, v155
	v_mul_f32_e32 v200, v157, v155
	v_fma_f32 v202, -v152, v200, v157
	v_fmac_f32_e32 v200, v202, v155
	v_fma_f32 v151, -v152, v200, v157
	s_mov_b64 vcc, s[42:43]
	v_rcp_f32_e32 v150, v115
	s_nop 0
	v_fma_f32 v164, -v115, v150, 1.0
	v_fma_f32 v115, v164, v150, v150
	v_div_fmas_f32 v150, v151, v155, v200
	v_div_fixup_f32 v114, v150, v114, 1.0
	v_rcp_f32_e32 v156, v125
	s_nop 0
	v_fma_f32 v201, -v125, v156, 1.0
	v_fma_f32 v125, v201, v156, v156
	v_pk_add_f32 v[122:123], v[122:123], 1.0 op_sel_hi:[1,0]
	v_rcp_f32_e32 v151, v124
	s_nop 0
	v_fma_f32 v153, -v124, v151, 1.0
	v_fma_f32 v124, v153, v151, v151
	v_mul_f32_e32 v116, 0xbfb8aa3b, v116
	v_mul_f32_e32 v117, 0xbfb8aa3b, v117
	v_exp_f32_e32 v116, v116
	v_exp_f32_e32 v117, v117
	v_rcp_f32_e32 v151, v123
	s_nop 0
	v_fma_f32 v154, -v123, v151, 1.0
	v_fma_f32 v123, v154, v151, v151
	v_pk_add_f32 v[116:117], v[116:117], 1.0 op_sel_hi:[1,0]
	v_rcp_f32_e32 v151, v122
	s_nop 0
	v_fma_f32 v153, -v122, v151, 1.0
	v_fma_f32 v122, v153, v151, v151
	v_and_b32_e32 v139, 0xffff0000, v139
	v_rcp_f32_e32 v154, v117
	s_nop 0
	v_fma_f32 v151, -v117, v154, 1.0
	v_fma_f32 v151, v151, v154, v154
	v_and_b32_e32 v167, 0xffff0000, v140
	v_lshlrev_b32_e32 v140, 16, v141
	v_and_b32_e32 v141, 0xffff0000, v141
	v_rcp_f32_e32 v154, v116
	s_nop 0
	v_fma_f32 v153, -v116, v154, 1.0
	v_fma_f32 v150, v153, v154, v154
	s_waitcnt vmcnt(3)
; #define NTL(p) __builtin_nontemporal_load((const f32x4*)(p))
; #define NTS(v, p) __builtin_nontemporal_store((v), (f32x4*)(p))
; __device__ __forceinline__ float bf_lo(unsigned w) { return __uint_as_float(w << 16); }
; __device__ __forceinline__ float bf_hi(unsigned w) { return __uint_as_float(w & 0xffff0000u); }
; __device__ __forceinline__ float sigmoidf_(float x) { return 1.0f / (1.0f + __expf(-x)); }
;     __device__ __forceinline__ void operator()(AccT& acc, const Unit& u, int wr, int wc, int fr, int fq) const {
;     ...
;             if (r < 7) { const int rn = row0 + ((r + 1) >> 2) * 128 + ((r + 1) & 3) * 16; const float* hn = H + (size_t)rn * DM + col0; const bf16_t* pn = ppbase + (((r + 1) >> 2) * 128 + ((r + 1) & 3) * 16) * 256;
;                 hv[(r + 1) & 1][0] = NTL(hn); hv[(r + 1) & 1][1] = NTL(hn + 4); hv[(r + 1) & 1][2] = NTL(hn + 128); hv[(r + 1) & 1][3] = NTL(hn + 132);
;                 pv[(r + 1) & 1][0] = *(const u32x4*)pn; pv[(r + 1) & 1][1] = *(const u32x4*)(pn + 128); rs[(r + 1) & 1] = rss2[rn]; }
;             float* hp = H + (size_t)row * DM + col0; float ss = 0.f; const float rstd = rsqrtf(rs[r & 1] * (1.0f / DM) + 1e-6f);
; #pragma unroll
;             for (int bj = 0; bj < 2; ++bj) { const u32x4 pw = pv[r & 1][bj];
;                 const f32x4 b0 = *(const f32x4*)(bias + col0 + bj * 128), b1 = *(const f32x4*)(bias + col0 + bj * 128 + 4);
;                 const f32x4 p0 = (f32x4){bf_lo(pw.x), bf_hi(pw.x), bf_lo(pw.y), bf_hi(pw.y)}, p1 = (f32x4){bf_lo(pw.z), bf_hi(pw.z), bf_lo(pw.w), bf_hi(pw.w)};
;                 f32x4 g0 = acc[ai][bj][m][0] * rstd + b0, g1 = acc[ai][bj][m][1] * rstd + b1;
; #pragma unroll
;                 for (int j = 0; j < 4; ++j) { g0[j] = sigmoidf_(g0[j]); g1[j] = sigmoidf_(g1[j]); }
;                 const f32x4 v0 = hv[r & 1][2 * bj] + p0 * g0, v1 = hv[r & 1][2 * bj + 1] + p1 * g1;
;                 NTS(v0, hp + bj * 128); NTS(v1, hp + bj * 128 + 4);
; #pragma unroll
;                 for (int j = 0; j < 4; ++j) ss += v0[j] * v0[j] + v1[j] * v1[j]; }
;             ss += __shfl_xor(ss, 16); ss += __shfl_xor(ss, 32);
;             if (fq == 0) unsafeAtomicAdd(rss3 + row, ss); __builtin_amdgcn_sched_barrier(0); }
	v_pk_fma_f32 v[116:117], v[124:125], v[138:139], v[196:197]
	v_pk_fma_f32 v[114:115], v[114:115], v[132:133], v[194:195]
	v_pk_fma_f32 v[124:125], v[150:151], v[140:141], v[172:173]
	v_pk_fma_f32 v[122:123], v[122:123], v[166:167], v[170:171]
	global_store_dwordx4 v[142:143], v[114:117], off nt
	global_store_dwordx4 v[142:143], v[122:125], off offset:16 nt
	s_nop 0
	s_nop 0
	global_load_dwordx4 v[204:207], v[142:143], off offset:528 nt
	global_load_dwordx4 v[226:229], v[142:143], off offset:512 nt
	v_mul_f32_e32 v122, v122, v122
	v_fmac_f32_e32 v122, v114, v114
	v_mul_f32_e32 v114, v123, v123
	v_fmac_f32_e32 v114, v115, v115
	v_mul_f32_e32 v115, v124, v124
	v_add_f32_e32 v114, v122, v114
	v_fmac_f32_e32 v115, v116, v116
	v_add_f32_e32 v114, v115, v114
	v_mul_f32_e32 v115, v125, v125
	v_fmac_f32_e32 v115, v117, v117
	v_add_f32_e32 v166, v115, v114
	s_waitcnt vmcnt(6)
	v_lshlrev_b32_e32 v114, 16, v134
	v_and_b32_e32 v115, 0xffff0000, v134
	v_lshlrev_b32_e32 v116, 16, v135
	v_and_b32_e32 v117, 0xffff0000, v135
	v_and_b32_e32 v133, 64, v203
	v_xor_b32_e32 v132, 16, v203
	v_add_u32_e32 v164, 64, v133
	v_cmp_lt_i32_e32 vcc, v132, v164
	v_lshlrev_b32_e32 v122, 16, v136
	v_and_b32_e32 v123, 0xffff0000, v136
	v_cndmask_b32_e32 v132, v203, v132, vcc
	v_lshlrev_b32_e32 v124, 16, v137
	v_and_b32_e32 v125, 0xffff0000, v137
	v_lshlrev_b32_e32 v225, 2, v132
	v_lshlrev_b64 v[132:133], 12, v[198:199]
	v_lshl_add_u64 v[132:133], s[22:23], 0, v[132:133]
	v_lshl_add_u64 v[200:201], v[132:133], 0, v[130:131]
	global_load_dwordx4 v[150:153], v[200:201], off offset:16 nt
	global_load_dwordx4 v[154:157], v[200:201], off nt
	global_load_dwordx4 v[130:133], v[200:201], off offset:528 nt
	global_load_dwordx4 v[138:141], v[200:201], off offset:512 nt
	v_cmp_eq_u32_e64 s[42:43], 0, v145
	v_pk_fma_f32 v[110:111], v[110:111], v[144:145], v[248:249] op_sel_hi:[1,0,1]
	s_nop 0
	v_mul_f32_e32 v110, 0xbfb8aa3b, v110
	v_mul_f32_e32 v111, 0xbfb8aa3b, v111
	v_exp_f32_e32 v110, v110
	v_exp_f32_e32 v111, v111
	v_pk_fma_f32 v[112:113], v[112:113], v[144:145], v[250:251] op_sel_hi:[1,0,1]
	v_pk_fma_f32 v[108:109], v[108:109], v[144:145], v[234:235] op_sel_hi:[1,0,1]
	v_pk_fma_f32 v[106:107], v[106:107], v[144:145], v[232:233] op_sel_hi:[1,0,1]
	v_pk_add_f32 v[110:111], v[110:111], 1.0 op_sel_hi:[1,0]
	v_mul_f32_e32 v112, 0xbfb8aa3b, v112
	v_mul_f32_e32 v113, 0xbfb8aa3b, v113
	v_exp_f32_e32 v112, v112
	v_exp_f32_e32 v113, v113
	v_div_scale_f32 v136, s[2:3], v110, v110, 1.0
	v_rcp_f32_e32 v144, v136
	v_rcp_f32_e32 v134, v111
	s_nop 0
	v_fma_f32 v137, -v111, v134, 1.0
	v_fma_f32 v135, v137, v134, v134
	v_pk_add_f32 v[112:113], v[112:113], 1.0 op_sel_hi:[1,0]
	v_fma_f32 v111, -v136, v144, 1.0
	v_fmac_f32_e32 v144, v111, v144
	v_div_scale_f32 v111, vcc, 1.0, v110, 1.0
	v_mul_f32_e32 v134, v111, v144
	v_fma_f32 v137, -v136, v134, v111
	v_fmac_f32_e32 v134, v137, v144
	v_fma_f32 v111, -v136, v134, v111
	v_div_scale_f32 v136, s[2:3], v113, v113, 1.0
	v_rcp_f32_e32 v137, v136
	v_div_fmas_f32 v111, v111, v144, v134
	v_div_fixup_f32 v134, v111, v110, 1.0
	v_mul_f32_e32 v106, 0xbfb8aa3b, v106
	v_fma_f32 v110, -v136, v137, 1.0
	v_fmac_f32_e32 v137, v110, v137
	v_div_scale_f32 v110, vcc, 1.0, v113, 1.0
	v_mul_f32_e32 v111, v110, v137
	v_fma_f32 v144, -v136, v111, v110
	v_fmac_f32_e32 v111, v144, v137
	v_fma_f32 v110, -v136, v111, v110
	v_div_scale_f32 v136, s[2:3], v112, v112, 1.0
	v_rcp_f32_e32 v144, v136
	v_mul_f32_e32 v107, 0xbfb8aa3b, v107
	v_div_fmas_f32 v110, v110, v137, v111
	v_exp_f32_e32 v106, v106
	v_exp_f32_e32 v107, v107
	v_div_fixup_f32 v111, v110, v113, 1.0
	v_fma_f32 v110, -v136, v144, 1.0
	v_fmac_f32_e32 v144, v110, v144
	v_div_scale_f32 v110, vcc, 1.0, v112, 1.0
	v_mul_f32_e32 v113, v110, v144
	v_fma_f32 v137, -v136, v113, v110
	v_fmac_f32_e32 v113, v137, v144
	v_pk_add_f32 v[106:107], v[106:107], 1.0 op_sel_hi:[1,0]
	v_fma_f32 v110, -v136, v113, v110
	v_div_scale_f32 v136, s[2:3], v107, v107, 1.0
	v_rcp_f32_e32 v137, v136
	v_div_fmas_f32 v110, v110, v144, v113
	v_div_fixup_f32 v110, v110, v112, 1.0
	v_mul_f32_e32 v108, 0xbfb8aa3b, v108
	v_fma_f32 v112, -v136, v137, 1.0
	v_fmac_f32_e32 v137, v112, v137
	v_div_scale_f32 v112, vcc, 1.0, v107, 1.0
	v_mul_f32_e32 v113, v112, v137
	v_fma_f32 v144, -v136, v113, v112
	v_fmac_f32_e32 v113, v144, v137
	v_fma_f32 v112, -v136, v113, v112
	v_div_scale_f32 v136, s[2:3], v106, v106, 1.0
	v_rcp_f32_e32 v144, v136
	v_mul_f32_e32 v109, 0xbfb8aa3b, v109
	v_div_fmas_f32 v112, v112, v137, v113
	v_exp_f32_e32 v108, v108
	v_exp_f32_e32 v109, v109
	v_div_fixup_f32 v107, v112, v107, 1.0
	v_fma_f32 v112, -v136, v144, 1.0
	v_fmac_f32_e32 v144, v112, v144
	v_div_scale_f32 v112, vcc, 1.0, v106, 1.0
	v_mul_f32_e32 v113, v112, v144
	v_fma_f32 v137, -v136, v113, v112
	v_pk_add_f32 v[108:109], v[108:109], 1.0 op_sel_hi:[1,0]
	v_fmac_f32_e32 v113, v137, v144
	v_fma_f32 v112, -v136, v113, v112
	v_div_scale_f32 v136, s[2:3], v109, v109, 1.0
	v_rcp_f32_e32 v137, v136
	v_div_fmas_f32 v112, v112, v144, v113
	v_div_fixup_f32 v106, v112, v106, 1.0
	s_waitcnt vmcnt(4)
	v_pk_fma_f32 v[110:111], v[110:111], v[116:117], v[228:229]
	v_fma_f32 v112, -v136, v137, 1.0
	v_fmac_f32_e32 v137, v112, v137
	v_div_scale_f32 v112, vcc, 1.0, v109, 1.0
	v_mul_f32_e32 v113, v112, v137
	v_fma_f32 v144, -v136, v113, v112
	v_fmac_f32_e32 v113, v144, v137
	v_fma_f32 v112, -v136, v113, v112
	v_div_fmas_f32 v112, v112, v137, v113
	v_div_fixup_f32 v113, v112, v109, 1.0
	v_xor_b32_e32 v116, 32, v203
	v_rcp_f32_e32 v144, v108
	s_nop 0
	v_fma_f32 v136, -v108, v144, 1.0
	v_fma_f32 v112, v136, v144, v144
	v_pk_fma_f32 v[108:109], v[134:135], v[114:115], v[226:227]
	v_pk_fma_f32 v[114:115], v[112:113], v[124:125], v[206:207]
	v_pk_fma_f32 v[112:113], v[106:107], v[122:123], v[204:205]
	v_cmp_lt_i32_e32 vcc, v116, v164
	v_mul_f32_e32 v106, v112, v112
	v_fmac_f32_e32 v106, v108, v108
	v_mul_f32_e32 v107, v113, v113
	v_add_f32_e32 v106, v106, v166
	v_fmac_f32_e32 v107, v109, v109
	v_add_f32_e32 v106, v107, v106
	v_mul_f32_e32 v107, v114, v114
	v_fmac_f32_e32 v107, v110, v110
	v_add_f32_e32 v106, v107, v106
	v_mul_f32_e32 v107, v115, v115
	v_fmac_f32_e32 v107, v111, v111
	v_add_f32_e32 v106, v107, v106
	ds_bpermute_b32 v107, v225, v106
	v_cndmask_b32_e32 v116, v203, v116, vcc
	v_lshlrev_b32_e32 v226, 2, v116
	global_store_dwordx4 v[142:143], v[108:111], off offset:512 nt
	global_store_dwordx4 v[142:143], v[112:115], off offset:528 nt
	s_waitcnt lgkmcnt(0)
	v_add_f32_e32 v106, v106, v107
	ds_bpermute_b32 v107, v226, v106
	s_and_saveexec_b64 s[2:3], s[42:43]
	s_cbranch_execz .LBB0_783
	v_lshl_add_u64 v[108:109], v[186:187], 2, s[36:37]
	s_waitcnt lgkmcnt(0)
	v_add_f32_e32 v106, v106, v107
	global_atomic_add_f32 v[108:109], v106, off
; #define NTL(p) __builtin_nontemporal_load((const f32x4*)(p))
; #define NTS(v, p) __builtin_nontemporal_store((v), (f32x4*)(p))
; __device__ __forceinline__ float bf_lo(unsigned w) { return __uint_as_float(w << 16); }
; __device__ __forceinline__ float bf_hi(unsigned w) { return __uint_as_float(w & 0xffff0000u); }
; __device__ __forceinline__ float sigmoidf_(float x) { return 1.0f / (1.0f + __expf(-x)); }
;     __device__ __forceinline__ void operator()(AccT& acc, const Unit& u, int wr, int wc, int fr, int fq) const {
;     ...
;             if (r < 7) { const int rn = row0 + ((r + 1) >> 2) * 128 + ((r + 1) & 3) * 16; const float* hn = H + (size_t)rn * DM + col0; const bf16_t* pn = ppbase + (((r + 1) >> 2) * 128 + ((r + 1) & 3) * 16) * 256;
;                 hv[(r + 1) & 1][0] = NTL(hn); hv[(r + 1) & 1][1] = NTL(hn + 4); hv[(r + 1) & 1][2] = NTL(hn + 128); hv[(r + 1) & 1][3] = NTL(hn + 132);
;                 pv[(r + 1) & 1][0] = *(const u32x4*)pn; pv[(r + 1) & 1][1] = *(const u32x4*)(pn + 128); rs[(r + 1) & 1] = rss2[rn]; }
;             float* hp = H + (size_t)row * DM + col0; float ss = 0.f; const float rstd = rsqrtf(rs[r & 1] * (1.0f / DM) + 1e-6f);
; #pragma unroll
;             for (int bj = 0; bj < 2; ++bj) { const u32x4 pw = pv[r & 1][bj];
;                 const f32x4 b0 = *(const f32x4*)(bias + col0 + bj * 128), b1 = *(const f32x4*)(bias + col0 + bj * 128 + 4);
;                 const f32x4 p0 = (f32x4){bf_lo(pw.x), bf_hi(pw.x), bf_lo(pw.y), bf_hi(pw.y)}, p1 = (f32x4){bf_lo(pw.z), bf_hi(pw.z), bf_lo(pw.w), bf_hi(pw.w)};
;                 f32x4 g0 = acc[ai][bj][m][0] * rstd + b0, g1 = acc[ai][bj][m][1] * rstd + b1;
; #pragma unroll
;                 for (int j = 0; j < 4; ++j) { g0[j] = sigmoidf_(g0[j]); g1[j] = sigmoidf_(g1[j]); }
;                 const f32x4 v0 = hv[r & 1][2 * bj] + p0 * g0, v1 = hv[r & 1][2 * bj + 1] + p1 * g1;
;                 NTS(v0, hp + bj * 128); NTS(v1, hp + bj * 128 + 4);
; #pragma unroll
;                 for (int j = 0; j < 4; ++j) ss += v0[j] * v0[j] + v1[j] * v1[j]; }
.LBB0_783:
	s_or_b64 exec, exec, s[2:3]
	v_add_u32_e32 v194, 32, v186
	v_ashrrev_i32_e32 v195, 31, v194
	s_waitcnt lgkmcnt(0)
	v_lshlrev_b64 v[106:107], 12, v[194:195]
	v_lshl_add_u64 v[106:107], s[22:23], 0, v[106:107]
	v_add_co_u32_e32 v114, vcc, 0x4000, v190
	v_lshl_add_u64 v[196:197], v[192:193], 2, v[106:107]
	s_nop 0
	v_addc_co_u32_e32 v115, vcc, 0, v191, vcc
	global_load_dwordx4 v[122:125], v[196:197], off offset:16 nt
	global_load_dwordx4 v[134:137], v[196:197], off nt
	global_load_dwordx4 v[106:109], v[196:197], off offset:528 nt
	global_load_dwordx4 v[110:113], v[196:197], off offset:512 nt
	global_load_dwordx4 v[142:145], v[114:115], off
	s_nop 0
	global_load_dwordx4 v[114:117], v[114:115], off offset:256
	s_nop 0
	global_load_dword v164, v[188:189], off offset:128
	v_fmamk_f32 v165, v165, 0x3a800000, v210
	v_cmp_gt_f32_e32 vcc, s30, v165
	v_mul_f32_e32 v166, 0x4b800000, v165
	v_lshlrev_b32_e32 v204, 16, v158
	v_cndmask_b32_e32 v165, v165, v166, vcc
	v_rsq_f32_e32 v165, v165
	v_and_b32_e32 v205, 0xffff0000, v158
	v_lshlrev_b32_e32 v206, 16, v159
	v_and_b32_e32 v207, 0xffff0000, v159
	v_mul_f32_e32 v166, 0x45800000, v165
	v_cndmask_b32_e32 v202, v165, v166, vcc
	v_lshlrev_b32_e32 v158, 16, v160
	v_and_b32_e32 v159, 0xffff0000, v160
	v_lshlrev_b32_e32 v160, 16, v161
	v_and_b32_e32 v161, 0xffff0000, v161
	v_pk_fma_f32 v[118:119], v[118:119], v[202:203], v[244:245] op_sel_hi:[1,0,1]
	v_pk_fma_f32 v[126:127], v[126:127], v[202:203], v[240:241] op_sel_hi:[1,0,1]
	v_mul_f32_e32 v118, 0xbfb8aa3b, v118
	v_mul_f32_e32 v126, 0xbfb8aa3b, v126
	v_pk_fma_f32 v[120:121], v[120:121], v[202:203], v[246:247] op_sel_hi:[1,0,1]
	v_exp_f32_e32 v166, v126
	v_exp_f32_e32 v126, v118
	v_mul_f32_e32 v118, 0xbfb8aa3b, v127
	v_pk_fma_f32 v[128:129], v[128:129], v[202:203], v[242:243] op_sel_hi:[1,0,1]
	v_exp_f32_e32 v167, v118
	v_mul_f32_e32 v118, 0xbfb8aa3b, v119
	v_mul_f32_e32 v119, 0xbfb8aa3b, v120
	v_exp_f32_e32 v127, v118
	v_mul_f32_e32 v118, 0xbfb8aa3b, v128
	v_exp_f32_e32 v120, v119
	v_mul_f32_e32 v119, 0xbfb8aa3b, v129
	v_exp_f32_e32 v118, v118
	v_exp_f32_e32 v119, v119
	v_pk_add_f32 v[126:127], v[126:127], 1.0 op_sel_hi:[1,0]
	v_mul_f32_e32 v121, 0xbfb8aa3b, v121
	v_exp_f32_e32 v121, v121
	v_pk_add_f32 v[128:129], v[118:119], 1.0 op_sel_hi:[1,0]
	v_pk_add_f32 v[118:119], v[166:167], 1.0 op_sel_hi:[1,0]
	v_pk_add_f32 v[120:121], v[120:121], 1.0 op_sel_hi:[1,0]
	s_nop 0
	v_rcp_f32_e32 v165, v119
	s_nop 0
	v_fma_f32 v170, -v119, v165, 1.0
	v_fma_f32 v119, v170, v165, v165
	s_nop 0
	v_rcp_f32_e32 v165, v118
	s_nop 0
	v_fma_f32 v170, -v118, v165, 1.0
	v_fma_f32 v118, v170, v165, v165
	s_waitcnt vmcnt(11)
	v_pk_fma_f32 v[118:119], v[118:119], v[204:205], v[154:155]
	v_rcp_f32_e32 v165, v129
	s_nop 0
	v_fma_f32 v170, -v129, v165, 1.0
	v_fma_f32 v129, v170, v165, v165
	s_nop 0
	v_rcp_f32_e32 v165, v128
	s_nop 0
	v_fma_f32 v170, -v128, v165, 1.0
	v_fma_f32 v128, v170, v165, v165
	s_nop 0
	v_rcp_f32_e32 v165, v127
	s_nop 0
	v_fma_f32 v170, -v127, v165, 1.0
	v_fma_f32 v127, v170, v165, v165
	s_nop 0
	v_rcp_f32_e32 v165, v126
	s_nop 0
	v_fma_f32 v170, -v126, v165, 1.0
	v_fma_f32 v126, v170, v165, v165
	v_pk_fma_f32 v[126:127], v[126:127], v[158:159], v[150:151]
	v_rcp_f32_e32 v165, v121
	s_nop 0
	v_fma_f32 v170, -v121, v165, 1.0
	v_fma_f32 v167, v170, v165, v165
	s_nop 0
	v_rcp_f32_e32 v121, v120
	s_nop 0
	v_fma_f32 v170, -v120, v121, 1.0
	v_fma_f32 v166, v170, v121, v121
	v_pk_fma_f32 v[120:121], v[128:129], v[206:207], v[156:157]
	v_pk_fma_f32 v[128:129], v[166:167], v[160:161], v[152:153]
	global_store_dwordx4 v[200:201], v[118:121], off nt
	global_store_dwordx4 v[200:201], v[126:129], off offset:16 nt
	s_nop 0
	s_nop 0
	v_mul_f32_e32 v126, v126, v126
	v_fmac_f32_e32 v126, v118, v118
	v_mul_f32_e32 v118, v127, v127
	v_fmac_f32_e32 v118, v119, v119
	v_add_f32_e32 v118, v126, v118
	v_mul_f32_e32 v119, v128, v128
	v_lshlrev_b32_e32 v126, 16, v146
	v_and_b32_e32 v127, 0xffff0000, v146
	v_fmac_f32_e32 v119, v120, v120
	v_add_f32_e32 v118, v119, v118
	v_mul_f32_e32 v119, v129, v129
	v_lshlrev_b32_e32 v128, 16, v147
	v_and_b32_e32 v129, 0xffff0000, v147
	v_fmac_f32_e32 v119, v121, v121
	v_add_f32_e32 v150, v119, v118
	v_lshlrev_b32_e32 v118, 16, v148
	v_and_b32_e32 v119, 0xffff0000, v148
	v_lshlrev_b32_e32 v120, 16, v149
	v_and_b32_e32 v121, 0xffff0000, v149
	v_pk_fma_f32 v[98:99], v[98:99], v[202:203], v[232:233] op_sel_hi:[1,0,1]
	v_pk_fma_f32 v[102:103], v[102:103], v[202:203], v[248:249] op_sel_hi:[1,0,1]
	v_mul_f32_e32 v98, 0xbfb8aa3b, v98
	v_pk_fma_f32 v[100:101], v[100:101], v[202:203], v[234:235] op_sel_hi:[1,0,1]
	v_exp_f32_e32 v146, v98
	v_mul_f32_e32 v98, 0xbfb8aa3b, v103
	v_pk_fma_f32 v[104:105], v[104:105], v[202:203], v[250:251] op_sel_hi:[1,0,1]
	v_exp_f32_e32 v103, v98
	v_mul_f32_e32 v98, 0xbfb8aa3b, v99
	v_mul_f32_e32 v99, 0xbfb8aa3b, v100
	v_mul_f32_e32 v102, 0xbfb8aa3b, v102
	v_exp_f32_e32 v147, v98
	v_mul_f32_e32 v98, 0xbfb8aa3b, v104
	v_exp_f32_e32 v100, v99
	v_mul_f32_e32 v99, 0xbfb8aa3b, v105
	v_exp_f32_e32 v102, v102
	v_exp_f32_e32 v98, v98
	v_exp_f32_e32 v99, v99
	v_mul_f32_e32 v101, 0xbfb8aa3b, v101
	v_exp_f32_e32 v101, v101
	v_pk_add_f32 v[104:105], v[98:99], 1.0 op_sel_hi:[1,0]
	v_pk_add_f32 v[98:99], v[102:103], 1.0 op_sel_hi:[1,0]
	v_pk_add_f32 v[100:101], v[100:101], 1.0 op_sel_hi:[1,0]
	s_nop 0
	v_rcp_f32_e32 v102, v99
	s_nop 0
	v_fma_f32 v149, -v99, v102, 1.0
	v_fma_f32 v99, v149, v102, v102
	s_nop 0
	v_rcp_f32_e32 v102, v98
	s_nop 0
	v_fma_f32 v149, -v98, v102, 1.0
	v_fma_f32 v98, v149, v102, v102
	s_waitcnt vmcnt(11)
; #define NTL(p) __builtin_nontemporal_load((const f32x4*)(p))
; #define NTS(v, p) __builtin_nontemporal_store((v), (f32x4*)(p))
; __device__ __forceinline__ float bf_lo(unsigned w) { return __uint_as_float(w << 16); }
; __device__ __forceinline__ float bf_hi(unsigned w) { return __uint_as_float(w & 0xffff0000u); }
; __device__ __forceinline__ float sigmoidf_(float x) { return 1.0f / (1.0f + __expf(-x)); }
;     __device__ __forceinline__ void operator()(AccT& acc, const Unit& u, int wr, int wc, int fr, int fq) const {
;     ...
;         for (int r = 0; r < 8; ++r) { const int ai = r >> 2, m = r & 3; const int row = row0 + ai * 128 + m * 16;
;             if (r < 7) { const int rn = row0 + ((r + 1) >> 2) * 128 + ((r + 1) & 3) * 16; const float* hn = H + (size_t)rn * DM + col0; const bf16_t* pn = ppbase + (((r + 1) >> 2) * 128 + ((r + 1) & 3) * 16) * 256;
;                 hv[(r + 1) & 1][0] = NTL(hn); hv[(r + 1) & 1][1] = NTL(hn + 4); hv[(r + 1) & 1][2] = NTL(hn + 128); hv[(r + 1) & 1][3] = NTL(hn + 132);
;                 pv[(r + 1) & 1][0] = *(const u32x4*)pn; pv[(r + 1) & 1][1] = *(const u32x4*)(pn + 128); rs[(r + 1) & 1] = rss2[rn]; }
;             float* hp = H + (size_t)row * DM + col0; float ss = 0.f; const float rstd = rsqrtf(rs[r & 1] * (1.0f / DM) + 1e-6f);
; #pragma unroll
;             for (int bj = 0; bj < 2; ++bj) { const u32x4 pw = pv[r & 1][bj];
;                 const f32x4 b0 = *(const f32x4*)(bias + col0 + bj * 128), b1 = *(const f32x4*)(bias + col0 + bj * 128 + 4);
;                 const f32x4 p0 = (f32x4){bf_lo(pw.x), bf_hi(pw.x), bf_lo(pw.y), bf_hi(pw.y)}, p1 = (f32x4){bf_lo(pw.z), bf_hi(pw.z), bf_lo(pw.w), bf_hi(pw.w)};
;                 f32x4 g0 = acc[ai][bj][m][0] * rstd + b0, g1 = acc[ai][bj][m][1] * rstd + b1;
; #pragma unroll
;                 for (int j = 0; j < 4; ++j) { g0[j] = sigmoidf_(g0[j]); g1[j] = sigmoidf_(g1[j]); }
;                 const f32x4 v0 = hv[r & 1][2 * bj] + p0 * g0, v1 = hv[r & 1][2 * bj + 1] + p1 * g1;
;                 NTS(v0, hp + bj * 128); NTS(v1, hp + bj * 128 + 4);
; #pragma unroll
;                 for (int j = 0; j < 4; ++j) ss += v0[j] * v0[j] + v1[j] * v1[j]; }
;             ss += __shfl_xor(ss, 16); ss += __shfl_xor(ss, 32);
;             if (fq == 0) unsafeAtomicAdd(rss3 + row, ss); __builtin_amdgcn_sched_barrier(0); }
	v_pk_fma_f32 v[98:99], v[98:99], v[126:127], v[138:139]
	v_rcp_f32_e32 v102, v105
	s_nop 0
	v_fma_f32 v149, -v105, v102, 1.0
	v_fma_f32 v103, v149, v102, v102
	s_nop 0
	v_rcp_f32_e32 v149, v104
	s_nop 0
	v_fma_f32 v151, -v104, v149, 1.0
	v_fma_f32 v102, v151, v149, v149
	v_pk_add_f32 v[104:105], v[146:147], 1.0 op_sel_hi:[1,0]
	s_nop 0
	s_nop 0
	v_rcp_f32_e32 v146, v105
	s_nop 0
	v_fma_f32 v149, -v105, v146, 1.0
	v_fma_f32 v147, v149, v146, v146
	s_nop 0
	v_rcp_f32_e32 v105, v104
	s_nop 0
	v_fma_f32 v149, -v104, v105, 1.0
	v_fma_f32 v146, v149, v105, v105
	s_nop 0
	v_rcp_f32_e32 v104, v101
	s_nop 0
	v_fma_f32 v149, -v101, v104, 1.0
	v_fma_f32 v105, v149, v104, v104
	s_nop 0
	v_rcp_f32_e32 v101, v100
	s_nop 0
	v_fma_f32 v149, -v100, v101, 1.0
	v_fma_f32 v104, v149, v101, v101
	v_pk_fma_f32 v[100:101], v[102:103], v[128:129], v[140:141]
	v_pk_fma_f32 v[102:103], v[146:147], v[118:119], v[130:131]
	v_pk_fma_f32 v[104:105], v[104:105], v[120:121], v[132:133]
	global_store_dwordx4 v[200:201], v[98:101], off offset:512 nt
	global_store_dwordx4 v[200:201], v[102:105], off offset:528 nt
	s_nop 1
	v_mul_f32_e32 v102, v102, v102
	v_fmac_f32_e32 v102, v98, v98
	v_add_f32_e32 v98, v150, v102
	v_mul_f32_e32 v102, v103, v103
	v_fmac_f32_e32 v102, v99, v99
	v_mul_f32_e32 v99, v104, v104
	v_add_f32_e32 v98, v102, v98
	v_fmac_f32_e32 v99, v100, v100
	v_add_f32_e32 v98, v99, v98
	v_mul_f32_e32 v99, v105, v105
	v_fmac_f32_e32 v99, v101, v101
	v_add_f32_e32 v98, v99, v98
	ds_bpermute_b32 v99, v225, v98
	s_waitcnt lgkmcnt(0)
	v_add_f32_e32 v98, v98, v99
	ds_bpermute_b32 v99, v226, v98
	s_and_saveexec_b64 s[2:3], s[42:43]
	s_cbranch_execz .LBB0_785
	v_lshl_add_u64 v[100:101], v[198:199], 2, s[36:37]
	s_waitcnt lgkmcnt(0)
	v_add_f32_e32 v98, v98, v99
	global_atomic_add_f32 v[100:101], v98, off
.LBB0_785:
	s_or_b64 exec, exec, s[2:3]
	v_add_u32_e32 v146, 48, v186
	v_ashrrev_i32_e32 v147, 31, v146
	s_waitcnt lgkmcnt(0)
	v_lshlrev_b64 v[98:99], 12, v[146:147]
	v_lshl_add_u64 v[98:99], s[22:23], 0, v[98:99]
	v_add_co_u32_e32 v118, vcc, 0x6000, v190
	v_lshl_add_u64 v[148:149], v[192:193], 2, v[98:99]
	s_nop 0
	v_addc_co_u32_e32 v119, vcc, 0, v191, vcc
	global_load_dwordx4 v[126:129], v[148:149], off offset:16 nt
	global_load_dwordx4 v[130:133], v[148:149], off nt
	global_load_dwordx4 v[98:101], v[148:149], off offset:528 nt
	global_load_dwordx4 v[102:105], v[148:149], off offset:512 nt
	global_load_dwordx4 v[138:141], v[118:119], off
	s_nop 0
	global_load_dwordx4 v[118:121], v[118:119], off offset:256
	s_nop 0
	global_load_dword v151, v[188:189], off offset:192
	s_waitcnt vmcnt(11)
	v_fmamk_f32 v150, v164, 0x3a800000, v210
	v_cmp_gt_f32_e32 vcc, s30, v150
	v_mul_f32_e32 v152, 0x4b800000, v150
	v_and_b32_e32 v153, 0xffff0000, v142
	v_cndmask_b32_e32 v150, v150, v152, vcc
	v_rsq_f32_e32 v150, v150
	v_lshlrev_b32_e32 v154, 16, v143
	v_and_b32_e32 v155, 0xffff0000, v143
	v_and_b32_e32 v143, 0xffff0000, v144
	v_mul_f32_e32 v152, 0x45800000, v150
	v_cndmask_b32_e32 v150, v150, v152, vcc
	v_lshlrev_b32_e32 v152, 16, v142
	v_lshlrev_b32_e32 v142, 16, v144
	v_lshlrev_b32_e32 v144, 16, v145
	v_and_b32_e32 v145, 0xffff0000, v145
	v_pk_fma_f32 v[90:91], v[90:91], v[150:151], v[244:245] op_sel_hi:[1,0,1]
	v_pk_fma_f32 v[94:95], v[94:95], v[150:151], v[240:241] op_sel_hi:[1,0,1]
	v_mul_f32_e32 v90, 0xbfb8aa3b, v90
	v_mul_f32_e32 v94, 0xbfb8aa3b, v94
	v_pk_fma_f32 v[92:93], v[92:93], v[150:151], v[246:247] op_sel_hi:[1,0,1]
	v_exp_f32_e32 v156, v94
	v_exp_f32_e32 v94, v90
	v_mul_f32_e32 v90, 0xbfb8aa3b, v95
	v_pk_fma_f32 v[96:97], v[96:97], v[150:151], v[242:243] op_sel_hi:[1,0,1]
	v_exp_f32_e32 v157, v90
	v_mul_f32_e32 v90, 0xbfb8aa3b, v91
	v_mul_f32_e32 v91, 0xbfb8aa3b, v92
	v_exp_f32_e32 v95, v90
	v_mul_f32_e32 v90, 0xbfb8aa3b, v96
	v_exp_f32_e32 v92, v91
	v_mul_f32_e32 v91, 0xbfb8aa3b, v97
	v_exp_f32_e32 v90, v90
	v_exp_f32_e32 v91, v91
	v_pk_add_f32 v[94:95], v[94:95], 1.0 op_sel_hi:[1,0]
	v_mul_f32_e32 v93, 0xbfb8aa3b, v93
	v_exp_f32_e32 v93, v93
	v_pk_add_f32 v[96:97], v[90:91], 1.0 op_sel_hi:[1,0]
	v_pk_add_f32 v[90:91], v[156:157], 1.0 op_sel_hi:[1,0]
	v_pk_add_f32 v[92:93], v[92:93], 1.0 op_sel_hi:[1,0]
	s_nop 0
	v_rcp_f32_e32 v156, v91
	s_nop 0
	v_fma_f32 v159, -v91, v156, 1.0
	v_fma_f32 v91, v159, v156, v156
	s_nop 0
	v_rcp_f32_e32 v156, v90
	s_nop 0
	v_fma_f32 v159, -v90, v156, 1.0
	v_fma_f32 v90, v159, v156, v156
	v_pk_fma_f32 v[90:91], v[90:91], v[152:153], v[134:135]
	v_rcp_f32_e32 v156, v97
	s_nop 0
	v_fma_f32 v159, -v97, v156, 1.0
	v_fma_f32 v97, v159, v156, v156
	s_nop 0
	v_rcp_f32_e32 v156, v96
	s_nop 0
	v_fma_f32 v159, -v96, v156, 1.0
	v_fma_f32 v96, v159, v156, v156
	s_nop 0
	v_rcp_f32_e32 v156, v95
	s_nop 0
	v_fma_f32 v159, -v95, v156, 1.0
	v_fma_f32 v95, v159, v156, v156
	s_nop 0
	v_rcp_f32_e32 v156, v94
	s_nop 0
	v_fma_f32 v159, -v94, v156, 1.0
	v_fma_f32 v94, v159, v156, v156
	v_pk_fma_f32 v[94:95], v[94:95], v[142:143], v[122:123]
	v_rcp_f32_e32 v156, v93
	s_nop 0
	v_fma_f32 v159, -v93, v156, 1.0
	v_fma_f32 v157, v159, v156, v156
	s_nop 0
	v_rcp_f32_e32 v93, v92
	s_nop 0
	v_fma_f32 v159, -v92, v93, 1.0
	v_fma_f32 v156, v159, v93, v93
	v_pk_fma_f32 v[92:93], v[96:97], v[154:155], v[136:137]
	v_pk_fma_f32 v[96:97], v[156:157], v[144:145], v[124:125]
	global_store_dwordx4 v[196:197], v[90:93], off nt
	global_store_dwordx4 v[196:197], v[94:97], off offset:16 nt
	s_nop 0
	s_nop 0
	v_mul_f32_e32 v94, v94, v94
	v_fmac_f32_e32 v94, v90, v90
	v_mul_f32_e32 v90, v95, v95
	v_fmac_f32_e32 v90, v91, v91
	v_add_f32_e32 v90, v94, v90
	v_mul_f32_e32 v91, v96, v96
	v_lshlrev_b32_e32 v94, 16, v114
	v_and_b32_e32 v95, 0xffff0000, v114
	v_fmac_f32_e32 v91, v92, v92
; #define NTL(p) __builtin_nontemporal_load((const f32x4*)(p))
; #define NTS(v, p) __builtin_nontemporal_store((v), (f32x4*)(p))
; __device__ __forceinline__ float bf_lo(unsigned w) { return __uint_as_float(w << 16); }
; __device__ __forceinline__ float bf_hi(unsigned w) { return __uint_as_float(w & 0xffff0000u); }
; __device__ __forceinline__ float sigmoidf_(float x) { return 1.0f / (1.0f + __expf(-x)); }
;     __device__ __forceinline__ void operator()(AccT& acc, const Unit& u, int wr, int wc, int fr, int fq) const {
;     ...
;         for (int r = 0; r < 8; ++r) { const int ai = r >> 2, m = r & 3; const int row = row0 + ai * 128 + m * 16;
;             if (r < 7) { const int rn = row0 + ((r + 1) >> 2) * 128 + ((r + 1) & 3) * 16; const float* hn = H + (size_t)rn * DM + col0; const bf16_t* pn = ppbase + (((r + 1) >> 2) * 128 + ((r + 1) & 3) * 16) * 256;
;                 hv[(r + 1) & 1][0] = NTL(hn); hv[(r + 1) & 1][1] = NTL(hn + 4); hv[(r + 1) & 1][2] = NTL(hn + 128); hv[(r + 1) & 1][3] = NTL(hn + 132);
;                 pv[(r + 1) & 1][0] = *(const u32x4*)pn; pv[(r + 1) & 1][1] = *(const u32x4*)(pn + 128); rs[(r + 1) & 1] = rss2[rn]; }
;             float* hp = H + (size_t)row * DM + col0; float ss = 0.f; const float rstd = rsqrtf(rs[r & 1] * (1.0f / DM) + 1e-6f);
; #pragma unroll
;             for (int bj = 0; bj < 2; ++bj) { const u32x4 pw = pv[r & 1][bj];
;                 const f32x4 b0 = *(const f32x4*)(bias + col0 + bj * 128), b1 = *(const f32x4*)(bias + col0 + bj * 128 + 4);
;                 const f32x4 p0 = (f32x4){bf_lo(pw.x), bf_hi(pw.x), bf_lo(pw.y), bf_hi(pw.y)}, p1 = (f32x4){bf_lo(pw.z), bf_hi(pw.z), bf_lo(pw.w), bf_hi(pw.w)};
;                 f32x4 g0 = acc[ai][bj][m][0] * rstd + b0, g1 = acc[ai][bj][m][1] * rstd + b1;
; #pragma unroll
;                 for (int j = 0; j < 4; ++j) { g0[j] = sigmoidf_(g0[j]); g1[j] = sigmoidf_(g1[j]); }
;                 const f32x4 v0 = hv[r & 1][2 * bj] + p0 * g0, v1 = hv[r & 1][2 * bj + 1] + p1 * g1;
;                 NTS(v0, hp + bj * 128); NTS(v1, hp + bj * 128 + 4);
; #pragma unroll
;                 for (int j = 0; j < 4; ++j) ss += v0[j] * v0[j] + v1[j] * v1[j]; }
;             ss += __shfl_xor(ss, 16); ss += __shfl_xor(ss, 32);
;             if (fq == 0) unsafeAtomicAdd(rss3 + row, ss); __builtin_amdgcn_sched_barrier(0); }
	v_add_f32_e32 v90, v91, v90
	v_mul_f32_e32 v91, v97, v97
	v_lshlrev_b32_e32 v96, 16, v115
	v_and_b32_e32 v97, 0xffff0000, v115
	v_fmac_f32_e32 v91, v93, v93
	v_add_f32_e32 v122, v91, v90
	v_lshlrev_b32_e32 v90, 16, v116
	v_and_b32_e32 v91, 0xffff0000, v116
	v_lshlrev_b32_e32 v92, 16, v117
	v_and_b32_e32 v93, 0xffff0000, v117
	v_pk_fma_f32 v[82:83], v[82:83], v[150:151], v[232:233] op_sel_hi:[1,0,1]
	v_pk_fma_f32 v[86:87], v[86:87], v[150:151], v[248:249] op_sel_hi:[1,0,1]
	v_mul_f32_e32 v82, 0xbfb8aa3b, v82
	v_pk_fma_f32 v[84:85], v[84:85], v[150:151], v[234:235] op_sel_hi:[1,0,1]
	v_exp_f32_e32 v114, v82
	v_mul_f32_e32 v82, 0xbfb8aa3b, v87
	v_pk_fma_f32 v[88:89], v[88:89], v[150:151], v[250:251] op_sel_hi:[1,0,1]
	v_exp_f32_e32 v87, v82
	v_mul_f32_e32 v82, 0xbfb8aa3b, v83
	v_mul_f32_e32 v83, 0xbfb8aa3b, v84
	v_mul_f32_e32 v86, 0xbfb8aa3b, v86
	v_exp_f32_e32 v115, v82
	v_mul_f32_e32 v82, 0xbfb8aa3b, v88
	v_exp_f32_e32 v84, v83
	v_mul_f32_e32 v83, 0xbfb8aa3b, v89
	v_exp_f32_e32 v86, v86
	v_exp_f32_e32 v82, v82
	v_exp_f32_e32 v83, v83
	v_mul_f32_e32 v85, 0xbfb8aa3b, v85
	v_exp_f32_e32 v85, v85
	v_pk_add_f32 v[88:89], v[82:83], 1.0 op_sel_hi:[1,0]
	v_pk_add_f32 v[82:83], v[86:87], 1.0 op_sel_hi:[1,0]
	v_pk_add_f32 v[84:85], v[84:85], 1.0 op_sel_hi:[1,0]
	s_nop 0
	v_rcp_f32_e32 v86, v83
	s_nop 0
	v_fma_f32 v117, -v83, v86, 1.0
	v_fma_f32 v83, v117, v86, v86
	s_nop 0
	v_rcp_f32_e32 v86, v82
	s_nop 0
	v_fma_f32 v117, -v82, v86, 1.0
	v_fma_f32 v82, v117, v86, v86
	v_pk_fma_f32 v[82:83], v[82:83], v[94:95], v[110:111]
	v_rcp_f32_e32 v86, v89
	s_nop 0
	v_fma_f32 v117, -v89, v86, 1.0
	v_fma_f32 v87, v117, v86, v86
	s_nop 0
	v_rcp_f32_e32 v117, v88
	s_nop 0
	v_fma_f32 v123, -v88, v117, 1.0
	v_fma_f32 v86, v123, v117, v117
	v_pk_add_f32 v[88:89], v[114:115], 1.0 op_sel_hi:[1,0]
	s_nop 0
	s_nop 0
	v_rcp_f32_e32 v114, v89
	s_nop 0
	v_fma_f32 v117, -v89, v114, 1.0
	v_fma_f32 v115, v117, v114, v114
	s_nop 0
	v_rcp_f32_e32 v89, v88
	s_nop 0
	v_fma_f32 v117, -v88, v89, 1.0
	v_fma_f32 v114, v117, v89, v89
	s_nop 0
	v_rcp_f32_e32 v88, v85
	s_nop 0
	v_fma_f32 v117, -v85, v88, 1.0
	v_fma_f32 v89, v117, v88, v88
	s_nop 0
	v_rcp_f32_e32 v85, v84
	s_nop 0
	v_fma_f32 v117, -v84, v85, 1.0
	v_fma_f32 v88, v117, v85, v85
	v_pk_fma_f32 v[84:85], v[86:87], v[96:97], v[112:113]
	v_pk_fma_f32 v[86:87], v[114:115], v[90:91], v[106:107]
	v_pk_fma_f32 v[88:89], v[88:89], v[92:93], v[108:109]
	global_store_dwordx4 v[196:197], v[82:85], off offset:512 nt
	global_store_dwordx4 v[196:197], v[86:89], off offset:528 nt
	s_nop 1
	v_mul_f32_e32 v86, v86, v86
	v_fmac_f32_e32 v86, v82, v82
	v_add_f32_e32 v82, v122, v86
	v_mul_f32_e32 v86, v87, v87
	v_fmac_f32_e32 v86, v83, v83
	v_mul_f32_e32 v83, v88, v88
	v_add_f32_e32 v82, v86, v82
	v_fmac_f32_e32 v83, v84, v84
	v_add_f32_e32 v82, v83, v82
	v_mul_f32_e32 v83, v89, v89
	v_fmac_f32_e32 v83, v85, v85
	v_add_f32_e32 v82, v83, v82
	ds_bpermute_b32 v83, v225, v82
	s_waitcnt lgkmcnt(0)
	v_add_f32_e32 v82, v82, v83
	ds_bpermute_b32 v83, v226, v82
	s_and_saveexec_b64 s[2:3], s[42:43]
	s_cbranch_execz .LBB0_787
	v_lshl_add_u64 v[84:85], v[194:195], 2, s[36:37]
	s_waitcnt lgkmcnt(0)
	v_add_f32_e32 v82, v82, v83
	global_atomic_add_f32 v[84:85], v82, off
.LBB0_787:
	s_or_b64 exec, exec, s[2:3]
	v_add_u32_e32 v114, 0x80, v186
	v_ashrrev_i32_e32 v115, 31, v114
	s_waitcnt lgkmcnt(0)
	v_lshlrev_b64 v[82:83], 12, v[114:115]
	v_lshl_add_u64 v[82:83], s[22:23], 0, v[82:83]
	v_add_co_u32_e32 v90, vcc, 0x10000, v190
	v_lshl_add_u64 v[122:123], v[192:193], 2, v[82:83]
	s_nop 0
	v_addc_co_u32_e32 v91, vcc, 0, v191, vcc
	global_load_dwordx4 v[94:97], v[122:123], off offset:16 nt
	global_load_dwordx4 v[106:109], v[122:123], off nt
	global_load_dwordx4 v[82:85], v[122:123], off offset:528 nt
	global_load_dwordx4 v[86:89], v[122:123], off offset:512 nt
	global_load_dwordx4 v[110:113], v[90:91], off
	s_nop 0
	global_load_dwordx4 v[90:93], v[90:91], off offset:256
	s_nop 0
	global_load_dword v142, v[188:189], off offset:512
	s_waitcnt vmcnt(11)
	v_fmamk_f32 v116, v151, 0x3a800000, v210
	v_cmp_gt_f32_e32 vcc, s30, v116
	v_mul_f32_e32 v117, 0x4b800000, v116
	v_lshlrev_b32_e32 v124, 16, v140
	v_cndmask_b32_e32 v116, v116, v117, vcc
	v_rsq_f32_e32 v116, v116
	v_and_b32_e32 v125, 0xffff0000, v140
	v_lshlrev_b32_e32 v134, 16, v141
	v_and_b32_e32 v135, 0xffff0000, v141
	v_mul_f32_e32 v117, 0x45800000, v116
	v_cndmask_b32_e32 v116, v116, v117, vcc
	v_lshlrev_b32_e32 v136, 16, v138
	v_and_b32_e32 v137, 0xffff0000, v138
	v_lshlrev_b32_e32 v138, 16, v139
	v_and_b32_e32 v139, 0xffff0000, v139
	v_pk_fma_f32 v[74:75], v[74:75], v[116:117], v[244:245] op_sel_hi:[1,0,1]
	v_pk_fma_f32 v[78:79], v[78:79], v[116:117], v[240:241] op_sel_hi:[1,0,1]
	v_mul_f32_e32 v74, 0xbfb8aa3b, v74
	v_mul_f32_e32 v78, 0xbfb8aa3b, v78
	v_pk_fma_f32 v[76:77], v[76:77], v[116:117], v[246:247] op_sel_hi:[1,0,1]
	v_exp_f32_e32 v140, v78
	v_exp_f32_e32 v78, v74
	v_mul_f32_e32 v74, 0xbfb8aa3b, v79
	v_pk_fma_f32 v[80:81], v[80:81], v[116:117], v[242:243] op_sel_hi:[1,0,1]
	v_exp_f32_e32 v141, v74
	v_mul_f32_e32 v74, 0xbfb8aa3b, v75
	v_mul_f32_e32 v75, 0xbfb8aa3b, v76
	v_exp_f32_e32 v79, v74
	v_mul_f32_e32 v74, 0xbfb8aa3b, v80
	v_exp_f32_e32 v76, v75
	v_mul_f32_e32 v75, 0xbfb8aa3b, v81
	v_exp_f32_e32 v74, v74
	v_exp_f32_e32 v75, v75
	v_pk_add_f32 v[78:79], v[78:79], 1.0 op_sel_hi:[1,0]
	v_mul_f32_e32 v77, 0xbfb8aa3b, v77
	v_exp_f32_e32 v77, v77
	v_pk_add_f32 v[80:81], v[74:75], 1.0 op_sel_hi:[1,0]
	v_pk_add_f32 v[74:75], v[140:141], 1.0 op_sel_hi:[1,0]
	v_pk_add_f32 v[76:77], v[76:77], 1.0 op_sel_hi:[1,0]
	s_nop 0
	v_rcp_f32_e32 v117, v75
	s_nop 0
	v_fma_f32 v143, -v75, v117, 1.0
	v_fma_f32 v75, v143, v117, v117
; #define NTL(p) __builtin_nontemporal_load((const f32x4*)(p))
; #define NTS(v, p) __builtin_nontemporal_store((v), (f32x4*)(p))
; __device__ __forceinline__ float bf_lo(unsigned w) { return __uint_as_float(w << 16); }
; __device__ __forceinline__ float bf_hi(unsigned w) { return __uint_as_float(w & 0xffff0000u); }
; __device__ __forceinline__ float sigmoidf_(float x) { return 1.0f / (1.0f + __expf(-x)); }
;     __device__ __forceinline__ void operator()(AccT& acc, const Unit& u, int wr, int wc, int fr, int fq) const {
;     ...
;         for (int r = 0; r < 8; ++r) { const int ai = r >> 2, m = r & 3; const int row = row0 + ai * 128 + m * 16;
;             if (r < 7) { const int rn = row0 + ((r + 1) >> 2) * 128 + ((r + 1) & 3) * 16; const float* hn = H + (size_t)rn * DM + col0; const bf16_t* pn = ppbase + (((r + 1) >> 2) * 128 + ((r + 1) & 3) * 16) * 256;
;                 hv[(r + 1) & 1][0] = NTL(hn); hv[(r + 1) & 1][1] = NTL(hn + 4); hv[(r + 1) & 1][2] = NTL(hn + 128); hv[(r + 1) & 1][3] = NTL(hn + 132);
;                 pv[(r + 1) & 1][0] = *(const u32x4*)pn; pv[(r + 1) & 1][1] = *(const u32x4*)(pn + 128); rs[(r + 1) & 1] = rss2[rn]; }
;             float* hp = H + (size_t)row * DM + col0; float ss = 0.f; const float rstd = rsqrtf(rs[r & 1] * (1.0f / DM) + 1e-6f);
; #pragma unroll
;             for (int bj = 0; bj < 2; ++bj) { const u32x4 pw = pv[r & 1][bj];
;                 const f32x4 b0 = *(const f32x4*)(bias + col0 + bj * 128), b1 = *(const f32x4*)(bias + col0 + bj * 128 + 4);
;                 const f32x4 p0 = (f32x4){bf_lo(pw.x), bf_hi(pw.x), bf_lo(pw.y), bf_hi(pw.y)}, p1 = (f32x4){bf_lo(pw.z), bf_hi(pw.z), bf_lo(pw.w), bf_hi(pw.w)};
;                 f32x4 g0 = acc[ai][bj][m][0] * rstd + b0, g1 = acc[ai][bj][m][1] * rstd + b1;
; #pragma unroll
;                 for (int j = 0; j < 4; ++j) { g0[j] = sigmoidf_(g0[j]); g1[j] = sigmoidf_(g1[j]); }
;                 const f32x4 v0 = hv[r & 1][2 * bj] + p0 * g0, v1 = hv[r & 1][2 * bj + 1] + p1 * g1;
;                 NTS(v0, hp + bj * 128); NTS(v1, hp + bj * 128 + 4);
; #pragma unroll
;                 for (int j = 0; j < 4; ++j) ss += v0[j] * v0[j] + v1[j] * v1[j]; }
;             ss += __shfl_xor(ss, 16); ss += __shfl_xor(ss, 32);
;             if (fq == 0) unsafeAtomicAdd(rss3 + row, ss); __builtin_amdgcn_sched_barrier(0); }
	s_nop 0
	v_rcp_f32_e32 v117, v74
	s_nop 0
	v_fma_f32 v143, -v74, v117, 1.0
	v_fma_f32 v74, v143, v117, v117
	v_pk_fma_f32 v[74:75], v[74:75], v[136:137], v[130:131]
	v_rcp_f32_e32 v117, v81
	s_nop 0
	v_fma_f32 v143, -v81, v117, 1.0
	v_fma_f32 v81, v143, v117, v117
	s_nop 0
	v_rcp_f32_e32 v117, v80
	s_nop 0
	v_fma_f32 v143, -v80, v117, 1.0
	v_fma_f32 v80, v143, v117, v117
	s_nop 0
	v_rcp_f32_e32 v117, v79
	s_nop 0
	v_fma_f32 v143, -v79, v117, 1.0
	v_fma_f32 v79, v143, v117, v117
	s_nop 0
	v_rcp_f32_e32 v117, v78
	s_nop 0
	v_fma_f32 v143, -v78, v117, 1.0
	v_fma_f32 v78, v143, v117, v117
	v_pk_fma_f32 v[78:79], v[78:79], v[124:125], v[126:127]
	v_rcp_f32_e32 v117, v77
	s_nop 0
	v_fma_f32 v143, -v77, v117, 1.0
	v_fma_f32 v141, v143, v117, v117
	s_nop 0
	v_rcp_f32_e32 v77, v76
	s_nop 0
	v_fma_f32 v143, -v76, v77, 1.0
	v_fma_f32 v140, v143, v77, v77
	v_pk_fma_f32 v[76:77], v[80:81], v[138:139], v[132:133]
	v_pk_fma_f32 v[80:81], v[140:141], v[134:135], v[128:129]
	global_store_dwordx4 v[148:149], v[74:77], off nt
	global_store_dwordx4 v[148:149], v[78:81], off offset:16 nt
	s_nop 0
	s_nop 0
	v_mul_f32_e32 v78, v78, v78
	v_fmac_f32_e32 v78, v74, v74
	v_mul_f32_e32 v74, v79, v79
	v_fmac_f32_e32 v74, v75, v75
	v_mul_f32_e32 v75, v80, v80
	v_add_f32_e32 v74, v78, v74
	v_fmac_f32_e32 v75, v76, v76
	v_add_f32_e32 v74, v75, v74
	v_mul_f32_e32 v75, v81, v81
	v_fmac_f32_e32 v75, v77, v77
	v_add_f32_e32 v117, v75, v74
	v_lshlrev_b32_e32 v78, 16, v118
	v_and_b32_e32 v79, 0xffff0000, v118
	v_lshlrev_b32_e32 v80, 16, v119
	v_and_b32_e32 v81, 0xffff0000, v119
	v_lshlrev_b32_e32 v74, 16, v120
	v_and_b32_e32 v75, 0xffff0000, v120
	v_lshlrev_b32_e32 v76, 16, v121
	v_and_b32_e32 v77, 0xffff0000, v121
	v_pk_fma_f32 v[66:67], v[66:67], v[116:117], v[232:233] op_sel_hi:[1,0,1]
	v_pk_fma_f32 v[70:71], v[70:71], v[116:117], v[248:249] op_sel_hi:[1,0,1]
	v_mul_f32_e32 v66, 0xbfb8aa3b, v66
	v_pk_fma_f32 v[68:69], v[68:69], v[116:117], v[234:235] op_sel_hi:[1,0,1]
	v_exp_f32_e32 v118, v66
	v_mul_f32_e32 v66, 0xbfb8aa3b, v71
	v_pk_fma_f32 v[72:73], v[72:73], v[116:117], v[250:251] op_sel_hi:[1,0,1]
	v_exp_f32_e32 v71, v66
	v_mul_f32_e32 v66, 0xbfb8aa3b, v67
	v_mul_f32_e32 v67, 0xbfb8aa3b, v68
	v_mul_f32_e32 v70, 0xbfb8aa3b, v70
	v_exp_f32_e32 v119, v66
	v_mul_f32_e32 v66, 0xbfb8aa3b, v72
	v_exp_f32_e32 v68, v67
	v_mul_f32_e32 v67, 0xbfb8aa3b, v73
	v_exp_f32_e32 v70, v70
	v_exp_f32_e32 v66, v66
	v_exp_f32_e32 v67, v67
	v_mul_f32_e32 v69, 0xbfb8aa3b, v69
	v_exp_f32_e32 v69, v69
	v_pk_add_f32 v[72:73], v[66:67], 1.0 op_sel_hi:[1,0]
	v_pk_add_f32 v[66:67], v[70:71], 1.0 op_sel_hi:[1,0]
	v_pk_add_f32 v[68:69], v[68:69], 1.0 op_sel_hi:[1,0]
	s_nop 0
	v_rcp_f32_e32 v70, v67
	s_nop 0
	v_fma_f32 v120, -v67, v70, 1.0
	v_fma_f32 v67, v120, v70, v70
	s_nop 0
	v_rcp_f32_e32 v70, v66
	s_nop 0
	v_fma_f32 v120, -v66, v70, 1.0
	v_fma_f32 v66, v120, v70, v70
	v_pk_fma_f32 v[66:67], v[66:67], v[78:79], v[102:103]
	v_rcp_f32_e32 v70, v73
	s_nop 0
	v_fma_f32 v120, -v73, v70, 1.0
	v_fma_f32 v71, v120, v70, v70
	s_nop 0
	v_rcp_f32_e32 v120, v72
	s_nop 0
	v_fma_f32 v121, -v72, v120, 1.0
	v_fma_f32 v70, v121, v120, v120
	v_pk_add_f32 v[72:73], v[118:119], 1.0 op_sel_hi:[1,0]
	s_nop 0
	s_nop 0
	v_rcp_f32_e32 v116, v73
	s_nop 0
	v_fma_f32 v120, -v73, v116, 1.0
	v_fma_f32 v119, v120, v116, v116
	s_nop 0
	v_rcp_f32_e32 v73, v72
	s_nop 0
	v_fma_f32 v120, -v72, v73, 1.0
	v_fma_f32 v118, v120, v73, v73
	s_nop 0
	v_rcp_f32_e32 v72, v69
	s_nop 0
	v_fma_f32 v120, -v69, v72, 1.0
	v_fma_f32 v73, v120, v72, v72
	s_nop 0
	v_rcp_f32_e32 v69, v68
	s_nop 0
	v_fma_f32 v120, -v68, v69, 1.0
	v_fma_f32 v72, v120, v69, v69
	v_pk_fma_f32 v[68:69], v[70:71], v[80:81], v[104:105]
	v_pk_fma_f32 v[70:71], v[118:119], v[74:75], v[98:99]
	v_pk_fma_f32 v[72:73], v[72:73], v[76:77], v[100:101]
	global_store_dwordx4 v[148:149], v[66:69], off offset:512 nt
	global_store_dwordx4 v[148:149], v[70:73], off offset:528 nt
	s_nop 1
	v_mul_f32_e32 v70, v70, v70
	v_fmac_f32_e32 v70, v66, v66
	v_add_f32_e32 v66, v117, v70
	v_mul_f32_e32 v70, v71, v71
	v_fmac_f32_e32 v70, v67, v67
	v_mul_f32_e32 v67, v72, v72
	v_add_f32_e32 v66, v70, v66
	v_fmac_f32_e32 v67, v68, v68
	v_add_f32_e32 v66, v67, v66
	v_mul_f32_e32 v67, v73, v73
	v_fmac_f32_e32 v67, v69, v69
	v_add_f32_e32 v66, v67, v66
	ds_bpermute_b32 v67, v225, v66
	s_waitcnt lgkmcnt(0)
	v_add_f32_e32 v66, v66, v67
	ds_bpermute_b32 v67, v226, v66
	s_and_saveexec_b64 s[2:3], s[42:43]
	s_cbranch_execz .LBB0_789
	v_lshl_add_u64 v[68:69], v[146:147], 2, s[36:37]
	s_waitcnt lgkmcnt(0)
	v_add_f32_e32 v66, v66, v67
	global_atomic_add_f32 v[68:69], v66, off
; #define NTL(p) __builtin_nontemporal_load((const f32x4*)(p))
; #define NTS(v, p) __builtin_nontemporal_store((v), (f32x4*)(p))
; __device__ __forceinline__ float bf_lo(unsigned w) { return __uint_as_float(w << 16); }
; __device__ __forceinline__ float bf_hi(unsigned w) { return __uint_as_float(w & 0xffff0000u); }
; __device__ __forceinline__ float sigmoidf_(float x) { return 1.0f / (1.0f + __expf(-x)); }
;     __device__ __forceinline__ void operator()(AccT& acc, const Unit& u, int wr, int wc, int fr, int fq) const {
;     ...
;         for (int r = 0; r < 8; ++r) { const int ai = r >> 2, m = r & 3; const int row = row0 + ai * 128 + m * 16;
;             if (r < 7) { const int rn = row0 + ((r + 1) >> 2) * 128 + ((r + 1) & 3) * 16; const float* hn = H + (size_t)rn * DM + col0; const bf16_t* pn = ppbase + (((r + 1) >> 2) * 128 + ((r + 1) & 3) * 16) * 256;
;                 hv[(r + 1) & 1][0] = NTL(hn); hv[(r + 1) & 1][1] = NTL(hn + 4); hv[(r + 1) & 1][2] = NTL(hn + 128); hv[(r + 1) & 1][3] = NTL(hn + 132);
;                 pv[(r + 1) & 1][0] = *(const u32x4*)pn; pv[(r + 1) & 1][1] = *(const u32x4*)(pn + 128); rs[(r + 1) & 1] = rss2[rn]; }
;             float* hp = H + (size_t)row * DM + col0; float ss = 0.f; const float rstd = rsqrtf(rs[r & 1] * (1.0f / DM) + 1e-6f);
; #pragma unroll
;             for (int bj = 0; bj < 2; ++bj) { const u32x4 pw = pv[r & 1][bj];
;                 const f32x4 b0 = *(const f32x4*)(bias + col0 + bj * 128), b1 = *(const f32x4*)(bias + col0 + bj * 128 + 4);
;                 const f32x4 p0 = (f32x4){bf_lo(pw.x), bf_hi(pw.x), bf_lo(pw.y), bf_hi(pw.y)}, p1 = (f32x4){bf_lo(pw.z), bf_hi(pw.z), bf_lo(pw.w), bf_hi(pw.w)};
;                 f32x4 g0 = acc[ai][bj][m][0] * rstd + b0, g1 = acc[ai][bj][m][1] * rstd + b1;
; #pragma unroll
;                 for (int j = 0; j < 4; ++j) { g0[j] = sigmoidf_(g0[j]); g1[j] = sigmoidf_(g1[j]); }
;                 const f32x4 v0 = hv[r & 1][2 * bj] + p0 * g0, v1 = hv[r & 1][2 * bj + 1] + p1 * g1;
;                 NTS(v0, hp + bj * 128); NTS(v1, hp + bj * 128 + 4);
; #pragma unroll
;                 for (int j = 0; j < 4; ++j) ss += v0[j] * v0[j] + v1[j] * v1[j]; }
;             ss += __shfl_xor(ss, 16); ss += __shfl_xor(ss, 32);
;             if (fq == 0) unsafeAtomicAdd(rss3 + row, ss); __builtin_amdgcn_sched_barrier(0); }
.LBB0_789:
	s_or_b64 exec, exec, s[2:3]
	v_add_u32_e32 v116, 0x90, v186
	v_ashrrev_i32_e32 v117, 31, v116
	s_waitcnt lgkmcnt(0)
	v_lshlrev_b64 v[66:67], 12, v[116:117]
	v_lshl_add_u64 v[66:67], s[22:23], 0, v[66:67]
	v_add_co_u32_e32 v74, vcc, 0x12000, v190
	v_lshl_add_u64 v[118:119], v[192:193], 2, v[66:67]
	s_nop 0
	v_addc_co_u32_e32 v75, vcc, 0, v191, vcc
	global_load_dwordx4 v[78:81], v[118:119], off offset:16 nt
	global_load_dwordx4 v[98:101], v[118:119], off nt
	global_load_dwordx4 v[66:69], v[118:119], off offset:528 nt
	global_load_dwordx4 v[70:73], v[118:119], off offset:512 nt
	global_load_dwordx4 v[102:105], v[74:75], off
	s_nop 0
	global_load_dwordx4 v[74:77], v[74:75], off offset:256
	s_nop 0
	global_load_dword v121, v[188:189], off offset:576
	s_waitcnt vmcnt(11)
	v_fmamk_f32 v120, v142, 0x3a800000, v210
	v_cmp_gt_f32_e32 vcc, s30, v120
	v_mul_f32_e32 v124, 0x4b800000, v120
	v_and_b32_e32 v125, 0xffff0000, v110
	v_cndmask_b32_e32 v120, v120, v124, vcc
	v_rsq_f32_e32 v120, v120
	v_lshlrev_b32_e32 v126, 16, v111
	v_and_b32_e32 v127, 0xffff0000, v111
	v_and_b32_e32 v111, 0xffff0000, v112
	v_mul_f32_e32 v124, 0x45800000, v120
	v_cndmask_b32_e32 v120, v120, v124, vcc
	v_lshlrev_b32_e32 v124, 16, v110
	v_lshlrev_b32_e32 v110, 16, v112
	v_lshlrev_b32_e32 v112, 16, v113
	v_and_b32_e32 v113, 0xffff0000, v113
	v_pk_fma_f32 v[58:59], v[58:59], v[120:121], v[244:245] op_sel_hi:[1,0,1]
	v_pk_fma_f32 v[62:63], v[62:63], v[120:121], v[240:241] op_sel_hi:[1,0,1]
	v_mul_f32_e32 v58, 0xbfb8aa3b, v58
	v_mul_f32_e32 v62, 0xbfb8aa3b, v62
	v_pk_fma_f32 v[60:61], v[60:61], v[120:121], v[246:247] op_sel_hi:[1,0,1]
	v_exp_f32_e32 v128, v62
	v_exp_f32_e32 v62, v58
	v_mul_f32_e32 v58, 0xbfb8aa3b, v63
	v_pk_fma_f32 v[64:65], v[64:65], v[120:121], v[242:243] op_sel_hi:[1,0,1]
	v_exp_f32_e32 v129, v58
	v_mul_f32_e32 v58, 0xbfb8aa3b, v59
	v_mul_f32_e32 v59, 0xbfb8aa3b, v60
	v_exp_f32_e32 v63, v58
	v_mul_f32_e32 v58, 0xbfb8aa3b, v64
	v_exp_f32_e32 v60, v59
	v_mul_f32_e32 v59, 0xbfb8aa3b, v65
	v_exp_f32_e32 v58, v58
	v_exp_f32_e32 v59, v59
	v_pk_add_f32 v[62:63], v[62:63], 1.0 op_sel_hi:[1,0]
	v_mul_f32_e32 v61, 0xbfb8aa3b, v61
	v_exp_f32_e32 v61, v61
	v_pk_add_f32 v[64:65], v[58:59], 1.0 op_sel_hi:[1,0]
	v_pk_add_f32 v[58:59], v[128:129], 1.0 op_sel_hi:[1,0]
	v_pk_add_f32 v[60:61], v[60:61], 1.0 op_sel_hi:[1,0]
	s_nop 0
	v_rcp_f32_e32 v128, v59
	s_nop 0
	v_fma_f32 v131, -v59, v128, 1.0
	v_fma_f32 v59, v131, v128, v128
	s_nop 0
	v_rcp_f32_e32 v128, v58
	s_nop 0
	v_fma_f32 v131, -v58, v128, 1.0
	v_fma_f32 v58, v131, v128, v128
	v_pk_fma_f32 v[58:59], v[58:59], v[124:125], v[106:107]
	v_rcp_f32_e32 v128, v65
	s_nop 0
	v_fma_f32 v131, -v65, v128, 1.0
	v_fma_f32 v65, v131, v128, v128
	s_nop 0
	v_rcp_f32_e32 v128, v64
	s_nop 0
	v_fma_f32 v131, -v64, v128, 1.0
	v_fma_f32 v64, v131, v128, v128
	s_nop 0
	v_rcp_f32_e32 v128, v63
	s_nop 0
	v_fma_f32 v131, -v63, v128, 1.0
	v_fma_f32 v63, v131, v128, v128
	s_nop 0
	v_rcp_f32_e32 v128, v62
	s_nop 0
	v_fma_f32 v131, -v62, v128, 1.0
	v_fma_f32 v62, v131, v128, v128
	v_pk_fma_f32 v[62:63], v[62:63], v[110:111], v[94:95]
	v_rcp_f32_e32 v128, v61
	s_nop 0
	v_fma_f32 v131, -v61, v128, 1.0
	v_fma_f32 v129, v131, v128, v128
	s_nop 0
	v_rcp_f32_e32 v61, v60
	s_nop 0
	v_fma_f32 v131, -v60, v61, 1.0
	v_fma_f32 v128, v131, v61, v61
	v_pk_fma_f32 v[60:61], v[64:65], v[126:127], v[108:109]
	v_pk_fma_f32 v[64:65], v[128:129], v[112:113], v[96:97]
	global_store_dwordx4 v[122:123], v[58:61], off nt
	global_store_dwordx4 v[122:123], v[62:65], off offset:16 nt
	s_nop 0
	s_nop 0
	v_mul_f32_e32 v62, v62, v62
	v_fmac_f32_e32 v62, v58, v58
	v_mul_f32_e32 v58, v63, v63
	v_fmac_f32_e32 v58, v59, v59
	v_add_f32_e32 v58, v62, v58
	v_mul_f32_e32 v59, v64, v64
	v_lshlrev_b32_e32 v62, 16, v90
	v_and_b32_e32 v63, 0xffff0000, v90
	v_fmac_f32_e32 v59, v60, v60
	v_add_f32_e32 v58, v59, v58
	v_mul_f32_e32 v59, v65, v65
	v_lshlrev_b32_e32 v64, 16, v91
	v_and_b32_e32 v65, 0xffff0000, v91
	v_fmac_f32_e32 v59, v61, v61
	v_add_f32_e32 v94, v59, v58
	v_lshlrev_b32_e32 v58, 16, v92
	v_and_b32_e32 v59, 0xffff0000, v92
	v_lshlrev_b32_e32 v60, 16, v93
	v_and_b32_e32 v61, 0xffff0000, v93
	v_pk_fma_f32 v[50:51], v[50:51], v[120:121], v[232:233] op_sel_hi:[1,0,1]
	v_pk_fma_f32 v[54:55], v[54:55], v[120:121], v[248:249] op_sel_hi:[1,0,1]
	v_mul_f32_e32 v50, 0xbfb8aa3b, v50
	v_pk_fma_f32 v[52:53], v[52:53], v[120:121], v[234:235] op_sel_hi:[1,0,1]
	v_exp_f32_e32 v90, v50
	v_mul_f32_e32 v50, 0xbfb8aa3b, v55
	v_pk_fma_f32 v[56:57], v[56:57], v[120:121], v[250:251] op_sel_hi:[1,0,1]
	v_exp_f32_e32 v55, v50
	v_mul_f32_e32 v50, 0xbfb8aa3b, v51
	v_mul_f32_e32 v51, 0xbfb8aa3b, v52
	v_mul_f32_e32 v54, 0xbfb8aa3b, v54
	v_exp_f32_e32 v91, v50
	v_mul_f32_e32 v50, 0xbfb8aa3b, v56
	v_exp_f32_e32 v52, v51
	v_mul_f32_e32 v51, 0xbfb8aa3b, v57
	v_exp_f32_e32 v54, v54
	v_exp_f32_e32 v50, v50
	v_exp_f32_e32 v51, v51
	v_mul_f32_e32 v53, 0xbfb8aa3b, v53
	v_exp_f32_e32 v53, v53
	v_pk_add_f32 v[56:57], v[50:51], 1.0 op_sel_hi:[1,0]
	v_pk_add_f32 v[50:51], v[54:55], 1.0 op_sel_hi:[1,0]
	v_pk_add_f32 v[52:53], v[52:53], 1.0 op_sel_hi:[1,0]
	s_nop 0
	v_rcp_f32_e32 v54, v51
	s_nop 0
	v_fma_f32 v93, -v51, v54, 1.0
	v_fma_f32 v51, v93, v54, v54
	s_nop 0
	v_rcp_f32_e32 v54, v50
	s_nop 0
	v_fma_f32 v93, -v50, v54, 1.0
	v_fma_f32 v50, v93, v54, v54
	v_pk_fma_f32 v[50:51], v[50:51], v[62:63], v[86:87]
	v_rcp_f32_e32 v54, v57
	s_nop 0
	v_fma_f32 v93, -v57, v54, 1.0
	v_fma_f32 v55, v93, v54, v54
	s_nop 0
	v_rcp_f32_e32 v93, v56
	s_nop 0
	v_fma_f32 v95, -v56, v93, 1.0
	v_fma_f32 v54, v95, v93, v93
	v_pk_add_f32 v[56:57], v[90:91], 1.0 op_sel_hi:[1,0]
	s_nop 0
	s_nop 0
	v_rcp_f32_e32 v90, v57
	s_nop 0
	v_fma_f32 v93, -v57, v90, 1.0
	v_fma_f32 v91, v93, v90, v90
	s_nop 0
	v_rcp_f32_e32 v57, v56
	s_nop 0
	v_fma_f32 v93, -v56, v57, 1.0
	v_fma_f32 v90, v93, v57, v57
	s_nop 0
	v_rcp_f32_e32 v56, v53
	s_nop 0
	v_fma_f32 v93, -v53, v56, 1.0
	v_fma_f32 v57, v93, v56, v56
	s_nop 0
	v_rcp_f32_e32 v53, v52
	s_nop 0
	v_fma_f32 v93, -v52, v53, 1.0
	v_fma_f32 v56, v93, v53, v53
	v_pk_fma_f32 v[52:53], v[54:55], v[64:65], v[88:89]
	v_pk_fma_f32 v[54:55], v[90:91], v[58:59], v[82:83]
	v_pk_fma_f32 v[56:57], v[56:57], v[60:61], v[84:85]
	global_store_dwordx4 v[122:123], v[50:53], off offset:512 nt
	global_store_dwordx4 v[122:123], v[54:57], off offset:528 nt
	s_nop 1
	v_mul_f32_e32 v54, v54, v54
	v_fmac_f32_e32 v54, v50, v50
	v_add_f32_e32 v50, v94, v54
	v_mul_f32_e32 v54, v55, v55
	v_fmac_f32_e32 v54, v51, v51
	v_mul_f32_e32 v51, v56, v56
	v_add_f32_e32 v50, v54, v50
	v_fmac_f32_e32 v51, v52, v52
	v_add_f32_e32 v50, v51, v50
	v_mul_f32_e32 v51, v57, v57
	v_fmac_f32_e32 v51, v53, v53
	v_add_f32_e32 v50, v51, v50
	ds_bpermute_b32 v51, v225, v50
	s_waitcnt lgkmcnt(0)
	v_add_f32_e32 v50, v50, v51
	ds_bpermute_b32 v51, v226, v50
	s_and_saveexec_b64 s[2:3], s[42:43]
	s_cbranch_execz .LBB0_791
	v_lshl_add_u64 v[52:53], v[114:115], 2, s[36:37]
	s_waitcnt lgkmcnt(0)
	v_add_f32_e32 v50, v50, v51
	global_atomic_add_f32 v[52:53], v50, off
; #define NTL(p) __builtin_nontemporal_load((const f32x4*)(p))
; #define NTS(v, p) __builtin_nontemporal_store((v), (f32x4*)(p))
; __device__ __forceinline__ float bf_lo(unsigned w) { return __uint_as_float(w << 16); }
; __device__ __forceinline__ float bf_hi(unsigned w) { return __uint_as_float(w & 0xffff0000u); }
; __device__ __forceinline__ float sigmoidf_(float x) { return 1.0f / (1.0f + __expf(-x)); }
;     __device__ __forceinline__ void operator()(AccT& acc, const Unit& u, int wr, int wc, int fr, int fq) const {
;     ...
;         for (int r = 0; r < 8; ++r) { const int ai = r >> 2, m = r & 3; const int row = row0 + ai * 128 + m * 16;
;             if (r < 7) { const int rn = row0 + ((r + 1) >> 2) * 128 + ((r + 1) & 3) * 16; const float* hn = H + (size_t)rn * DM + col0; const bf16_t* pn = ppbase + (((r + 1) >> 2) * 128 + ((r + 1) & 3) * 16) * 256;
;                 hv[(r + 1) & 1][0] = NTL(hn); hv[(r + 1) & 1][1] = NTL(hn + 4); hv[(r + 1) & 1][2] = NTL(hn + 128); hv[(r + 1) & 1][3] = NTL(hn + 132);
;                 pv[(r + 1) & 1][0] = *(const u32x4*)pn; pv[(r + 1) & 1][1] = *(const u32x4*)(pn + 128); rs[(r + 1) & 1] = rss2[rn]; }
;             float* hp = H + (size_t)row * DM + col0; float ss = 0.f; const float rstd = rsqrtf(rs[r & 1] * (1.0f / DM) + 1e-6f);
; #pragma unroll
;             for (int bj = 0; bj < 2; ++bj) { const u32x4 pw = pv[r & 1][bj];
;                 const f32x4 b0 = *(const f32x4*)(bias + col0 + bj * 128), b1 = *(const f32x4*)(bias + col0 + bj * 128 + 4);
;                 const f32x4 p0 = (f32x4){bf_lo(pw.x), bf_hi(pw.x), bf_lo(pw.y), bf_hi(pw.y)}, p1 = (f32x4){bf_lo(pw.z), bf_hi(pw.z), bf_lo(pw.w), bf_hi(pw.w)};
;                 f32x4 g0 = acc[ai][bj][m][0] * rstd + b0, g1 = acc[ai][bj][m][1] * rstd + b1;
; #pragma unroll
;                 for (int j = 0; j < 4; ++j) { g0[j] = sigmoidf_(g0[j]); g1[j] = sigmoidf_(g1[j]); }
;                 const f32x4 v0 = hv[r & 1][2 * bj] + p0 * g0, v1 = hv[r & 1][2 * bj + 1] + p1 * g1;
;                 NTS(v0, hp + bj * 128); NTS(v1, hp + bj * 128 + 4);
; #pragma unroll
;                 for (int j = 0; j < 4; ++j) ss += v0[j] * v0[j] + v1[j] * v1[j]; }
;             ss += __shfl_xor(ss, 16); ss += __shfl_xor(ss, 32);
;             if (fq == 0) unsafeAtomicAdd(rss3 + row, ss); __builtin_amdgcn_sched_barrier(0); }
.LBB0_791:
	s_or_b64 exec, exec, s[2:3]
	v_add_u32_e32 v90, 0xa0, v186
	v_ashrrev_i32_e32 v91, 31, v90
	s_waitcnt lgkmcnt(0)
	v_lshlrev_b64 v[50:51], 12, v[90:91]
	v_lshl_add_u64 v[50:51], s[22:23], 0, v[50:51]
	v_add_co_u32_e32 v58, vcc, 0x14000, v190
	v_lshl_add_u64 v[92:93], v[192:193], 2, v[50:51]
	s_nop 0
	v_addc_co_u32_e32 v59, vcc, 0, v191, vcc
	global_load_dwordx4 v[62:65], v[92:93], off offset:16 nt
	global_load_dwordx4 v[82:85], v[92:93], off nt
	global_load_dwordx4 v[50:53], v[92:93], off offset:528 nt
	global_load_dwordx4 v[54:57], v[92:93], off offset:512 nt
	global_load_dwordx4 v[86:89], v[58:59], off
	s_nop 0
	global_load_dwordx4 v[58:61], v[58:59], off offset:256
	s_nop 0
	global_load_dword v95, v[188:189], off offset:640
	s_waitcnt vmcnt(11)
	v_fmamk_f32 v94, v121, 0x3a800000, v210
	v_cmp_gt_f32_e32 vcc, s30, v94
	v_mul_f32_e32 v96, 0x4b800000, v94
	v_and_b32_e32 v97, 0xffff0000, v104
	v_cndmask_b32_e32 v94, v94, v96, vcc
	v_rsq_f32_e32 v94, v94
	v_lshlrev_b32_e32 v106, 16, v102
	v_and_b32_e32 v107, 0xffff0000, v102
	v_lshlrev_b32_e32 v108, 16, v103
	v_mul_f32_e32 v96, 0x45800000, v94
	v_cndmask_b32_e32 v94, v94, v96, vcc
	v_lshlrev_b32_e32 v96, 16, v104
	v_and_b32_e32 v109, 0xffff0000, v103
	v_lshlrev_b32_e32 v102, 16, v105
	v_and_b32_e32 v103, 0xffff0000, v105
	v_pk_fma_f32 v[42:43], v[42:43], v[94:95], v[244:245] op_sel_hi:[1,0,1]
	v_pk_fma_f32 v[46:47], v[46:47], v[94:95], v[240:241] op_sel_hi:[1,0,1]
	v_mul_f32_e32 v42, 0xbfb8aa3b, v42
	v_mul_f32_e32 v46, 0xbfb8aa3b, v46
	v_pk_fma_f32 v[44:45], v[44:45], v[94:95], v[246:247] op_sel_hi:[1,0,1]
	v_exp_f32_e32 v104, v46
	v_exp_f32_e32 v46, v42
	v_mul_f32_e32 v42, 0xbfb8aa3b, v47
	v_pk_fma_f32 v[48:49], v[48:49], v[94:95], v[242:243] op_sel_hi:[1,0,1]
	v_exp_f32_e32 v105, v42
	v_mul_f32_e32 v42, 0xbfb8aa3b, v43
	v_mul_f32_e32 v43, 0xbfb8aa3b, v44
	v_exp_f32_e32 v47, v42
	v_mul_f32_e32 v42, 0xbfb8aa3b, v48
	v_exp_f32_e32 v44, v43
	v_mul_f32_e32 v43, 0xbfb8aa3b, v49
	v_exp_f32_e32 v42, v42
	v_exp_f32_e32 v43, v43
	v_pk_add_f32 v[46:47], v[46:47], 1.0 op_sel_hi:[1,0]
	v_mul_f32_e32 v45, 0xbfb8aa3b, v45
	v_exp_f32_e32 v45, v45
	v_pk_add_f32 v[48:49], v[42:43], 1.0 op_sel_hi:[1,0]
	v_pk_add_f32 v[42:43], v[104:105], 1.0 op_sel_hi:[1,0]
	v_pk_add_f32 v[44:45], v[44:45], 1.0 op_sel_hi:[1,0]
	s_nop 0
	v_rcp_f32_e32 v104, v43
	s_nop 0
	v_fma_f32 v111, -v43, v104, 1.0
	v_fma_f32 v43, v111, v104, v104
	s_nop 0
	v_rcp_f32_e32 v104, v42
	s_nop 0
	v_fma_f32 v111, -v42, v104, 1.0
	v_fma_f32 v42, v111, v104, v104
	v_pk_fma_f32 v[42:43], v[42:43], v[106:107], v[98:99]
	v_rcp_f32_e32 v104, v49
	s_nop 0
	v_fma_f32 v111, -v49, v104, 1.0
	v_fma_f32 v49, v111, v104, v104
	s_nop 0
	v_rcp_f32_e32 v104, v48
	s_nop 0
	v_fma_f32 v111, -v48, v104, 1.0
	v_fma_f32 v48, v111, v104, v104
	s_nop 0
	v_rcp_f32_e32 v104, v47
	s_nop 0
	v_fma_f32 v111, -v47, v104, 1.0
	v_fma_f32 v47, v111, v104, v104
	s_nop 0
	v_rcp_f32_e32 v104, v46
	s_nop 0
	v_fma_f32 v111, -v46, v104, 1.0
	v_fma_f32 v46, v111, v104, v104
	v_pk_fma_f32 v[46:47], v[46:47], v[96:97], v[78:79]
	v_rcp_f32_e32 v104, v45
	s_nop 0
	v_fma_f32 v111, -v45, v104, 1.0
	v_fma_f32 v105, v111, v104, v104
	s_nop 0
	v_rcp_f32_e32 v45, v44
	s_nop 0
	v_fma_f32 v111, -v44, v45, 1.0
	v_fma_f32 v104, v111, v45, v45
	v_pk_fma_f32 v[44:45], v[48:49], v[108:109], v[100:101]
	v_pk_fma_f32 v[48:49], v[104:105], v[102:103], v[80:81]
	global_store_dwordx4 v[118:119], v[42:45], off nt
	global_store_dwordx4 v[118:119], v[46:49], off offset:16 nt
	s_nop 0
	s_nop 0
	v_mul_f32_e32 v46, v46, v46
	v_fmac_f32_e32 v46, v42, v42
	v_mul_f32_e32 v42, v47, v47
	v_fmac_f32_e32 v42, v43, v43
	v_add_f32_e32 v42, v46, v42
	v_mul_f32_e32 v43, v48, v48
	v_lshlrev_b32_e32 v46, 16, v74
	v_and_b32_e32 v47, 0xffff0000, v74
	v_fmac_f32_e32 v43, v44, v44
	v_add_f32_e32 v42, v43, v42
	v_mul_f32_e32 v43, v49, v49
	v_lshlrev_b32_e32 v48, 16, v75
	v_and_b32_e32 v49, 0xffff0000, v75
	v_fmac_f32_e32 v43, v45, v45
	v_add_f32_e32 v78, v43, v42
	v_lshlrev_b32_e32 v42, 16, v76
	v_and_b32_e32 v43, 0xffff0000, v76
	v_lshlrev_b32_e32 v44, 16, v77
	v_and_b32_e32 v45, 0xffff0000, v77
	v_pk_fma_f32 v[34:35], v[34:35], v[94:95], v[232:233] op_sel_hi:[1,0,1]
	v_pk_fma_f32 v[38:39], v[38:39], v[94:95], v[248:249] op_sel_hi:[1,0,1]
	v_mul_f32_e32 v34, 0xbfb8aa3b, v34
	v_pk_fma_f32 v[36:37], v[36:37], v[94:95], v[234:235] op_sel_hi:[1,0,1]
	v_exp_f32_e32 v74, v34
	v_mul_f32_e32 v34, 0xbfb8aa3b, v39
	v_pk_fma_f32 v[40:41], v[40:41], v[94:95], v[250:251] op_sel_hi:[1,0,1]
	v_exp_f32_e32 v39, v34
	v_mul_f32_e32 v34, 0xbfb8aa3b, v35
	v_mul_f32_e32 v35, 0xbfb8aa3b, v36
	v_mul_f32_e32 v38, 0xbfb8aa3b, v38
	v_exp_f32_e32 v75, v34
	v_mul_f32_e32 v34, 0xbfb8aa3b, v40
	v_exp_f32_e32 v36, v35
	v_mul_f32_e32 v35, 0xbfb8aa3b, v41
	v_exp_f32_e32 v38, v38
	v_exp_f32_e32 v34, v34
	v_exp_f32_e32 v35, v35
	v_mul_f32_e32 v37, 0xbfb8aa3b, v37
	v_exp_f32_e32 v37, v37
	v_pk_add_f32 v[40:41], v[34:35], 1.0 op_sel_hi:[1,0]
	v_pk_add_f32 v[34:35], v[38:39], 1.0 op_sel_hi:[1,0]
	v_pk_add_f32 v[36:37], v[36:37], 1.0 op_sel_hi:[1,0]
	s_nop 0
	v_rcp_f32_e32 v38, v35
	s_nop 0
	v_fma_f32 v77, -v35, v38, 1.0
	v_fma_f32 v35, v77, v38, v38
	s_nop 0
	v_rcp_f32_e32 v38, v34
	s_nop 0
	v_fma_f32 v77, -v34, v38, 1.0
	v_fma_f32 v34, v77, v38, v38
	v_pk_fma_f32 v[34:35], v[34:35], v[46:47], v[70:71]
	v_rcp_f32_e32 v38, v41
	s_nop 0
	v_fma_f32 v77, -v41, v38, 1.0
	v_fma_f32 v39, v77, v38, v38
	s_nop 0
	v_rcp_f32_e32 v77, v40
	s_nop 0
	v_fma_f32 v79, -v40, v77, 1.0
	v_fma_f32 v38, v79, v77, v77
	v_pk_add_f32 v[40:41], v[74:75], 1.0 op_sel_hi:[1,0]
	s_nop 0
	s_nop 0
	v_rcp_f32_e32 v74, v41
	s_nop 0
	v_fma_f32 v77, -v41, v74, 1.0
	v_fma_f32 v75, v77, v74, v74
	s_nop 0
	v_rcp_f32_e32 v41, v40
	s_nop 0
	v_fma_f32 v77, -v40, v41, 1.0
	v_fma_f32 v74, v77, v41, v41
	s_nop 0
	v_rcp_f32_e32 v40, v37
	s_nop 0
	v_fma_f32 v77, -v37, v40, 1.0
	v_fma_f32 v41, v77, v40, v40
	s_nop 0
	v_rcp_f32_e32 v37, v36
	s_nop 0
	v_fma_f32 v77, -v36, v37, 1.0
	v_fma_f32 v40, v77, v37, v37
	v_pk_fma_f32 v[36:37], v[38:39], v[48:49], v[72:73]
	v_pk_fma_f32 v[38:39], v[74:75], v[42:43], v[66:67]
	v_pk_fma_f32 v[40:41], v[40:41], v[44:45], v[68:69]
	global_store_dwordx4 v[118:119], v[34:37], off offset:512 nt
	global_store_dwordx4 v[118:119], v[38:41], off offset:528 nt
	s_nop 1
	v_mul_f32_e32 v38, v38, v38
	v_fmac_f32_e32 v38, v34, v34
	v_add_f32_e32 v34, v78, v38
	v_mul_f32_e32 v38, v39, v39
	v_fmac_f32_e32 v38, v35, v35
	v_mul_f32_e32 v35, v40, v40
	v_add_f32_e32 v34, v38, v34
	v_fmac_f32_e32 v35, v36, v36
	v_add_f32_e32 v34, v35, v34
	v_mul_f32_e32 v35, v41, v41
	v_fmac_f32_e32 v35, v37, v37
	v_add_f32_e32 v34, v35, v34
	ds_bpermute_b32 v35, v225, v34
	s_waitcnt lgkmcnt(0)
	v_add_f32_e32 v34, v34, v35
	ds_bpermute_b32 v35, v226, v34
	s_and_saveexec_b64 s[2:3], s[42:43]
	s_cbranch_execz .LBB0_793
	v_lshl_add_u64 v[36:37], v[116:117], 2, s[36:37]
	s_waitcnt lgkmcnt(0)
	v_add_f32_e32 v34, v34, v35
	global_atomic_add_f32 v[36:37], v34, off
; #define NTL(p) __builtin_nontemporal_load((const f32x4*)(p))
; #define NTS(v, p) __builtin_nontemporal_store((v), (f32x4*)(p))
; __device__ __forceinline__ float bf_lo(unsigned w) { return __uint_as_float(w << 16); }
; __device__ __forceinline__ float bf_hi(unsigned w) { return __uint_as_float(w & 0xffff0000u); }
; __device__ __forceinline__ float sigmoidf_(float x) { return 1.0f / (1.0f + __expf(-x)); }
;     __device__ __forceinline__ void operator()(AccT& acc, const Unit& u, int wr, int wc, int fr, int fq) const {
;     ...
;         for (int r = 0; r < 8; ++r) { const int ai = r >> 2, m = r & 3; const int row = row0 + ai * 128 + m * 16;
;             if (r < 7) { const int rn = row0 + ((r + 1) >> 2) * 128 + ((r + 1) & 3) * 16; const float* hn = H + (size_t)rn * DM + col0; const bf16_t* pn = ppbase + (((r + 1) >> 2) * 128 + ((r + 1) & 3) * 16) * 256;
;                 hv[(r + 1) & 1][0] = NTL(hn); hv[(r + 1) & 1][1] = NTL(hn + 4); hv[(r + 1) & 1][2] = NTL(hn + 128); hv[(r + 1) & 1][3] = NTL(hn + 132);
;                 pv[(r + 1) & 1][0] = *(const u32x4*)pn; pv[(r + 1) & 1][1] = *(const u32x4*)(pn + 128); rs[(r + 1) & 1] = rss2[rn]; }
;             float* hp = H + (size_t)row * DM + col0; float ss = 0.f; const float rstd = rsqrtf(rs[r & 1] * (1.0f / DM) + 1e-6f);
; #pragma unroll
;             for (int bj = 0; bj < 2; ++bj) { const u32x4 pw = pv[r & 1][bj];
;                 const f32x4 b0 = *(const f32x4*)(bias + col0 + bj * 128), b1 = *(const f32x4*)(bias + col0 + bj * 128 + 4);
;                 const f32x4 p0 = (f32x4){bf_lo(pw.x), bf_hi(pw.x), bf_lo(pw.y), bf_hi(pw.y)}, p1 = (f32x4){bf_lo(pw.z), bf_hi(pw.z), bf_lo(pw.w), bf_hi(pw.w)};
;                 f32x4 g0 = acc[ai][bj][m][0] * rstd + b0, g1 = acc[ai][bj][m][1] * rstd + b1;
; #pragma unroll
;                 for (int j = 0; j < 4; ++j) { g0[j] = sigmoidf_(g0[j]); g1[j] = sigmoidf_(g1[j]); }
;                 const f32x4 v0 = hv[r & 1][2 * bj] + p0 * g0, v1 = hv[r & 1][2 * bj + 1] + p1 * g1;
;                 NTS(v0, hp + bj * 128); NTS(v1, hp + bj * 128 + 4);
; #pragma unroll
;                 for (int j = 0; j < 4; ++j) ss += v0[j] * v0[j] + v1[j] * v1[j]; }
;             ss += __shfl_xor(ss, 16); ss += __shfl_xor(ss, 32);
;             if (fq == 0) unsafeAtomicAdd(rss3 + row, ss); __builtin_amdgcn_sched_barrier(0); }
.LBB0_793:
	s_or_b64 exec, exec, s[2:3]
	v_add_u32_e32 v74, 0xb0, v186
	v_ashrrev_i32_e32 v75, 31, v74
	s_waitcnt lgkmcnt(0)
	v_lshlrev_b64 v[34:35], 12, v[74:75]
	v_lshl_add_u64 v[34:35], s[22:23], 0, v[34:35]
	v_add_co_u32_e32 v42, vcc, 0x16000, v190
	v_lshl_add_u64 v[76:77], v[192:193], 2, v[34:35]
	s_nop 0
	v_addc_co_u32_e32 v43, vcc, 0, v191, vcc
	global_load_dwordx4 v[46:49], v[76:77], off offset:16 nt
	global_load_dwordx4 v[66:69], v[76:77], off nt
	global_load_dwordx4 v[34:37], v[76:77], off offset:528 nt
	global_load_dwordx4 v[38:41], v[76:77], off offset:512 nt
	global_load_dwordx4 v[70:73], v[42:43], off
	s_nop 0
	global_load_dwordx4 v[42:45], v[42:43], off offset:256
	s_nop 0
	global_load_dword v79, v[188:189], off offset:704
	s_waitcnt vmcnt(11)
	v_fmamk_f32 v78, v95, 0x3a800000, v210
	v_cmp_gt_f32_e32 vcc, s30, v78
	v_mul_f32_e32 v80, 0x4b800000, v78
	v_and_b32_e32 v81, 0xffff0000, v88
	v_cndmask_b32_e32 v78, v78, v80, vcc
	v_rsq_f32_e32 v78, v78
	v_lshlrev_b32_e32 v94, 16, v86
	v_and_b32_e32 v95, 0xffff0000, v86
	v_lshlrev_b32_e32 v96, 16, v87
	v_mul_f32_e32 v80, 0x45800000, v78
	v_cndmask_b32_e32 v78, v78, v80, vcc
	v_lshlrev_b32_e32 v80, 16, v88
	v_and_b32_e32 v97, 0xffff0000, v87
	v_lshlrev_b32_e32 v86, 16, v89
	v_and_b32_e32 v87, 0xffff0000, v89
	v_pk_fma_f32 v[26:27], v[26:27], v[78:79], v[244:245] op_sel_hi:[1,0,1]
	v_pk_fma_f32 v[30:31], v[30:31], v[78:79], v[240:241] op_sel_hi:[1,0,1]
	v_mul_f32_e32 v26, 0xbfb8aa3b, v26
	v_mul_f32_e32 v30, 0xbfb8aa3b, v30
	v_pk_fma_f32 v[28:29], v[28:29], v[78:79], v[246:247] op_sel_hi:[1,0,1]
	v_exp_f32_e32 v88, v30
	v_exp_f32_e32 v30, v26
	v_mul_f32_e32 v26, 0xbfb8aa3b, v31
	v_pk_fma_f32 v[32:33], v[32:33], v[78:79], v[242:243] op_sel_hi:[1,0,1]
	v_exp_f32_e32 v89, v26
	v_mul_f32_e32 v26, 0xbfb8aa3b, v27
	v_mul_f32_e32 v27, 0xbfb8aa3b, v28
	v_exp_f32_e32 v31, v26
	v_mul_f32_e32 v26, 0xbfb8aa3b, v32
	v_exp_f32_e32 v28, v27
	v_mul_f32_e32 v27, 0xbfb8aa3b, v33
	v_exp_f32_e32 v26, v26
	v_exp_f32_e32 v27, v27
	v_pk_add_f32 v[30:31], v[30:31], 1.0 op_sel_hi:[1,0]
	v_mul_f32_e32 v29, 0xbfb8aa3b, v29
	v_exp_f32_e32 v29, v29
	v_pk_add_f32 v[32:33], v[26:27], 1.0 op_sel_hi:[1,0]
	v_pk_add_f32 v[26:27], v[88:89], 1.0 op_sel_hi:[1,0]
	v_pk_add_f32 v[28:29], v[28:29], 1.0 op_sel_hi:[1,0]
	s_nop 0
	v_rcp_f32_e32 v88, v27
	s_nop 0
	v_fma_f32 v99, -v27, v88, 1.0
	v_fma_f32 v27, v99, v88, v88
	s_nop 0
	v_rcp_f32_e32 v88, v26
	s_nop 0
	v_fma_f32 v99, -v26, v88, 1.0
	v_fma_f32 v26, v99, v88, v88
	v_pk_fma_f32 v[26:27], v[26:27], v[94:95], v[82:83]
	v_rcp_f32_e32 v88, v33
	s_nop 0
	v_fma_f32 v99, -v33, v88, 1.0
	v_fma_f32 v33, v99, v88, v88
	s_nop 0
	v_rcp_f32_e32 v88, v32
	s_nop 0
	v_fma_f32 v99, -v32, v88, 1.0
	v_fma_f32 v32, v99, v88, v88
	s_nop 0
	v_rcp_f32_e32 v88, v31
	s_nop 0
	v_fma_f32 v99, -v31, v88, 1.0
	v_fma_f32 v31, v99, v88, v88
	s_nop 0
	v_rcp_f32_e32 v88, v30
	s_nop 0
	v_fma_f32 v99, -v30, v88, 1.0
	v_fma_f32 v30, v99, v88, v88
	v_pk_fma_f32 v[30:31], v[30:31], v[80:81], v[62:63]
	v_rcp_f32_e32 v88, v29
	s_nop 0
	v_fma_f32 v99, -v29, v88, 1.0
	v_fma_f32 v89, v99, v88, v88
	s_nop 0
	v_rcp_f32_e32 v29, v28
	s_nop 0
	v_fma_f32 v99, -v28, v29, 1.0
	v_fma_f32 v88, v99, v29, v29
	v_pk_fma_f32 v[28:29], v[32:33], v[96:97], v[84:85]
	v_pk_fma_f32 v[32:33], v[88:89], v[86:87], v[64:65]
	global_store_dwordx4 v[92:93], v[26:29], off nt
	global_store_dwordx4 v[92:93], v[30:33], off offset:16 nt
	s_nop 0
	s_nop 0
	v_mul_f32_e32 v30, v30, v30
	v_fmac_f32_e32 v30, v26, v26
	v_mul_f32_e32 v26, v31, v31
	v_fmac_f32_e32 v26, v27, v27
	v_add_f32_e32 v26, v30, v26
	v_mul_f32_e32 v27, v32, v32
	v_lshlrev_b32_e32 v30, 16, v58
	v_and_b32_e32 v31, 0xffff0000, v58
	v_fmac_f32_e32 v27, v28, v28
	v_add_f32_e32 v26, v27, v26
	v_mul_f32_e32 v27, v33, v33
	v_lshlrev_b32_e32 v32, 16, v59
	v_and_b32_e32 v33, 0xffff0000, v59
	v_fmac_f32_e32 v27, v29, v29
	v_add_f32_e32 v62, v27, v26
	v_lshlrev_b32_e32 v26, 16, v60
	v_and_b32_e32 v27, 0xffff0000, v60
	v_lshlrev_b32_e32 v28, 16, v61
	v_and_b32_e32 v29, 0xffff0000, v61
	v_pk_fma_f32 v[18:19], v[18:19], v[78:79], v[232:233] op_sel_hi:[1,0,1]
	v_pk_fma_f32 v[22:23], v[22:23], v[78:79], v[248:249] op_sel_hi:[1,0,1]
	v_mul_f32_e32 v18, 0xbfb8aa3b, v18
	v_pk_fma_f32 v[20:21], v[20:21], v[78:79], v[234:235] op_sel_hi:[1,0,1]
	v_exp_f32_e32 v58, v18
	v_mul_f32_e32 v18, 0xbfb8aa3b, v23
	v_pk_fma_f32 v[24:25], v[24:25], v[78:79], v[250:251] op_sel_hi:[1,0,1]
	v_exp_f32_e32 v23, v18
	v_mul_f32_e32 v18, 0xbfb8aa3b, v19
	v_mul_f32_e32 v19, 0xbfb8aa3b, v20
	v_mul_f32_e32 v22, 0xbfb8aa3b, v22
	v_exp_f32_e32 v59, v18
	v_mul_f32_e32 v18, 0xbfb8aa3b, v24
	v_exp_f32_e32 v20, v19
	v_mul_f32_e32 v19, 0xbfb8aa3b, v25
	v_exp_f32_e32 v22, v22
	v_exp_f32_e32 v18, v18
	v_exp_f32_e32 v19, v19
	v_mul_f32_e32 v21, 0xbfb8aa3b, v21
	v_exp_f32_e32 v21, v21
	v_pk_add_f32 v[24:25], v[18:19], 1.0 op_sel_hi:[1,0]
	v_pk_add_f32 v[18:19], v[22:23], 1.0 op_sel_hi:[1,0]
	v_pk_add_f32 v[20:21], v[20:21], 1.0 op_sel_hi:[1,0]
	s_nop 0
	v_rcp_f32_e32 v22, v19
	s_nop 0
	v_fma_f32 v61, -v19, v22, 1.0
	v_fma_f32 v19, v61, v22, v22
	s_nop 0
	v_rcp_f32_e32 v22, v18
	s_nop 0
	v_fma_f32 v61, -v18, v22, 1.0
	v_fma_f32 v18, v61, v22, v22
	v_pk_fma_f32 v[18:19], v[18:19], v[30:31], v[54:55]
	v_rcp_f32_e32 v22, v25
	s_nop 0
	v_fma_f32 v61, -v25, v22, 1.0
	v_fma_f32 v23, v61, v22, v22
	s_nop 0
	v_rcp_f32_e32 v61, v24
	s_nop 0
	v_fma_f32 v63, -v24, v61, 1.0
	v_fma_f32 v22, v63, v61, v61
	v_pk_add_f32 v[24:25], v[58:59], 1.0 op_sel_hi:[1,0]
	s_nop 0
	s_nop 0
	v_rcp_f32_e32 v58, v25
	s_nop 0
	v_fma_f32 v61, -v25, v58, 1.0
	v_fma_f32 v59, v61, v58, v58
	s_nop 0
	v_rcp_f32_e32 v25, v24
	s_nop 0
	v_fma_f32 v61, -v24, v25, 1.0
	v_fma_f32 v58, v61, v25, v25
	s_nop 0
	v_rcp_f32_e32 v24, v21
	s_nop 0
	v_fma_f32 v61, -v21, v24, 1.0
	v_fma_f32 v25, v61, v24, v24
	s_nop 0
	v_rcp_f32_e32 v21, v20
	s_nop 0
	v_fma_f32 v61, -v20, v21, 1.0
	v_fma_f32 v24, v61, v21, v21
	v_pk_fma_f32 v[20:21], v[22:23], v[32:33], v[56:57]
	v_pk_fma_f32 v[22:23], v[58:59], v[26:27], v[50:51]
	v_pk_fma_f32 v[24:25], v[24:25], v[28:29], v[52:53]
	global_store_dwordx4 v[92:93], v[18:21], off offset:512 nt
	global_store_dwordx4 v[92:93], v[22:25], off offset:528 nt
	s_nop 1
	v_mul_f32_e32 v22, v22, v22
	v_fmac_f32_e32 v22, v18, v18
	v_add_f32_e32 v18, v62, v22
	v_mul_f32_e32 v22, v23, v23
	v_fmac_f32_e32 v22, v19, v19
	v_mul_f32_e32 v19, v24, v24
	v_add_f32_e32 v18, v22, v18
	v_fmac_f32_e32 v19, v20, v20
	v_add_f32_e32 v18, v19, v18
	v_mul_f32_e32 v19, v25, v25
	v_fmac_f32_e32 v19, v21, v21
	v_add_f32_e32 v18, v19, v18
	ds_bpermute_b32 v19, v225, v18
	s_waitcnt lgkmcnt(0)
	v_add_f32_e32 v18, v18, v19
	ds_bpermute_b32 v19, v226, v18
	s_and_saveexec_b64 s[2:3], s[42:43]
	s_cbranch_execz .LBB0_795
	v_lshl_add_u64 v[20:21], v[90:91], 2, s[36:37]
	s_waitcnt lgkmcnt(0)
	v_add_f32_e32 v18, v18, v19
	global_atomic_add_f32 v[20:21], v18, off
; #define NTS(v, p) __builtin_nontemporal_store((v), (f32x4*)(p))
; __device__ __forceinline__ float bf_lo(unsigned w) { return __uint_as_float(w << 16); }
; __device__ __forceinline__ float bf_hi(unsigned w) { return __uint_as_float(w & 0xffff0000u); }
; __device__ __forceinline__ float sigmoidf_(float x) { return 1.0f / (1.0f + __expf(-x)); }
;     __device__ __forceinline__ void operator()(AccT& acc, const Unit& u, int wr, int wc, int fr, int fq) const {
;     ...
;             float* hp = H + (size_t)row * DM + col0; float ss = 0.f; const float rstd = rsqrtf(rs[r & 1] * (1.0f / DM) + 1e-6f);
; #pragma unroll
;             for (int bj = 0; bj < 2; ++bj) { const u32x4 pw = pv[r & 1][bj];
;                 const f32x4 b0 = *(const f32x4*)(bias + col0 + bj * 128), b1 = *(const f32x4*)(bias + col0 + bj * 128 + 4);
;                 const f32x4 p0 = (f32x4){bf_lo(pw.x), bf_hi(pw.x), bf_lo(pw.y), bf_hi(pw.y)}, p1 = (f32x4){bf_lo(pw.z), bf_hi(pw.z), bf_lo(pw.w), bf_hi(pw.w)};
;                 f32x4 g0 = acc[ai][bj][m][0] * rstd + b0, g1 = acc[ai][bj][m][1] * rstd + b1;
; #pragma unroll
;                 for (int j = 0; j < 4; ++j) { g0[j] = sigmoidf_(g0[j]); g1[j] = sigmoidf_(g1[j]); }
;                 const f32x4 v0 = hv[r & 1][2 * bj] + p0 * g0, v1 = hv[r & 1][2 * bj + 1] + p1 * g1;
;                 NTS(v0, hp + bj * 128); NTS(v1, hp + bj * 128 + 4);
; #pragma unroll
;                 for (int j = 0; j < 4; ++j) ss += v0[j] * v0[j] + v1[j] * v1[j]; }
;             ss += __shfl_xor(ss, 16); ss += __shfl_xor(ss, 32);
;             if (fq == 0) unsafeAtomicAdd(rss3 + row, ss); __builtin_amdgcn_sched_barrier(0); }
.LBB0_795:
	s_or_b64 exec, exec, s[2:3]
	s_waitcnt vmcnt(4)
	v_fmamk_f32 v18, v79, 0x3a800000, v210
	v_cmp_gt_f32_e32 vcc, s30, v18
	s_waitcnt lgkmcnt(0)
	v_mul_f32_e32 v19, 0x4b800000, v18
	v_lshlrev_b32_e32 v22, 16, v70
	v_cndmask_b32_e32 v18, v18, v19, vcc
	v_rsq_f32_e32 v18, v18
	v_and_b32_e32 v23, 0xffff0000, v70
	v_lshlrev_b32_e32 v24, 16, v71
	v_and_b32_e32 v25, 0xffff0000, v71
	v_mul_f32_e32 v19, 0x45800000, v18
	v_cndmask_b32_e32 v18, v18, v19, vcc
	v_lshlrev_b32_e32 v20, 16, v72
	v_and_b32_e32 v21, 0xffff0000, v72
	v_lshlrev_b32_e32 v26, 16, v73
	v_and_b32_e32 v27, 0xffff0000, v73
	v_pk_fma_f32 v[10:11], v[10:11], v[18:19], v[244:245] op_sel_hi:[1,0,1]
	v_pk_fma_f32 v[14:15], v[14:15], v[18:19], v[240:241] op_sel_hi:[1,0,1]
	v_mul_f32_e32 v10, 0xbfb8aa3b, v10
	v_pk_fma_f32 v[32:33], v[16:17], v[18:19], v[242:243] op_sel_hi:[1,0,1]
	v_pk_fma_f32 v[16:17], v[12:13], v[18:19], v[246:247] op_sel_hi:[1,0,1]
	v_mul_f32_e32 v12, 0xbfb8aa3b, v14
	v_exp_f32_e32 v14, v10
	v_mul_f32_e32 v10, 0xbfb8aa3b, v15
	v_exp_f32_e32 v13, v10
	v_mul_f32_e32 v10, 0xbfb8aa3b, v11
	v_mul_f32_e32 v11, 0xbfb8aa3b, v16
	v_exp_f32_e32 v15, v10
	v_mul_f32_e32 v10, 0xbfb8aa3b, v32
	v_exp_f32_e32 v16, v11
	v_mul_f32_e32 v11, 0xbfb8aa3b, v33
	v_exp_f32_e32 v12, v12
	v_exp_f32_e32 v10, v10
	v_exp_f32_e32 v11, v11
	v_pk_add_f32 v[14:15], v[14:15], 1.0 op_sel_hi:[1,0]
	v_mul_f32_e32 v17, 0xbfb8aa3b, v17
	v_exp_f32_e32 v17, v17
	v_pk_add_f32 v[28:29], v[10:11], 1.0 op_sel_hi:[1,0]
	v_pk_add_f32 v[10:11], v[12:13], 1.0 op_sel_hi:[1,0]
	v_pk_add_f32 v[16:17], v[16:17], 1.0 op_sel_hi:[1,0]
	s_nop 0
	v_rcp_f32_e32 v12, v11
	s_nop 0
	v_fma_f32 v30, -v11, v12, 1.0
	v_fma_f32 v11, v30, v12, v12
	s_nop 0
	v_rcp_f32_e32 v12, v10
	s_nop 0
	v_fma_f32 v30, -v10, v12, 1.0
	v_fma_f32 v10, v30, v12, v12
	v_pk_fma_f32 v[10:11], v[10:11], v[22:23], v[66:67]
	v_rcp_f32_e32 v12, v29
	s_nop 0
	v_fma_f32 v30, -v29, v12, 1.0
	v_fma_f32 v13, v30, v12, v12
	s_nop 0
	v_rcp_f32_e32 v30, v28
	s_nop 0
	v_fma_f32 v31, -v28, v30, 1.0
	v_fma_f32 v12, v31, v30, v30
	v_pk_fma_f32 v[12:13], v[12:13], v[24:25], v[68:69]
	v_rcp_f32_e32 v19, v15
	s_nop 0
	v_fma_f32 v30, -v15, v19, 1.0
	v_fma_f32 v15, v30, v19, v19
	s_nop 0
	v_rcp_f32_e32 v19, v14
	s_nop 0
	v_fma_f32 v30, -v14, v19, 1.0
	v_fma_f32 v14, v30, v19, v19
	v_pk_fma_f32 v[14:15], v[14:15], v[20:21], v[46:47]
	v_rcp_f32_e32 v19, v17
	s_nop 0
	v_fma_f32 v30, -v17, v19, 1.0
	v_fma_f32 v17, v30, v19, v19
	s_nop 0
	v_rcp_f32_e32 v19, v16
	s_nop 0
	v_fma_f32 v30, -v16, v19, 1.0
	v_fma_f32 v16, v30, v19, v19
	v_pk_fma_f32 v[16:17], v[16:17], v[26:27], v[48:49]
	global_store_dwordx4 v[76:77], v[10:13], off nt
	global_store_dwordx4 v[76:77], v[14:17], off offset:16 nt
	s_nop 0
	s_nop 0
	v_mul_f32_e32 v14, v14, v14
	v_fmac_f32_e32 v14, v10, v10
	v_mul_f32_e32 v10, v15, v15
	v_fmac_f32_e32 v10, v11, v11
	v_mul_f32_e32 v11, v16, v16
	v_add_f32_e32 v10, v14, v10
	v_fmac_f32_e32 v11, v12, v12
	v_add_f32_e32 v10, v11, v10
	v_mul_f32_e32 v11, v17, v17
	v_fmac_f32_e32 v11, v13, v13
	v_add_f32_e32 v19, v11, v10
	v_lshlrev_b32_e32 v14, 16, v42
	v_and_b32_e32 v15, 0xffff0000, v42
	v_lshlrev_b32_e32 v16, 16, v43
	v_and_b32_e32 v17, 0xffff0000, v43
	v_lshlrev_b32_e32 v10, 16, v44
	v_and_b32_e32 v11, 0xffff0000, v44
	v_lshlrev_b32_e32 v12, 16, v45
	v_and_b32_e32 v13, 0xffff0000, v45
	v_pk_fma_f32 v[2:3], v[2:3], v[18:19], v[232:233] op_sel_hi:[1,0,1]
	v_pk_fma_f32 v[6:7], v[6:7], v[18:19], v[248:249] op_sel_hi:[1,0,1]
	v_mul_f32_e32 v2, 0xbfb8aa3b, v2
	v_pk_fma_f32 v[4:5], v[4:5], v[18:19], v[234:235] op_sel_hi:[1,0,1]
	v_exp_f32_e32 v20, v2
	v_mul_f32_e32 v2, 0xbfb8aa3b, v7
	v_pk_fma_f32 v[8:9], v[8:9], v[18:19], v[250:251] op_sel_hi:[1,0,1]
	v_exp_f32_e32 v7, v2
	v_mul_f32_e32 v2, 0xbfb8aa3b, v3
	v_mul_f32_e32 v3, 0xbfb8aa3b, v4
	v_mul_f32_e32 v6, 0xbfb8aa3b, v6
	v_exp_f32_e32 v21, v2
	v_mul_f32_e32 v2, 0xbfb8aa3b, v8
	v_exp_f32_e32 v4, v3
	v_mul_f32_e32 v3, 0xbfb8aa3b, v9
	v_exp_f32_e32 v6, v6
	v_exp_f32_e32 v2, v2
	v_exp_f32_e32 v3, v3
	v_mul_f32_e32 v5, 0xbfb8aa3b, v5
	v_exp_f32_e32 v5, v5
	v_pk_add_f32 v[8:9], v[2:3], 1.0 op_sel_hi:[1,0]
	v_pk_add_f32 v[2:3], v[6:7], 1.0 op_sel_hi:[1,0]
	v_pk_add_f32 v[4:5], v[4:5], 1.0 op_sel_hi:[1,0]
	s_nop 0
	v_rcp_f32_e32 v6, v3
	s_nop 0
	v_fma_f32 v22, -v3, v6, 1.0
	v_fma_f32 v3, v22, v6, v6
	s_nop 0
	v_rcp_f32_e32 v6, v2
	s_nop 0
	v_fma_f32 v22, -v2, v6, 1.0
	v_fma_f32 v2, v22, v6, v6
	v_pk_fma_f32 v[2:3], v[2:3], v[14:15], v[38:39]
	v_rcp_f32_e32 v6, v9
	s_nop 0
	v_fma_f32 v22, -v9, v6, 1.0
	v_fma_f32 v7, v22, v6, v6
	s_nop 0
	v_rcp_f32_e32 v22, v8
	s_nop 0
	v_fma_f32 v23, -v8, v22, 1.0
	v_fma_f32 v6, v23, v22, v22
	v_pk_add_f32 v[8:9], v[20:21], 1.0 op_sel_hi:[1,0]
	s_nop 0
	s_nop 0
	v_rcp_f32_e32 v18, v9
	s_nop 0
	v_fma_f32 v22, -v9, v18, 1.0
	v_fma_f32 v21, v22, v18, v18
	s_nop 0
	v_rcp_f32_e32 v9, v8
	s_nop 0
	v_fma_f32 v22, -v8, v9, 1.0
	v_fma_f32 v20, v22, v9, v9
	s_nop 0
	v_rcp_f32_e32 v8, v5
	s_nop 0
	v_fma_f32 v22, -v5, v8, 1.0
	v_fma_f32 v9, v22, v8, v8
	s_nop 0
	v_rcp_f32_e32 v5, v4
	s_nop 0
	v_fma_f32 v22, -v4, v5, 1.0
	v_fma_f32 v8, v22, v5, v5
	v_pk_fma_f32 v[4:5], v[6:7], v[16:17], v[40:41]
	v_pk_fma_f32 v[6:7], v[20:21], v[10:11], v[34:35]
	v_pk_fma_f32 v[8:9], v[8:9], v[12:13], v[36:37]
	global_store_dwordx4 v[76:77], v[2:5], off offset:512 nt
	global_store_dwordx4 v[76:77], v[6:9], off offset:528 nt
	s_nop 1
	v_mul_f32_e32 v6, v6, v6
	v_fmac_f32_e32 v6, v2, v2
	v_add_f32_e32 v2, v19, v6
	v_mul_f32_e32 v6, v7, v7
	v_fmac_f32_e32 v6, v3, v3
	v_mul_f32_e32 v3, v8, v8
	v_add_f32_e32 v2, v6, v2
	v_fmac_f32_e32 v3, v4, v4
	v_add_f32_e32 v2, v3, v2
	v_mul_f32_e32 v3, v9, v9
	v_fmac_f32_e32 v3, v5, v5
	v_add_f32_e32 v2, v3, v2
	ds_bpermute_b32 v3, v225, v2
	s_waitcnt lgkmcnt(0)
	v_add_f32_e32 v2, v2, v3
	ds_bpermute_b32 v3, v226, v2
	s_and_saveexec_b64 s[2:3], s[42:43]
	s_cbranch_execz .LBB0_766
	v_lshl_add_u64 v[4:5], v[74:75], 2, s[36:37]
	s_waitcnt lgkmcnt(0)
	v_add_f32_e32 v2, v2, v3
	global_atomic_add_f32 v[4:5], v2, off
	s_branch .LBB0_766
